# GEMM K loops: loop-carried scalar updates and exit compare moved in front of the iteration's last barrier (back-edge rotation), 14 loops
# baseline (speedup 1.0000x reference)
; #define PG8_STAGE(bufoff, gbase, voff) do { _Pragma("unroll") for (int _i = 0; _i < 2; ++_i) \
;         __builtin_amdgcn_global_load_lds((const unsigned*)((const char*)(gbase) + (voff)[_i]), (LAS unsigned*)(lds + (bufoff) + ldsw + _i * 8192), 16, 0, 0); } while (0)
; #define PG8_LDA(dst, b, h) do { _Pragma("unroll") for (int m = 0; m < 4; ++m) _Pragma("unroll") for (int k = 0; k < 2; ++k) dst[m][k] = *(const LAS bf16x8*)(lds + PG8_SA(b, h) + aoff + m * 2048 + k * 1024); } while (0)
; #define PG8_LDB(dst, b, h) do { _Pragma("unroll") for (int n = 0; n < 2; ++n) _Pragma("unroll") for (int k = 0; k < 2; ++k) dst[n][k] = *(const LAS bf16x8*)(lds + PG8_SB(b, h) + boff + n * 2048 + k * 1024); } while (0)
; #define PG8_MMA(ai, bj, At, Bt) do { __builtin_amdgcn_s_setprio(1); _Pragma("unroll") for (int m = 0; m < 4; ++m) _Pragma("unroll") for (int n = 0; n < 2; ++n) _Pragma("unroll") for (int k = 0; k < 2; ++k) \
;         acc[ai][bj][m][n] = __builtin_amdgcn_mfma_f32_16x16x32_bf16(Bt[n][k], At[m][k], acc[ai][bj][m][n], 0, 0, 0); __builtin_amdgcn_s_setprio(0); } while (0)
; #define PG8_WAIT_V(n) asm volatile("s_waitcnt vmcnt(" #n ")" ::: "memory")
; #define PG8_WAIT_L(n) asm volatile("s_waitcnt lgkmcnt(" #n ")" ::: "memory")
; #define PG8_BAR __builtin_amdgcn_s_barrier()
; #define PG8_SCHED __builtin_amdgcn_sched_barrier(0)
; template <class Epi>
; DI void gemm_phase(int wv, LAS unsigned char* lds, const Gemm g, const StaticOrder& S, const Epi& E) {
;     ...
;         for (int t = 0; t < nt; t += 2) {
;             const bool last = (t == nt - 2);
;             const char* a1 = cA + (size_t)(t + 1) * kstep;
;             const char* a2 = last ? nA : cA + (size_t)(t + 2) * kstep; const char* b2 = last ? nB : cB + (size_t)(t + 2) * kstep;
;             const char* a3 = a2 + kstep; const char* b3 = b2 + kstep;
;             PG8_LDB(B0, 0, 0); PG8_LDB(B1, 0, 1); PG8_SCHED; PG8_LDA(At, 0, 0); PG8_STAGE(PG8_SA(1, 1), a1 + hA, voffA);
;             PG8_WAIT_V(8); PG8_WAIT_L(0); PG8_BAR; PG8_MMA(0, 0, At, B0); PG8_MMA(0, 1, At, B1); PG8_BAR; PG8_SCHED;
;             PG8_LDA(At, 0, 1); PG8_STAGE(PG8_SB(0, 0), b2, voffB); PG8_STAGE(PG8_SB(0, 1), b2 + hB, voffB); PG8_STAGE(PG8_SA(0, 0), a2, voffA);
.LBB0_377:
	ds_read_b128 v[150:153], v147
	ds_read_b128 v[154:157], v147 offset:1024
	ds_read_b128 v[158:161], v147 offset:2048
	ds_read_b128 v[162:165], v147 offset:3072
	ds_read_b128 v[166:169], v148
	ds_read_b128 v[170:173], v148 offset:1024
	ds_read_b128 v[174:177], v148 offset:2048
	ds_read_b128 v[178:181], v148 offset:3072
	s_add_u32 s26, s24, 0xfffc0080
	s_addc_u32 s27, s25, -1
	s_cmp_eq_u32 s58, 12
	s_cselect_b32 s29, s17, s27
	s_cselect_b32 s28, s54, s26
	s_cselect_b32 s27, s15, s57
	s_cselect_b32 s26, s55, s56
	v_lshl_add_u64 v[214:215], s[24:25], 0, v[138:139]
	s_add_i32 m0, s23, 0xc000
	ds_read_b128 v[182:185], v149
	ds_read_b128 v[186:189], v149 offset:1024
	ds_read_b128 v[190:193], v149 offset:2048
	ds_read_b128 v[194:197], v149 offset:3072
	ds_read_b128 v[198:201], v149 offset:4096
	ds_read_b128 v[202:205], v149 offset:5120
	ds_read_b128 v[206:209], v149 offset:6144
	ds_read_b128 v[210:213], v149 offset:7168
	global_load_lds_dwordx4 v[214:215], off
	v_lshl_add_u64 v[214:215], s[24:25], 0, v[136:137]
	s_add_i32 m0, s23, 0xe000
	s_nop 0
	global_load_lds_dwordx4 v[214:215], off
	s_waitcnt vmcnt(8)
	s_waitcnt lgkmcnt(0)
	s_barrier
	s_setprio 1
	s_waitcnt lgkmcnt(0)
	v_mfma_f32_16x16x32_bf16 v[124:127], v[150:153], v[182:185], v[124:127]
	v_mfma_f32_16x16x32_bf16 v[116:119], v[158:161], v[182:185], v[116:119]
	v_mfma_f32_16x16x32_bf16 v[108:111], v[150:153], v[190:193], v[108:111]
	v_mfma_f32_16x16x32_bf16 v[100:103], v[158:161], v[190:193], v[100:103]
	v_mfma_f32_16x16x32_bf16 v[92:95], v[150:153], v[198:201], v[92:95]
	v_mfma_f32_16x16x32_bf16 v[84:87], v[158:161], v[198:201], v[84:87]
	v_mfma_f32_16x16x32_bf16 v[76:79], v[150:153], v[206:209], v[76:79]
	v_mfma_f32_16x16x32_bf16 v[68:71], v[158:161], v[206:209], v[68:71]
	v_mfma_f32_16x16x32_bf16 v[124:127], v[154:157], v[186:189], v[124:127]
	v_mfma_f32_16x16x32_bf16 v[116:119], v[162:165], v[186:189], v[116:119]
	v_mfma_f32_16x16x32_bf16 v[108:111], v[154:157], v[194:197], v[108:111]
	v_mfma_f32_16x16x32_bf16 v[100:103], v[162:165], v[194:197], v[100:103]
	v_mfma_f32_16x16x32_bf16 v[92:95], v[154:157], v[202:205], v[92:95]
	v_mfma_f32_16x16x32_bf16 v[84:87], v[162:165], v[202:205], v[84:87]
	v_mfma_f32_16x16x32_bf16 v[76:79], v[154:157], v[210:213], v[76:79]
	v_mfma_f32_16x16x32_bf16 v[68:71], v[162:165], v[210:213], v[68:71]
	s_setprio 0
	s_setprio 1
	v_mfma_f32_16x16x32_bf16 v[120:123], v[166:169], v[182:185], v[120:123]
	v_mfma_f32_16x16x32_bf16 v[112:115], v[174:177], v[182:185], v[112:115]
	v_mfma_f32_16x16x32_bf16 v[104:107], v[166:169], v[190:193], v[104:107]
	v_mfma_f32_16x16x32_bf16 v[96:99], v[174:177], v[190:193], v[96:99]
	v_mfma_f32_16x16x32_bf16 v[88:91], v[166:169], v[198:201], v[88:91]
	v_mfma_f32_16x16x32_bf16 v[80:83], v[174:177], v[198:201], v[80:83]
	v_mfma_f32_16x16x32_bf16 v[72:75], v[166:169], v[206:209], v[72:75]
	v_mfma_f32_16x16x32_bf16 v[64:67], v[174:177], v[206:209], v[64:67]
	v_mfma_f32_16x16x32_bf16 v[120:123], v[170:173], v[186:189], v[120:123]
	v_mfma_f32_16x16x32_bf16 v[112:115], v[178:181], v[186:189], v[112:115]
	v_mfma_f32_16x16x32_bf16 v[104:107], v[170:173], v[194:197], v[104:107]
	v_mfma_f32_16x16x32_bf16 v[96:99], v[178:181], v[194:197], v[96:99]
	v_mfma_f32_16x16x32_bf16 v[88:91], v[170:173], v[202:205], v[88:91]
	v_mfma_f32_16x16x32_bf16 v[80:83], v[178:181], v[202:205], v[80:83]
	v_mfma_f32_16x16x32_bf16 v[72:75], v[170:173], v[210:213], v[72:75]
	v_mfma_f32_16x16x32_bf16 v[64:67], v[178:181], v[210:213], v[64:67]
	s_setprio 0
	s_barrier
	s_add_i32 s59, s46, s34
	v_lshl_add_u64 v[214:215], s[26:27], 0, v[132:133]
	s_mov_b32 m0, s59
	ds_read_b128 v[182:185], v149 offset:16384
	ds_read_b128 v[186:189], v149 offset:17408
	ds_read_b128 v[190:193], v149 offset:18432
	ds_read_b128 v[194:197], v149 offset:19456
	ds_read_b128 v[198:201], v149 offset:20480
	ds_read_b128 v[202:205], v149 offset:21504
	ds_read_b128 v[206:209], v149 offset:22528
	ds_read_b128 v[210:213], v149 offset:23552
	global_load_lds_dwordx4 v[214:215], off
	s_add_i32 m0, s59, 0x2000
	s_add_u32 s60, s26, 0x40000
	v_lshl_add_u64 v[216:217], s[26:27], 0, v[128:129]
	s_addc_u32 s61, s27, 0
	s_add_i32 s59, s47, s34
	global_load_lds_dwordx4 v[216:217], off
	v_lshl_add_u64 v[218:219], s[60:61], 0, v[132:133]
	s_mov_b32 m0, s59
	v_lshl_add_u64 v[220:221], s[28:29], 0, v[130:131]
	global_load_lds_dwordx4 v[218:219], off
	v_lshl_add_u64 v[218:219], s[60:61], 0, v[128:129]
	s_add_i32 m0, s59, 0x2000
	s_nop 0
	global_load_lds_dwordx4 v[218:219], off
	v_lshl_add_u64 v[218:219], s[28:29], 0, v[134:135]
	s_mov_b32 m0, s23
	s_nop 0
	global_load_lds_dwordx4 v[218:219], off
	s_mov_b32 m0, s37
	s_nop 0
	global_load_lds_dwordx4 v[220:221], off
	s_waitcnt vmcnt(8)
	s_waitcnt lgkmcnt(0)
	s_barrier
; #define PG8_STAGE(bufoff, gbase, voff) do { _Pragma("unroll") for (int _i = 0; _i < 2; ++_i) \
;         __builtin_amdgcn_global_load_lds((const unsigned*)((const char*)(gbase) + (voff)[_i]), (LAS unsigned*)(lds + (bufoff) + ldsw + _i * 8192), 16, 0, 0); } while (0)
; #define PG8_LDA(dst, b, h) do { _Pragma("unroll") for (int m = 0; m < 4; ++m) _Pragma("unroll") for (int k = 0; k < 2; ++k) dst[m][k] = *(const LAS bf16x8*)(lds + PG8_SA(b, h) + aoff + m * 2048 + k * 1024); } while (0)
; #define PG8_LDB(dst, b, h) do { _Pragma("unroll") for (int n = 0; n < 2; ++n) _Pragma("unroll") for (int k = 0; k < 2; ++k) dst[n][k] = *(const LAS bf16x8*)(lds + PG8_SB(b, h) + boff + n * 2048 + k * 1024); } while (0)
; #define PG8_MMA(ai, bj, At, Bt) do { __builtin_amdgcn_s_setprio(1); _Pragma("unroll") for (int m = 0; m < 4; ++m) _Pragma("unroll") for (int n = 0; n < 2; ++n) _Pragma("unroll") for (int k = 0; k < 2; ++k) \
;         acc[ai][bj][m][n] = __builtin_amdgcn_mfma_f32_16x16x32_bf16(Bt[n][k], At[m][k], acc[ai][bj][m][n], 0, 0, 0); __builtin_amdgcn_s_setprio(0); } while (0)
; #define PG8_WAIT_V(n) asm volatile("s_waitcnt vmcnt(" #n ")" ::: "memory")
; #define PG8_WAIT_L(n) asm volatile("s_waitcnt lgkmcnt(" #n ")" ::: "memory")
; #define PG8_BAR __builtin_amdgcn_s_barrier()
; #define PG8_SCHED __builtin_amdgcn_sched_barrier(0)
; template <class Epi>
; DI void gemm_phase(int wv, LAS unsigned char* lds, const Gemm g, const StaticOrder& S, const Epi& E) {
;     ...
;             PG8_WAIT_V(8); PG8_WAIT_L(0); PG8_BAR; PG8_MMA(1, 0, At, B0); PG8_MMA(1, 1, At, B1); PG8_BAR; PG8_SCHED;
;             PG8_LDB(B0, 1, 0); PG8_LDB(B1, 1, 1); PG8_SCHED; PG8_LDA(At, 1, 0); PG8_STAGE(PG8_SA(0, 1), a2 + hA, voffA);
;             PG8_WAIT_V(8); PG8_WAIT_L(0); PG8_BAR; PG8_MMA(0, 0, At, B0); PG8_MMA(0, 1, At, B1); PG8_BAR; PG8_SCHED;
	s_setprio 1
	s_waitcnt lgkmcnt(0)
	v_mfma_f32_16x16x32_bf16 v[60:63], v[150:153], v[182:185], v[60:63]
	v_mfma_f32_16x16x32_bf16 v[52:55], v[158:161], v[182:185], v[52:55]
	v_mfma_f32_16x16x32_bf16 v[44:47], v[150:153], v[190:193], v[44:47]
	v_mfma_f32_16x16x32_bf16 v[36:39], v[158:161], v[190:193], v[36:39]
	v_mfma_f32_16x16x32_bf16 v[28:31], v[150:153], v[198:201], v[28:31]
	v_mfma_f32_16x16x32_bf16 v[20:23], v[158:161], v[198:201], v[20:23]
	v_mfma_f32_16x16x32_bf16 v[12:15], v[150:153], v[206:209], v[12:15]
	v_mfma_f32_16x16x32_bf16 v[4:7], v[158:161], v[206:209], v[4:7]
	v_mfma_f32_16x16x32_bf16 v[60:63], v[154:157], v[186:189], v[60:63]
	v_mfma_f32_16x16x32_bf16 v[52:55], v[162:165], v[186:189], v[52:55]
	v_mfma_f32_16x16x32_bf16 v[44:47], v[154:157], v[194:197], v[44:47]
	v_mfma_f32_16x16x32_bf16 v[36:39], v[162:165], v[194:197], v[36:39]
	v_mfma_f32_16x16x32_bf16 v[28:31], v[154:157], v[202:205], v[28:31]
	v_mfma_f32_16x16x32_bf16 v[20:23], v[162:165], v[202:205], v[20:23]
	v_mfma_f32_16x16x32_bf16 v[12:15], v[154:157], v[210:213], v[12:15]
	v_mfma_f32_16x16x32_bf16 v[4:7], v[162:165], v[210:213], v[4:7]
	s_setprio 0
	s_setprio 1
	v_mfma_f32_16x16x32_bf16 v[56:59], v[166:169], v[182:185], v[56:59]
	v_mfma_f32_16x16x32_bf16 v[48:51], v[174:177], v[182:185], v[48:51]
	v_mfma_f32_16x16x32_bf16 v[40:43], v[166:169], v[190:193], v[40:43]
	v_mfma_f32_16x16x32_bf16 v[32:35], v[174:177], v[190:193], v[32:35]
	v_mfma_f32_16x16x32_bf16 v[24:27], v[166:169], v[198:201], v[24:27]
	v_mfma_f32_16x16x32_bf16 v[16:19], v[174:177], v[198:201], v[16:19]
	v_mfma_f32_16x16x32_bf16 v[8:11], v[166:169], v[206:209], v[8:11]
	v_mfma_f32_16x16x32_bf16 v[0:3], v[174:177], v[206:209], v[0:3]
	v_mfma_f32_16x16x32_bf16 v[56:59], v[170:173], v[186:189], v[56:59]
	v_mfma_f32_16x16x32_bf16 v[48:51], v[178:181], v[186:189], v[48:51]
	v_mfma_f32_16x16x32_bf16 v[40:43], v[170:173], v[194:197], v[40:43]
	v_mfma_f32_16x16x32_bf16 v[32:35], v[178:181], v[194:197], v[32:35]
	v_mfma_f32_16x16x32_bf16 v[24:27], v[170:173], v[202:205], v[24:27]
	v_mfma_f32_16x16x32_bf16 v[16:19], v[178:181], v[202:205], v[16:19]
	v_mfma_f32_16x16x32_bf16 v[8:11], v[170:173], v[210:213], v[8:11]
	v_mfma_f32_16x16x32_bf16 v[0:3], v[178:181], v[210:213], v[0:3]
	s_setprio 0
	s_barrier
	s_add_i32 s59, 0, 0x18000
	s_add_i32 s60, 0, 0x1c000
	v_add_u32_e32 v162, s59, v146
	v_add_u32_e32 v178, s60, v146
	ds_read_b128 v[150:153], v162
	ds_read_b128 v[154:157], v162 offset:1024
	ds_read_b128 v[158:161], v162 offset:2048
	ds_read_b128 v[162:165], v162 offset:3072
	ds_read_b128 v[166:169], v178
	ds_read_b128 v[170:173], v178 offset:1024
	ds_read_b128 v[174:177], v178 offset:2048
	ds_read_b128 v[178:181], v178 offset:3072
	s_add_u32 s28, s28, 0x40000
	s_addc_u32 s29, s29, 0
	s_mov_b32 m0, s38
	v_lshl_add_u64 v[222:223], s[28:29], 0, v[134:135]
	ds_read_b128 v[182:185], v149 offset:32768
	ds_read_b128 v[186:189], v149 offset:33792
	ds_read_b128 v[190:193], v149 offset:34816
	ds_read_b128 v[194:197], v149 offset:35840
	ds_read_b128 v[198:201], v149 offset:36864
	ds_read_b128 v[202:205], v149 offset:37888
	ds_read_b128 v[206:209], v149 offset:38912
	ds_read_b128 v[210:213], v149 offset:39936
	global_load_lds_dwordx4 v[222:223], off
	v_lshl_add_u64 v[222:223], s[28:29], 0, v[130:131]
	s_mov_b32 m0, s39
	s_nop 0
	global_load_lds_dwordx4 v[222:223], off
	s_waitcnt vmcnt(8)
	s_waitcnt lgkmcnt(0)
	s_barrier
	s_setprio 1
	s_waitcnt lgkmcnt(0)
	v_mfma_f32_16x16x32_bf16 v[124:127], v[150:153], v[182:185], v[124:127]
	v_mfma_f32_16x16x32_bf16 v[116:119], v[158:161], v[182:185], v[116:119]
	v_mfma_f32_16x16x32_bf16 v[108:111], v[150:153], v[190:193], v[108:111]
	v_mfma_f32_16x16x32_bf16 v[100:103], v[158:161], v[190:193], v[100:103]
	v_mfma_f32_16x16x32_bf16 v[92:95], v[150:153], v[198:201], v[92:95]
	v_mfma_f32_16x16x32_bf16 v[84:87], v[158:161], v[198:201], v[84:87]
	v_mfma_f32_16x16x32_bf16 v[76:79], v[150:153], v[206:209], v[76:79]
	v_mfma_f32_16x16x32_bf16 v[68:71], v[158:161], v[206:209], v[68:71]
	v_mfma_f32_16x16x32_bf16 v[124:127], v[154:157], v[186:189], v[124:127]
	v_mfma_f32_16x16x32_bf16 v[116:119], v[162:165], v[186:189], v[116:119]
	v_mfma_f32_16x16x32_bf16 v[108:111], v[154:157], v[194:197], v[108:111]
	v_mfma_f32_16x16x32_bf16 v[100:103], v[162:165], v[194:197], v[100:103]
	v_mfma_f32_16x16x32_bf16 v[92:95], v[154:157], v[202:205], v[92:95]
	v_mfma_f32_16x16x32_bf16 v[84:87], v[162:165], v[202:205], v[84:87]
	v_mfma_f32_16x16x32_bf16 v[76:79], v[154:157], v[210:213], v[76:79]
	v_mfma_f32_16x16x32_bf16 v[68:71], v[162:165], v[210:213], v[68:71]
	s_setprio 0
	s_setprio 1
	v_mfma_f32_16x16x32_bf16 v[120:123], v[166:169], v[182:185], v[120:123]
	v_mfma_f32_16x16x32_bf16 v[112:115], v[174:177], v[182:185], v[112:115]
	v_mfma_f32_16x16x32_bf16 v[104:107], v[166:169], v[190:193], v[104:107]
	v_mfma_f32_16x16x32_bf16 v[96:99], v[174:177], v[190:193], v[96:99]
	v_mfma_f32_16x16x32_bf16 v[88:91], v[166:169], v[198:201], v[88:91]
	v_mfma_f32_16x16x32_bf16 v[80:83], v[174:177], v[198:201], v[80:83]
	v_mfma_f32_16x16x32_bf16 v[72:75], v[166:169], v[206:209], v[72:75]
	v_mfma_f32_16x16x32_bf16 v[64:67], v[174:177], v[206:209], v[64:67]
	v_mfma_f32_16x16x32_bf16 v[120:123], v[170:173], v[186:189], v[120:123]
	v_mfma_f32_16x16x32_bf16 v[112:115], v[178:181], v[186:189], v[112:115]
	v_mfma_f32_16x16x32_bf16 v[104:107], v[170:173], v[194:197], v[104:107]
	v_mfma_f32_16x16x32_bf16 v[96:99], v[178:181], v[194:197], v[96:99]
	v_mfma_f32_16x16x32_bf16 v[88:91], v[170:173], v[202:205], v[88:91]
	v_mfma_f32_16x16x32_bf16 v[80:83], v[178:181], v[202:205], v[80:83]
	v_mfma_f32_16x16x32_bf16 v[72:75], v[170:173], v[210:213], v[72:75]
	v_mfma_f32_16x16x32_bf16 v[64:67], v[178:181], v[210:213], v[64:67]
	s_setprio 0
	s_barrier
; #define PG8_STAGE(bufoff, gbase, voff) do { _Pragma("unroll") for (int _i = 0; _i < 2; ++_i) \
;         __builtin_amdgcn_global_load_lds((const unsigned*)((const char*)(gbase) + (voff)[_i]), (LAS unsigned*)(lds + (bufoff) + ldsw + _i * 8192), 16, 0, 0); } while (0)
; #define PG8_LDA(dst, b, h) do { _Pragma("unroll") for (int m = 0; m < 4; ++m) _Pragma("unroll") for (int k = 0; k < 2; ++k) dst[m][k] = *(const LAS bf16x8*)(lds + PG8_SA(b, h) + aoff + m * 2048 + k * 1024); } while (0)
; #define PG8_MMA(ai, bj, At, Bt) do { __builtin_amdgcn_s_setprio(1); _Pragma("unroll") for (int m = 0; m < 4; ++m) _Pragma("unroll") for (int n = 0; n < 2; ++n) _Pragma("unroll") for (int k = 0; k < 2; ++k) \
;         acc[ai][bj][m][n] = __builtin_amdgcn_mfma_f32_16x16x32_bf16(Bt[n][k], At[m][k], acc[ai][bj][m][n], 0, 0, 0); __builtin_amdgcn_s_setprio(0); } while (0)
; #define PG8_WAIT_V(n) asm volatile("s_waitcnt vmcnt(" #n ")" ::: "memory")
; #define PG8_WAIT_L(n) asm volatile("s_waitcnt lgkmcnt(" #n ")" ::: "memory")
; #define PG8_BAR __builtin_amdgcn_s_barrier()
; #define PG8_SCHED __builtin_amdgcn_sched_barrier(0)
; template <class Epi>
; DI void gemm_phase(int wv, LAS unsigned char* lds, const Gemm g, const StaticOrder& S, const Epi& E) {
;     ...
;             PG8_LDA(At, 1, 1); PG8_STAGE(PG8_SB(1, 0), b3, voffB); PG8_STAGE(PG8_SB(1, 1), b3 + hB, voffB); PG8_STAGE(PG8_SA(1, 0), a3, voffA);
;             PG8_WAIT_V(8); PG8_WAIT_L(0); PG8_BAR; PG8_MMA(1, 0, At, B0); PG8_MMA(1, 1, At, B1); PG8_BAR; PG8_SCHED;
;         }
	s_add_i32 s28, s59, s34
	v_lshl_add_u64 v[214:215], v[214:215], 0, s[10:11]
	s_mov_b32 m0, s28
	ds_read_b128 v[182:185], v149 offset:49152
	ds_read_b128 v[186:189], v149 offset:50176
	ds_read_b128 v[190:193], v149 offset:51200
	ds_read_b128 v[194:197], v149 offset:52224
	ds_read_b128 v[198:201], v149 offset:53248
	ds_read_b128 v[202:205], v149 offset:54272
	ds_read_b128 v[206:209], v149 offset:55296
	ds_read_b128 v[210:213], v149 offset:56320
	global_load_lds_dwordx4 v[214:215], off
	s_add_i32 m0, s28, 0x2000
	s_add_u32 s26, s26, 0x40080
	v_lshl_add_u64 v[214:215], v[216:217], 0, s[10:11]
	s_addc_u32 s27, s27, 0
	s_add_i32 s28, s60, s34
	global_load_lds_dwordx4 v[214:215], off
	v_lshl_add_u64 v[214:215], s[26:27], 0, v[132:133]
	s_mov_b32 m0, s28
	s_nop 0
	global_load_lds_dwordx4 v[214:215], off
	v_lshl_add_u64 v[214:215], s[26:27], 0, v[128:129]
	s_add_i32 m0, s28, 0x2000
	s_nop 0
	global_load_lds_dwordx4 v[214:215], off
	v_lshl_add_u64 v[214:215], v[218:219], 0, s[10:11]
	s_mov_b32 m0, s42
	s_nop 0
	global_load_lds_dwordx4 v[214:215], off
	v_lshl_add_u64 v[214:215], v[220:221], 0, s[10:11]
	s_mov_b32 m0, s43
	s_nop 0
	global_load_lds_dwordx4 v[214:215], off
	s_waitcnt vmcnt(8)
	s_waitcnt lgkmcnt(0)
	s_barrier
	s_setprio 1
	s_waitcnt lgkmcnt(0)
	v_mfma_f32_16x16x32_bf16 v[60:63], v[150:153], v[182:185], v[60:63]
	v_mfma_f32_16x16x32_bf16 v[52:55], v[158:161], v[182:185], v[52:55]
	v_mfma_f32_16x16x32_bf16 v[44:47], v[150:153], v[190:193], v[44:47]
	v_mfma_f32_16x16x32_bf16 v[36:39], v[158:161], v[190:193], v[36:39]
	v_mfma_f32_16x16x32_bf16 v[28:31], v[150:153], v[198:201], v[28:31]
	v_mfma_f32_16x16x32_bf16 v[20:23], v[158:161], v[198:201], v[20:23]
	v_mfma_f32_16x16x32_bf16 v[12:15], v[150:153], v[206:209], v[12:15]
	v_mfma_f32_16x16x32_bf16 v[4:7], v[158:161], v[206:209], v[4:7]
	v_mfma_f32_16x16x32_bf16 v[60:63], v[154:157], v[186:189], v[60:63]
	v_mfma_f32_16x16x32_bf16 v[52:55], v[162:165], v[186:189], v[52:55]
	v_mfma_f32_16x16x32_bf16 v[44:47], v[154:157], v[194:197], v[44:47]
	v_mfma_f32_16x16x32_bf16 v[36:39], v[162:165], v[194:197], v[36:39]
	v_mfma_f32_16x16x32_bf16 v[28:31], v[154:157], v[202:205], v[28:31]
	v_mfma_f32_16x16x32_bf16 v[20:23], v[162:165], v[202:205], v[20:23]
	v_mfma_f32_16x16x32_bf16 v[12:15], v[154:157], v[210:213], v[12:15]
	v_mfma_f32_16x16x32_bf16 v[4:7], v[162:165], v[210:213], v[4:7]
	s_setprio 0
	s_setprio 1
	v_mfma_f32_16x16x32_bf16 v[56:59], v[166:169], v[182:185], v[56:59]
	v_mfma_f32_16x16x32_bf16 v[48:51], v[174:177], v[182:185], v[48:51]
	v_mfma_f32_16x16x32_bf16 v[40:43], v[166:169], v[190:193], v[40:43]
	v_mfma_f32_16x16x32_bf16 v[32:35], v[174:177], v[190:193], v[32:35]
	v_mfma_f32_16x16x32_bf16 v[24:27], v[166:169], v[198:201], v[24:27]
	v_mfma_f32_16x16x32_bf16 v[16:19], v[174:177], v[198:201], v[16:19]
	v_mfma_f32_16x16x32_bf16 v[8:11], v[166:169], v[206:209], v[8:11]
	v_mfma_f32_16x16x32_bf16 v[0:3], v[174:177], v[206:209], v[0:3]
	v_mfma_f32_16x16x32_bf16 v[56:59], v[170:173], v[186:189], v[56:59]
	v_mfma_f32_16x16x32_bf16 v[48:51], v[178:181], v[186:189], v[48:51]
	v_mfma_f32_16x16x32_bf16 v[40:43], v[170:173], v[194:197], v[40:43]
	v_mfma_f32_16x16x32_bf16 v[32:35], v[178:181], v[194:197], v[32:35]
	v_mfma_f32_16x16x32_bf16 v[24:27], v[170:173], v[202:205], v[24:27]
	v_mfma_f32_16x16x32_bf16 v[16:19], v[178:181], v[202:205], v[16:19]
	v_mfma_f32_16x16x32_bf16 v[8:11], v[170:173], v[210:213], v[8:11]
	v_mfma_f32_16x16x32_bf16 v[0:3], v[178:181], v[210:213], v[0:3]
	s_setprio 0
	s_add_i32 s58, s58, 2
	s_add_u32 s56, s56, 0x100
	s_addc_u32 s57, s57, 0
	s_add_u32 s24, s24, 0x100
	s_addc_u32 s25, s25, 0
	s_cmp_gt_u32 s58, 13
	s_barrier
	s_cbranch_scc0 .LBB0_377
	s_and_b64 vcc, exec, s[12:13]
	s_cbranch_vccz .LBB0_380
	s_barrier

; #define PG8_STAGE(bufoff, gbase, voff) do { _Pragma("unroll") for (int _i = 0; _i < 2; ++_i) \
;         __builtin_amdgcn_global_load_lds((const unsigned*)((const char*)(gbase) + (voff)[_i]), (LAS unsigned*)(lds + (bufoff) + ldsw + _i * 8192), 16, 0, 0); } while (0)
; #define PG8_LDA(dst, b, h) do { _Pragma("unroll") for (int m = 0; m < 4; ++m) _Pragma("unroll") for (int k = 0; k < 2; ++k) dst[m][k] = *(const LAS bf16x8*)(lds + PG8_SA(b, h) + aoff + m * 2048 + k * 1024); } while (0)
; #define PG8_LDB(dst, b, h) do { _Pragma("unroll") for (int n = 0; n < 2; ++n) _Pragma("unroll") for (int k = 0; k < 2; ++k) dst[n][k] = *(const LAS bf16x8*)(lds + PG8_SB(b, h) + boff + n * 2048 + k * 1024); } while (0)
; #define PG8_MMA(ai, bj, At, Bt) do { __builtin_amdgcn_s_setprio(1); _Pragma("unroll") for (int m = 0; m < 4; ++m) _Pragma("unroll") for (int n = 0; n < 2; ++n) _Pragma("unroll") for (int k = 0; k < 2; ++k) \
;         acc[ai][bj][m][n] = __builtin_amdgcn_mfma_f32_16x16x32_bf16(Bt[n][k], At[m][k], acc[ai][bj][m][n], 0, 0, 0); __builtin_amdgcn_s_setprio(0); } while (0)
; #define PG8_WAIT_V(n) asm volatile("s_waitcnt vmcnt(" #n ")" ::: "memory")
; #define PG8_WAIT_L(n) asm volatile("s_waitcnt lgkmcnt(" #n ")" ::: "memory")
; #define PG8_BAR __builtin_amdgcn_s_barrier()
; #define PG8_SCHED __builtin_amdgcn_sched_barrier(0)
; template <class Epi>
; DI void gemm_phase(int wv, LAS unsigned char* lds, const Gemm g, const StaticOrder& S, const Epi& E) {
;     ...
;         for (int t = 0; t < nt; t += 2) {
;             const bool last = (t == nt - 2);
;             const char* a1 = cA + (size_t)(t + 1) * kstep;
;             const char* a2 = last ? nA : cA + (size_t)(t + 2) * kstep; const char* b2 = last ? nB : cB + (size_t)(t + 2) * kstep;
;             const char* a3 = a2 + kstep; const char* b3 = b2 + kstep;
;             PG8_LDB(B0, 0, 0); PG8_LDB(B1, 0, 1); PG8_SCHED; PG8_LDA(At, 0, 0); PG8_STAGE(PG8_SA(1, 1), a1 + hA, voffA);
;             PG8_WAIT_V(8); PG8_WAIT_L(0); PG8_BAR; PG8_MMA(0, 0, At, B0); PG8_MMA(0, 1, At, B1); PG8_BAR; PG8_SCHED;
;             PG8_LDA(At, 0, 1); PG8_STAGE(PG8_SB(0, 0), b2, voffB); PG8_STAGE(PG8_SB(0, 1), b2 + hB, voffB); PG8_STAGE(PG8_SA(0, 0), a2, voffA);
.LBB0_458:
	ds_read_b128 v[150:153], v147
	ds_read_b128 v[154:157], v147 offset:1024
	ds_read_b128 v[158:161], v147 offset:2048
	ds_read_b128 v[162:165], v147 offset:3072
	ds_read_b128 v[166:169], v148
	ds_read_b128 v[170:173], v148 offset:1024
	ds_read_b128 v[174:177], v148 offset:2048
	ds_read_b128 v[178:181], v148 offset:3072
	s_add_u32 s20, s18, 0x100
	s_addc_u32 s21, s19, 0
	s_cmp_eq_u32 s56, 40
	s_cselect_b32 s25, s5, s21
	s_cselect_b32 s24, s4, s20
	s_cselect_b32 s23, s17, s55
	s_cselect_b32 s22, s16, s54
	v_lshl_add_u64 v[214:215], s[18:19], 0, v[138:139]
	s_add_i32 m0, s34, 0xc000
	ds_read_b128 v[182:185], v149
	ds_read_b128 v[186:189], v149 offset:1024
	ds_read_b128 v[190:193], v149 offset:2048
	ds_read_b128 v[194:197], v149 offset:3072
	ds_read_b128 v[198:201], v149 offset:4096
	ds_read_b128 v[202:205], v149 offset:5120
	ds_read_b128 v[206:209], v149 offset:6144
	ds_read_b128 v[210:213], v149 offset:7168
	global_load_lds_dwordx4 v[214:215], off
	v_lshl_add_u64 v[214:215], s[18:19], 0, v[136:137]
	s_add_i32 m0, s34, 0xe000
	s_nop 0
	global_load_lds_dwordx4 v[214:215], off
	s_waitcnt vmcnt(8)
	s_waitcnt lgkmcnt(0)
	s_barrier
	s_setprio 1
	s_waitcnt lgkmcnt(0)
	v_mfma_f32_16x16x32_bf16 v[124:127], v[150:153], v[182:185], v[124:127]
	v_mfma_f32_16x16x32_bf16 v[120:123], v[158:161], v[182:185], v[120:123]
	v_mfma_f32_16x16x32_bf16 v[116:119], v[150:153], v[190:193], v[116:119]
	v_mfma_f32_16x16x32_bf16 v[112:115], v[158:161], v[190:193], v[112:115]
	v_mfma_f32_16x16x32_bf16 v[100:103], v[150:153], v[198:201], v[100:103]
	v_mfma_f32_16x16x32_bf16 v[96:99], v[158:161], v[198:201], v[96:99]
	v_mfma_f32_16x16x32_bf16 v[84:87], v[150:153], v[206:209], v[84:87]
	v_mfma_f32_16x16x32_bf16 v[80:83], v[158:161], v[206:209], v[80:83]
	v_mfma_f32_16x16x32_bf16 v[124:127], v[154:157], v[186:189], v[124:127]
	v_mfma_f32_16x16x32_bf16 v[120:123], v[162:165], v[186:189], v[120:123]
	v_mfma_f32_16x16x32_bf16 v[116:119], v[154:157], v[194:197], v[116:119]
	v_mfma_f32_16x16x32_bf16 v[112:115], v[162:165], v[194:197], v[112:115]
	v_mfma_f32_16x16x32_bf16 v[100:103], v[154:157], v[202:205], v[100:103]
	v_mfma_f32_16x16x32_bf16 v[96:99], v[162:165], v[202:205], v[96:99]
	v_mfma_f32_16x16x32_bf16 v[84:87], v[154:157], v[210:213], v[84:87]
	v_mfma_f32_16x16x32_bf16 v[80:83], v[162:165], v[210:213], v[80:83]
	s_setprio 0
	s_setprio 1
	v_mfma_f32_16x16x32_bf16 v[108:111], v[166:169], v[182:185], v[108:111]
	v_mfma_f32_16x16x32_bf16 v[104:107], v[174:177], v[182:185], v[104:107]
	v_mfma_f32_16x16x32_bf16 v[92:95], v[166:169], v[190:193], v[92:95]
	v_mfma_f32_16x16x32_bf16 v[88:91], v[174:177], v[190:193], v[88:91]
	v_mfma_f32_16x16x32_bf16 v[76:79], v[166:169], v[198:201], v[76:79]
	v_mfma_f32_16x16x32_bf16 v[72:75], v[174:177], v[198:201], v[72:75]
	v_mfma_f32_16x16x32_bf16 v[68:71], v[166:169], v[206:209], v[68:71]
	v_mfma_f32_16x16x32_bf16 v[64:67], v[174:177], v[206:209], v[64:67]
	v_mfma_f32_16x16x32_bf16 v[108:111], v[170:173], v[186:189], v[108:111]
	v_mfma_f32_16x16x32_bf16 v[104:107], v[178:181], v[186:189], v[104:107]
	v_mfma_f32_16x16x32_bf16 v[92:95], v[170:173], v[194:197], v[92:95]
	v_mfma_f32_16x16x32_bf16 v[88:91], v[178:181], v[194:197], v[88:91]
	v_mfma_f32_16x16x32_bf16 v[76:79], v[170:173], v[202:205], v[76:79]
	v_mfma_f32_16x16x32_bf16 v[72:75], v[178:181], v[202:205], v[72:75]
	v_mfma_f32_16x16x32_bf16 v[68:71], v[170:173], v[210:213], v[68:71]
	v_mfma_f32_16x16x32_bf16 v[64:67], v[178:181], v[210:213], v[64:67]
	s_setprio 0
	s_barrier
	s_add_i32 s18, s44, s31
	v_lshl_add_u64 v[214:215], s[22:23], 0, v[130:131]
	s_mov_b32 m0, s18
	ds_read_b128 v[182:185], v149 offset:16384
	ds_read_b128 v[186:189], v149 offset:17408
	ds_read_b128 v[190:193], v149 offset:18432
	ds_read_b128 v[194:197], v149 offset:19456
	ds_read_b128 v[198:201], v149 offset:20480
	ds_read_b128 v[202:205], v149 offset:21504
	ds_read_b128 v[206:209], v149 offset:22528
	ds_read_b128 v[210:213], v149 offset:23552
	global_load_lds_dwordx4 v[214:215], off
	s_add_i32 m0, s18, 0x2000
	s_add_u32 s18, s22, 0xb0000
	v_lshl_add_u64 v[216:217], s[22:23], 0, v[134:135]
	s_addc_u32 s19, s23, 0
	s_add_i32 s57, s45, s31
	global_load_lds_dwordx4 v[216:217], off
	v_lshl_add_u64 v[218:219], s[18:19], 0, v[130:131]
	s_mov_b32 m0, s57
	v_lshl_add_u64 v[220:221], s[24:25], 0, v[132:133]
	global_load_lds_dwordx4 v[218:219], off
	v_lshl_add_u64 v[218:219], s[18:19], 0, v[134:135]
	s_add_i32 m0, s57, 0x2000
	s_nop 0
	global_load_lds_dwordx4 v[218:219], off
	v_lshl_add_u64 v[218:219], s[24:25], 0, v[128:129]
	s_mov_b32 m0, s34
	s_nop 0
	global_load_lds_dwordx4 v[218:219], off
	s_mov_b32 m0, s35
	s_nop 0
	global_load_lds_dwordx4 v[220:221], off
	s_waitcnt vmcnt(8)
	s_waitcnt lgkmcnt(0)
	s_barrier
; #define PG8_STAGE(bufoff, gbase, voff) do { _Pragma("unroll") for (int _i = 0; _i < 2; ++_i) \
;         __builtin_amdgcn_global_load_lds((const unsigned*)((const char*)(gbase) + (voff)[_i]), (LAS unsigned*)(lds + (bufoff) + ldsw + _i * 8192), 16, 0, 0); } while (0)
; #define PG8_LDA(dst, b, h) do { _Pragma("unroll") for (int m = 0; m < 4; ++m) _Pragma("unroll") for (int k = 0; k < 2; ++k) dst[m][k] = *(const LAS bf16x8*)(lds + PG8_SA(b, h) + aoff + m * 2048 + k * 1024); } while (0)
; #define PG8_LDB(dst, b, h) do { _Pragma("unroll") for (int n = 0; n < 2; ++n) _Pragma("unroll") for (int k = 0; k < 2; ++k) dst[n][k] = *(const LAS bf16x8*)(lds + PG8_SB(b, h) + boff + n * 2048 + k * 1024); } while (0)
; #define PG8_MMA(ai, bj, At, Bt) do { __builtin_amdgcn_s_setprio(1); _Pragma("unroll") for (int m = 0; m < 4; ++m) _Pragma("unroll") for (int n = 0; n < 2; ++n) _Pragma("unroll") for (int k = 0; k < 2; ++k) \
;         acc[ai][bj][m][n] = __builtin_amdgcn_mfma_f32_16x16x32_bf16(Bt[n][k], At[m][k], acc[ai][bj][m][n], 0, 0, 0); __builtin_amdgcn_s_setprio(0); } while (0)
; #define PG8_WAIT_V(n) asm volatile("s_waitcnt vmcnt(" #n ")" ::: "memory")
; #define PG8_WAIT_L(n) asm volatile("s_waitcnt lgkmcnt(" #n ")" ::: "memory")
; #define PG8_BAR __builtin_amdgcn_s_barrier()
; #define PG8_SCHED __builtin_amdgcn_sched_barrier(0)
; template <class Epi>
; DI void gemm_phase(int wv, LAS unsigned char* lds, const Gemm g, const StaticOrder& S, const Epi& E) {
;     ...
;             PG8_WAIT_V(8); PG8_WAIT_L(0); PG8_BAR; PG8_MMA(1, 0, At, B0); PG8_MMA(1, 1, At, B1); PG8_BAR; PG8_SCHED;
;             PG8_LDB(B0, 1, 0); PG8_LDB(B1, 1, 1); PG8_SCHED; PG8_LDA(At, 1, 0); PG8_STAGE(PG8_SA(0, 1), a2 + hA, voffA);
;             PG8_WAIT_V(8); PG8_WAIT_L(0); PG8_BAR; PG8_MMA(0, 0, At, B0); PG8_MMA(0, 1, At, B1); PG8_BAR; PG8_SCHED;
	s_setprio 1
	s_waitcnt lgkmcnt(0)
	v_mfma_f32_16x16x32_bf16 v[60:63], v[150:153], v[182:185], v[60:63]
	v_mfma_f32_16x16x32_bf16 v[56:59], v[158:161], v[182:185], v[56:59]
	v_mfma_f32_16x16x32_bf16 v[52:55], v[150:153], v[190:193], v[52:55]
	v_mfma_f32_16x16x32_bf16 v[48:51], v[158:161], v[190:193], v[48:51]
	v_mfma_f32_16x16x32_bf16 v[36:39], v[150:153], v[198:201], v[36:39]
	v_mfma_f32_16x16x32_bf16 v[32:35], v[158:161], v[198:201], v[32:35]
	v_mfma_f32_16x16x32_bf16 v[20:23], v[150:153], v[206:209], v[20:23]
	v_mfma_f32_16x16x32_bf16 v[16:19], v[158:161], v[206:209], v[16:19]
	v_mfma_f32_16x16x32_bf16 v[60:63], v[154:157], v[186:189], v[60:63]
	v_mfma_f32_16x16x32_bf16 v[56:59], v[162:165], v[186:189], v[56:59]
	v_mfma_f32_16x16x32_bf16 v[52:55], v[154:157], v[194:197], v[52:55]
	v_mfma_f32_16x16x32_bf16 v[48:51], v[162:165], v[194:197], v[48:51]
	v_mfma_f32_16x16x32_bf16 v[36:39], v[154:157], v[202:205], v[36:39]
	v_mfma_f32_16x16x32_bf16 v[32:35], v[162:165], v[202:205], v[32:35]
	v_mfma_f32_16x16x32_bf16 v[20:23], v[154:157], v[210:213], v[20:23]
	v_mfma_f32_16x16x32_bf16 v[16:19], v[162:165], v[210:213], v[16:19]
	s_setprio 0
	s_setprio 1
	v_mfma_f32_16x16x32_bf16 v[44:47], v[166:169], v[182:185], v[44:47]
	v_mfma_f32_16x16x32_bf16 v[40:43], v[174:177], v[182:185], v[40:43]
	v_mfma_f32_16x16x32_bf16 v[28:31], v[166:169], v[190:193], v[28:31]
	v_mfma_f32_16x16x32_bf16 v[24:27], v[174:177], v[190:193], v[24:27]
	v_mfma_f32_16x16x32_bf16 v[12:15], v[166:169], v[198:201], v[12:15]
	v_mfma_f32_16x16x32_bf16 v[8:11], v[174:177], v[198:201], v[8:11]
	v_mfma_f32_16x16x32_bf16 v[4:7], v[166:169], v[206:209], v[4:7]
	v_mfma_f32_16x16x32_bf16 v[0:3], v[174:177], v[206:209], v[0:3]
	v_mfma_f32_16x16x32_bf16 v[44:47], v[170:173], v[186:189], v[44:47]
	v_mfma_f32_16x16x32_bf16 v[40:43], v[178:181], v[186:189], v[40:43]
	v_mfma_f32_16x16x32_bf16 v[28:31], v[170:173], v[194:197], v[28:31]
	v_mfma_f32_16x16x32_bf16 v[24:27], v[178:181], v[194:197], v[24:27]
	v_mfma_f32_16x16x32_bf16 v[12:15], v[170:173], v[202:205], v[12:15]
	v_mfma_f32_16x16x32_bf16 v[8:11], v[178:181], v[202:205], v[8:11]
	v_mfma_f32_16x16x32_bf16 v[4:7], v[170:173], v[210:213], v[4:7]
	v_mfma_f32_16x16x32_bf16 v[0:3], v[178:181], v[210:213], v[0:3]
	s_setprio 0
	s_barrier
	s_add_i32 s57, 0, 0x18000
	s_add_i32 s58, 0, 0x1c000
	v_add_u32_e32 v162, s57, v146
	v_add_u32_e32 v178, s58, v146
	ds_read_b128 v[150:153], v162
	ds_read_b128 v[154:157], v162 offset:1024
	ds_read_b128 v[158:161], v162 offset:2048
	ds_read_b128 v[162:165], v162 offset:3072
	ds_read_b128 v[166:169], v178
	ds_read_b128 v[170:173], v178 offset:1024
	ds_read_b128 v[174:177], v178 offset:2048
	ds_read_b128 v[178:181], v178 offset:3072
	s_add_u32 s18, s24, 0xb0000
	s_addc_u32 s19, s25, 0
	s_mov_b32 m0, s36
	v_lshl_add_u64 v[222:223], s[18:19], 0, v[128:129]
	ds_read_b128 v[182:185], v149 offset:32768
	ds_read_b128 v[186:189], v149 offset:33792
	ds_read_b128 v[190:193], v149 offset:34816
	ds_read_b128 v[194:197], v149 offset:35840
	ds_read_b128 v[198:201], v149 offset:36864
	ds_read_b128 v[202:205], v149 offset:37888
	ds_read_b128 v[206:209], v149 offset:38912
	ds_read_b128 v[210:213], v149 offset:39936
	global_load_lds_dwordx4 v[222:223], off
	v_lshl_add_u64 v[222:223], s[18:19], 0, v[132:133]
	s_mov_b32 m0, s37
	s_nop 0
	global_load_lds_dwordx4 v[222:223], off
	s_waitcnt vmcnt(8)
	s_waitcnt lgkmcnt(0)
	s_barrier
	s_setprio 1
	s_waitcnt lgkmcnt(0)
	v_mfma_f32_16x16x32_bf16 v[124:127], v[150:153], v[182:185], v[124:127]
	v_mfma_f32_16x16x32_bf16 v[120:123], v[158:161], v[182:185], v[120:123]
	v_mfma_f32_16x16x32_bf16 v[116:119], v[150:153], v[190:193], v[116:119]
	v_mfma_f32_16x16x32_bf16 v[112:115], v[158:161], v[190:193], v[112:115]
	v_mfma_f32_16x16x32_bf16 v[100:103], v[150:153], v[198:201], v[100:103]
	v_mfma_f32_16x16x32_bf16 v[96:99], v[158:161], v[198:201], v[96:99]
	v_mfma_f32_16x16x32_bf16 v[84:87], v[150:153], v[206:209], v[84:87]
	v_mfma_f32_16x16x32_bf16 v[80:83], v[158:161], v[206:209], v[80:83]
	v_mfma_f32_16x16x32_bf16 v[124:127], v[154:157], v[186:189], v[124:127]
	v_mfma_f32_16x16x32_bf16 v[120:123], v[162:165], v[186:189], v[120:123]
	v_mfma_f32_16x16x32_bf16 v[116:119], v[154:157], v[194:197], v[116:119]
	v_mfma_f32_16x16x32_bf16 v[112:115], v[162:165], v[194:197], v[112:115]
	v_mfma_f32_16x16x32_bf16 v[100:103], v[154:157], v[202:205], v[100:103]
	v_mfma_f32_16x16x32_bf16 v[96:99], v[162:165], v[202:205], v[96:99]
	v_mfma_f32_16x16x32_bf16 v[84:87], v[154:157], v[210:213], v[84:87]
	v_mfma_f32_16x16x32_bf16 v[80:83], v[162:165], v[210:213], v[80:83]
	s_setprio 0
	s_setprio 1
	v_mfma_f32_16x16x32_bf16 v[108:111], v[166:169], v[182:185], v[108:111]
	v_mfma_f32_16x16x32_bf16 v[104:107], v[174:177], v[182:185], v[104:107]
	v_mfma_f32_16x16x32_bf16 v[92:95], v[166:169], v[190:193], v[92:95]
	v_mfma_f32_16x16x32_bf16 v[88:91], v[174:177], v[190:193], v[88:91]
	v_mfma_f32_16x16x32_bf16 v[76:79], v[166:169], v[198:201], v[76:79]
	v_mfma_f32_16x16x32_bf16 v[72:75], v[174:177], v[198:201], v[72:75]
	v_mfma_f32_16x16x32_bf16 v[68:71], v[166:169], v[206:209], v[68:71]
	v_mfma_f32_16x16x32_bf16 v[64:67], v[174:177], v[206:209], v[64:67]
	v_mfma_f32_16x16x32_bf16 v[108:111], v[170:173], v[186:189], v[108:111]
	v_mfma_f32_16x16x32_bf16 v[104:107], v[178:181], v[186:189], v[104:107]
	v_mfma_f32_16x16x32_bf16 v[92:95], v[170:173], v[194:197], v[92:95]
	v_mfma_f32_16x16x32_bf16 v[88:91], v[178:181], v[194:197], v[88:91]
	v_mfma_f32_16x16x32_bf16 v[76:79], v[170:173], v[202:205], v[76:79]
	v_mfma_f32_16x16x32_bf16 v[72:75], v[178:181], v[202:205], v[72:75]
	v_mfma_f32_16x16x32_bf16 v[68:71], v[170:173], v[210:213], v[68:71]
	v_mfma_f32_16x16x32_bf16 v[64:67], v[178:181], v[210:213], v[64:67]
	s_setprio 0
	s_barrier
; #define PG8_STAGE(bufoff, gbase, voff) do { _Pragma("unroll") for (int _i = 0; _i < 2; ++_i) \
;         __builtin_amdgcn_global_load_lds((const unsigned*)((const char*)(gbase) + (voff)[_i]), (LAS unsigned*)(lds + (bufoff) + ldsw + _i * 8192), 16, 0, 0); } while (0)
; #define PG8_LDA(dst, b, h) do { _Pragma("unroll") for (int m = 0; m < 4; ++m) _Pragma("unroll") for (int k = 0; k < 2; ++k) dst[m][k] = *(const LAS bf16x8*)(lds + PG8_SA(b, h) + aoff + m * 2048 + k * 1024); } while (0)
; #define PG8_MMA(ai, bj, At, Bt) do { __builtin_amdgcn_s_setprio(1); _Pragma("unroll") for (int m = 0; m < 4; ++m) _Pragma("unroll") for (int n = 0; n < 2; ++n) _Pragma("unroll") for (int k = 0; k < 2; ++k) \
;         acc[ai][bj][m][n] = __builtin_amdgcn_mfma_f32_16x16x32_bf16(Bt[n][k], At[m][k], acc[ai][bj][m][n], 0, 0, 0); __builtin_amdgcn_s_setprio(0); } while (0)
; #define PG8_WAIT_V(n) asm volatile("s_waitcnt vmcnt(" #n ")" ::: "memory")
; #define PG8_WAIT_L(n) asm volatile("s_waitcnt lgkmcnt(" #n ")" ::: "memory")
; #define PG8_BAR __builtin_amdgcn_s_barrier()
; #define PG8_SCHED __builtin_amdgcn_sched_barrier(0)
; template <class Epi>
; DI void gemm_phase(int wv, LAS unsigned char* lds, const Gemm g, const StaticOrder& S, const Epi& E) {
;     ...
;             PG8_LDA(At, 1, 1); PG8_STAGE(PG8_SB(1, 0), b3, voffB); PG8_STAGE(PG8_SB(1, 1), b3 + hB, voffB); PG8_STAGE(PG8_SA(1, 0), a3, voffA);
;             PG8_WAIT_V(8); PG8_WAIT_L(0); PG8_BAR; PG8_MMA(1, 0, At, B0); PG8_MMA(1, 1, At, B1); PG8_BAR; PG8_SCHED;
;         }
	s_add_i32 s18, s57, s31
	v_lshl_add_u64 v[214:215], v[214:215], 0, s[10:11]
	s_mov_b32 m0, s18
	ds_read_b128 v[182:185], v149 offset:49152
	ds_read_b128 v[186:189], v149 offset:50176
	ds_read_b128 v[190:193], v149 offset:51200
	ds_read_b128 v[194:197], v149 offset:52224
	ds_read_b128 v[198:201], v149 offset:53248
	ds_read_b128 v[202:205], v149 offset:54272
	ds_read_b128 v[206:209], v149 offset:55296
	ds_read_b128 v[210:213], v149 offset:56320
	global_load_lds_dwordx4 v[214:215], off
	s_add_i32 m0, s18, 0x2000
	s_add_u32 s18, s22, 0xb0080
	v_lshl_add_u64 v[214:215], v[216:217], 0, s[10:11]
	s_addc_u32 s19, s23, 0
	s_add_i32 s22, s58, s31
	global_load_lds_dwordx4 v[214:215], off
	v_lshl_add_u64 v[214:215], s[18:19], 0, v[130:131]
	s_mov_b32 m0, s22
	s_nop 0
	global_load_lds_dwordx4 v[214:215], off
	v_lshl_add_u64 v[214:215], s[18:19], 0, v[134:135]
	s_add_i32 m0, s22, 0x2000
	s_nop 0
	global_load_lds_dwordx4 v[214:215], off
	v_lshl_add_u64 v[214:215], v[218:219], 0, s[10:11]
	s_mov_b32 m0, s41
	s_nop 0
	global_load_lds_dwordx4 v[214:215], off
	v_lshl_add_u64 v[214:215], v[220:221], 0, s[10:11]
	s_mov_b32 m0, s42
	s_nop 0
	global_load_lds_dwordx4 v[214:215], off
	s_waitcnt vmcnt(8)
	s_waitcnt lgkmcnt(0)
	s_barrier
	s_setprio 1
	s_waitcnt lgkmcnt(0)
	v_mfma_f32_16x16x32_bf16 v[60:63], v[150:153], v[182:185], v[60:63]
	v_mfma_f32_16x16x32_bf16 v[56:59], v[158:161], v[182:185], v[56:59]
	v_mfma_f32_16x16x32_bf16 v[52:55], v[150:153], v[190:193], v[52:55]
	v_mfma_f32_16x16x32_bf16 v[48:51], v[158:161], v[190:193], v[48:51]
	v_mfma_f32_16x16x32_bf16 v[36:39], v[150:153], v[198:201], v[36:39]
	v_mfma_f32_16x16x32_bf16 v[32:35], v[158:161], v[198:201], v[32:35]
	v_mfma_f32_16x16x32_bf16 v[20:23], v[150:153], v[206:209], v[20:23]
	v_mfma_f32_16x16x32_bf16 v[16:19], v[158:161], v[206:209], v[16:19]
	v_mfma_f32_16x16x32_bf16 v[60:63], v[154:157], v[186:189], v[60:63]
	v_mfma_f32_16x16x32_bf16 v[56:59], v[162:165], v[186:189], v[56:59]
	v_mfma_f32_16x16x32_bf16 v[52:55], v[154:157], v[194:197], v[52:55]
	v_mfma_f32_16x16x32_bf16 v[48:51], v[162:165], v[194:197], v[48:51]
	v_mfma_f32_16x16x32_bf16 v[36:39], v[154:157], v[202:205], v[36:39]
	v_mfma_f32_16x16x32_bf16 v[32:35], v[162:165], v[202:205], v[32:35]
	v_mfma_f32_16x16x32_bf16 v[20:23], v[154:157], v[210:213], v[20:23]
	v_mfma_f32_16x16x32_bf16 v[16:19], v[162:165], v[210:213], v[16:19]
	s_setprio 0
	s_setprio 1
	v_mfma_f32_16x16x32_bf16 v[44:47], v[166:169], v[182:185], v[44:47]
	v_mfma_f32_16x16x32_bf16 v[40:43], v[174:177], v[182:185], v[40:43]
	v_mfma_f32_16x16x32_bf16 v[28:31], v[166:169], v[190:193], v[28:31]
	v_mfma_f32_16x16x32_bf16 v[24:27], v[174:177], v[190:193], v[24:27]
	v_mfma_f32_16x16x32_bf16 v[12:15], v[166:169], v[198:201], v[12:15]
	v_mfma_f32_16x16x32_bf16 v[8:11], v[174:177], v[198:201], v[8:11]
	v_mfma_f32_16x16x32_bf16 v[4:7], v[166:169], v[206:209], v[4:7]
	v_mfma_f32_16x16x32_bf16 v[0:3], v[174:177], v[206:209], v[0:3]
	v_mfma_f32_16x16x32_bf16 v[44:47], v[170:173], v[186:189], v[44:47]
	v_mfma_f32_16x16x32_bf16 v[40:43], v[178:181], v[186:189], v[40:43]
	v_mfma_f32_16x16x32_bf16 v[28:31], v[170:173], v[194:197], v[28:31]
	v_mfma_f32_16x16x32_bf16 v[24:27], v[178:181], v[194:197], v[24:27]
	v_mfma_f32_16x16x32_bf16 v[12:15], v[170:173], v[202:205], v[12:15]
	v_mfma_f32_16x16x32_bf16 v[8:11], v[178:181], v[202:205], v[8:11]
	v_mfma_f32_16x16x32_bf16 v[4:7], v[170:173], v[210:213], v[4:7]
	v_mfma_f32_16x16x32_bf16 v[0:3], v[178:181], v[210:213], v[0:3]
	s_setprio 0
	s_add_i32 s56, s56, 2
	s_add_u32 s54, s54, 0x100
	s_addc_u32 s55, s55, 0
	s_cmp_gt_u32 s56, 41
	s_mov_b64 s[18:19], s[20:21]
	s_barrier
	s_cbranch_scc0 .LBB0_458
	s_and_b64 vcc, exec, s[12:13]
	s_cbranch_vccz .LBB0_461
	s_barrier

; #define PG8_STAGE(bufoff, gbase, voff) do { _Pragma("unroll") for (int _i = 0; _i < 2; ++_i) \
;         __builtin_amdgcn_global_load_lds((const unsigned*)((const char*)(gbase) + (voff)[_i]), (LAS unsigned*)(lds + (bufoff) + ldsw + _i * 8192), 16, 0, 0); } while (0)
; #define PG8_LDA(dst, b, h) do { _Pragma("unroll") for (int m = 0; m < 4; ++m) _Pragma("unroll") for (int k = 0; k < 2; ++k) dst[m][k] = *(const LAS bf16x8*)(lds + PG8_SA(b, h) + aoff + m * 2048 + k * 1024); } while (0)
; #define PG8_LDB(dst, b, h) do { _Pragma("unroll") for (int n = 0; n < 2; ++n) _Pragma("unroll") for (int k = 0; k < 2; ++k) dst[n][k] = *(const LAS bf16x8*)(lds + PG8_SB(b, h) + boff + n * 2048 + k * 1024); } while (0)
; #define PG8_MMA(ai, bj, At, Bt) do { __builtin_amdgcn_s_setprio(1); _Pragma("unroll") for (int m = 0; m < 4; ++m) _Pragma("unroll") for (int n = 0; n < 2; ++n) _Pragma("unroll") for (int k = 0; k < 2; ++k) \
;         acc[ai][bj][m][n] = __builtin_amdgcn_mfma_f32_16x16x32_bf16(Bt[n][k], At[m][k], acc[ai][bj][m][n], 0, 0, 0); __builtin_amdgcn_s_setprio(0); } while (0)
; #define PG8_WAIT_V(n) asm volatile("s_waitcnt vmcnt(" #n ")" ::: "memory")
; #define PG8_WAIT_L(n) asm volatile("s_waitcnt lgkmcnt(" #n ")" ::: "memory")
; #define PG8_BAR __builtin_amdgcn_s_barrier()
; #define PG8_SCHED __builtin_amdgcn_sched_barrier(0)
; template <class Epi>
; DI void gemm_phase(int wv, LAS unsigned char* lds, const Gemm g, const StaticOrder& S, const Epi& E) {
;     ...
;         for (int t = 0; t < nt; t += 2) {
;             const bool last = (t == nt - 2);
;             const char* a1 = cA + (size_t)(t + 1) * kstep;
;             const char* a2 = last ? nA : cA + (size_t)(t + 2) * kstep; const char* b2 = last ? nB : cB + (size_t)(t + 2) * kstep;
;             const char* a3 = a2 + kstep; const char* b3 = b2 + kstep;
;             PG8_LDB(B0, 0, 0); PG8_LDB(B1, 0, 1); PG8_SCHED; PG8_LDA(At, 0, 0); PG8_STAGE(PG8_SA(1, 1), a1 + hA, voffA);
;             PG8_WAIT_V(8); PG8_WAIT_L(0); PG8_BAR; PG8_MMA(0, 0, At, B0); PG8_MMA(0, 1, At, B1); PG8_BAR; PG8_SCHED;
;             PG8_LDA(At, 0, 1); PG8_STAGE(PG8_SB(0, 0), b2, voffB); PG8_STAGE(PG8_SB(0, 1), b2 + hB, voffB); PG8_STAGE(PG8_SA(0, 0), a2, voffA);
.LBB0_873:
	ds_read_b128 v[128:131], v191
	ds_read_b128 v[132:135], v191 offset:1024
	ds_read_b128 v[136:139], v191 offset:2048
	ds_read_b128 v[140:143], v191 offset:3072
	ds_read_b128 v[162:165], v192
	ds_read_b128 v[166:169], v192 offset:1024
	ds_read_b128 v[170:173], v192 offset:2048
	ds_read_b128 v[174:177], v192 offset:3072
	s_add_u32 s6, s4, 0xfffc0080
	s_addc_u32 s7, s5, -1
	s_cmp_eq_u32 s16, 12
	s_cselect_b32 s9, s10, s7
	s_cselect_b32 s8, s11, s6
	s_cselect_b32 s7, s12, s15
	s_cselect_b32 s6, s13, s14
	v_lshl_add_u64 v[186:187], s[4:5], 0, v[156:157]
	s_add_i32 m0, s67, 0xc000
	ds_read_b128 v[178:181], v193
	ds_read_b128 v[182:185], v193 offset:1024
	ds_read_b128 v[196:199], v193 offset:2048
	ds_read_b128 v[200:203], v193 offset:3072
	ds_read_b128 v[204:207], v193 offset:4096
	ds_read_b128 v[208:211], v193 offset:5120
	ds_read_b128 v[212:215], v193 offset:6144
	ds_read_b128 v[216:219], v193 offset:7168
	global_load_lds_dwordx4 v[186:187], off
	v_lshl_add_u64 v[186:187], s[4:5], 0, v[154:155]
	s_add_i32 m0, s67, 0xe000
	s_nop 0
	global_load_lds_dwordx4 v[186:187], off
	s_waitcnt vmcnt(8)
	s_waitcnt lgkmcnt(0)
	s_barrier
	s_setprio 1
	s_waitcnt lgkmcnt(0)
	v_mfma_f32_16x16x32_bf16 v[124:127], v[128:131], v[178:181], v[124:127]
	v_mfma_f32_16x16x32_bf16 v[120:123], v[136:139], v[178:181], v[120:123]
	v_mfma_f32_16x16x32_bf16 v[108:111], v[128:131], v[196:199], v[108:111]
	v_mfma_f32_16x16x32_bf16 v[104:107], v[136:139], v[196:199], v[104:107]
	v_mfma_f32_16x16x32_bf16 v[92:95], v[128:131], v[204:207], v[92:95]
	v_mfma_f32_16x16x32_bf16 v[88:91], v[136:139], v[204:207], v[88:91]
	v_mfma_f32_16x16x32_bf16 v[76:79], v[128:131], v[212:215], v[76:79]
	v_mfma_f32_16x16x32_bf16 v[72:75], v[136:139], v[212:215], v[72:75]
	v_mfma_f32_16x16x32_bf16 v[124:127], v[132:135], v[182:185], v[124:127]
	v_mfma_f32_16x16x32_bf16 v[120:123], v[140:143], v[182:185], v[120:123]
	v_mfma_f32_16x16x32_bf16 v[108:111], v[132:135], v[200:203], v[108:111]
	v_mfma_f32_16x16x32_bf16 v[104:107], v[140:143], v[200:203], v[104:107]
	v_mfma_f32_16x16x32_bf16 v[92:95], v[132:135], v[208:211], v[92:95]
	v_mfma_f32_16x16x32_bf16 v[88:91], v[140:143], v[208:211], v[88:91]
	v_mfma_f32_16x16x32_bf16 v[76:79], v[132:135], v[216:219], v[76:79]
	v_mfma_f32_16x16x32_bf16 v[72:75], v[140:143], v[216:219], v[72:75]
	s_setprio 0
	s_setprio 1
	v_mfma_f32_16x16x32_bf16 v[116:119], v[162:165], v[178:181], v[116:119]
	v_mfma_f32_16x16x32_bf16 v[112:115], v[170:173], v[178:181], v[112:115]
	v_mfma_f32_16x16x32_bf16 v[100:103], v[162:165], v[196:199], v[100:103]
	v_mfma_f32_16x16x32_bf16 v[96:99], v[170:173], v[196:199], v[96:99]
	v_mfma_f32_16x16x32_bf16 v[84:87], v[162:165], v[204:207], v[84:87]
	v_mfma_f32_16x16x32_bf16 v[80:83], v[170:173], v[204:207], v[80:83]
	v_mfma_f32_16x16x32_bf16 v[68:71], v[162:165], v[212:215], v[68:71]
	v_mfma_f32_16x16x32_bf16 v[64:67], v[170:173], v[212:215], v[64:67]
	v_mfma_f32_16x16x32_bf16 v[116:119], v[166:169], v[182:185], v[116:119]
	v_mfma_f32_16x16x32_bf16 v[112:115], v[174:177], v[182:185], v[112:115]
	v_mfma_f32_16x16x32_bf16 v[100:103], v[166:169], v[200:203], v[100:103]
	v_mfma_f32_16x16x32_bf16 v[96:99], v[174:177], v[200:203], v[96:99]
	v_mfma_f32_16x16x32_bf16 v[84:87], v[166:169], v[208:211], v[84:87]
	v_mfma_f32_16x16x32_bf16 v[80:83], v[174:177], v[208:211], v[80:83]
	v_mfma_f32_16x16x32_bf16 v[68:71], v[166:169], v[216:219], v[68:71]
	v_mfma_f32_16x16x32_bf16 v[64:67], v[174:177], v[216:219], v[64:67]
	s_setprio 0
	s_barrier
	s_add_i32 s17, s44, s66
	v_lshl_add_u64 v[186:187], s[6:7], 0, v[146:147]
	s_mov_b32 m0, s17
	ds_read_b128 v[178:181], v193 offset:16384
	ds_read_b128 v[182:185], v193 offset:17408
	ds_read_b128 v[196:199], v193 offset:18432
	ds_read_b128 v[200:203], v193 offset:19456
	ds_read_b128 v[204:207], v193 offset:20480
	ds_read_b128 v[208:211], v193 offset:21504
	ds_read_b128 v[212:215], v193 offset:22528
	ds_read_b128 v[216:219], v193 offset:23552
	global_load_lds_dwordx4 v[186:187], off
	s_add_i32 m0, s17, 0x2000
	s_add_u32 s18, s6, 0x40000
	v_lshl_add_u64 v[220:221], s[6:7], 0, v[150:151]
	s_addc_u32 s19, s7, 0
	s_add_i32 s17, s45, s66
	global_load_lds_dwordx4 v[220:221], off
	v_lshl_add_u64 v[222:223], s[18:19], 0, v[146:147]
	s_mov_b32 m0, s17
	v_lshl_add_u64 v[224:225], s[8:9], 0, v[148:149]
	global_load_lds_dwordx4 v[222:223], off
	v_lshl_add_u64 v[222:223], s[18:19], 0, v[150:151]
	s_add_i32 m0, s17, 0x2000
	s_nop 0
	global_load_lds_dwordx4 v[222:223], off
	v_lshl_add_u64 v[222:223], s[8:9], 0, v[144:145]
	s_mov_b32 m0, s67
	s_nop 0
	global_load_lds_dwordx4 v[222:223], off
	s_mov_b32 m0, s87
	s_nop 0
	global_load_lds_dwordx4 v[224:225], off
	s_waitcnt vmcnt(8)
	s_waitcnt lgkmcnt(0)
	s_barrier
; #define PG8_STAGE(bufoff, gbase, voff) do { _Pragma("unroll") for (int _i = 0; _i < 2; ++_i) \
;         __builtin_amdgcn_global_load_lds((const unsigned*)((const char*)(gbase) + (voff)[_i]), (LAS unsigned*)(lds + (bufoff) + ldsw + _i * 8192), 16, 0, 0); } while (0)
; #define PG8_LDA(dst, b, h) do { _Pragma("unroll") for (int m = 0; m < 4; ++m) _Pragma("unroll") for (int k = 0; k < 2; ++k) dst[m][k] = *(const LAS bf16x8*)(lds + PG8_SA(b, h) + aoff + m * 2048 + k * 1024); } while (0)
; #define PG8_LDB(dst, b, h) do { _Pragma("unroll") for (int n = 0; n < 2; ++n) _Pragma("unroll") for (int k = 0; k < 2; ++k) dst[n][k] = *(const LAS bf16x8*)(lds + PG8_SB(b, h) + boff + n * 2048 + k * 1024); } while (0)
; #define PG8_MMA(ai, bj, At, Bt) do { __builtin_amdgcn_s_setprio(1); _Pragma("unroll") for (int m = 0; m < 4; ++m) _Pragma("unroll") for (int n = 0; n < 2; ++n) _Pragma("unroll") for (int k = 0; k < 2; ++k) \
;         acc[ai][bj][m][n] = __builtin_amdgcn_mfma_f32_16x16x32_bf16(Bt[n][k], At[m][k], acc[ai][bj][m][n], 0, 0, 0); __builtin_amdgcn_s_setprio(0); } while (0)
; #define PG8_WAIT_V(n) asm volatile("s_waitcnt vmcnt(" #n ")" ::: "memory")
; #define PG8_WAIT_L(n) asm volatile("s_waitcnt lgkmcnt(" #n ")" ::: "memory")
; #define PG8_BAR __builtin_amdgcn_s_barrier()
; #define PG8_SCHED __builtin_amdgcn_sched_barrier(0)
; template <class Epi>
; DI void gemm_phase(int wv, LAS unsigned char* lds, const Gemm g, const StaticOrder& S, const Epi& E) {
;     ...
;             PG8_WAIT_V(8); PG8_WAIT_L(0); PG8_BAR; PG8_MMA(1, 0, At, B0); PG8_MMA(1, 1, At, B1); PG8_BAR; PG8_SCHED;
;             PG8_LDB(B0, 1, 0); PG8_LDB(B1, 1, 1); PG8_SCHED; PG8_LDA(At, 1, 0); PG8_STAGE(PG8_SA(0, 1), a2 + hA, voffA);
;             PG8_WAIT_V(8); PG8_WAIT_L(0); PG8_BAR; PG8_MMA(0, 0, At, B0); PG8_MMA(0, 1, At, B1); PG8_BAR; PG8_SCHED;
	s_setprio 1
	s_waitcnt lgkmcnt(0)
	v_mfma_f32_16x16x32_bf16 v[60:63], v[128:131], v[178:181], v[60:63]
	v_mfma_f32_16x16x32_bf16 v[56:59], v[136:139], v[178:181], v[56:59]
	v_mfma_f32_16x16x32_bf16 v[44:47], v[128:131], v[196:199], v[44:47]
	v_mfma_f32_16x16x32_bf16 v[40:43], v[136:139], v[196:199], v[40:43]
	v_mfma_f32_16x16x32_bf16 v[28:31], v[128:131], v[204:207], v[28:31]
	v_mfma_f32_16x16x32_bf16 v[24:27], v[136:139], v[204:207], v[24:27]
	v_mfma_f32_16x16x32_bf16 v[12:15], v[128:131], v[212:215], v[12:15]
	v_mfma_f32_16x16x32_bf16 v[8:11], v[136:139], v[212:215], v[8:11]
	v_mfma_f32_16x16x32_bf16 v[60:63], v[132:135], v[182:185], v[60:63]
	v_mfma_f32_16x16x32_bf16 v[56:59], v[140:143], v[182:185], v[56:59]
	v_mfma_f32_16x16x32_bf16 v[44:47], v[132:135], v[200:203], v[44:47]
	v_mfma_f32_16x16x32_bf16 v[40:43], v[140:143], v[200:203], v[40:43]
	v_mfma_f32_16x16x32_bf16 v[28:31], v[132:135], v[208:211], v[28:31]
	v_mfma_f32_16x16x32_bf16 v[24:27], v[140:143], v[208:211], v[24:27]
	v_mfma_f32_16x16x32_bf16 v[12:15], v[132:135], v[216:219], v[12:15]
	v_mfma_f32_16x16x32_bf16 v[8:11], v[140:143], v[216:219], v[8:11]
	s_setprio 0
	s_setprio 1
	v_mfma_f32_16x16x32_bf16 v[52:55], v[162:165], v[178:181], v[52:55]
	v_mfma_f32_16x16x32_bf16 v[48:51], v[170:173], v[178:181], v[48:51]
	v_mfma_f32_16x16x32_bf16 v[36:39], v[162:165], v[196:199], v[36:39]
	v_mfma_f32_16x16x32_bf16 v[32:35], v[170:173], v[196:199], v[32:35]
	v_mfma_f32_16x16x32_bf16 v[20:23], v[162:165], v[204:207], v[20:23]
	v_mfma_f32_16x16x32_bf16 v[16:19], v[170:173], v[204:207], v[16:19]
	v_mfma_f32_16x16x32_bf16 v[4:7], v[162:165], v[212:215], v[4:7]
	v_mfma_f32_16x16x32_bf16 v[0:3], v[170:173], v[212:215], v[0:3]
	v_mfma_f32_16x16x32_bf16 v[52:55], v[166:169], v[182:185], v[52:55]
	v_mfma_f32_16x16x32_bf16 v[48:51], v[174:177], v[182:185], v[48:51]
	v_mfma_f32_16x16x32_bf16 v[36:39], v[166:169], v[200:203], v[36:39]
	v_mfma_f32_16x16x32_bf16 v[32:35], v[174:177], v[200:203], v[32:35]
	v_mfma_f32_16x16x32_bf16 v[20:23], v[166:169], v[208:211], v[20:23]
	v_mfma_f32_16x16x32_bf16 v[16:19], v[174:177], v[208:211], v[16:19]
	v_mfma_f32_16x16x32_bf16 v[4:7], v[166:169], v[216:219], v[4:7]
	v_mfma_f32_16x16x32_bf16 v[0:3], v[174:177], v[216:219], v[0:3]
	s_setprio 0
	s_barrier
	s_add_i32 s17, 0, 0x18000
	s_add_i32 s18, 0, 0x1c000
	v_add_u32_e32 v140, s17, v190
	v_add_u32_e32 v152, s18, v190
	ds_read_b128 v[128:131], v140
	ds_read_b128 v[132:135], v140 offset:1024
	ds_read_b128 v[136:139], v140 offset:2048
	ds_read_b128 v[140:143], v140 offset:3072
	ds_read_b128 v[162:165], v152
	ds_read_b128 v[166:169], v152 offset:1024
	ds_read_b128 v[170:173], v152 offset:2048
	ds_read_b128 v[174:177], v152 offset:3072
	s_add_u32 s8, s8, 0x40000
	s_addc_u32 s9, s9, 0
	s_mov_b32 m0, s89
	v_lshl_add_u64 v[226:227], s[8:9], 0, v[144:145]
	ds_read_b128 v[178:181], v193 offset:32768
	ds_read_b128 v[182:185], v193 offset:33792
	ds_read_b128 v[196:199], v193 offset:34816
	ds_read_b128 v[200:203], v193 offset:35840
	ds_read_b128 v[204:207], v193 offset:36864
	ds_read_b128 v[208:211], v193 offset:37888
	ds_read_b128 v[212:215], v193 offset:38912
	ds_read_b128 v[216:219], v193 offset:39936
	global_load_lds_dwordx4 v[226:227], off
	v_lshl_add_u64 v[226:227], s[8:9], 0, v[148:149]
	s_mov_b32 m0, s77
	s_nop 0
	global_load_lds_dwordx4 v[226:227], off
	s_waitcnt vmcnt(8)
	s_waitcnt lgkmcnt(0)
	s_barrier
	s_setprio 1
	s_waitcnt lgkmcnt(0)
	v_mfma_f32_16x16x32_bf16 v[124:127], v[128:131], v[178:181], v[124:127]
	v_mfma_f32_16x16x32_bf16 v[120:123], v[136:139], v[178:181], v[120:123]
	v_mfma_f32_16x16x32_bf16 v[108:111], v[128:131], v[196:199], v[108:111]
	v_mfma_f32_16x16x32_bf16 v[104:107], v[136:139], v[196:199], v[104:107]
	v_mfma_f32_16x16x32_bf16 v[92:95], v[128:131], v[204:207], v[92:95]
	v_mfma_f32_16x16x32_bf16 v[88:91], v[136:139], v[204:207], v[88:91]
	v_mfma_f32_16x16x32_bf16 v[76:79], v[128:131], v[212:215], v[76:79]
	v_mfma_f32_16x16x32_bf16 v[72:75], v[136:139], v[212:215], v[72:75]
	v_mfma_f32_16x16x32_bf16 v[124:127], v[132:135], v[182:185], v[124:127]
	v_mfma_f32_16x16x32_bf16 v[120:123], v[140:143], v[182:185], v[120:123]
	v_mfma_f32_16x16x32_bf16 v[108:111], v[132:135], v[200:203], v[108:111]
	v_mfma_f32_16x16x32_bf16 v[104:107], v[140:143], v[200:203], v[104:107]
	v_mfma_f32_16x16x32_bf16 v[92:95], v[132:135], v[208:211], v[92:95]
	v_mfma_f32_16x16x32_bf16 v[88:91], v[140:143], v[208:211], v[88:91]
	v_mfma_f32_16x16x32_bf16 v[76:79], v[132:135], v[216:219], v[76:79]
	v_mfma_f32_16x16x32_bf16 v[72:75], v[140:143], v[216:219], v[72:75]
	s_setprio 0
	s_setprio 1
	v_mfma_f32_16x16x32_bf16 v[116:119], v[162:165], v[178:181], v[116:119]
	v_mfma_f32_16x16x32_bf16 v[112:115], v[170:173], v[178:181], v[112:115]
	v_mfma_f32_16x16x32_bf16 v[100:103], v[162:165], v[196:199], v[100:103]
	v_mfma_f32_16x16x32_bf16 v[96:99], v[170:173], v[196:199], v[96:99]
	v_mfma_f32_16x16x32_bf16 v[84:87], v[162:165], v[204:207], v[84:87]
	v_mfma_f32_16x16x32_bf16 v[80:83], v[170:173], v[204:207], v[80:83]
	v_mfma_f32_16x16x32_bf16 v[68:71], v[162:165], v[212:215], v[68:71]
	v_mfma_f32_16x16x32_bf16 v[64:67], v[170:173], v[212:215], v[64:67]
	v_mfma_f32_16x16x32_bf16 v[116:119], v[166:169], v[182:185], v[116:119]
	v_mfma_f32_16x16x32_bf16 v[112:115], v[174:177], v[182:185], v[112:115]
	v_mfma_f32_16x16x32_bf16 v[100:103], v[166:169], v[200:203], v[100:103]
	v_mfma_f32_16x16x32_bf16 v[96:99], v[174:177], v[200:203], v[96:99]
	v_mfma_f32_16x16x32_bf16 v[84:87], v[166:169], v[208:211], v[84:87]
	v_mfma_f32_16x16x32_bf16 v[80:83], v[174:177], v[208:211], v[80:83]
	v_mfma_f32_16x16x32_bf16 v[68:71], v[166:169], v[216:219], v[68:71]
	v_mfma_f32_16x16x32_bf16 v[64:67], v[174:177], v[216:219], v[64:67]
	s_setprio 0
	s_barrier
; #define PG8_STAGE(bufoff, gbase, voff) do { _Pragma("unroll") for (int _i = 0; _i < 2; ++_i) \
;         __builtin_amdgcn_global_load_lds((const unsigned*)((const char*)(gbase) + (voff)[_i]), (LAS unsigned*)(lds + (bufoff) + ldsw + _i * 8192), 16, 0, 0); } while (0)
; #define PG8_LDA(dst, b, h) do { _Pragma("unroll") for (int m = 0; m < 4; ++m) _Pragma("unroll") for (int k = 0; k < 2; ++k) dst[m][k] = *(const LAS bf16x8*)(lds + PG8_SA(b, h) + aoff + m * 2048 + k * 1024); } while (0)
; #define PG8_MMA(ai, bj, At, Bt) do { __builtin_amdgcn_s_setprio(1); _Pragma("unroll") for (int m = 0; m < 4; ++m) _Pragma("unroll") for (int n = 0; n < 2; ++n) _Pragma("unroll") for (int k = 0; k < 2; ++k) \
;         acc[ai][bj][m][n] = __builtin_amdgcn_mfma_f32_16x16x32_bf16(Bt[n][k], At[m][k], acc[ai][bj][m][n], 0, 0, 0); __builtin_amdgcn_s_setprio(0); } while (0)
; #define PG8_WAIT_V(n) asm volatile("s_waitcnt vmcnt(" #n ")" ::: "memory")
; #define PG8_WAIT_L(n) asm volatile("s_waitcnt lgkmcnt(" #n ")" ::: "memory")
; #define PG8_BAR __builtin_amdgcn_s_barrier()
; #define PG8_SCHED __builtin_amdgcn_sched_barrier(0)
; template <class Epi>
; DI void gemm_phase(int wv, LAS unsigned char* lds, const Gemm g, const StaticOrder& S, const Epi& E) {
;     ...
;             PG8_LDA(At, 1, 1); PG8_STAGE(PG8_SB(1, 0), b3, voffB); PG8_STAGE(PG8_SB(1, 1), b3 + hB, voffB); PG8_STAGE(PG8_SA(1, 0), a3, voffA);
;             PG8_WAIT_V(8); PG8_WAIT_L(0); PG8_BAR; PG8_MMA(1, 0, At, B0); PG8_MMA(1, 1, At, B1); PG8_BAR; PG8_SCHED;
;         }
	s_add_i32 s8, s17, s66
	v_lshl_add_u64 v[186:187], v[186:187], 0, s[68:69]
	s_mov_b32 m0, s8
	ds_read_b128 v[178:181], v193 offset:49152
	ds_read_b128 v[182:185], v193 offset:50176
	ds_read_b128 v[196:199], v193 offset:51200
	ds_read_b128 v[200:203], v193 offset:52224
	ds_read_b128 v[204:207], v193 offset:53248
	ds_read_b128 v[208:211], v193 offset:54272
	ds_read_b128 v[212:215], v193 offset:55296
	ds_read_b128 v[216:219], v193 offset:56320
	global_load_lds_dwordx4 v[186:187], off
	s_add_i32 m0, s8, 0x2000
	s_add_u32 s6, s6, 0x40080
	v_lshl_add_u64 v[186:187], v[220:221], 0, s[68:69]
	s_addc_u32 s7, s7, 0
	s_add_i32 s8, s18, s66
	global_load_lds_dwordx4 v[186:187], off
	v_lshl_add_u64 v[186:187], s[6:7], 0, v[146:147]
	s_mov_b32 m0, s8
	s_nop 0
	global_load_lds_dwordx4 v[186:187], off
	v_lshl_add_u64 v[186:187], s[6:7], 0, v[150:151]
	s_add_i32 m0, s8, 0x2000
	s_nop 0
	global_load_lds_dwordx4 v[186:187], off
	v_lshl_add_u64 v[186:187], v[222:223], 0, s[68:69]
	s_mov_b32 m0, s39
	s_nop 0
	global_load_lds_dwordx4 v[186:187], off
	v_lshl_add_u64 v[186:187], v[224:225], 0, s[68:69]
	s_mov_b32 m0, s62
	s_nop 0
	global_load_lds_dwordx4 v[186:187], off
	s_waitcnt vmcnt(8)
	s_waitcnt lgkmcnt(0)
	s_barrier
	s_setprio 1
	s_waitcnt lgkmcnt(0)
	v_mfma_f32_16x16x32_bf16 v[60:63], v[128:131], v[178:181], v[60:63]
	v_mfma_f32_16x16x32_bf16 v[56:59], v[136:139], v[178:181], v[56:59]
	v_mfma_f32_16x16x32_bf16 v[44:47], v[128:131], v[196:199], v[44:47]
	v_mfma_f32_16x16x32_bf16 v[40:43], v[136:139], v[196:199], v[40:43]
	v_mfma_f32_16x16x32_bf16 v[28:31], v[128:131], v[204:207], v[28:31]
	v_mfma_f32_16x16x32_bf16 v[24:27], v[136:139], v[204:207], v[24:27]
	v_mfma_f32_16x16x32_bf16 v[12:15], v[128:131], v[212:215], v[12:15]
	v_mfma_f32_16x16x32_bf16 v[8:11], v[136:139], v[212:215], v[8:11]
	v_mfma_f32_16x16x32_bf16 v[60:63], v[132:135], v[182:185], v[60:63]
	v_mfma_f32_16x16x32_bf16 v[56:59], v[140:143], v[182:185], v[56:59]
	v_mfma_f32_16x16x32_bf16 v[44:47], v[132:135], v[200:203], v[44:47]
	v_mfma_f32_16x16x32_bf16 v[40:43], v[140:143], v[200:203], v[40:43]
	v_mfma_f32_16x16x32_bf16 v[28:31], v[132:135], v[208:211], v[28:31]
	v_mfma_f32_16x16x32_bf16 v[24:27], v[140:143], v[208:211], v[24:27]
	v_mfma_f32_16x16x32_bf16 v[12:15], v[132:135], v[216:219], v[12:15]
	v_mfma_f32_16x16x32_bf16 v[8:11], v[140:143], v[216:219], v[8:11]
	s_setprio 0
	s_setprio 1
	v_mfma_f32_16x16x32_bf16 v[52:55], v[162:165], v[178:181], v[52:55]
	v_mfma_f32_16x16x32_bf16 v[48:51], v[170:173], v[178:181], v[48:51]
	v_mfma_f32_16x16x32_bf16 v[36:39], v[162:165], v[196:199], v[36:39]
	v_mfma_f32_16x16x32_bf16 v[32:35], v[170:173], v[196:199], v[32:35]
	v_mfma_f32_16x16x32_bf16 v[20:23], v[162:165], v[204:207], v[20:23]
	v_mfma_f32_16x16x32_bf16 v[16:19], v[170:173], v[204:207], v[16:19]
	v_mfma_f32_16x16x32_bf16 v[4:7], v[162:165], v[212:215], v[4:7]
	v_mfma_f32_16x16x32_bf16 v[0:3], v[170:173], v[212:215], v[0:3]
	v_mfma_f32_16x16x32_bf16 v[52:55], v[166:169], v[182:185], v[52:55]
	v_mfma_f32_16x16x32_bf16 v[48:51], v[174:177], v[182:185], v[48:51]
	v_mfma_f32_16x16x32_bf16 v[36:39], v[166:169], v[200:203], v[36:39]
	v_mfma_f32_16x16x32_bf16 v[32:35], v[174:177], v[200:203], v[32:35]
	v_mfma_f32_16x16x32_bf16 v[20:23], v[166:169], v[208:211], v[20:23]
	v_mfma_f32_16x16x32_bf16 v[16:19], v[174:177], v[208:211], v[16:19]
	v_mfma_f32_16x16x32_bf16 v[4:7], v[166:169], v[216:219], v[4:7]
	v_mfma_f32_16x16x32_bf16 v[0:3], v[174:177], v[216:219], v[0:3]
	s_setprio 0
	s_add_i32 s16, s16, 2
	s_add_u32 s14, s14, 0x100
	s_addc_u32 s15, s15, 0
	s_add_u32 s4, s4, 0x100
	s_addc_u32 s5, s5, 0
	s_cmp_gt_u32 s16, 13
	s_barrier
	s_cbranch_scc0 .LBB0_873
	s_and_b64 vcc, exec, s[70:71]
	s_cbranch_vccz .LBB0_876
	s_barrier

; #define PG8_STAGE(bufoff, gbase, voff) do { _Pragma("unroll") for (int _i = 0; _i < 2; ++_i) \
;         __builtin_amdgcn_global_load_lds((const unsigned*)((const char*)(gbase) + (voff)[_i]), (LAS unsigned*)(lds + (bufoff) + ldsw + _i * 8192), 16, 0, 0); } while (0)
; #define PG8_LDA(dst, b, h) do { _Pragma("unroll") for (int m = 0; m < 4; ++m) _Pragma("unroll") for (int k = 0; k < 2; ++k) dst[m][k] = *(const LAS bf16x8*)(lds + PG8_SA(b, h) + aoff + m * 2048 + k * 1024); } while (0)
; #define PG8_LDB(dst, b, h) do { _Pragma("unroll") for (int n = 0; n < 2; ++n) _Pragma("unroll") for (int k = 0; k < 2; ++k) dst[n][k] = *(const LAS bf16x8*)(lds + PG8_SB(b, h) + boff + n * 2048 + k * 1024); } while (0)
; #define PG8_MMA(ai, bj, At, Bt) do { __builtin_amdgcn_s_setprio(1); _Pragma("unroll") for (int m = 0; m < 4; ++m) _Pragma("unroll") for (int n = 0; n < 2; ++n) _Pragma("unroll") for (int k = 0; k < 2; ++k) \
;         acc[ai][bj][m][n] = __builtin_amdgcn_mfma_f32_16x16x32_bf16(Bt[n][k], At[m][k], acc[ai][bj][m][n], 0, 0, 0); __builtin_amdgcn_s_setprio(0); } while (0)
; #define PG8_WAIT_V(n) asm volatile("s_waitcnt vmcnt(" #n ")" ::: "memory")
; #define PG8_WAIT_L(n) asm volatile("s_waitcnt lgkmcnt(" #n ")" ::: "memory")
; #define PG8_BAR __builtin_amdgcn_s_barrier()
; #define PG8_SCHED __builtin_amdgcn_sched_barrier(0)
; template <class Epi>
; DI void gemm_phase(int wv, LAS unsigned char* lds, const Gemm g, const StaticOrder& S, const Epi& E) {
;     ...
;         for (int t = 0; t < nt; t += 2) {
;             const bool last = (t == nt - 2);
;             const char* a1 = cA + (size_t)(t + 1) * kstep;
;             const char* a2 = last ? nA : cA + (size_t)(t + 2) * kstep; const char* b2 = last ? nB : cB + (size_t)(t + 2) * kstep;
;             const char* a3 = a2 + kstep; const char* b3 = b2 + kstep;
;             PG8_LDB(B0, 0, 0); PG8_LDB(B1, 0, 1); PG8_SCHED; PG8_LDA(At, 0, 0); PG8_STAGE(PG8_SA(1, 1), a1 + hA, voffA);
;             PG8_WAIT_V(8); PG8_WAIT_L(0); PG8_BAR; PG8_MMA(0, 0, At, B0); PG8_MMA(0, 1, At, B1); PG8_BAR; PG8_SCHED;
;             PG8_LDA(At, 0, 1); PG8_STAGE(PG8_SB(0, 0), b2, voffB); PG8_STAGE(PG8_SB(0, 1), b2 + hB, voffB); PG8_STAGE(PG8_SA(0, 0), a2, voffA);
.LBB0_1278:
	ds_read_b128 v[146:149], v143
	ds_read_b128 v[150:153], v143 offset:1024
	ds_read_b128 v[154:157], v143 offset:2048
	ds_read_b128 v[158:161], v143 offset:3072
	ds_read_b128 v[162:165], v144
	ds_read_b128 v[166:169], v144 offset:1024
	ds_read_b128 v[170:173], v144 offset:2048
	ds_read_b128 v[174:177], v144 offset:3072
	s_add_u32 s24, s22, 0xfffc0080
	s_addc_u32 s25, s23, -1
	s_cmp_eq_u32 s55, 12
	s_cselect_b32 s27, s15, s25
	s_cselect_b32 s26, s47, s24
	s_cselect_b32 s25, s13, s54
	s_cselect_b32 s24, s50, s51
	v_lshl_add_u64 v[210:211], s[22:23], 0, v[138:139]
	s_add_i32 m0, s36, 0xc000
	ds_read_b128 v[178:181], v145
	ds_read_b128 v[182:185], v145 offset:1024
	ds_read_b128 v[186:189], v145 offset:2048
	ds_read_b128 v[190:193], v145 offset:3072
	ds_read_b128 v[194:197], v145 offset:4096
	ds_read_b128 v[198:201], v145 offset:5120
	ds_read_b128 v[202:205], v145 offset:6144
	ds_read_b128 v[206:209], v145 offset:7168
	global_load_lds_dwordx4 v[210:211], off
	v_lshl_add_u64 v[210:211], s[22:23], 0, v[136:137]
	s_add_i32 m0, s36, 0xe000
	s_nop 0
	global_load_lds_dwordx4 v[210:211], off
	s_waitcnt vmcnt(8)
	s_waitcnt lgkmcnt(0)
	s_barrier
	s_setprio 1
	s_waitcnt lgkmcnt(0)
	v_mfma_f32_16x16x32_bf16 v[124:127], v[146:149], v[178:181], v[124:127]
	v_mfma_f32_16x16x32_bf16 v[120:123], v[154:157], v[178:181], v[120:123]
	v_mfma_f32_16x16x32_bf16 v[116:119], v[146:149], v[186:189], v[116:119]
	v_mfma_f32_16x16x32_bf16 v[112:115], v[154:157], v[186:189], v[112:115]
	v_mfma_f32_16x16x32_bf16 v[104:107], v[146:149], v[194:197], v[104:107]
	v_mfma_f32_16x16x32_bf16 v[96:99], v[154:157], v[194:197], v[96:99]
	v_mfma_f32_16x16x32_bf16 v[88:91], v[146:149], v[202:205], v[88:91]
	v_mfma_f32_16x16x32_bf16 v[80:83], v[154:157], v[202:205], v[80:83]
	v_mfma_f32_16x16x32_bf16 v[124:127], v[150:153], v[182:185], v[124:127]
	v_mfma_f32_16x16x32_bf16 v[120:123], v[158:161], v[182:185], v[120:123]
	v_mfma_f32_16x16x32_bf16 v[116:119], v[150:153], v[190:193], v[116:119]
	v_mfma_f32_16x16x32_bf16 v[112:115], v[158:161], v[190:193], v[112:115]
	v_mfma_f32_16x16x32_bf16 v[104:107], v[150:153], v[198:201], v[104:107]
	v_mfma_f32_16x16x32_bf16 v[96:99], v[158:161], v[198:201], v[96:99]
	v_mfma_f32_16x16x32_bf16 v[88:91], v[150:153], v[206:209], v[88:91]
	v_mfma_f32_16x16x32_bf16 v[80:83], v[158:161], v[206:209], v[80:83]
	s_setprio 0
	s_setprio 1
	v_mfma_f32_16x16x32_bf16 v[108:111], v[162:165], v[178:181], v[108:111]
	v_mfma_f32_16x16x32_bf16 v[100:103], v[170:173], v[178:181], v[100:103]
	v_mfma_f32_16x16x32_bf16 v[92:95], v[162:165], v[186:189], v[92:95]
	v_mfma_f32_16x16x32_bf16 v[84:87], v[170:173], v[186:189], v[84:87]
	v_mfma_f32_16x16x32_bf16 v[76:79], v[162:165], v[194:197], v[76:79]
	v_mfma_f32_16x16x32_bf16 v[72:75], v[170:173], v[194:197], v[72:75]
	v_mfma_f32_16x16x32_bf16 v[68:71], v[162:165], v[202:205], v[68:71]
	v_mfma_f32_16x16x32_bf16 v[64:67], v[170:173], v[202:205], v[64:67]
	v_mfma_f32_16x16x32_bf16 v[108:111], v[166:169], v[182:185], v[108:111]
	v_mfma_f32_16x16x32_bf16 v[100:103], v[174:177], v[182:185], v[100:103]
	v_mfma_f32_16x16x32_bf16 v[92:95], v[166:169], v[190:193], v[92:95]
	v_mfma_f32_16x16x32_bf16 v[84:87], v[174:177], v[190:193], v[84:87]
	v_mfma_f32_16x16x32_bf16 v[76:79], v[166:169], v[198:201], v[76:79]
	v_mfma_f32_16x16x32_bf16 v[72:75], v[174:177], v[198:201], v[72:75]
	v_mfma_f32_16x16x32_bf16 v[68:71], v[166:169], v[206:209], v[68:71]
	v_mfma_f32_16x16x32_bf16 v[64:67], v[174:177], v[206:209], v[64:67]
	s_setprio 0
	s_barrier
	s_add_i32 s57, s45, s34
	v_lshl_add_u64 v[210:211], s[24:25], 0, v[132:133]
	s_mov_b32 m0, s57
	ds_read_b128 v[178:181], v145 offset:16384
	ds_read_b128 v[182:185], v145 offset:17408
	ds_read_b128 v[186:189], v145 offset:18432
	ds_read_b128 v[190:193], v145 offset:19456
	ds_read_b128 v[194:197], v145 offset:20480
	ds_read_b128 v[198:201], v145 offset:21504
	ds_read_b128 v[202:205], v145 offset:22528
	ds_read_b128 v[206:209], v145 offset:23552
	global_load_lds_dwordx4 v[210:211], off
	s_add_i32 m0, s57, 0x2000
	s_add_u32 s60, s24, 0x40000
	v_lshl_add_u64 v[212:213], s[24:25], 0, v[128:129]
	s_addc_u32 s61, s25, 0
	s_add_i32 s57, s46, s34
	global_load_lds_dwordx4 v[212:213], off
	v_lshl_add_u64 v[214:215], s[60:61], 0, v[132:133]
	s_mov_b32 m0, s57
	v_lshl_add_u64 v[216:217], s[26:27], 0, v[130:131]
	global_load_lds_dwordx4 v[214:215], off
	v_lshl_add_u64 v[214:215], s[60:61], 0, v[128:129]
	s_add_i32 m0, s57, 0x2000
	s_nop 0
	global_load_lds_dwordx4 v[214:215], off
	v_lshl_add_u64 v[214:215], s[26:27], 0, v[134:135]
	s_mov_b32 m0, s36
	s_nop 0
	global_load_lds_dwordx4 v[214:215], off
	s_mov_b32 m0, s37
	s_nop 0
	global_load_lds_dwordx4 v[216:217], off
	s_waitcnt vmcnt(8)
	s_waitcnt lgkmcnt(0)
	s_barrier
; #define PG8_STAGE(bufoff, gbase, voff) do { _Pragma("unroll") for (int _i = 0; _i < 2; ++_i) \
;         __builtin_amdgcn_global_load_lds((const unsigned*)((const char*)(gbase) + (voff)[_i]), (LAS unsigned*)(lds + (bufoff) + ldsw + _i * 8192), 16, 0, 0); } while (0)
; #define PG8_LDA(dst, b, h) do { _Pragma("unroll") for (int m = 0; m < 4; ++m) _Pragma("unroll") for (int k = 0; k < 2; ++k) dst[m][k] = *(const LAS bf16x8*)(lds + PG8_SA(b, h) + aoff + m * 2048 + k * 1024); } while (0)
; #define PG8_LDB(dst, b, h) do { _Pragma("unroll") for (int n = 0; n < 2; ++n) _Pragma("unroll") for (int k = 0; k < 2; ++k) dst[n][k] = *(const LAS bf16x8*)(lds + PG8_SB(b, h) + boff + n * 2048 + k * 1024); } while (0)
; #define PG8_MMA(ai, bj, At, Bt) do { __builtin_amdgcn_s_setprio(1); _Pragma("unroll") for (int m = 0; m < 4; ++m) _Pragma("unroll") for (int n = 0; n < 2; ++n) _Pragma("unroll") for (int k = 0; k < 2; ++k) \
;         acc[ai][bj][m][n] = __builtin_amdgcn_mfma_f32_16x16x32_bf16(Bt[n][k], At[m][k], acc[ai][bj][m][n], 0, 0, 0); __builtin_amdgcn_s_setprio(0); } while (0)
; #define PG8_WAIT_V(n) asm volatile("s_waitcnt vmcnt(" #n ")" ::: "memory")
; #define PG8_WAIT_L(n) asm volatile("s_waitcnt lgkmcnt(" #n ")" ::: "memory")
; #define PG8_BAR __builtin_amdgcn_s_barrier()
; #define PG8_SCHED __builtin_amdgcn_sched_barrier(0)
; template <class Epi>
; DI void gemm_phase(int wv, LAS unsigned char* lds, const Gemm g, const StaticOrder& S, const Epi& E) {
;     ...
;             PG8_WAIT_V(8); PG8_WAIT_L(0); PG8_BAR; PG8_MMA(1, 0, At, B0); PG8_MMA(1, 1, At, B1); PG8_BAR; PG8_SCHED;
;             PG8_LDB(B0, 1, 0); PG8_LDB(B1, 1, 1); PG8_SCHED; PG8_LDA(At, 1, 0); PG8_STAGE(PG8_SA(0, 1), a2 + hA, voffA);
;             PG8_WAIT_V(8); PG8_WAIT_L(0); PG8_BAR; PG8_MMA(0, 0, At, B0); PG8_MMA(0, 1, At, B1); PG8_BAR; PG8_SCHED;
	s_setprio 1
	s_waitcnt lgkmcnt(0)
	v_mfma_f32_16x16x32_bf16 v[60:63], v[146:149], v[178:181], v[60:63]
	v_mfma_f32_16x16x32_bf16 v[56:59], v[154:157], v[178:181], v[56:59]
	v_mfma_f32_16x16x32_bf16 v[52:55], v[146:149], v[186:189], v[52:55]
	v_mfma_f32_16x16x32_bf16 v[48:51], v[154:157], v[186:189], v[48:51]
	v_mfma_f32_16x16x32_bf16 v[40:43], v[146:149], v[194:197], v[40:43]
	v_mfma_f32_16x16x32_bf16 v[32:35], v[154:157], v[194:197], v[32:35]
	v_mfma_f32_16x16x32_bf16 v[24:27], v[146:149], v[202:205], v[24:27]
	v_mfma_f32_16x16x32_bf16 v[16:19], v[154:157], v[202:205], v[16:19]
	v_mfma_f32_16x16x32_bf16 v[60:63], v[150:153], v[182:185], v[60:63]
	v_mfma_f32_16x16x32_bf16 v[56:59], v[158:161], v[182:185], v[56:59]
	v_mfma_f32_16x16x32_bf16 v[52:55], v[150:153], v[190:193], v[52:55]
	v_mfma_f32_16x16x32_bf16 v[48:51], v[158:161], v[190:193], v[48:51]
	v_mfma_f32_16x16x32_bf16 v[40:43], v[150:153], v[198:201], v[40:43]
	v_mfma_f32_16x16x32_bf16 v[32:35], v[158:161], v[198:201], v[32:35]
	v_mfma_f32_16x16x32_bf16 v[24:27], v[150:153], v[206:209], v[24:27]
	v_mfma_f32_16x16x32_bf16 v[16:19], v[158:161], v[206:209], v[16:19]
	s_setprio 0
	s_setprio 1
	v_mfma_f32_16x16x32_bf16 v[44:47], v[162:165], v[178:181], v[44:47]
	v_mfma_f32_16x16x32_bf16 v[36:39], v[170:173], v[178:181], v[36:39]
	v_mfma_f32_16x16x32_bf16 v[28:31], v[162:165], v[186:189], v[28:31]
	v_mfma_f32_16x16x32_bf16 v[20:23], v[170:173], v[186:189], v[20:23]
	v_mfma_f32_16x16x32_bf16 v[12:15], v[162:165], v[194:197], v[12:15]
	v_mfma_f32_16x16x32_bf16 v[8:11], v[170:173], v[194:197], v[8:11]
	v_mfma_f32_16x16x32_bf16 v[4:7], v[162:165], v[202:205], v[4:7]
	v_mfma_f32_16x16x32_bf16 v[0:3], v[170:173], v[202:205], v[0:3]
	v_mfma_f32_16x16x32_bf16 v[44:47], v[166:169], v[182:185], v[44:47]
	v_mfma_f32_16x16x32_bf16 v[36:39], v[174:177], v[182:185], v[36:39]
	v_mfma_f32_16x16x32_bf16 v[28:31], v[166:169], v[190:193], v[28:31]
	v_mfma_f32_16x16x32_bf16 v[20:23], v[174:177], v[190:193], v[20:23]
	v_mfma_f32_16x16x32_bf16 v[12:15], v[166:169], v[198:201], v[12:15]
	v_mfma_f32_16x16x32_bf16 v[8:11], v[174:177], v[198:201], v[8:11]
	v_mfma_f32_16x16x32_bf16 v[4:7], v[166:169], v[206:209], v[4:7]
	v_mfma_f32_16x16x32_bf16 v[0:3], v[174:177], v[206:209], v[0:3]
	s_setprio 0
	s_barrier
	s_add_i32 s57, 0, 0x18000
	s_add_i32 s60, 0, 0x1c000
	v_add_u32_e32 v158, s57, v142
	v_add_u32_e32 v174, s60, v142
	ds_read_b128 v[146:149], v158
	ds_read_b128 v[150:153], v158 offset:1024
	ds_read_b128 v[154:157], v158 offset:2048
	ds_read_b128 v[158:161], v158 offset:3072
	ds_read_b128 v[162:165], v174
	ds_read_b128 v[166:169], v174 offset:1024
	ds_read_b128 v[170:173], v174 offset:2048
	ds_read_b128 v[174:177], v174 offset:3072
	s_add_u32 s26, s26, 0x40000
	s_addc_u32 s27, s27, 0
	s_mov_b32 m0, s38
	v_lshl_add_u64 v[218:219], s[26:27], 0, v[134:135]
	ds_read_b128 v[178:181], v145 offset:32768
	ds_read_b128 v[182:185], v145 offset:33792
	ds_read_b128 v[186:189], v145 offset:34816
	ds_read_b128 v[190:193], v145 offset:35840
	ds_read_b128 v[194:197], v145 offset:36864
	ds_read_b128 v[198:201], v145 offset:37888
	ds_read_b128 v[202:205], v145 offset:38912
	ds_read_b128 v[206:209], v145 offset:39936
	global_load_lds_dwordx4 v[218:219], off
	v_lshl_add_u64 v[218:219], s[26:27], 0, v[130:131]
	s_mov_b32 m0, s39
	s_nop 0
	global_load_lds_dwordx4 v[218:219], off
	s_waitcnt vmcnt(8)
	s_waitcnt lgkmcnt(0)
	s_barrier
	s_setprio 1
	s_waitcnt lgkmcnt(0)
	v_mfma_f32_16x16x32_bf16 v[124:127], v[146:149], v[178:181], v[124:127]
	v_mfma_f32_16x16x32_bf16 v[120:123], v[154:157], v[178:181], v[120:123]
	v_mfma_f32_16x16x32_bf16 v[116:119], v[146:149], v[186:189], v[116:119]
	v_mfma_f32_16x16x32_bf16 v[112:115], v[154:157], v[186:189], v[112:115]
	v_mfma_f32_16x16x32_bf16 v[104:107], v[146:149], v[194:197], v[104:107]
	v_mfma_f32_16x16x32_bf16 v[96:99], v[154:157], v[194:197], v[96:99]
	v_mfma_f32_16x16x32_bf16 v[88:91], v[146:149], v[202:205], v[88:91]
	v_mfma_f32_16x16x32_bf16 v[80:83], v[154:157], v[202:205], v[80:83]
	v_mfma_f32_16x16x32_bf16 v[124:127], v[150:153], v[182:185], v[124:127]
	v_mfma_f32_16x16x32_bf16 v[120:123], v[158:161], v[182:185], v[120:123]
	v_mfma_f32_16x16x32_bf16 v[116:119], v[150:153], v[190:193], v[116:119]
	v_mfma_f32_16x16x32_bf16 v[112:115], v[158:161], v[190:193], v[112:115]
	v_mfma_f32_16x16x32_bf16 v[104:107], v[150:153], v[198:201], v[104:107]
	v_mfma_f32_16x16x32_bf16 v[96:99], v[158:161], v[198:201], v[96:99]
	v_mfma_f32_16x16x32_bf16 v[88:91], v[150:153], v[206:209], v[88:91]
	v_mfma_f32_16x16x32_bf16 v[80:83], v[158:161], v[206:209], v[80:83]
	s_setprio 0
	s_setprio 1
	v_mfma_f32_16x16x32_bf16 v[108:111], v[162:165], v[178:181], v[108:111]
	v_mfma_f32_16x16x32_bf16 v[100:103], v[170:173], v[178:181], v[100:103]
	v_mfma_f32_16x16x32_bf16 v[92:95], v[162:165], v[186:189], v[92:95]
	v_mfma_f32_16x16x32_bf16 v[84:87], v[170:173], v[186:189], v[84:87]
	v_mfma_f32_16x16x32_bf16 v[76:79], v[162:165], v[194:197], v[76:79]
	v_mfma_f32_16x16x32_bf16 v[72:75], v[170:173], v[194:197], v[72:75]
	v_mfma_f32_16x16x32_bf16 v[68:71], v[162:165], v[202:205], v[68:71]
	v_mfma_f32_16x16x32_bf16 v[64:67], v[170:173], v[202:205], v[64:67]
	v_mfma_f32_16x16x32_bf16 v[108:111], v[166:169], v[182:185], v[108:111]
	v_mfma_f32_16x16x32_bf16 v[100:103], v[174:177], v[182:185], v[100:103]
	v_mfma_f32_16x16x32_bf16 v[92:95], v[166:169], v[190:193], v[92:95]
	v_mfma_f32_16x16x32_bf16 v[84:87], v[174:177], v[190:193], v[84:87]
	v_mfma_f32_16x16x32_bf16 v[76:79], v[166:169], v[198:201], v[76:79]
	v_mfma_f32_16x16x32_bf16 v[72:75], v[174:177], v[198:201], v[72:75]
	v_mfma_f32_16x16x32_bf16 v[68:71], v[166:169], v[206:209], v[68:71]
	v_mfma_f32_16x16x32_bf16 v[64:67], v[174:177], v[206:209], v[64:67]
	s_setprio 0
	s_barrier
; #define PG8_STAGE(bufoff, gbase, voff) do { _Pragma("unroll") for (int _i = 0; _i < 2; ++_i) \
;         __builtin_amdgcn_global_load_lds((const unsigned*)((const char*)(gbase) + (voff)[_i]), (LAS unsigned*)(lds + (bufoff) + ldsw + _i * 8192), 16, 0, 0); } while (0)
; #define PG8_LDA(dst, b, h) do { _Pragma("unroll") for (int m = 0; m < 4; ++m) _Pragma("unroll") for (int k = 0; k < 2; ++k) dst[m][k] = *(const LAS bf16x8*)(lds + PG8_SA(b, h) + aoff + m * 2048 + k * 1024); } while (0)
; #define PG8_MMA(ai, bj, At, Bt) do { __builtin_amdgcn_s_setprio(1); _Pragma("unroll") for (int m = 0; m < 4; ++m) _Pragma("unroll") for (int n = 0; n < 2; ++n) _Pragma("unroll") for (int k = 0; k < 2; ++k) \
;         acc[ai][bj][m][n] = __builtin_amdgcn_mfma_f32_16x16x32_bf16(Bt[n][k], At[m][k], acc[ai][bj][m][n], 0, 0, 0); __builtin_amdgcn_s_setprio(0); } while (0)
; #define PG8_WAIT_V(n) asm volatile("s_waitcnt vmcnt(" #n ")" ::: "memory")
; #define PG8_WAIT_L(n) asm volatile("s_waitcnt lgkmcnt(" #n ")" ::: "memory")
; #define PG8_BAR __builtin_amdgcn_s_barrier()
; #define PG8_SCHED __builtin_amdgcn_sched_barrier(0)
; template <class Epi>
; DI void gemm_phase(int wv, LAS unsigned char* lds, const Gemm g, const StaticOrder& S, const Epi& E) {
;     ...
;             PG8_LDA(At, 1, 1); PG8_STAGE(PG8_SB(1, 0), b3, voffB); PG8_STAGE(PG8_SB(1, 1), b3 + hB, voffB); PG8_STAGE(PG8_SA(1, 0), a3, voffA);
;             PG8_WAIT_V(8); PG8_WAIT_L(0); PG8_BAR; PG8_MMA(1, 0, At, B0); PG8_MMA(1, 1, At, B1); PG8_BAR; PG8_SCHED;
;         }
;         if (wr == 0) PG8_BAR;
	s_add_i32 s26, s57, s34
	v_lshl_add_u64 v[210:211], v[210:211], 0, s[6:7]
	s_mov_b32 m0, s26
	ds_read_b128 v[178:181], v145 offset:49152
	ds_read_b128 v[182:185], v145 offset:50176
	ds_read_b128 v[186:189], v145 offset:51200
	ds_read_b128 v[190:193], v145 offset:52224
	ds_read_b128 v[194:197], v145 offset:53248
	ds_read_b128 v[198:201], v145 offset:54272
	ds_read_b128 v[202:205], v145 offset:55296
	ds_read_b128 v[206:209], v145 offset:56320
	global_load_lds_dwordx4 v[210:211], off
	s_add_i32 m0, s26, 0x2000
	s_add_u32 s24, s24, 0x40080
	v_lshl_add_u64 v[210:211], v[212:213], 0, s[6:7]
	s_addc_u32 s25, s25, 0
	s_add_i32 s26, s60, s34
	global_load_lds_dwordx4 v[210:211], off
	v_lshl_add_u64 v[210:211], s[24:25], 0, v[132:133]
	s_mov_b32 m0, s26
	s_nop 0
	global_load_lds_dwordx4 v[210:211], off
	v_lshl_add_u64 v[210:211], s[24:25], 0, v[128:129]
	s_add_i32 m0, s26, 0x2000
	s_nop 0
	global_load_lds_dwordx4 v[210:211], off
	v_lshl_add_u64 v[210:211], v[214:215], 0, s[6:7]
	s_mov_b32 m0, s43
	s_nop 0
	global_load_lds_dwordx4 v[210:211], off
	v_lshl_add_u64 v[210:211], v[216:217], 0, s[6:7]
	s_mov_b32 m0, s44
	s_nop 0
	global_load_lds_dwordx4 v[210:211], off
	s_waitcnt vmcnt(8)
	s_waitcnt lgkmcnt(0)
	s_barrier
	s_setprio 1
	s_waitcnt lgkmcnt(0)
	v_mfma_f32_16x16x32_bf16 v[60:63], v[146:149], v[178:181], v[60:63]
	v_mfma_f32_16x16x32_bf16 v[56:59], v[154:157], v[178:181], v[56:59]
	v_mfma_f32_16x16x32_bf16 v[52:55], v[146:149], v[186:189], v[52:55]
	v_mfma_f32_16x16x32_bf16 v[48:51], v[154:157], v[186:189], v[48:51]
	v_mfma_f32_16x16x32_bf16 v[40:43], v[146:149], v[194:197], v[40:43]
	v_mfma_f32_16x16x32_bf16 v[32:35], v[154:157], v[194:197], v[32:35]
	v_mfma_f32_16x16x32_bf16 v[24:27], v[146:149], v[202:205], v[24:27]
	v_mfma_f32_16x16x32_bf16 v[16:19], v[154:157], v[202:205], v[16:19]
	v_mfma_f32_16x16x32_bf16 v[60:63], v[150:153], v[182:185], v[60:63]
	v_mfma_f32_16x16x32_bf16 v[56:59], v[158:161], v[182:185], v[56:59]
	v_mfma_f32_16x16x32_bf16 v[52:55], v[150:153], v[190:193], v[52:55]
	v_mfma_f32_16x16x32_bf16 v[48:51], v[158:161], v[190:193], v[48:51]
	v_mfma_f32_16x16x32_bf16 v[40:43], v[150:153], v[198:201], v[40:43]
	v_mfma_f32_16x16x32_bf16 v[32:35], v[158:161], v[198:201], v[32:35]
	v_mfma_f32_16x16x32_bf16 v[24:27], v[150:153], v[206:209], v[24:27]
	v_mfma_f32_16x16x32_bf16 v[16:19], v[158:161], v[206:209], v[16:19]
	s_setprio 0
	s_setprio 1
	v_mfma_f32_16x16x32_bf16 v[44:47], v[162:165], v[178:181], v[44:47]
	v_mfma_f32_16x16x32_bf16 v[36:39], v[170:173], v[178:181], v[36:39]
	v_mfma_f32_16x16x32_bf16 v[28:31], v[162:165], v[186:189], v[28:31]
	v_mfma_f32_16x16x32_bf16 v[20:23], v[170:173], v[186:189], v[20:23]
	v_mfma_f32_16x16x32_bf16 v[12:15], v[162:165], v[194:197], v[12:15]
	v_mfma_f32_16x16x32_bf16 v[8:11], v[170:173], v[194:197], v[8:11]
	v_mfma_f32_16x16x32_bf16 v[4:7], v[162:165], v[202:205], v[4:7]
	v_mfma_f32_16x16x32_bf16 v[0:3], v[170:173], v[202:205], v[0:3]
	v_mfma_f32_16x16x32_bf16 v[44:47], v[166:169], v[182:185], v[44:47]
	v_mfma_f32_16x16x32_bf16 v[36:39], v[174:177], v[182:185], v[36:39]
	v_mfma_f32_16x16x32_bf16 v[28:31], v[166:169], v[190:193], v[28:31]
	v_mfma_f32_16x16x32_bf16 v[20:23], v[174:177], v[190:193], v[20:23]
	v_mfma_f32_16x16x32_bf16 v[12:15], v[166:169], v[198:201], v[12:15]
	v_mfma_f32_16x16x32_bf16 v[8:11], v[174:177], v[198:201], v[8:11]
	v_mfma_f32_16x16x32_bf16 v[4:7], v[166:169], v[206:209], v[4:7]
	v_mfma_f32_16x16x32_bf16 v[0:3], v[174:177], v[206:209], v[0:3]
	s_setprio 0
	s_add_i32 s55, s55, 2
	s_add_u32 s51, s51, 0x100
	s_addc_u32 s54, s54, 0
	s_add_u32 s22, s22, 0x100
	s_addc_u32 s23, s23, 0
	s_cmp_gt_u32 s55, 13
	s_barrier
	s_cbranch_scc0 .LBB0_1278
	s_and_b64 vcc, exec, s[10:11]
	s_cbranch_vccz .LBB0_1281
	s_barrier

; #define PG8_STAGE(bufoff, gbase, voff) do { _Pragma("unroll") for (int _i = 0; _i < 2; ++_i) \
;         __builtin_amdgcn_global_load_lds((const unsigned*)((const char*)(gbase) + (voff)[_i]), (LAS unsigned*)(lds + (bufoff) + ldsw + _i * 8192), 16, 0, 0); } while (0)
; #define PG8_LDA(dst, b, h) do { _Pragma("unroll") for (int m = 0; m < 4; ++m) _Pragma("unroll") for (int k = 0; k < 2; ++k) dst[m][k] = *(const LAS bf16x8*)(lds + PG8_SA(b, h) + aoff + m * 2048 + k * 1024); } while (0)
; #define PG8_LDB(dst, b, h) do { _Pragma("unroll") for (int n = 0; n < 2; ++n) _Pragma("unroll") for (int k = 0; k < 2; ++k) dst[n][k] = *(const LAS bf16x8*)(lds + PG8_SB(b, h) + boff + n * 2048 + k * 1024); } while (0)
; #define PG8_MMA(ai, bj, At, Bt) do { __builtin_amdgcn_s_setprio(1); _Pragma("unroll") for (int m = 0; m < 4; ++m) _Pragma("unroll") for (int n = 0; n < 2; ++n) _Pragma("unroll") for (int k = 0; k < 2; ++k) \
;         acc[ai][bj][m][n] = __builtin_amdgcn_mfma_f32_16x16x32_bf16(Bt[n][k], At[m][k], acc[ai][bj][m][n], 0, 0, 0); __builtin_amdgcn_s_setprio(0); } while (0)
; #define PG8_WAIT_V(n) asm volatile("s_waitcnt vmcnt(" #n ")" ::: "memory")
; #define PG8_WAIT_L(n) asm volatile("s_waitcnt lgkmcnt(" #n ")" ::: "memory")
; #define PG8_BAR __builtin_amdgcn_s_barrier()
; #define PG8_SCHED __builtin_amdgcn_sched_barrier(0)
; template <class Epi>
; DI void gemm_phase(int wv, LAS unsigned char* lds, const Gemm g, const StaticOrder& S, const Epi& E) {
;     ...
;         for (int t = 0; t < nt; t += 2) {
;             const bool last = (t == nt - 2);
;             const char* a1 = cA + (size_t)(t + 1) * kstep;
;             const char* a2 = last ? nA : cA + (size_t)(t + 2) * kstep; const char* b2 = last ? nB : cB + (size_t)(t + 2) * kstep;
;             const char* a3 = a2 + kstep; const char* b3 = b2 + kstep;
;             PG8_LDB(B0, 0, 0); PG8_LDB(B1, 0, 1); PG8_SCHED; PG8_LDA(At, 0, 0); PG8_STAGE(PG8_SA(1, 1), a1 + hA, voffA);
;             PG8_WAIT_V(8); PG8_WAIT_L(0); PG8_BAR; PG8_MMA(0, 0, At, B0); PG8_MMA(0, 1, At, B1); PG8_BAR; PG8_SCHED;
;             PG8_LDA(At, 0, 1); PG8_STAGE(PG8_SB(0, 0), b2, voffB); PG8_STAGE(PG8_SB(0, 1), b2 + hB, voffB); PG8_STAGE(PG8_SA(0, 0), a2, voffA);
;             PG8_WAIT_V(8); PG8_WAIT_L(0); PG8_BAR; PG8_MMA(1, 0, At, B0); PG8_MMA(1, 1, At, B1); PG8_BAR; PG8_SCHED;
.LBB0_1294:
	ds_read_b128 v[146:149], v143
	ds_read_b128 v[150:153], v143 offset:1024
	ds_read_b128 v[154:157], v143 offset:2048
	ds_read_b128 v[158:161], v143 offset:3072
	ds_read_b128 v[162:165], v144
	ds_read_b128 v[166:169], v144 offset:1024
	ds_read_b128 v[170:173], v144 offset:2048
	ds_read_b128 v[174:177], v144 offset:3072
	s_add_u32 s24, s22, 0xfffc0080
	s_addc_u32 s25, s23, -1
	s_cmp_eq_u32 s57, 12
	s_cselect_b32 s27, s15, s25
	s_cselect_b32 s26, s50, s24
	s_cselect_b32 s25, s13, s55
	s_cselect_b32 s24, s51, s54
	v_lshl_add_u64 v[210:211], s[22:23], 0, v[138:139]
	s_add_i32 m0, s37, 0xc000
	ds_read_b128 v[178:181], v145
	ds_read_b128 v[182:185], v145 offset:1024
	ds_read_b128 v[186:189], v145 offset:2048
	ds_read_b128 v[190:193], v145 offset:3072
	ds_read_b128 v[194:197], v145 offset:4096
	ds_read_b128 v[198:201], v145 offset:5120
	ds_read_b128 v[202:205], v145 offset:6144
	ds_read_b128 v[206:209], v145 offset:7168
	global_load_lds_dwordx4 v[210:211], off
	v_lshl_add_u64 v[210:211], s[22:23], 0, v[136:137]
	s_add_i32 m0, s37, 0xe000
	s_nop 0
	global_load_lds_dwordx4 v[210:211], off
	s_waitcnt vmcnt(8)
	s_waitcnt lgkmcnt(0)
	s_barrier
	s_setprio 1
	s_waitcnt lgkmcnt(0)
	v_mfma_f32_16x16x32_bf16 v[124:127], v[146:149], v[178:181], v[124:127]
	v_mfma_f32_16x16x32_bf16 v[120:123], v[154:157], v[178:181], v[120:123]
	v_mfma_f32_16x16x32_bf16 v[116:119], v[146:149], v[186:189], v[116:119]
	v_mfma_f32_16x16x32_bf16 v[112:115], v[154:157], v[186:189], v[112:115]
	v_mfma_f32_16x16x32_bf16 v[104:107], v[146:149], v[194:197], v[104:107]
	v_mfma_f32_16x16x32_bf16 v[96:99], v[154:157], v[194:197], v[96:99]
	v_mfma_f32_16x16x32_bf16 v[88:91], v[146:149], v[202:205], v[88:91]
	v_mfma_f32_16x16x32_bf16 v[80:83], v[154:157], v[202:205], v[80:83]
	v_mfma_f32_16x16x32_bf16 v[124:127], v[150:153], v[182:185], v[124:127]
	v_mfma_f32_16x16x32_bf16 v[120:123], v[158:161], v[182:185], v[120:123]
	v_mfma_f32_16x16x32_bf16 v[116:119], v[150:153], v[190:193], v[116:119]
	v_mfma_f32_16x16x32_bf16 v[112:115], v[158:161], v[190:193], v[112:115]
	v_mfma_f32_16x16x32_bf16 v[104:107], v[150:153], v[198:201], v[104:107]
	v_mfma_f32_16x16x32_bf16 v[96:99], v[158:161], v[198:201], v[96:99]
	v_mfma_f32_16x16x32_bf16 v[88:91], v[150:153], v[206:209], v[88:91]
	v_mfma_f32_16x16x32_bf16 v[80:83], v[158:161], v[206:209], v[80:83]
	s_setprio 0
	s_setprio 1
	v_mfma_f32_16x16x32_bf16 v[108:111], v[162:165], v[178:181], v[108:111]
	v_mfma_f32_16x16x32_bf16 v[100:103], v[170:173], v[178:181], v[100:103]
	v_mfma_f32_16x16x32_bf16 v[92:95], v[162:165], v[186:189], v[92:95]
	v_mfma_f32_16x16x32_bf16 v[84:87], v[170:173], v[186:189], v[84:87]
	v_mfma_f32_16x16x32_bf16 v[76:79], v[162:165], v[194:197], v[76:79]
	v_mfma_f32_16x16x32_bf16 v[72:75], v[170:173], v[194:197], v[72:75]
	v_mfma_f32_16x16x32_bf16 v[68:71], v[162:165], v[202:205], v[68:71]
	v_mfma_f32_16x16x32_bf16 v[64:67], v[170:173], v[202:205], v[64:67]
	v_mfma_f32_16x16x32_bf16 v[108:111], v[166:169], v[182:185], v[108:111]
	v_mfma_f32_16x16x32_bf16 v[100:103], v[174:177], v[182:185], v[100:103]
	v_mfma_f32_16x16x32_bf16 v[92:95], v[166:169], v[190:193], v[92:95]
	v_mfma_f32_16x16x32_bf16 v[84:87], v[174:177], v[190:193], v[84:87]
	v_mfma_f32_16x16x32_bf16 v[76:79], v[166:169], v[198:201], v[76:79]
	v_mfma_f32_16x16x32_bf16 v[72:75], v[174:177], v[198:201], v[72:75]
	v_mfma_f32_16x16x32_bf16 v[68:71], v[166:169], v[206:209], v[68:71]
	v_mfma_f32_16x16x32_bf16 v[64:67], v[174:177], v[206:209], v[64:67]
	s_setprio 0
	s_barrier
	s_add_i32 s60, s46, s35
	v_lshl_add_u64 v[210:211], s[24:25], 0, v[132:133]
	s_mov_b32 m0, s60
	ds_read_b128 v[178:181], v145 offset:16384
	ds_read_b128 v[182:185], v145 offset:17408
	ds_read_b128 v[186:189], v145 offset:18432
	ds_read_b128 v[190:193], v145 offset:19456
	ds_read_b128 v[194:197], v145 offset:20480
	ds_read_b128 v[198:201], v145 offset:21504
	ds_read_b128 v[202:205], v145 offset:22528
	ds_read_b128 v[206:209], v145 offset:23552
	global_load_lds_dwordx4 v[210:211], off
	s_add_i32 m0, s60, 0x2000
	s_add_u32 s60, s24, 0x40000
	v_lshl_add_u64 v[212:213], s[24:25], 0, v[128:129]
	s_addc_u32 s61, s25, 0
	s_add_i32 s62, s47, s35
	global_load_lds_dwordx4 v[212:213], off
	v_lshl_add_u64 v[214:215], s[60:61], 0, v[132:133]
	s_mov_b32 m0, s62
	v_lshl_add_u64 v[216:217], s[26:27], 0, v[130:131]
	global_load_lds_dwordx4 v[214:215], off
	v_lshl_add_u64 v[214:215], s[60:61], 0, v[128:129]
	s_add_i32 m0, s62, 0x2000
	s_nop 0
	global_load_lds_dwordx4 v[214:215], off
	v_lshl_add_u64 v[214:215], s[26:27], 0, v[134:135]
	s_mov_b32 m0, s37
	s_nop 0
	global_load_lds_dwordx4 v[214:215], off
	s_mov_b32 m0, s38
	s_nop 0
	global_load_lds_dwordx4 v[216:217], off
	s_waitcnt vmcnt(8)
	s_waitcnt lgkmcnt(0)
	s_barrier
; #define PG8_STAGE(bufoff, gbase, voff) do { _Pragma("unroll") for (int _i = 0; _i < 2; ++_i) \
;         __builtin_amdgcn_global_load_lds((const unsigned*)((const char*)(gbase) + (voff)[_i]), (LAS unsigned*)(lds + (bufoff) + ldsw + _i * 8192), 16, 0, 0); } while (0)
; #define PG8_LDA(dst, b, h) do { _Pragma("unroll") for (int m = 0; m < 4; ++m) _Pragma("unroll") for (int k = 0; k < 2; ++k) dst[m][k] = *(const LAS bf16x8*)(lds + PG8_SA(b, h) + aoff + m * 2048 + k * 1024); } while (0)
; #define PG8_LDB(dst, b, h) do { _Pragma("unroll") for (int n = 0; n < 2; ++n) _Pragma("unroll") for (int k = 0; k < 2; ++k) dst[n][k] = *(const LAS bf16x8*)(lds + PG8_SB(b, h) + boff + n * 2048 + k * 1024); } while (0)
; #define PG8_MMA(ai, bj, At, Bt) do { __builtin_amdgcn_s_setprio(1); _Pragma("unroll") for (int m = 0; m < 4; ++m) _Pragma("unroll") for (int n = 0; n < 2; ++n) _Pragma("unroll") for (int k = 0; k < 2; ++k) \
;         acc[ai][bj][m][n] = __builtin_amdgcn_mfma_f32_16x16x32_bf16(Bt[n][k], At[m][k], acc[ai][bj][m][n], 0, 0, 0); __builtin_amdgcn_s_setprio(0); } while (0)
; #define PG8_WAIT_V(n) asm volatile("s_waitcnt vmcnt(" #n ")" ::: "memory")
; #define PG8_WAIT_L(n) asm volatile("s_waitcnt lgkmcnt(" #n ")" ::: "memory")
; #define PG8_BAR __builtin_amdgcn_s_barrier()
; #define PG8_SCHED __builtin_amdgcn_sched_barrier(0)
; template <class Epi>
; DI void gemm_phase(int wv, LAS unsigned char* lds, const Gemm g, const StaticOrder& S, const Epi& E) {
;     ...
;             PG8_WAIT_V(8); PG8_WAIT_L(0); PG8_BAR; PG8_MMA(1, 0, At, B0); PG8_MMA(1, 1, At, B1); PG8_BAR; PG8_SCHED;
;             PG8_LDB(B0, 1, 0); PG8_LDB(B1, 1, 1); PG8_SCHED; PG8_LDA(At, 1, 0); PG8_STAGE(PG8_SA(0, 1), a2 + hA, voffA);
;             PG8_WAIT_V(8); PG8_WAIT_L(0); PG8_BAR; PG8_MMA(0, 0, At, B0); PG8_MMA(0, 1, At, B1); PG8_BAR; PG8_SCHED;
	s_setprio 1
	s_waitcnt lgkmcnt(0)
	v_mfma_f32_16x16x32_bf16 v[60:63], v[146:149], v[178:181], v[60:63]
	v_mfma_f32_16x16x32_bf16 v[56:59], v[154:157], v[178:181], v[56:59]
	v_mfma_f32_16x16x32_bf16 v[52:55], v[146:149], v[186:189], v[52:55]
	v_mfma_f32_16x16x32_bf16 v[48:51], v[154:157], v[186:189], v[48:51]
	v_mfma_f32_16x16x32_bf16 v[40:43], v[146:149], v[194:197], v[40:43]
	v_mfma_f32_16x16x32_bf16 v[32:35], v[154:157], v[194:197], v[32:35]
	v_mfma_f32_16x16x32_bf16 v[24:27], v[146:149], v[202:205], v[24:27]
	v_mfma_f32_16x16x32_bf16 v[16:19], v[154:157], v[202:205], v[16:19]
	v_mfma_f32_16x16x32_bf16 v[60:63], v[150:153], v[182:185], v[60:63]
	v_mfma_f32_16x16x32_bf16 v[56:59], v[158:161], v[182:185], v[56:59]
	v_mfma_f32_16x16x32_bf16 v[52:55], v[150:153], v[190:193], v[52:55]
	v_mfma_f32_16x16x32_bf16 v[48:51], v[158:161], v[190:193], v[48:51]
	v_mfma_f32_16x16x32_bf16 v[40:43], v[150:153], v[198:201], v[40:43]
	v_mfma_f32_16x16x32_bf16 v[32:35], v[158:161], v[198:201], v[32:35]
	v_mfma_f32_16x16x32_bf16 v[24:27], v[150:153], v[206:209], v[24:27]
	v_mfma_f32_16x16x32_bf16 v[16:19], v[158:161], v[206:209], v[16:19]
	s_setprio 0
	s_setprio 1
	v_mfma_f32_16x16x32_bf16 v[44:47], v[162:165], v[178:181], v[44:47]
	v_mfma_f32_16x16x32_bf16 v[36:39], v[170:173], v[178:181], v[36:39]
	v_mfma_f32_16x16x32_bf16 v[28:31], v[162:165], v[186:189], v[28:31]
	v_mfma_f32_16x16x32_bf16 v[20:23], v[170:173], v[186:189], v[20:23]
	v_mfma_f32_16x16x32_bf16 v[12:15], v[162:165], v[194:197], v[12:15]
	v_mfma_f32_16x16x32_bf16 v[8:11], v[170:173], v[194:197], v[8:11]
	v_mfma_f32_16x16x32_bf16 v[4:7], v[162:165], v[202:205], v[4:7]
	v_mfma_f32_16x16x32_bf16 v[0:3], v[170:173], v[202:205], v[0:3]
	v_mfma_f32_16x16x32_bf16 v[44:47], v[166:169], v[182:185], v[44:47]
	v_mfma_f32_16x16x32_bf16 v[36:39], v[174:177], v[182:185], v[36:39]
	v_mfma_f32_16x16x32_bf16 v[28:31], v[166:169], v[190:193], v[28:31]
	v_mfma_f32_16x16x32_bf16 v[20:23], v[174:177], v[190:193], v[20:23]
	v_mfma_f32_16x16x32_bf16 v[12:15], v[166:169], v[198:201], v[12:15]
	v_mfma_f32_16x16x32_bf16 v[8:11], v[174:177], v[198:201], v[8:11]
	v_mfma_f32_16x16x32_bf16 v[4:7], v[166:169], v[206:209], v[4:7]
	v_mfma_f32_16x16x32_bf16 v[0:3], v[174:177], v[206:209], v[0:3]
	s_setprio 0
	s_barrier
	s_add_i32 s60, 0, 0x18000
	s_add_i32 s61, 0, 0x1c000
	v_add_u32_e32 v158, s60, v142
	v_add_u32_e32 v174, s61, v142
	ds_read_b128 v[146:149], v158
	ds_read_b128 v[150:153], v158 offset:1024
	ds_read_b128 v[154:157], v158 offset:2048
	ds_read_b128 v[158:161], v158 offset:3072
	ds_read_b128 v[162:165], v174
	ds_read_b128 v[166:169], v174 offset:1024
	ds_read_b128 v[170:173], v174 offset:2048
	ds_read_b128 v[174:177], v174 offset:3072
	s_add_u32 s26, s26, 0x40000
	s_addc_u32 s27, s27, 0
	s_mov_b32 m0, s39
	v_lshl_add_u64 v[218:219], s[26:27], 0, v[134:135]
	ds_read_b128 v[178:181], v145 offset:32768
	ds_read_b128 v[182:185], v145 offset:33792
	ds_read_b128 v[186:189], v145 offset:34816
	ds_read_b128 v[190:193], v145 offset:35840
	ds_read_b128 v[194:197], v145 offset:36864
	ds_read_b128 v[198:201], v145 offset:37888
	ds_read_b128 v[202:205], v145 offset:38912
	ds_read_b128 v[206:209], v145 offset:39936
	global_load_lds_dwordx4 v[218:219], off
	v_lshl_add_u64 v[218:219], s[26:27], 0, v[130:131]
	s_mov_b32 m0, s40
	s_nop 0
	global_load_lds_dwordx4 v[218:219], off
	s_waitcnt vmcnt(8)
	s_waitcnt lgkmcnt(0)
	s_barrier
	s_setprio 1
	s_waitcnt lgkmcnt(0)
	v_mfma_f32_16x16x32_bf16 v[124:127], v[146:149], v[178:181], v[124:127]
	v_mfma_f32_16x16x32_bf16 v[120:123], v[154:157], v[178:181], v[120:123]
	v_mfma_f32_16x16x32_bf16 v[116:119], v[146:149], v[186:189], v[116:119]
	v_mfma_f32_16x16x32_bf16 v[112:115], v[154:157], v[186:189], v[112:115]
	v_mfma_f32_16x16x32_bf16 v[104:107], v[146:149], v[194:197], v[104:107]
	v_mfma_f32_16x16x32_bf16 v[96:99], v[154:157], v[194:197], v[96:99]
	v_mfma_f32_16x16x32_bf16 v[88:91], v[146:149], v[202:205], v[88:91]
	v_mfma_f32_16x16x32_bf16 v[80:83], v[154:157], v[202:205], v[80:83]
	v_mfma_f32_16x16x32_bf16 v[124:127], v[150:153], v[182:185], v[124:127]
	v_mfma_f32_16x16x32_bf16 v[120:123], v[158:161], v[182:185], v[120:123]
	v_mfma_f32_16x16x32_bf16 v[116:119], v[150:153], v[190:193], v[116:119]
	v_mfma_f32_16x16x32_bf16 v[112:115], v[158:161], v[190:193], v[112:115]
	v_mfma_f32_16x16x32_bf16 v[104:107], v[150:153], v[198:201], v[104:107]
	v_mfma_f32_16x16x32_bf16 v[96:99], v[158:161], v[198:201], v[96:99]
	v_mfma_f32_16x16x32_bf16 v[88:91], v[150:153], v[206:209], v[88:91]
	v_mfma_f32_16x16x32_bf16 v[80:83], v[158:161], v[206:209], v[80:83]
	s_setprio 0
	s_setprio 1
	v_mfma_f32_16x16x32_bf16 v[108:111], v[162:165], v[178:181], v[108:111]
	v_mfma_f32_16x16x32_bf16 v[100:103], v[170:173], v[178:181], v[100:103]
	v_mfma_f32_16x16x32_bf16 v[92:95], v[162:165], v[186:189], v[92:95]
	v_mfma_f32_16x16x32_bf16 v[84:87], v[170:173], v[186:189], v[84:87]
	v_mfma_f32_16x16x32_bf16 v[76:79], v[162:165], v[194:197], v[76:79]
	v_mfma_f32_16x16x32_bf16 v[72:75], v[170:173], v[194:197], v[72:75]
	v_mfma_f32_16x16x32_bf16 v[68:71], v[162:165], v[202:205], v[68:71]
	v_mfma_f32_16x16x32_bf16 v[64:67], v[170:173], v[202:205], v[64:67]
	v_mfma_f32_16x16x32_bf16 v[108:111], v[166:169], v[182:185], v[108:111]
	v_mfma_f32_16x16x32_bf16 v[100:103], v[174:177], v[182:185], v[100:103]
	v_mfma_f32_16x16x32_bf16 v[92:95], v[166:169], v[190:193], v[92:95]
	v_mfma_f32_16x16x32_bf16 v[84:87], v[174:177], v[190:193], v[84:87]
	v_mfma_f32_16x16x32_bf16 v[76:79], v[166:169], v[198:201], v[76:79]
	v_mfma_f32_16x16x32_bf16 v[72:75], v[174:177], v[198:201], v[72:75]
	v_mfma_f32_16x16x32_bf16 v[68:71], v[166:169], v[206:209], v[68:71]
	v_mfma_f32_16x16x32_bf16 v[64:67], v[174:177], v[206:209], v[64:67]
	s_setprio 0
	s_barrier
; #define PG8_STAGE(bufoff, gbase, voff) do { _Pragma("unroll") for (int _i = 0; _i < 2; ++_i) \
;         __builtin_amdgcn_global_load_lds((const unsigned*)((const char*)(gbase) + (voff)[_i]), (LAS unsigned*)(lds + (bufoff) + ldsw + _i * 8192), 16, 0, 0); } while (0)
; #define PG8_LDA(dst, b, h) do { _Pragma("unroll") for (int m = 0; m < 4; ++m) _Pragma("unroll") for (int k = 0; k < 2; ++k) dst[m][k] = *(const LAS bf16x8*)(lds + PG8_SA(b, h) + aoff + m * 2048 + k * 1024); } while (0)
; #define PG8_MMA(ai, bj, At, Bt) do { __builtin_amdgcn_s_setprio(1); _Pragma("unroll") for (int m = 0; m < 4; ++m) _Pragma("unroll") for (int n = 0; n < 2; ++n) _Pragma("unroll") for (int k = 0; k < 2; ++k) \
;         acc[ai][bj][m][n] = __builtin_amdgcn_mfma_f32_16x16x32_bf16(Bt[n][k], At[m][k], acc[ai][bj][m][n], 0, 0, 0); __builtin_amdgcn_s_setprio(0); } while (0)
; #define PG8_WAIT_V(n) asm volatile("s_waitcnt vmcnt(" #n ")" ::: "memory")
; #define PG8_WAIT_L(n) asm volatile("s_waitcnt lgkmcnt(" #n ")" ::: "memory")
; #define PG8_BAR __builtin_amdgcn_s_barrier()
; #define PG8_SCHED __builtin_amdgcn_sched_barrier(0)
; template <class Epi>
; DI void gemm_phase(int wv, LAS unsigned char* lds, const Gemm g, const StaticOrder& S, const Epi& E) {
;     ...
;             PG8_LDA(At, 1, 1); PG8_STAGE(PG8_SB(1, 0), b3, voffB); PG8_STAGE(PG8_SB(1, 1), b3 + hB, voffB); PG8_STAGE(PG8_SA(1, 0), a3, voffA);
;             PG8_WAIT_V(8); PG8_WAIT_L(0); PG8_BAR; PG8_MMA(1, 0, At, B0); PG8_MMA(1, 1, At, B1); PG8_BAR; PG8_SCHED;
;         }
;         if (wr == 0) PG8_BAR;
	s_add_i32 s26, s60, s35
	v_lshl_add_u64 v[210:211], v[210:211], 0, s[6:7]
	s_mov_b32 m0, s26
	ds_read_b128 v[178:181], v145 offset:49152
	ds_read_b128 v[182:185], v145 offset:50176
	ds_read_b128 v[186:189], v145 offset:51200
	ds_read_b128 v[190:193], v145 offset:52224
	ds_read_b128 v[194:197], v145 offset:53248
	ds_read_b128 v[198:201], v145 offset:54272
	ds_read_b128 v[202:205], v145 offset:55296
	ds_read_b128 v[206:209], v145 offset:56320
	global_load_lds_dwordx4 v[210:211], off
	s_add_i32 m0, s26, 0x2000
	s_add_u32 s24, s24, 0x40080
	v_lshl_add_u64 v[210:211], v[212:213], 0, s[6:7]
	s_addc_u32 s25, s25, 0
	s_add_i32 s26, s61, s35
	global_load_lds_dwordx4 v[210:211], off
	v_lshl_add_u64 v[210:211], s[24:25], 0, v[132:133]
	s_mov_b32 m0, s26
	s_nop 0
	global_load_lds_dwordx4 v[210:211], off
	v_lshl_add_u64 v[210:211], s[24:25], 0, v[128:129]
	s_add_i32 m0, s26, 0x2000
	s_nop 0
	global_load_lds_dwordx4 v[210:211], off
	v_lshl_add_u64 v[210:211], v[214:215], 0, s[6:7]
	s_mov_b32 m0, s44
	s_nop 0
	global_load_lds_dwordx4 v[210:211], off
	v_lshl_add_u64 v[210:211], v[216:217], 0, s[6:7]
	s_mov_b32 m0, s45
	s_nop 0
	global_load_lds_dwordx4 v[210:211], off
	s_waitcnt vmcnt(8)
	s_waitcnt lgkmcnt(0)
	s_barrier
	s_setprio 1
	s_waitcnt lgkmcnt(0)
	v_mfma_f32_16x16x32_bf16 v[60:63], v[146:149], v[178:181], v[60:63]
	v_mfma_f32_16x16x32_bf16 v[56:59], v[154:157], v[178:181], v[56:59]
	v_mfma_f32_16x16x32_bf16 v[52:55], v[146:149], v[186:189], v[52:55]
	v_mfma_f32_16x16x32_bf16 v[48:51], v[154:157], v[186:189], v[48:51]
	v_mfma_f32_16x16x32_bf16 v[40:43], v[146:149], v[194:197], v[40:43]
	v_mfma_f32_16x16x32_bf16 v[32:35], v[154:157], v[194:197], v[32:35]
	v_mfma_f32_16x16x32_bf16 v[24:27], v[146:149], v[202:205], v[24:27]
	v_mfma_f32_16x16x32_bf16 v[16:19], v[154:157], v[202:205], v[16:19]
	v_mfma_f32_16x16x32_bf16 v[60:63], v[150:153], v[182:185], v[60:63]
	v_mfma_f32_16x16x32_bf16 v[56:59], v[158:161], v[182:185], v[56:59]
	v_mfma_f32_16x16x32_bf16 v[52:55], v[150:153], v[190:193], v[52:55]
	v_mfma_f32_16x16x32_bf16 v[48:51], v[158:161], v[190:193], v[48:51]
	v_mfma_f32_16x16x32_bf16 v[40:43], v[150:153], v[198:201], v[40:43]
	v_mfma_f32_16x16x32_bf16 v[32:35], v[158:161], v[198:201], v[32:35]
	v_mfma_f32_16x16x32_bf16 v[24:27], v[150:153], v[206:209], v[24:27]
	v_mfma_f32_16x16x32_bf16 v[16:19], v[158:161], v[206:209], v[16:19]
	s_setprio 0
	s_setprio 1
	v_mfma_f32_16x16x32_bf16 v[44:47], v[162:165], v[178:181], v[44:47]
	v_mfma_f32_16x16x32_bf16 v[36:39], v[170:173], v[178:181], v[36:39]
	v_mfma_f32_16x16x32_bf16 v[28:31], v[162:165], v[186:189], v[28:31]
	v_mfma_f32_16x16x32_bf16 v[20:23], v[170:173], v[186:189], v[20:23]
	v_mfma_f32_16x16x32_bf16 v[12:15], v[162:165], v[194:197], v[12:15]
	v_mfma_f32_16x16x32_bf16 v[8:11], v[170:173], v[194:197], v[8:11]
	v_mfma_f32_16x16x32_bf16 v[4:7], v[162:165], v[202:205], v[4:7]
	v_mfma_f32_16x16x32_bf16 v[0:3], v[170:173], v[202:205], v[0:3]
	v_mfma_f32_16x16x32_bf16 v[44:47], v[166:169], v[182:185], v[44:47]
	v_mfma_f32_16x16x32_bf16 v[36:39], v[174:177], v[182:185], v[36:39]
	v_mfma_f32_16x16x32_bf16 v[28:31], v[166:169], v[190:193], v[28:31]
	v_mfma_f32_16x16x32_bf16 v[20:23], v[174:177], v[190:193], v[20:23]
	v_mfma_f32_16x16x32_bf16 v[12:15], v[166:169], v[198:201], v[12:15]
	v_mfma_f32_16x16x32_bf16 v[8:11], v[174:177], v[198:201], v[8:11]
	v_mfma_f32_16x16x32_bf16 v[4:7], v[166:169], v[206:209], v[4:7]
	v_mfma_f32_16x16x32_bf16 v[0:3], v[174:177], v[206:209], v[0:3]
	s_setprio 0
	s_add_i32 s57, s57, 2
	s_add_u32 s54, s54, 0x100
	s_addc_u32 s55, s55, 0
	s_add_u32 s22, s22, 0x100
	s_addc_u32 s23, s23, 0
	s_cmp_gt_u32 s57, 13
	s_barrier
	s_cbranch_scc0 .LBB0_1294
	s_and_b64 vcc, exec, s[10:11]
	s_cbranch_vccz .LBB0_1297
	s_barrier

; #define PG8_STAGE(bufoff, gbase, voff) do { _Pragma("unroll") for (int _i = 0; _i < 2; ++_i) \
;         __builtin_amdgcn_global_load_lds((const unsigned*)((const char*)(gbase) + (voff)[_i]), (LAS unsigned*)(lds + (bufoff) + ldsw + _i * 8192), 16, 0, 0); } while (0)
; #define PG8_LDA(dst, b, h) do { _Pragma("unroll") for (int m = 0; m < 4; ++m) _Pragma("unroll") for (int k = 0; k < 2; ++k) dst[m][k] = *(const LAS bf16x8*)(lds + PG8_SA(b, h) + aoff + m * 2048 + k * 1024); } while (0)
; #define PG8_LDB(dst, b, h) do { _Pragma("unroll") for (int n = 0; n < 2; ++n) _Pragma("unroll") for (int k = 0; k < 2; ++k) dst[n][k] = *(const LAS bf16x8*)(lds + PG8_SB(b, h) + boff + n * 2048 + k * 1024); } while (0)
; #define PG8_MMA(ai, bj, At, Bt) do { __builtin_amdgcn_s_setprio(1); _Pragma("unroll") for (int m = 0; m < 4; ++m) _Pragma("unroll") for (int n = 0; n < 2; ++n) _Pragma("unroll") for (int k = 0; k < 2; ++k) \
;         acc[ai][bj][m][n] = __builtin_amdgcn_mfma_f32_16x16x32_bf16(Bt[n][k], At[m][k], acc[ai][bj][m][n], 0, 0, 0); __builtin_amdgcn_s_setprio(0); } while (0)
; #define PG8_WAIT_V(n) asm volatile("s_waitcnt vmcnt(" #n ")" ::: "memory")
; #define PG8_WAIT_L(n) asm volatile("s_waitcnt lgkmcnt(" #n ")" ::: "memory")
; #define PG8_BAR __builtin_amdgcn_s_barrier()
; #define PG8_SCHED __builtin_amdgcn_sched_barrier(0)
; template <class Epi>
; DI void gemm_phase(int wv, LAS unsigned char* lds, const Gemm g, const StaticOrder& S, const Epi& E) {
;     ...
;         for (int t = 0; t < nt; t += 2) {
;             const bool last = (t == nt - 2);
;             const char* a1 = cA + (size_t)(t + 1) * kstep;
;             const char* a2 = last ? nA : cA + (size_t)(t + 2) * kstep; const char* b2 = last ? nB : cB + (size_t)(t + 2) * kstep;
;             const char* a3 = a2 + kstep; const char* b3 = b2 + kstep;
;             PG8_LDB(B0, 0, 0); PG8_LDB(B1, 0, 1); PG8_SCHED; PG8_LDA(At, 0, 0); PG8_STAGE(PG8_SA(1, 1), a1 + hA, voffA);
;             PG8_WAIT_V(8); PG8_WAIT_L(0); PG8_BAR; PG8_MMA(0, 0, At, B0); PG8_MMA(0, 1, At, B1); PG8_BAR; PG8_SCHED;
;             PG8_LDA(At, 0, 1); PG8_STAGE(PG8_SB(0, 0), b2, voffB); PG8_STAGE(PG8_SB(0, 1), b2 + hB, voffB); PG8_STAGE(PG8_SA(0, 0), a2, voffA);
;             PG8_WAIT_V(8); PG8_WAIT_L(0); PG8_BAR; PG8_MMA(1, 0, At, B0); PG8_MMA(1, 1, At, B1); PG8_BAR; PG8_SCHED;
.LBB0_1769:
	ds_read_b128 v[150:153], v147
	ds_read_b128 v[154:157], v147 offset:1024
	ds_read_b128 v[158:161], v147 offset:2048
	ds_read_b128 v[162:165], v147 offset:3072
	ds_read_b128 v[166:169], v148
	ds_read_b128 v[170:173], v148 offset:1024
	ds_read_b128 v[174:177], v148 offset:2048
	ds_read_b128 v[178:181], v148 offset:3072
	s_add_u32 s20, s18, 0x100
	s_addc_u32 s21, s19, 0
	s_cmp_eq_u32 s57, 20
	s_cselect_b32 s25, s5, s21
	s_cselect_b32 s24, s4, s20
	s_cselect_b32 s23, s17, s55
	s_cselect_b32 s22, s16, s51
	v_lshl_add_u64 v[214:215], s[18:19], 0, v[138:139]
	s_add_i32 m0, s34, 0xc000
	ds_read_b128 v[182:185], v149
	ds_read_b128 v[186:189], v149 offset:1024
	ds_read_b128 v[190:193], v149 offset:2048
	ds_read_b128 v[194:197], v149 offset:3072
	ds_read_b128 v[198:201], v149 offset:4096
	ds_read_b128 v[202:205], v149 offset:5120
	ds_read_b128 v[206:209], v149 offset:6144
	ds_read_b128 v[210:213], v149 offset:7168
	global_load_lds_dwordx4 v[214:215], off
	v_lshl_add_u64 v[214:215], s[18:19], 0, v[136:137]
	s_add_i32 m0, s34, 0xe000
	s_nop 0
	global_load_lds_dwordx4 v[214:215], off
	s_waitcnt vmcnt(8)
	s_waitcnt lgkmcnt(0)
	s_barrier
	s_setprio 1
	s_waitcnt lgkmcnt(0)
	v_mfma_f32_16x16x32_bf16 v[124:127], v[150:153], v[182:185], v[124:127]
	v_mfma_f32_16x16x32_bf16 v[120:123], v[158:161], v[182:185], v[120:123]
	v_mfma_f32_16x16x32_bf16 v[116:119], v[150:153], v[190:193], v[116:119]
	v_mfma_f32_16x16x32_bf16 v[112:115], v[158:161], v[190:193], v[112:115]
	v_mfma_f32_16x16x32_bf16 v[100:103], v[150:153], v[198:201], v[100:103]
	v_mfma_f32_16x16x32_bf16 v[96:99], v[158:161], v[198:201], v[96:99]
	v_mfma_f32_16x16x32_bf16 v[84:87], v[150:153], v[206:209], v[84:87]
	v_mfma_f32_16x16x32_bf16 v[80:83], v[158:161], v[206:209], v[80:83]
	v_mfma_f32_16x16x32_bf16 v[124:127], v[154:157], v[186:189], v[124:127]
	v_mfma_f32_16x16x32_bf16 v[120:123], v[162:165], v[186:189], v[120:123]
	v_mfma_f32_16x16x32_bf16 v[116:119], v[154:157], v[194:197], v[116:119]
	v_mfma_f32_16x16x32_bf16 v[112:115], v[162:165], v[194:197], v[112:115]
	v_mfma_f32_16x16x32_bf16 v[100:103], v[154:157], v[202:205], v[100:103]
	v_mfma_f32_16x16x32_bf16 v[96:99], v[162:165], v[202:205], v[96:99]
	v_mfma_f32_16x16x32_bf16 v[84:87], v[154:157], v[210:213], v[84:87]
	v_mfma_f32_16x16x32_bf16 v[80:83], v[162:165], v[210:213], v[80:83]
	s_setprio 0
	s_setprio 1
	v_mfma_f32_16x16x32_bf16 v[108:111], v[166:169], v[182:185], v[108:111]
	v_mfma_f32_16x16x32_bf16 v[104:107], v[174:177], v[182:185], v[104:107]
	v_mfma_f32_16x16x32_bf16 v[92:95], v[166:169], v[190:193], v[92:95]
	v_mfma_f32_16x16x32_bf16 v[88:91], v[174:177], v[190:193], v[88:91]
	v_mfma_f32_16x16x32_bf16 v[76:79], v[166:169], v[198:201], v[76:79]
	v_mfma_f32_16x16x32_bf16 v[72:75], v[174:177], v[198:201], v[72:75]
	v_mfma_f32_16x16x32_bf16 v[68:71], v[166:169], v[206:209], v[68:71]
	v_mfma_f32_16x16x32_bf16 v[64:67], v[174:177], v[206:209], v[64:67]
	v_mfma_f32_16x16x32_bf16 v[108:111], v[170:173], v[186:189], v[108:111]
	v_mfma_f32_16x16x32_bf16 v[104:107], v[178:181], v[186:189], v[104:107]
	v_mfma_f32_16x16x32_bf16 v[92:95], v[170:173], v[194:197], v[92:95]
	v_mfma_f32_16x16x32_bf16 v[88:91], v[178:181], v[194:197], v[88:91]
	v_mfma_f32_16x16x32_bf16 v[76:79], v[170:173], v[202:205], v[76:79]
	v_mfma_f32_16x16x32_bf16 v[72:75], v[178:181], v[202:205], v[72:75]
	v_mfma_f32_16x16x32_bf16 v[68:71], v[170:173], v[210:213], v[68:71]
	v_mfma_f32_16x16x32_bf16 v[64:67], v[178:181], v[210:213], v[64:67]
	s_setprio 0
	s_barrier
	s_add_i32 s18, s43, s31
	v_lshl_add_u64 v[214:215], s[22:23], 0, v[130:131]
	s_mov_b32 m0, s18
	ds_read_b128 v[182:185], v149 offset:16384
	ds_read_b128 v[186:189], v149 offset:17408
	ds_read_b128 v[190:193], v149 offset:18432
	ds_read_b128 v[194:197], v149 offset:19456
	ds_read_b128 v[198:201], v149 offset:20480
	ds_read_b128 v[202:205], v149 offset:21504
	ds_read_b128 v[206:209], v149 offset:22528
	ds_read_b128 v[210:213], v149 offset:23552
	global_load_lds_dwordx4 v[214:215], off
	s_add_i32 m0, s18, 0x2000
	s_add_u32 s18, s22, 0x60000
	v_lshl_add_u64 v[216:217], s[22:23], 0, v[134:135]
	s_addc_u32 s19, s23, 0
	s_add_i32 s60, s44, s31
	global_load_lds_dwordx4 v[216:217], off
	v_lshl_add_u64 v[218:219], s[18:19], 0, v[130:131]
	s_mov_b32 m0, s60
	v_lshl_add_u64 v[220:221], s[24:25], 0, v[132:133]
	global_load_lds_dwordx4 v[218:219], off
	v_lshl_add_u64 v[218:219], s[18:19], 0, v[134:135]
	s_add_i32 m0, s60, 0x2000
	s_nop 0
	global_load_lds_dwordx4 v[218:219], off
	v_lshl_add_u64 v[218:219], s[24:25], 0, v[128:129]
	s_mov_b32 m0, s34
	s_nop 0
	global_load_lds_dwordx4 v[218:219], off
	s_mov_b32 m0, s35
	s_nop 0
	global_load_lds_dwordx4 v[220:221], off
	s_waitcnt vmcnt(8)
	s_waitcnt lgkmcnt(0)
	s_barrier
; #define PG8_STAGE(bufoff, gbase, voff) do { _Pragma("unroll") for (int _i = 0; _i < 2; ++_i) \
;         __builtin_amdgcn_global_load_lds((const unsigned*)((const char*)(gbase) + (voff)[_i]), (LAS unsigned*)(lds + (bufoff) + ldsw + _i * 8192), 16, 0, 0); } while (0)
; #define PG8_LDA(dst, b, h) do { _Pragma("unroll") for (int m = 0; m < 4; ++m) _Pragma("unroll") for (int k = 0; k < 2; ++k) dst[m][k] = *(const LAS bf16x8*)(lds + PG8_SA(b, h) + aoff + m * 2048 + k * 1024); } while (0)
; #define PG8_LDB(dst, b, h) do { _Pragma("unroll") for (int n = 0; n < 2; ++n) _Pragma("unroll") for (int k = 0; k < 2; ++k) dst[n][k] = *(const LAS bf16x8*)(lds + PG8_SB(b, h) + boff + n * 2048 + k * 1024); } while (0)
; #define PG8_MMA(ai, bj, At, Bt) do { __builtin_amdgcn_s_setprio(1); _Pragma("unroll") for (int m = 0; m < 4; ++m) _Pragma("unroll") for (int n = 0; n < 2; ++n) _Pragma("unroll") for (int k = 0; k < 2; ++k) \
;         acc[ai][bj][m][n] = __builtin_amdgcn_mfma_f32_16x16x32_bf16(Bt[n][k], At[m][k], acc[ai][bj][m][n], 0, 0, 0); __builtin_amdgcn_s_setprio(0); } while (0)
; #define PG8_WAIT_V(n) asm volatile("s_waitcnt vmcnt(" #n ")" ::: "memory")
; #define PG8_WAIT_L(n) asm volatile("s_waitcnt lgkmcnt(" #n ")" ::: "memory")
; #define PG8_BAR __builtin_amdgcn_s_barrier()
; #define PG8_SCHED __builtin_amdgcn_sched_barrier(0)
; template <class Epi>
; DI void gemm_phase(int wv, LAS unsigned char* lds, const Gemm g, const StaticOrder& S, const Epi& E) {
;     ...
;             PG8_WAIT_V(8); PG8_WAIT_L(0); PG8_BAR; PG8_MMA(1, 0, At, B0); PG8_MMA(1, 1, At, B1); PG8_BAR; PG8_SCHED;
;             PG8_LDB(B0, 1, 0); PG8_LDB(B1, 1, 1); PG8_SCHED; PG8_LDA(At, 1, 0); PG8_STAGE(PG8_SA(0, 1), a2 + hA, voffA);
;             PG8_WAIT_V(8); PG8_WAIT_L(0); PG8_BAR; PG8_MMA(0, 0, At, B0); PG8_MMA(0, 1, At, B1); PG8_BAR; PG8_SCHED;
	s_setprio 1
	s_waitcnt lgkmcnt(0)
	v_mfma_f32_16x16x32_bf16 v[60:63], v[150:153], v[182:185], v[60:63]
	v_mfma_f32_16x16x32_bf16 v[56:59], v[158:161], v[182:185], v[56:59]
	v_mfma_f32_16x16x32_bf16 v[52:55], v[150:153], v[190:193], v[52:55]
	v_mfma_f32_16x16x32_bf16 v[48:51], v[158:161], v[190:193], v[48:51]
	v_mfma_f32_16x16x32_bf16 v[36:39], v[150:153], v[198:201], v[36:39]
	v_mfma_f32_16x16x32_bf16 v[32:35], v[158:161], v[198:201], v[32:35]
	v_mfma_f32_16x16x32_bf16 v[20:23], v[150:153], v[206:209], v[20:23]
	v_mfma_f32_16x16x32_bf16 v[16:19], v[158:161], v[206:209], v[16:19]
	v_mfma_f32_16x16x32_bf16 v[60:63], v[154:157], v[186:189], v[60:63]
	v_mfma_f32_16x16x32_bf16 v[56:59], v[162:165], v[186:189], v[56:59]
	v_mfma_f32_16x16x32_bf16 v[52:55], v[154:157], v[194:197], v[52:55]
	v_mfma_f32_16x16x32_bf16 v[48:51], v[162:165], v[194:197], v[48:51]
	v_mfma_f32_16x16x32_bf16 v[36:39], v[154:157], v[202:205], v[36:39]
	v_mfma_f32_16x16x32_bf16 v[32:35], v[162:165], v[202:205], v[32:35]
	v_mfma_f32_16x16x32_bf16 v[20:23], v[154:157], v[210:213], v[20:23]
	v_mfma_f32_16x16x32_bf16 v[16:19], v[162:165], v[210:213], v[16:19]
	s_setprio 0
	s_setprio 1
	v_mfma_f32_16x16x32_bf16 v[44:47], v[166:169], v[182:185], v[44:47]
	v_mfma_f32_16x16x32_bf16 v[40:43], v[174:177], v[182:185], v[40:43]
	v_mfma_f32_16x16x32_bf16 v[28:31], v[166:169], v[190:193], v[28:31]
	v_mfma_f32_16x16x32_bf16 v[24:27], v[174:177], v[190:193], v[24:27]
	v_mfma_f32_16x16x32_bf16 v[12:15], v[166:169], v[198:201], v[12:15]
	v_mfma_f32_16x16x32_bf16 v[8:11], v[174:177], v[198:201], v[8:11]
	v_mfma_f32_16x16x32_bf16 v[4:7], v[166:169], v[206:209], v[4:7]
	v_mfma_f32_16x16x32_bf16 v[0:3], v[174:177], v[206:209], v[0:3]
	v_mfma_f32_16x16x32_bf16 v[44:47], v[170:173], v[186:189], v[44:47]
	v_mfma_f32_16x16x32_bf16 v[40:43], v[178:181], v[186:189], v[40:43]
	v_mfma_f32_16x16x32_bf16 v[28:31], v[170:173], v[194:197], v[28:31]
	v_mfma_f32_16x16x32_bf16 v[24:27], v[178:181], v[194:197], v[24:27]
	v_mfma_f32_16x16x32_bf16 v[12:15], v[170:173], v[202:205], v[12:15]
	v_mfma_f32_16x16x32_bf16 v[8:11], v[178:181], v[202:205], v[8:11]
	v_mfma_f32_16x16x32_bf16 v[4:7], v[170:173], v[210:213], v[4:7]
	v_mfma_f32_16x16x32_bf16 v[0:3], v[178:181], v[210:213], v[0:3]
	s_setprio 0
	s_barrier
	s_add_i32 s60, 0, 0x18000
	s_add_i32 s61, 0, 0x1c000
	v_add_u32_e32 v162, s60, v146
	v_add_u32_e32 v178, s61, v146
	ds_read_b128 v[150:153], v162
	ds_read_b128 v[154:157], v162 offset:1024
	ds_read_b128 v[158:161], v162 offset:2048
	ds_read_b128 v[162:165], v162 offset:3072
	ds_read_b128 v[166:169], v178
	ds_read_b128 v[170:173], v178 offset:1024
	ds_read_b128 v[174:177], v178 offset:2048
	ds_read_b128 v[178:181], v178 offset:3072
	s_add_u32 s18, s24, 0x60000
	s_addc_u32 s19, s25, 0
	s_mov_b32 m0, s36
	v_lshl_add_u64 v[222:223], s[18:19], 0, v[128:129]
	ds_read_b128 v[182:185], v149 offset:32768
	ds_read_b128 v[186:189], v149 offset:33792
	ds_read_b128 v[190:193], v149 offset:34816
	ds_read_b128 v[194:197], v149 offset:35840
	ds_read_b128 v[198:201], v149 offset:36864
	ds_read_b128 v[202:205], v149 offset:37888
	ds_read_b128 v[206:209], v149 offset:38912
	ds_read_b128 v[210:213], v149 offset:39936
	global_load_lds_dwordx4 v[222:223], off
	v_lshl_add_u64 v[222:223], s[18:19], 0, v[132:133]
	s_mov_b32 m0, s37
	s_nop 0
	global_load_lds_dwordx4 v[222:223], off
	s_waitcnt vmcnt(8)
	s_waitcnt lgkmcnt(0)
	s_barrier
	s_setprio 1
	s_waitcnt lgkmcnt(0)
	v_mfma_f32_16x16x32_bf16 v[124:127], v[150:153], v[182:185], v[124:127]
	v_mfma_f32_16x16x32_bf16 v[120:123], v[158:161], v[182:185], v[120:123]
	v_mfma_f32_16x16x32_bf16 v[116:119], v[150:153], v[190:193], v[116:119]
	v_mfma_f32_16x16x32_bf16 v[112:115], v[158:161], v[190:193], v[112:115]
	v_mfma_f32_16x16x32_bf16 v[100:103], v[150:153], v[198:201], v[100:103]
	v_mfma_f32_16x16x32_bf16 v[96:99], v[158:161], v[198:201], v[96:99]
	v_mfma_f32_16x16x32_bf16 v[84:87], v[150:153], v[206:209], v[84:87]
	v_mfma_f32_16x16x32_bf16 v[80:83], v[158:161], v[206:209], v[80:83]
	v_mfma_f32_16x16x32_bf16 v[124:127], v[154:157], v[186:189], v[124:127]
	v_mfma_f32_16x16x32_bf16 v[120:123], v[162:165], v[186:189], v[120:123]
	v_mfma_f32_16x16x32_bf16 v[116:119], v[154:157], v[194:197], v[116:119]
	v_mfma_f32_16x16x32_bf16 v[112:115], v[162:165], v[194:197], v[112:115]
	v_mfma_f32_16x16x32_bf16 v[100:103], v[154:157], v[202:205], v[100:103]
	v_mfma_f32_16x16x32_bf16 v[96:99], v[162:165], v[202:205], v[96:99]
	v_mfma_f32_16x16x32_bf16 v[84:87], v[154:157], v[210:213], v[84:87]
	v_mfma_f32_16x16x32_bf16 v[80:83], v[162:165], v[210:213], v[80:83]
	s_setprio 0
	s_setprio 1
	v_mfma_f32_16x16x32_bf16 v[108:111], v[166:169], v[182:185], v[108:111]
	v_mfma_f32_16x16x32_bf16 v[104:107], v[174:177], v[182:185], v[104:107]
	v_mfma_f32_16x16x32_bf16 v[92:95], v[166:169], v[190:193], v[92:95]
	v_mfma_f32_16x16x32_bf16 v[88:91], v[174:177], v[190:193], v[88:91]
	v_mfma_f32_16x16x32_bf16 v[76:79], v[166:169], v[198:201], v[76:79]
	v_mfma_f32_16x16x32_bf16 v[72:75], v[174:177], v[198:201], v[72:75]
	v_mfma_f32_16x16x32_bf16 v[68:71], v[166:169], v[206:209], v[68:71]
	v_mfma_f32_16x16x32_bf16 v[64:67], v[174:177], v[206:209], v[64:67]
	v_mfma_f32_16x16x32_bf16 v[108:111], v[170:173], v[186:189], v[108:111]
	v_mfma_f32_16x16x32_bf16 v[104:107], v[178:181], v[186:189], v[104:107]
	v_mfma_f32_16x16x32_bf16 v[92:95], v[170:173], v[194:197], v[92:95]
	v_mfma_f32_16x16x32_bf16 v[88:91], v[178:181], v[194:197], v[88:91]
	v_mfma_f32_16x16x32_bf16 v[76:79], v[170:173], v[202:205], v[76:79]
	v_mfma_f32_16x16x32_bf16 v[72:75], v[178:181], v[202:205], v[72:75]
	v_mfma_f32_16x16x32_bf16 v[68:71], v[170:173], v[210:213], v[68:71]
	v_mfma_f32_16x16x32_bf16 v[64:67], v[178:181], v[210:213], v[64:67]
	s_setprio 0
	s_barrier
; #define PG8_STAGE(bufoff, gbase, voff) do { _Pragma("unroll") for (int _i = 0; _i < 2; ++_i) \
;         __builtin_amdgcn_global_load_lds((const unsigned*)((const char*)(gbase) + (voff)[_i]), (LAS unsigned*)(lds + (bufoff) + ldsw + _i * 8192), 16, 0, 0); } while (0)
; #define PG8_LDA(dst, b, h) do { _Pragma("unroll") for (int m = 0; m < 4; ++m) _Pragma("unroll") for (int k = 0; k < 2; ++k) dst[m][k] = *(const LAS bf16x8*)(lds + PG8_SA(b, h) + aoff + m * 2048 + k * 1024); } while (0)
; #define PG8_MMA(ai, bj, At, Bt) do { __builtin_amdgcn_s_setprio(1); _Pragma("unroll") for (int m = 0; m < 4; ++m) _Pragma("unroll") for (int n = 0; n < 2; ++n) _Pragma("unroll") for (int k = 0; k < 2; ++k) \
;         acc[ai][bj][m][n] = __builtin_amdgcn_mfma_f32_16x16x32_bf16(Bt[n][k], At[m][k], acc[ai][bj][m][n], 0, 0, 0); __builtin_amdgcn_s_setprio(0); } while (0)
; #define PG8_WAIT_V(n) asm volatile("s_waitcnt vmcnt(" #n ")" ::: "memory")
; #define PG8_WAIT_L(n) asm volatile("s_waitcnt lgkmcnt(" #n ")" ::: "memory")
; #define PG8_BAR __builtin_amdgcn_s_barrier()
; #define PG8_SCHED __builtin_amdgcn_sched_barrier(0)
; template <class Epi>
; DI void gemm_phase(int wv, LAS unsigned char* lds, const Gemm g, const StaticOrder& S, const Epi& E) {
;     ...
;             PG8_LDA(At, 1, 1); PG8_STAGE(PG8_SB(1, 0), b3, voffB); PG8_STAGE(PG8_SB(1, 1), b3 + hB, voffB); PG8_STAGE(PG8_SA(1, 0), a3, voffA);
;             PG8_WAIT_V(8); PG8_WAIT_L(0); PG8_BAR; PG8_MMA(1, 0, At, B0); PG8_MMA(1, 1, At, B1); PG8_BAR; PG8_SCHED;
;         }
;         if (wr == 0) PG8_BAR;
	s_add_i32 s18, s60, s31
	v_lshl_add_u64 v[214:215], v[214:215], 0, s[10:11]
	s_mov_b32 m0, s18
	ds_read_b128 v[182:185], v149 offset:49152
	ds_read_b128 v[186:189], v149 offset:50176
	ds_read_b128 v[190:193], v149 offset:51200
	ds_read_b128 v[194:197], v149 offset:52224
	ds_read_b128 v[198:201], v149 offset:53248
	ds_read_b128 v[202:205], v149 offset:54272
	ds_read_b128 v[206:209], v149 offset:55296
	ds_read_b128 v[210:213], v149 offset:56320
	global_load_lds_dwordx4 v[214:215], off
	s_add_i32 m0, s18, 0x2000
	s_add_u32 s18, s22, 0x60080
	v_lshl_add_u64 v[214:215], v[216:217], 0, s[10:11]
	s_addc_u32 s19, s23, 0
	s_add_i32 s22, s61, s31
	global_load_lds_dwordx4 v[214:215], off
	v_lshl_add_u64 v[214:215], s[18:19], 0, v[130:131]
	s_mov_b32 m0, s22
	s_nop 0
	global_load_lds_dwordx4 v[214:215], off
	v_lshl_add_u64 v[214:215], s[18:19], 0, v[134:135]
	s_add_i32 m0, s22, 0x2000
	s_nop 0
	global_load_lds_dwordx4 v[214:215], off
	v_lshl_add_u64 v[214:215], v[218:219], 0, s[10:11]
	s_mov_b32 m0, s41
	s_nop 0
	global_load_lds_dwordx4 v[214:215], off
	v_lshl_add_u64 v[214:215], v[220:221], 0, s[10:11]
	s_mov_b32 m0, s42
	s_nop 0
	global_load_lds_dwordx4 v[214:215], off
	s_waitcnt vmcnt(8)
	s_waitcnt lgkmcnt(0)
	s_barrier
	s_setprio 1
	s_waitcnt lgkmcnt(0)
	v_mfma_f32_16x16x32_bf16 v[60:63], v[150:153], v[182:185], v[60:63]
	v_mfma_f32_16x16x32_bf16 v[56:59], v[158:161], v[182:185], v[56:59]
	v_mfma_f32_16x16x32_bf16 v[52:55], v[150:153], v[190:193], v[52:55]
	v_mfma_f32_16x16x32_bf16 v[48:51], v[158:161], v[190:193], v[48:51]
	v_mfma_f32_16x16x32_bf16 v[36:39], v[150:153], v[198:201], v[36:39]
	v_mfma_f32_16x16x32_bf16 v[32:35], v[158:161], v[198:201], v[32:35]
	v_mfma_f32_16x16x32_bf16 v[20:23], v[150:153], v[206:209], v[20:23]
	v_mfma_f32_16x16x32_bf16 v[16:19], v[158:161], v[206:209], v[16:19]
	v_mfma_f32_16x16x32_bf16 v[60:63], v[154:157], v[186:189], v[60:63]
	v_mfma_f32_16x16x32_bf16 v[56:59], v[162:165], v[186:189], v[56:59]
	v_mfma_f32_16x16x32_bf16 v[52:55], v[154:157], v[194:197], v[52:55]
	v_mfma_f32_16x16x32_bf16 v[48:51], v[162:165], v[194:197], v[48:51]
	v_mfma_f32_16x16x32_bf16 v[36:39], v[154:157], v[202:205], v[36:39]
	v_mfma_f32_16x16x32_bf16 v[32:35], v[162:165], v[202:205], v[32:35]
	v_mfma_f32_16x16x32_bf16 v[20:23], v[154:157], v[210:213], v[20:23]
	v_mfma_f32_16x16x32_bf16 v[16:19], v[162:165], v[210:213], v[16:19]
	s_setprio 0
	s_setprio 1
	v_mfma_f32_16x16x32_bf16 v[44:47], v[166:169], v[182:185], v[44:47]
	v_mfma_f32_16x16x32_bf16 v[40:43], v[174:177], v[182:185], v[40:43]
	v_mfma_f32_16x16x32_bf16 v[28:31], v[166:169], v[190:193], v[28:31]
	v_mfma_f32_16x16x32_bf16 v[24:27], v[174:177], v[190:193], v[24:27]
	v_mfma_f32_16x16x32_bf16 v[12:15], v[166:169], v[198:201], v[12:15]
	v_mfma_f32_16x16x32_bf16 v[8:11], v[174:177], v[198:201], v[8:11]
	v_mfma_f32_16x16x32_bf16 v[4:7], v[166:169], v[206:209], v[4:7]
	v_mfma_f32_16x16x32_bf16 v[0:3], v[174:177], v[206:209], v[0:3]
	v_mfma_f32_16x16x32_bf16 v[44:47], v[170:173], v[186:189], v[44:47]
	v_mfma_f32_16x16x32_bf16 v[40:43], v[178:181], v[186:189], v[40:43]
	v_mfma_f32_16x16x32_bf16 v[28:31], v[170:173], v[194:197], v[28:31]
	v_mfma_f32_16x16x32_bf16 v[24:27], v[178:181], v[194:197], v[24:27]
	v_mfma_f32_16x16x32_bf16 v[12:15], v[170:173], v[202:205], v[12:15]
	v_mfma_f32_16x16x32_bf16 v[8:11], v[178:181], v[202:205], v[8:11]
	v_mfma_f32_16x16x32_bf16 v[4:7], v[170:173], v[210:213], v[4:7]
	v_mfma_f32_16x16x32_bf16 v[0:3], v[178:181], v[210:213], v[0:3]
	s_setprio 0
	s_add_i32 s57, s57, 2
	s_add_u32 s51, s51, 0x100
	s_addc_u32 s55, s55, 0
	s_cmp_gt_u32 s57, 21
	s_mov_b64 s[18:19], s[20:21]
	s_barrier
	s_cbranch_scc0 .LBB0_1769
	s_and_b64 vcc, exec, s[12:13]
	s_cbranch_vccz .LBB0_1772
	s_barrier

; #define PG8_STAGE(bufoff, gbase, voff) do { _Pragma("unroll") for (int _i = 0; _i < 2; ++_i) \
;         __builtin_amdgcn_global_load_lds((const unsigned*)((const char*)(gbase) + (voff)[_i]), (LAS unsigned*)(lds + (bufoff) + ldsw + _i * 8192), 16, 0, 0); } while (0)
; #define PG8_LDA(dst, b, h) do { _Pragma("unroll") for (int m = 0; m < 4; ++m) _Pragma("unroll") for (int k = 0; k < 2; ++k) dst[m][k] = *(const LAS bf16x8*)(lds + PG8_SA(b, h) + aoff + m * 2048 + k * 1024); } while (0)
; #define PG8_LDB(dst, b, h) do { _Pragma("unroll") for (int n = 0; n < 2; ++n) _Pragma("unroll") for (int k = 0; k < 2; ++k) dst[n][k] = *(const LAS bf16x8*)(lds + PG8_SB(b, h) + boff + n * 2048 + k * 1024); } while (0)
; #define PG8_MMA(ai, bj, At, Bt) do { __builtin_amdgcn_s_setprio(1); _Pragma("unroll") for (int m = 0; m < 4; ++m) _Pragma("unroll") for (int n = 0; n < 2; ++n) _Pragma("unroll") for (int k = 0; k < 2; ++k) \
;         acc[ai][bj][m][n] = __builtin_amdgcn_mfma_f32_16x16x32_bf16(Bt[n][k], At[m][k], acc[ai][bj][m][n], 0, 0, 0); __builtin_amdgcn_s_setprio(0); } while (0)
; #define PG8_WAIT_V(n) asm volatile("s_waitcnt vmcnt(" #n ")" ::: "memory")
; #define PG8_WAIT_L(n) asm volatile("s_waitcnt lgkmcnt(" #n ")" ::: "memory")
; #define PG8_BAR __builtin_amdgcn_s_barrier()
; #define PG8_SCHED __builtin_amdgcn_sched_barrier(0)
; template <class Epi>
; DI void gemm_phase(int wv, LAS unsigned char* lds, const Gemm g, const StaticOrder& S, const Epi& E) {
;     ...
;         for (int t = 0; t < nt; t += 2) {
;             const bool last = (t == nt - 2);
;             const char* a1 = cA + (size_t)(t + 1) * kstep;
;             const char* a2 = last ? nA : cA + (size_t)(t + 2) * kstep; const char* b2 = last ? nB : cB + (size_t)(t + 2) * kstep;
;             const char* a3 = a2 + kstep; const char* b3 = b2 + kstep;
;             PG8_LDB(B0, 0, 0); PG8_LDB(B1, 0, 1); PG8_SCHED; PG8_LDA(At, 0, 0); PG8_STAGE(PG8_SA(1, 1), a1 + hA, voffA);
;             PG8_WAIT_V(8); PG8_WAIT_L(0); PG8_BAR; PG8_MMA(0, 0, At, B0); PG8_MMA(0, 1, At, B1); PG8_BAR; PG8_SCHED;
;             PG8_LDA(At, 0, 1); PG8_STAGE(PG8_SB(0, 0), b2, voffB); PG8_STAGE(PG8_SB(0, 1), b2 + hB, voffB); PG8_STAGE(PG8_SA(0, 0), a2, voffA);
;             PG8_WAIT_V(8); PG8_WAIT_L(0); PG8_BAR; PG8_MMA(1, 0, At, B0); PG8_MMA(1, 1, At, B1); PG8_BAR; PG8_SCHED;
.LBB0_1888:
	ds_read_b128 v[150:153], v147
	ds_read_b128 v[154:157], v147 offset:1024
	ds_read_b128 v[158:161], v147 offset:2048
	ds_read_b128 v[162:165], v147 offset:3072
	ds_read_b128 v[166:169], v148
	ds_read_b128 v[170:173], v148 offset:1024
	ds_read_b128 v[174:177], v148 offset:2048
	ds_read_b128 v[178:181], v148 offset:3072
	s_add_u32 s26, s24, 0xfffc0080
	s_addc_u32 s27, s25, -1
	s_cmp_eq_u32 s61, 12
	s_cselect_b32 s29, s17, s27
	s_cselect_b32 s28, s51, s26
	s_cselect_b32 s27, s15, s60
	s_cselect_b32 s26, s55, s57
	v_lshl_add_u64 v[214:215], s[24:25], 0, v[138:139]
	s_add_i32 m0, s23, 0xc000
	ds_read_b128 v[182:185], v149
	ds_read_b128 v[186:189], v149 offset:1024
	ds_read_b128 v[190:193], v149 offset:2048
	ds_read_b128 v[194:197], v149 offset:3072
	ds_read_b128 v[198:201], v149 offset:4096
	ds_read_b128 v[202:205], v149 offset:5120
	ds_read_b128 v[206:209], v149 offset:6144
	ds_read_b128 v[210:213], v149 offset:7168
	global_load_lds_dwordx4 v[214:215], off
	v_lshl_add_u64 v[214:215], s[24:25], 0, v[136:137]
	s_add_i32 m0, s23, 0xe000
	s_nop 0
	global_load_lds_dwordx4 v[214:215], off
	s_waitcnt vmcnt(8)
	s_waitcnt lgkmcnt(0)
	s_barrier
	s_setprio 1
	s_waitcnt lgkmcnt(0)
	v_mfma_f32_16x16x32_bf16 v[124:127], v[150:153], v[182:185], v[124:127]
	v_mfma_f32_16x16x32_bf16 v[116:119], v[158:161], v[182:185], v[116:119]
	v_mfma_f32_16x16x32_bf16 v[108:111], v[150:153], v[190:193], v[108:111]
	v_mfma_f32_16x16x32_bf16 v[100:103], v[158:161], v[190:193], v[100:103]
	v_mfma_f32_16x16x32_bf16 v[92:95], v[150:153], v[198:201], v[92:95]
	v_mfma_f32_16x16x32_bf16 v[84:87], v[158:161], v[198:201], v[84:87]
	v_mfma_f32_16x16x32_bf16 v[76:79], v[150:153], v[206:209], v[76:79]
	v_mfma_f32_16x16x32_bf16 v[68:71], v[158:161], v[206:209], v[68:71]
	v_mfma_f32_16x16x32_bf16 v[124:127], v[154:157], v[186:189], v[124:127]
	v_mfma_f32_16x16x32_bf16 v[116:119], v[162:165], v[186:189], v[116:119]
	v_mfma_f32_16x16x32_bf16 v[108:111], v[154:157], v[194:197], v[108:111]
	v_mfma_f32_16x16x32_bf16 v[100:103], v[162:165], v[194:197], v[100:103]
	v_mfma_f32_16x16x32_bf16 v[92:95], v[154:157], v[202:205], v[92:95]
	v_mfma_f32_16x16x32_bf16 v[84:87], v[162:165], v[202:205], v[84:87]
	v_mfma_f32_16x16x32_bf16 v[76:79], v[154:157], v[210:213], v[76:79]
	v_mfma_f32_16x16x32_bf16 v[68:71], v[162:165], v[210:213], v[68:71]
	s_setprio 0
	s_setprio 1
	v_mfma_f32_16x16x32_bf16 v[120:123], v[166:169], v[182:185], v[120:123]
	v_mfma_f32_16x16x32_bf16 v[112:115], v[174:177], v[182:185], v[112:115]
	v_mfma_f32_16x16x32_bf16 v[104:107], v[166:169], v[190:193], v[104:107]
	v_mfma_f32_16x16x32_bf16 v[96:99], v[174:177], v[190:193], v[96:99]
	v_mfma_f32_16x16x32_bf16 v[88:91], v[166:169], v[198:201], v[88:91]
	v_mfma_f32_16x16x32_bf16 v[80:83], v[174:177], v[198:201], v[80:83]
	v_mfma_f32_16x16x32_bf16 v[72:75], v[166:169], v[206:209], v[72:75]
	v_mfma_f32_16x16x32_bf16 v[64:67], v[174:177], v[206:209], v[64:67]
	v_mfma_f32_16x16x32_bf16 v[120:123], v[170:173], v[186:189], v[120:123]
	v_mfma_f32_16x16x32_bf16 v[112:115], v[178:181], v[186:189], v[112:115]
	v_mfma_f32_16x16x32_bf16 v[104:107], v[170:173], v[194:197], v[104:107]
	v_mfma_f32_16x16x32_bf16 v[96:99], v[178:181], v[194:197], v[96:99]
	v_mfma_f32_16x16x32_bf16 v[88:91], v[170:173], v[202:205], v[88:91]
	v_mfma_f32_16x16x32_bf16 v[80:83], v[178:181], v[202:205], v[80:83]
	v_mfma_f32_16x16x32_bf16 v[72:75], v[170:173], v[210:213], v[72:75]
	v_mfma_f32_16x16x32_bf16 v[64:67], v[178:181], v[210:213], v[64:67]
	s_setprio 0
	s_barrier
	s_add_i32 s66, s45, s34
	v_lshl_add_u64 v[214:215], s[26:27], 0, v[132:133]
	s_mov_b32 m0, s66
	ds_read_b128 v[182:185], v149 offset:16384
	ds_read_b128 v[186:189], v149 offset:17408
	ds_read_b128 v[190:193], v149 offset:18432
	ds_read_b128 v[194:197], v149 offset:19456
	ds_read_b128 v[198:201], v149 offset:20480
	ds_read_b128 v[202:205], v149 offset:21504
	ds_read_b128 v[206:209], v149 offset:22528
	ds_read_b128 v[210:213], v149 offset:23552
	global_load_lds_dwordx4 v[214:215], off
	s_add_i32 m0, s66, 0x2000
	s_add_u32 s66, s26, 0x40000
	v_lshl_add_u64 v[216:217], s[26:27], 0, v[128:129]
	s_addc_u32 s67, s27, 0
	s_add_i32 s68, s46, s34
	global_load_lds_dwordx4 v[216:217], off
	v_lshl_add_u64 v[218:219], s[66:67], 0, v[132:133]
	s_mov_b32 m0, s68
	v_lshl_add_u64 v[220:221], s[28:29], 0, v[130:131]
	global_load_lds_dwordx4 v[218:219], off
	v_lshl_add_u64 v[218:219], s[66:67], 0, v[128:129]
	s_add_i32 m0, s68, 0x2000
	s_nop 0
	global_load_lds_dwordx4 v[218:219], off
	v_lshl_add_u64 v[218:219], s[28:29], 0, v[134:135]
	s_mov_b32 m0, s23
	s_nop 0
	global_load_lds_dwordx4 v[218:219], off
	s_mov_b32 m0, s37
	s_nop 0
	global_load_lds_dwordx4 v[220:221], off
	s_waitcnt vmcnt(8)
	s_waitcnt lgkmcnt(0)
	s_barrier
; #define PG8_STAGE(bufoff, gbase, voff) do { _Pragma("unroll") for (int _i = 0; _i < 2; ++_i) \
;         __builtin_amdgcn_global_load_lds((const unsigned*)((const char*)(gbase) + (voff)[_i]), (LAS unsigned*)(lds + (bufoff) + ldsw + _i * 8192), 16, 0, 0); } while (0)
; #define PG8_LDA(dst, b, h) do { _Pragma("unroll") for (int m = 0; m < 4; ++m) _Pragma("unroll") for (int k = 0; k < 2; ++k) dst[m][k] = *(const LAS bf16x8*)(lds + PG8_SA(b, h) + aoff + m * 2048 + k * 1024); } while (0)
; #define PG8_LDB(dst, b, h) do { _Pragma("unroll") for (int n = 0; n < 2; ++n) _Pragma("unroll") for (int k = 0; k < 2; ++k) dst[n][k] = *(const LAS bf16x8*)(lds + PG8_SB(b, h) + boff + n * 2048 + k * 1024); } while (0)
; #define PG8_MMA(ai, bj, At, Bt) do { __builtin_amdgcn_s_setprio(1); _Pragma("unroll") for (int m = 0; m < 4; ++m) _Pragma("unroll") for (int n = 0; n < 2; ++n) _Pragma("unroll") for (int k = 0; k < 2; ++k) \
;         acc[ai][bj][m][n] = __builtin_amdgcn_mfma_f32_16x16x32_bf16(Bt[n][k], At[m][k], acc[ai][bj][m][n], 0, 0, 0); __builtin_amdgcn_s_setprio(0); } while (0)
; #define PG8_WAIT_V(n) asm volatile("s_waitcnt vmcnt(" #n ")" ::: "memory")
; #define PG8_WAIT_L(n) asm volatile("s_waitcnt lgkmcnt(" #n ")" ::: "memory")
; #define PG8_BAR __builtin_amdgcn_s_barrier()
; #define PG8_SCHED __builtin_amdgcn_sched_barrier(0)
; template <class Epi>
; DI void gemm_phase(int wv, LAS unsigned char* lds, const Gemm g, const StaticOrder& S, const Epi& E) {
;     ...
;             PG8_WAIT_V(8); PG8_WAIT_L(0); PG8_BAR; PG8_MMA(1, 0, At, B0); PG8_MMA(1, 1, At, B1); PG8_BAR; PG8_SCHED;
;             PG8_LDB(B0, 1, 0); PG8_LDB(B1, 1, 1); PG8_SCHED; PG8_LDA(At, 1, 0); PG8_STAGE(PG8_SA(0, 1), a2 + hA, voffA);
;             PG8_WAIT_V(8); PG8_WAIT_L(0); PG8_BAR; PG8_MMA(0, 0, At, B0); PG8_MMA(0, 1, At, B1); PG8_BAR; PG8_SCHED;
	s_setprio 1
	s_waitcnt lgkmcnt(0)
	v_mfma_f32_16x16x32_bf16 v[60:63], v[150:153], v[182:185], v[60:63]
	v_mfma_f32_16x16x32_bf16 v[52:55], v[158:161], v[182:185], v[52:55]
	v_mfma_f32_16x16x32_bf16 v[44:47], v[150:153], v[190:193], v[44:47]
	v_mfma_f32_16x16x32_bf16 v[36:39], v[158:161], v[190:193], v[36:39]
	v_mfma_f32_16x16x32_bf16 v[28:31], v[150:153], v[198:201], v[28:31]
	v_mfma_f32_16x16x32_bf16 v[20:23], v[158:161], v[198:201], v[20:23]
	v_mfma_f32_16x16x32_bf16 v[12:15], v[150:153], v[206:209], v[12:15]
	v_mfma_f32_16x16x32_bf16 v[4:7], v[158:161], v[206:209], v[4:7]
	v_mfma_f32_16x16x32_bf16 v[60:63], v[154:157], v[186:189], v[60:63]
	v_mfma_f32_16x16x32_bf16 v[52:55], v[162:165], v[186:189], v[52:55]
	v_mfma_f32_16x16x32_bf16 v[44:47], v[154:157], v[194:197], v[44:47]
	v_mfma_f32_16x16x32_bf16 v[36:39], v[162:165], v[194:197], v[36:39]
	v_mfma_f32_16x16x32_bf16 v[28:31], v[154:157], v[202:205], v[28:31]
	v_mfma_f32_16x16x32_bf16 v[20:23], v[162:165], v[202:205], v[20:23]
	v_mfma_f32_16x16x32_bf16 v[12:15], v[154:157], v[210:213], v[12:15]
	v_mfma_f32_16x16x32_bf16 v[4:7], v[162:165], v[210:213], v[4:7]
	s_setprio 0
	s_setprio 1
	v_mfma_f32_16x16x32_bf16 v[56:59], v[166:169], v[182:185], v[56:59]
	v_mfma_f32_16x16x32_bf16 v[48:51], v[174:177], v[182:185], v[48:51]
	v_mfma_f32_16x16x32_bf16 v[40:43], v[166:169], v[190:193], v[40:43]
	v_mfma_f32_16x16x32_bf16 v[32:35], v[174:177], v[190:193], v[32:35]
	v_mfma_f32_16x16x32_bf16 v[24:27], v[166:169], v[198:201], v[24:27]
	v_mfma_f32_16x16x32_bf16 v[16:19], v[174:177], v[198:201], v[16:19]
	v_mfma_f32_16x16x32_bf16 v[8:11], v[166:169], v[206:209], v[8:11]
	v_mfma_f32_16x16x32_bf16 v[0:3], v[174:177], v[206:209], v[0:3]
	v_mfma_f32_16x16x32_bf16 v[56:59], v[170:173], v[186:189], v[56:59]
	v_mfma_f32_16x16x32_bf16 v[48:51], v[178:181], v[186:189], v[48:51]
	v_mfma_f32_16x16x32_bf16 v[40:43], v[170:173], v[194:197], v[40:43]
	v_mfma_f32_16x16x32_bf16 v[32:35], v[178:181], v[194:197], v[32:35]
	v_mfma_f32_16x16x32_bf16 v[24:27], v[170:173], v[202:205], v[24:27]
	v_mfma_f32_16x16x32_bf16 v[16:19], v[178:181], v[202:205], v[16:19]
	v_mfma_f32_16x16x32_bf16 v[8:11], v[170:173], v[210:213], v[8:11]
	v_mfma_f32_16x16x32_bf16 v[0:3], v[178:181], v[210:213], v[0:3]
	s_setprio 0
	s_barrier
	s_add_i32 s66, 0, 0x18000
	s_add_i32 s67, 0, 0x1c000
	v_add_u32_e32 v162, s66, v146
	v_add_u32_e32 v178, s67, v146
	ds_read_b128 v[150:153], v162
	ds_read_b128 v[154:157], v162 offset:1024
	ds_read_b128 v[158:161], v162 offset:2048
	ds_read_b128 v[162:165], v162 offset:3072
	ds_read_b128 v[166:169], v178
	ds_read_b128 v[170:173], v178 offset:1024
	ds_read_b128 v[174:177], v178 offset:2048
	ds_read_b128 v[178:181], v178 offset:3072
	s_add_u32 s28, s28, 0x40000
	s_addc_u32 s29, s29, 0
	s_mov_b32 m0, s38
	v_lshl_add_u64 v[222:223], s[28:29], 0, v[134:135]
	ds_read_b128 v[182:185], v149 offset:32768
	ds_read_b128 v[186:189], v149 offset:33792
	ds_read_b128 v[190:193], v149 offset:34816
	ds_read_b128 v[194:197], v149 offset:35840
	ds_read_b128 v[198:201], v149 offset:36864
	ds_read_b128 v[202:205], v149 offset:37888
	ds_read_b128 v[206:209], v149 offset:38912
	ds_read_b128 v[210:213], v149 offset:39936
	global_load_lds_dwordx4 v[222:223], off
	v_lshl_add_u64 v[222:223], s[28:29], 0, v[130:131]
	s_mov_b32 m0, s39
	s_nop 0
	global_load_lds_dwordx4 v[222:223], off
	s_waitcnt vmcnt(8)
	s_waitcnt lgkmcnt(0)
	s_barrier
	s_setprio 1
	s_waitcnt lgkmcnt(0)
	v_mfma_f32_16x16x32_bf16 v[124:127], v[150:153], v[182:185], v[124:127]
	v_mfma_f32_16x16x32_bf16 v[116:119], v[158:161], v[182:185], v[116:119]
	v_mfma_f32_16x16x32_bf16 v[108:111], v[150:153], v[190:193], v[108:111]
	v_mfma_f32_16x16x32_bf16 v[100:103], v[158:161], v[190:193], v[100:103]
	v_mfma_f32_16x16x32_bf16 v[92:95], v[150:153], v[198:201], v[92:95]
	v_mfma_f32_16x16x32_bf16 v[84:87], v[158:161], v[198:201], v[84:87]
	v_mfma_f32_16x16x32_bf16 v[76:79], v[150:153], v[206:209], v[76:79]
	v_mfma_f32_16x16x32_bf16 v[68:71], v[158:161], v[206:209], v[68:71]
	v_mfma_f32_16x16x32_bf16 v[124:127], v[154:157], v[186:189], v[124:127]
	v_mfma_f32_16x16x32_bf16 v[116:119], v[162:165], v[186:189], v[116:119]
	v_mfma_f32_16x16x32_bf16 v[108:111], v[154:157], v[194:197], v[108:111]
	v_mfma_f32_16x16x32_bf16 v[100:103], v[162:165], v[194:197], v[100:103]
	v_mfma_f32_16x16x32_bf16 v[92:95], v[154:157], v[202:205], v[92:95]
	v_mfma_f32_16x16x32_bf16 v[84:87], v[162:165], v[202:205], v[84:87]
	v_mfma_f32_16x16x32_bf16 v[76:79], v[154:157], v[210:213], v[76:79]
	v_mfma_f32_16x16x32_bf16 v[68:71], v[162:165], v[210:213], v[68:71]
	s_setprio 0
	s_setprio 1
	v_mfma_f32_16x16x32_bf16 v[120:123], v[166:169], v[182:185], v[120:123]
	v_mfma_f32_16x16x32_bf16 v[112:115], v[174:177], v[182:185], v[112:115]
	v_mfma_f32_16x16x32_bf16 v[104:107], v[166:169], v[190:193], v[104:107]
	v_mfma_f32_16x16x32_bf16 v[96:99], v[174:177], v[190:193], v[96:99]
	v_mfma_f32_16x16x32_bf16 v[88:91], v[166:169], v[198:201], v[88:91]
	v_mfma_f32_16x16x32_bf16 v[80:83], v[174:177], v[198:201], v[80:83]
	v_mfma_f32_16x16x32_bf16 v[72:75], v[166:169], v[206:209], v[72:75]
	v_mfma_f32_16x16x32_bf16 v[64:67], v[174:177], v[206:209], v[64:67]
	v_mfma_f32_16x16x32_bf16 v[120:123], v[170:173], v[186:189], v[120:123]
	v_mfma_f32_16x16x32_bf16 v[112:115], v[178:181], v[186:189], v[112:115]
	v_mfma_f32_16x16x32_bf16 v[104:107], v[170:173], v[194:197], v[104:107]
	v_mfma_f32_16x16x32_bf16 v[96:99], v[178:181], v[194:197], v[96:99]
	v_mfma_f32_16x16x32_bf16 v[88:91], v[170:173], v[202:205], v[88:91]
	v_mfma_f32_16x16x32_bf16 v[80:83], v[178:181], v[202:205], v[80:83]
	v_mfma_f32_16x16x32_bf16 v[72:75], v[170:173], v[210:213], v[72:75]
	v_mfma_f32_16x16x32_bf16 v[64:67], v[178:181], v[210:213], v[64:67]
	s_setprio 0
	s_barrier
; #define PG8_STAGE(bufoff, gbase, voff) do { _Pragma("unroll") for (int _i = 0; _i < 2; ++_i) \
;         __builtin_amdgcn_global_load_lds((const unsigned*)((const char*)(gbase) + (voff)[_i]), (LAS unsigned*)(lds + (bufoff) + ldsw + _i * 8192), 16, 0, 0); } while (0)
; #define PG8_LDA(dst, b, h) do { _Pragma("unroll") for (int m = 0; m < 4; ++m) _Pragma("unroll") for (int k = 0; k < 2; ++k) dst[m][k] = *(const LAS bf16x8*)(lds + PG8_SA(b, h) + aoff + m * 2048 + k * 1024); } while (0)
; #define PG8_MMA(ai, bj, At, Bt) do { __builtin_amdgcn_s_setprio(1); _Pragma("unroll") for (int m = 0; m < 4; ++m) _Pragma("unroll") for (int n = 0; n < 2; ++n) _Pragma("unroll") for (int k = 0; k < 2; ++k) \
;         acc[ai][bj][m][n] = __builtin_amdgcn_mfma_f32_16x16x32_bf16(Bt[n][k], At[m][k], acc[ai][bj][m][n], 0, 0, 0); __builtin_amdgcn_s_setprio(0); } while (0)
; #define PG8_WAIT_V(n) asm volatile("s_waitcnt vmcnt(" #n ")" ::: "memory")
; #define PG8_WAIT_L(n) asm volatile("s_waitcnt lgkmcnt(" #n ")" ::: "memory")
; #define PG8_BAR __builtin_amdgcn_s_barrier()
; #define PG8_SCHED __builtin_amdgcn_sched_barrier(0)
; template <class Epi>
; DI void gemm_phase(int wv, LAS unsigned char* lds, const Gemm g, const StaticOrder& S, const Epi& E) {
;     ...
;             PG8_LDA(At, 1, 1); PG8_STAGE(PG8_SB(1, 0), b3, voffB); PG8_STAGE(PG8_SB(1, 1), b3 + hB, voffB); PG8_STAGE(PG8_SA(1, 0), a3, voffA);
;             PG8_WAIT_V(8); PG8_WAIT_L(0); PG8_BAR; PG8_MMA(1, 0, At, B0); PG8_MMA(1, 1, At, B1); PG8_BAR; PG8_SCHED;
;         }
;         if (wr == 0) PG8_BAR;
	s_add_i32 s28, s66, s34
	v_lshl_add_u64 v[214:215], v[214:215], 0, s[10:11]
	s_mov_b32 m0, s28
	ds_read_b128 v[182:185], v149 offset:49152
	ds_read_b128 v[186:189], v149 offset:50176
	ds_read_b128 v[190:193], v149 offset:51200
	ds_read_b128 v[194:197], v149 offset:52224
	ds_read_b128 v[198:201], v149 offset:53248
	ds_read_b128 v[202:205], v149 offset:54272
	ds_read_b128 v[206:209], v149 offset:55296
	ds_read_b128 v[210:213], v149 offset:56320
	global_load_lds_dwordx4 v[214:215], off
	s_add_i32 m0, s28, 0x2000
	s_add_u32 s26, s26, 0x40080
	v_lshl_add_u64 v[214:215], v[216:217], 0, s[10:11]
	s_addc_u32 s27, s27, 0
	s_add_i32 s28, s67, s34
	global_load_lds_dwordx4 v[214:215], off
	v_lshl_add_u64 v[214:215], s[26:27], 0, v[132:133]
	s_mov_b32 m0, s28
	s_nop 0
	global_load_lds_dwordx4 v[214:215], off
	v_lshl_add_u64 v[214:215], s[26:27], 0, v[128:129]
	s_add_i32 m0, s28, 0x2000
	s_nop 0
	global_load_lds_dwordx4 v[214:215], off
	v_lshl_add_u64 v[214:215], v[218:219], 0, s[10:11]
	s_mov_b32 m0, s43
	s_nop 0
	global_load_lds_dwordx4 v[214:215], off
	v_lshl_add_u64 v[214:215], v[220:221], 0, s[10:11]
	s_mov_b32 m0, s44
	s_nop 0
	global_load_lds_dwordx4 v[214:215], off
	s_waitcnt vmcnt(8)
	s_waitcnt lgkmcnt(0)
	s_barrier
	s_setprio 1
	s_waitcnt lgkmcnt(0)
	v_mfma_f32_16x16x32_bf16 v[60:63], v[150:153], v[182:185], v[60:63]
	v_mfma_f32_16x16x32_bf16 v[52:55], v[158:161], v[182:185], v[52:55]
	v_mfma_f32_16x16x32_bf16 v[44:47], v[150:153], v[190:193], v[44:47]
	v_mfma_f32_16x16x32_bf16 v[36:39], v[158:161], v[190:193], v[36:39]
	v_mfma_f32_16x16x32_bf16 v[28:31], v[150:153], v[198:201], v[28:31]
	v_mfma_f32_16x16x32_bf16 v[20:23], v[158:161], v[198:201], v[20:23]
	v_mfma_f32_16x16x32_bf16 v[12:15], v[150:153], v[206:209], v[12:15]
	v_mfma_f32_16x16x32_bf16 v[4:7], v[158:161], v[206:209], v[4:7]
	v_mfma_f32_16x16x32_bf16 v[60:63], v[154:157], v[186:189], v[60:63]
	v_mfma_f32_16x16x32_bf16 v[52:55], v[162:165], v[186:189], v[52:55]
	v_mfma_f32_16x16x32_bf16 v[44:47], v[154:157], v[194:197], v[44:47]
	v_mfma_f32_16x16x32_bf16 v[36:39], v[162:165], v[194:197], v[36:39]
	v_mfma_f32_16x16x32_bf16 v[28:31], v[154:157], v[202:205], v[28:31]
	v_mfma_f32_16x16x32_bf16 v[20:23], v[162:165], v[202:205], v[20:23]
	v_mfma_f32_16x16x32_bf16 v[12:15], v[154:157], v[210:213], v[12:15]
	v_mfma_f32_16x16x32_bf16 v[4:7], v[162:165], v[210:213], v[4:7]
	s_setprio 0
	s_setprio 1
	v_mfma_f32_16x16x32_bf16 v[56:59], v[166:169], v[182:185], v[56:59]
	v_mfma_f32_16x16x32_bf16 v[48:51], v[174:177], v[182:185], v[48:51]
	v_mfma_f32_16x16x32_bf16 v[40:43], v[166:169], v[190:193], v[40:43]
	v_mfma_f32_16x16x32_bf16 v[32:35], v[174:177], v[190:193], v[32:35]
	v_mfma_f32_16x16x32_bf16 v[24:27], v[166:169], v[198:201], v[24:27]
	v_mfma_f32_16x16x32_bf16 v[16:19], v[174:177], v[198:201], v[16:19]
	v_mfma_f32_16x16x32_bf16 v[8:11], v[166:169], v[206:209], v[8:11]
	v_mfma_f32_16x16x32_bf16 v[0:3], v[174:177], v[206:209], v[0:3]
	v_mfma_f32_16x16x32_bf16 v[56:59], v[170:173], v[186:189], v[56:59]
	v_mfma_f32_16x16x32_bf16 v[48:51], v[178:181], v[186:189], v[48:51]
	v_mfma_f32_16x16x32_bf16 v[40:43], v[170:173], v[194:197], v[40:43]
	v_mfma_f32_16x16x32_bf16 v[32:35], v[178:181], v[194:197], v[32:35]
	v_mfma_f32_16x16x32_bf16 v[24:27], v[170:173], v[202:205], v[24:27]
	v_mfma_f32_16x16x32_bf16 v[16:19], v[178:181], v[202:205], v[16:19]
	v_mfma_f32_16x16x32_bf16 v[8:11], v[170:173], v[210:213], v[8:11]
	v_mfma_f32_16x16x32_bf16 v[0:3], v[178:181], v[210:213], v[0:3]
	s_setprio 0
	s_add_i32 s61, s61, 2
	s_add_u32 s57, s57, 0x100
	s_addc_u32 s60, s60, 0
	s_add_u32 s24, s24, 0x100
	s_addc_u32 s25, s25, 0
	s_cmp_gt_u32 s61, 13
	s_barrier
	s_cbranch_scc0 .LBB0_1888
	s_and_b64 vcc, exec, s[12:13]
	s_cbranch_vccz .LBB0_1891
	s_barrier

; #define PG8_STAGE(bufoff, gbase, voff) do { _Pragma("unroll") for (int _i = 0; _i < 2; ++_i) \
;         __builtin_amdgcn_global_load_lds((const unsigned*)((const char*)(gbase) + (voff)[_i]), (LAS unsigned*)(lds + (bufoff) + ldsw + _i * 8192), 16, 0, 0); } while (0)
; #define PG8_LDA(dst, b, h) do { _Pragma("unroll") for (int m = 0; m < 4; ++m) _Pragma("unroll") for (int k = 0; k < 2; ++k) dst[m][k] = *(const LAS bf16x8*)(lds + PG8_SA(b, h) + aoff + m * 2048 + k * 1024); } while (0)
; #define PG8_LDB(dst, b, h) do { _Pragma("unroll") for (int n = 0; n < 2; ++n) _Pragma("unroll") for (int k = 0; k < 2; ++k) dst[n][k] = *(const LAS bf16x8*)(lds + PG8_SB(b, h) + boff + n * 2048 + k * 1024); } while (0)
; #define PG8_MMA(ai, bj, At, Bt) do { __builtin_amdgcn_s_setprio(1); _Pragma("unroll") for (int m = 0; m < 4; ++m) _Pragma("unroll") for (int n = 0; n < 2; ++n) _Pragma("unroll") for (int k = 0; k < 2; ++k) \
;         acc[ai][bj][m][n] = __builtin_amdgcn_mfma_f32_16x16x32_bf16(Bt[n][k], At[m][k], acc[ai][bj][m][n], 0, 0, 0); __builtin_amdgcn_s_setprio(0); } while (0)
; #define PG8_WAIT_V(n) asm volatile("s_waitcnt vmcnt(" #n ")" ::: "memory")
; #define PG8_WAIT_L(n) asm volatile("s_waitcnt lgkmcnt(" #n ")" ::: "memory")
; #define PG8_BAR __builtin_amdgcn_s_barrier()
; #define PG8_SCHED __builtin_amdgcn_sched_barrier(0)
; template <class Epi>
; DI void gemm_phase(int wv, LAS unsigned char* lds, const Gemm g, const StaticOrder& S, const Epi& E) {
;     ...
;         for (int t = 0; t < nt; t += 2) {
;             const bool last = (t == nt - 2);
;             const char* a1 = cA + (size_t)(t + 1) * kstep;
;             const char* a2 = last ? nA : cA + (size_t)(t + 2) * kstep; const char* b2 = last ? nB : cB + (size_t)(t + 2) * kstep;
;             const char* a3 = a2 + kstep; const char* b3 = b2 + kstep;
;             PG8_LDB(B0, 0, 0); PG8_LDB(B1, 0, 1); PG8_SCHED; PG8_LDA(At, 0, 0); PG8_STAGE(PG8_SA(1, 1), a1 + hA, voffA);
;             PG8_WAIT_V(8); PG8_WAIT_L(0); PG8_BAR; PG8_MMA(0, 0, At, B0); PG8_MMA(0, 1, At, B1); PG8_BAR; PG8_SCHED;
;             PG8_LDA(At, 0, 1); PG8_STAGE(PG8_SB(0, 0), b2, voffB); PG8_STAGE(PG8_SB(0, 1), b2 + hB, voffB); PG8_STAGE(PG8_SA(0, 0), a2, voffA);
;             PG8_WAIT_V(8); PG8_WAIT_L(0); PG8_BAR; PG8_MMA(1, 0, At, B0); PG8_MMA(1, 1, At, B1); PG8_BAR; PG8_SCHED;
.LBB0_1969:
	ds_read_b128 v[150:153], v147
	ds_read_b128 v[154:157], v147 offset:1024
	ds_read_b128 v[158:161], v147 offset:2048
	ds_read_b128 v[162:165], v147 offset:3072
	ds_read_b128 v[166:169], v148
	ds_read_b128 v[170:173], v148 offset:1024
	ds_read_b128 v[174:177], v148 offset:2048
	ds_read_b128 v[178:181], v148 offset:3072
	s_add_u32 s20, s18, 0x100
	s_addc_u32 s21, s19, 0
	s_cmp_eq_u32 s57, 40
	s_cselect_b32 s25, s5, s21
	s_cselect_b32 s24, s4, s20
	s_cselect_b32 s23, s17, s55
	s_cselect_b32 s22, s16, s51
	v_lshl_add_u64 v[214:215], s[18:19], 0, v[138:139]
	s_add_i32 m0, s34, 0xc000
	ds_read_b128 v[182:185], v149
	ds_read_b128 v[186:189], v149 offset:1024
	ds_read_b128 v[190:193], v149 offset:2048
	ds_read_b128 v[194:197], v149 offset:3072
	ds_read_b128 v[198:201], v149 offset:4096
	ds_read_b128 v[202:205], v149 offset:5120
	ds_read_b128 v[206:209], v149 offset:6144
	ds_read_b128 v[210:213], v149 offset:7168
	global_load_lds_dwordx4 v[214:215], off
	v_lshl_add_u64 v[214:215], s[18:19], 0, v[136:137]
	s_add_i32 m0, s34, 0xe000
	s_nop 0
	global_load_lds_dwordx4 v[214:215], off
	s_waitcnt vmcnt(8)
	s_waitcnt lgkmcnt(0)
	s_barrier
	s_setprio 1
	s_waitcnt lgkmcnt(0)
	v_mfma_f32_16x16x32_bf16 v[124:127], v[150:153], v[182:185], v[124:127]
	v_mfma_f32_16x16x32_bf16 v[120:123], v[158:161], v[182:185], v[120:123]
	v_mfma_f32_16x16x32_bf16 v[116:119], v[150:153], v[190:193], v[116:119]
	v_mfma_f32_16x16x32_bf16 v[112:115], v[158:161], v[190:193], v[112:115]
	v_mfma_f32_16x16x32_bf16 v[100:103], v[150:153], v[198:201], v[100:103]
	v_mfma_f32_16x16x32_bf16 v[96:99], v[158:161], v[198:201], v[96:99]
	v_mfma_f32_16x16x32_bf16 v[84:87], v[150:153], v[206:209], v[84:87]
	v_mfma_f32_16x16x32_bf16 v[80:83], v[158:161], v[206:209], v[80:83]
	v_mfma_f32_16x16x32_bf16 v[124:127], v[154:157], v[186:189], v[124:127]
	v_mfma_f32_16x16x32_bf16 v[120:123], v[162:165], v[186:189], v[120:123]
	v_mfma_f32_16x16x32_bf16 v[116:119], v[154:157], v[194:197], v[116:119]
	v_mfma_f32_16x16x32_bf16 v[112:115], v[162:165], v[194:197], v[112:115]
	v_mfma_f32_16x16x32_bf16 v[100:103], v[154:157], v[202:205], v[100:103]
	v_mfma_f32_16x16x32_bf16 v[96:99], v[162:165], v[202:205], v[96:99]
	v_mfma_f32_16x16x32_bf16 v[84:87], v[154:157], v[210:213], v[84:87]
	v_mfma_f32_16x16x32_bf16 v[80:83], v[162:165], v[210:213], v[80:83]
	s_setprio 0
	s_setprio 1
	v_mfma_f32_16x16x32_bf16 v[108:111], v[166:169], v[182:185], v[108:111]
	v_mfma_f32_16x16x32_bf16 v[104:107], v[174:177], v[182:185], v[104:107]
	v_mfma_f32_16x16x32_bf16 v[92:95], v[166:169], v[190:193], v[92:95]
	v_mfma_f32_16x16x32_bf16 v[88:91], v[174:177], v[190:193], v[88:91]
	v_mfma_f32_16x16x32_bf16 v[76:79], v[166:169], v[198:201], v[76:79]
	v_mfma_f32_16x16x32_bf16 v[72:75], v[174:177], v[198:201], v[72:75]
	v_mfma_f32_16x16x32_bf16 v[68:71], v[166:169], v[206:209], v[68:71]
	v_mfma_f32_16x16x32_bf16 v[64:67], v[174:177], v[206:209], v[64:67]
	v_mfma_f32_16x16x32_bf16 v[108:111], v[170:173], v[186:189], v[108:111]
	v_mfma_f32_16x16x32_bf16 v[104:107], v[178:181], v[186:189], v[104:107]
	v_mfma_f32_16x16x32_bf16 v[92:95], v[170:173], v[194:197], v[92:95]
	v_mfma_f32_16x16x32_bf16 v[88:91], v[178:181], v[194:197], v[88:91]
	v_mfma_f32_16x16x32_bf16 v[76:79], v[170:173], v[202:205], v[76:79]
	v_mfma_f32_16x16x32_bf16 v[72:75], v[178:181], v[202:205], v[72:75]
	v_mfma_f32_16x16x32_bf16 v[68:71], v[170:173], v[210:213], v[68:71]
	v_mfma_f32_16x16x32_bf16 v[64:67], v[178:181], v[210:213], v[64:67]
	s_setprio 0
	s_barrier
	s_add_i32 s18, s43, s31
	v_lshl_add_u64 v[214:215], s[22:23], 0, v[130:131]
	s_mov_b32 m0, s18
	ds_read_b128 v[182:185], v149 offset:16384
	ds_read_b128 v[186:189], v149 offset:17408
	ds_read_b128 v[190:193], v149 offset:18432
	ds_read_b128 v[194:197], v149 offset:19456
	ds_read_b128 v[198:201], v149 offset:20480
	ds_read_b128 v[202:205], v149 offset:21504
	ds_read_b128 v[206:209], v149 offset:22528
	ds_read_b128 v[210:213], v149 offset:23552
	global_load_lds_dwordx4 v[214:215], off
	s_add_i32 m0, s18, 0x2000
	s_add_u32 s18, s22, 0xb0000
	v_lshl_add_u64 v[216:217], s[22:23], 0, v[134:135]
	s_addc_u32 s19, s23, 0
	s_add_i32 s60, s44, s31
	global_load_lds_dwordx4 v[216:217], off
	v_lshl_add_u64 v[218:219], s[18:19], 0, v[130:131]
	s_mov_b32 m0, s60
	v_lshl_add_u64 v[220:221], s[24:25], 0, v[132:133]
	global_load_lds_dwordx4 v[218:219], off
	v_lshl_add_u64 v[218:219], s[18:19], 0, v[134:135]
	s_add_i32 m0, s60, 0x2000
	s_nop 0
	global_load_lds_dwordx4 v[218:219], off
	v_lshl_add_u64 v[218:219], s[24:25], 0, v[128:129]
	s_mov_b32 m0, s34
	s_nop 0
	global_load_lds_dwordx4 v[218:219], off
	s_mov_b32 m0, s35
	s_nop 0
	global_load_lds_dwordx4 v[220:221], off
	s_waitcnt vmcnt(8)
	s_waitcnt lgkmcnt(0)
	s_barrier
; #define PG8_STAGE(bufoff, gbase, voff) do { _Pragma("unroll") for (int _i = 0; _i < 2; ++_i) \
;         __builtin_amdgcn_global_load_lds((const unsigned*)((const char*)(gbase) + (voff)[_i]), (LAS unsigned*)(lds + (bufoff) + ldsw + _i * 8192), 16, 0, 0); } while (0)
; #define PG8_LDA(dst, b, h) do { _Pragma("unroll") for (int m = 0; m < 4; ++m) _Pragma("unroll") for (int k = 0; k < 2; ++k) dst[m][k] = *(const LAS bf16x8*)(lds + PG8_SA(b, h) + aoff + m * 2048 + k * 1024); } while (0)
; #define PG8_LDB(dst, b, h) do { _Pragma("unroll") for (int n = 0; n < 2; ++n) _Pragma("unroll") for (int k = 0; k < 2; ++k) dst[n][k] = *(const LAS bf16x8*)(lds + PG8_SB(b, h) + boff + n * 2048 + k * 1024); } while (0)
; #define PG8_MMA(ai, bj, At, Bt) do { __builtin_amdgcn_s_setprio(1); _Pragma("unroll") for (int m = 0; m < 4; ++m) _Pragma("unroll") for (int n = 0; n < 2; ++n) _Pragma("unroll") for (int k = 0; k < 2; ++k) \
;         acc[ai][bj][m][n] = __builtin_amdgcn_mfma_f32_16x16x32_bf16(Bt[n][k], At[m][k], acc[ai][bj][m][n], 0, 0, 0); __builtin_amdgcn_s_setprio(0); } while (0)
; #define PG8_WAIT_V(n) asm volatile("s_waitcnt vmcnt(" #n ")" ::: "memory")
; #define PG8_WAIT_L(n) asm volatile("s_waitcnt lgkmcnt(" #n ")" ::: "memory")
; #define PG8_BAR __builtin_amdgcn_s_barrier()
; #define PG8_SCHED __builtin_amdgcn_sched_barrier(0)
; template <class Epi>
; DI void gemm_phase(int wv, LAS unsigned char* lds, const Gemm g, const StaticOrder& S, const Epi& E) {
;     ...
;             PG8_WAIT_V(8); PG8_WAIT_L(0); PG8_BAR; PG8_MMA(1, 0, At, B0); PG8_MMA(1, 1, At, B1); PG8_BAR; PG8_SCHED;
;             PG8_LDB(B0, 1, 0); PG8_LDB(B1, 1, 1); PG8_SCHED; PG8_LDA(At, 1, 0); PG8_STAGE(PG8_SA(0, 1), a2 + hA, voffA);
;             PG8_WAIT_V(8); PG8_WAIT_L(0); PG8_BAR; PG8_MMA(0, 0, At, B0); PG8_MMA(0, 1, At, B1); PG8_BAR; PG8_SCHED;
	s_setprio 1
	s_waitcnt lgkmcnt(0)
	v_mfma_f32_16x16x32_bf16 v[60:63], v[150:153], v[182:185], v[60:63]
	v_mfma_f32_16x16x32_bf16 v[56:59], v[158:161], v[182:185], v[56:59]
	v_mfma_f32_16x16x32_bf16 v[52:55], v[150:153], v[190:193], v[52:55]
	v_mfma_f32_16x16x32_bf16 v[48:51], v[158:161], v[190:193], v[48:51]
	v_mfma_f32_16x16x32_bf16 v[36:39], v[150:153], v[198:201], v[36:39]
	v_mfma_f32_16x16x32_bf16 v[32:35], v[158:161], v[198:201], v[32:35]
	v_mfma_f32_16x16x32_bf16 v[20:23], v[150:153], v[206:209], v[20:23]
	v_mfma_f32_16x16x32_bf16 v[16:19], v[158:161], v[206:209], v[16:19]
	v_mfma_f32_16x16x32_bf16 v[60:63], v[154:157], v[186:189], v[60:63]
	v_mfma_f32_16x16x32_bf16 v[56:59], v[162:165], v[186:189], v[56:59]
	v_mfma_f32_16x16x32_bf16 v[52:55], v[154:157], v[194:197], v[52:55]
	v_mfma_f32_16x16x32_bf16 v[48:51], v[162:165], v[194:197], v[48:51]
	v_mfma_f32_16x16x32_bf16 v[36:39], v[154:157], v[202:205], v[36:39]
	v_mfma_f32_16x16x32_bf16 v[32:35], v[162:165], v[202:205], v[32:35]
	v_mfma_f32_16x16x32_bf16 v[20:23], v[154:157], v[210:213], v[20:23]
	v_mfma_f32_16x16x32_bf16 v[16:19], v[162:165], v[210:213], v[16:19]
	s_setprio 0
	s_setprio 1
	v_mfma_f32_16x16x32_bf16 v[44:47], v[166:169], v[182:185], v[44:47]
	v_mfma_f32_16x16x32_bf16 v[40:43], v[174:177], v[182:185], v[40:43]
	v_mfma_f32_16x16x32_bf16 v[28:31], v[166:169], v[190:193], v[28:31]
	v_mfma_f32_16x16x32_bf16 v[24:27], v[174:177], v[190:193], v[24:27]
	v_mfma_f32_16x16x32_bf16 v[12:15], v[166:169], v[198:201], v[12:15]
	v_mfma_f32_16x16x32_bf16 v[8:11], v[174:177], v[198:201], v[8:11]
	v_mfma_f32_16x16x32_bf16 v[4:7], v[166:169], v[206:209], v[4:7]
	v_mfma_f32_16x16x32_bf16 v[0:3], v[174:177], v[206:209], v[0:3]
	v_mfma_f32_16x16x32_bf16 v[44:47], v[170:173], v[186:189], v[44:47]
	v_mfma_f32_16x16x32_bf16 v[40:43], v[178:181], v[186:189], v[40:43]
	v_mfma_f32_16x16x32_bf16 v[28:31], v[170:173], v[194:197], v[28:31]
	v_mfma_f32_16x16x32_bf16 v[24:27], v[178:181], v[194:197], v[24:27]
	v_mfma_f32_16x16x32_bf16 v[12:15], v[170:173], v[202:205], v[12:15]
	v_mfma_f32_16x16x32_bf16 v[8:11], v[178:181], v[202:205], v[8:11]
	v_mfma_f32_16x16x32_bf16 v[4:7], v[170:173], v[210:213], v[4:7]
	v_mfma_f32_16x16x32_bf16 v[0:3], v[178:181], v[210:213], v[0:3]
	s_setprio 0
	s_barrier
	s_add_i32 s60, 0, 0x18000
	s_add_i32 s61, 0, 0x1c000
	v_add_u32_e32 v162, s60, v146
	v_add_u32_e32 v178, s61, v146
	ds_read_b128 v[150:153], v162
	ds_read_b128 v[154:157], v162 offset:1024
	ds_read_b128 v[158:161], v162 offset:2048
	ds_read_b128 v[162:165], v162 offset:3072
	ds_read_b128 v[166:169], v178
	ds_read_b128 v[170:173], v178 offset:1024
	ds_read_b128 v[174:177], v178 offset:2048
	ds_read_b128 v[178:181], v178 offset:3072
	s_add_u32 s18, s24, 0xb0000
	s_addc_u32 s19, s25, 0
	s_mov_b32 m0, s36
	v_lshl_add_u64 v[222:223], s[18:19], 0, v[128:129]
	ds_read_b128 v[182:185], v149 offset:32768
	ds_read_b128 v[186:189], v149 offset:33792
	ds_read_b128 v[190:193], v149 offset:34816
	ds_read_b128 v[194:197], v149 offset:35840
	ds_read_b128 v[198:201], v149 offset:36864
	ds_read_b128 v[202:205], v149 offset:37888
	ds_read_b128 v[206:209], v149 offset:38912
	ds_read_b128 v[210:213], v149 offset:39936
	global_load_lds_dwordx4 v[222:223], off
	v_lshl_add_u64 v[222:223], s[18:19], 0, v[132:133]
	s_mov_b32 m0, s37
	s_nop 0
	global_load_lds_dwordx4 v[222:223], off
	s_waitcnt vmcnt(8)
	s_waitcnt lgkmcnt(0)
	s_barrier
	s_setprio 1
	s_waitcnt lgkmcnt(0)
	v_mfma_f32_16x16x32_bf16 v[124:127], v[150:153], v[182:185], v[124:127]
	v_mfma_f32_16x16x32_bf16 v[120:123], v[158:161], v[182:185], v[120:123]
	v_mfma_f32_16x16x32_bf16 v[116:119], v[150:153], v[190:193], v[116:119]
	v_mfma_f32_16x16x32_bf16 v[112:115], v[158:161], v[190:193], v[112:115]
	v_mfma_f32_16x16x32_bf16 v[100:103], v[150:153], v[198:201], v[100:103]
	v_mfma_f32_16x16x32_bf16 v[96:99], v[158:161], v[198:201], v[96:99]
	v_mfma_f32_16x16x32_bf16 v[84:87], v[150:153], v[206:209], v[84:87]
	v_mfma_f32_16x16x32_bf16 v[80:83], v[158:161], v[206:209], v[80:83]
	v_mfma_f32_16x16x32_bf16 v[124:127], v[154:157], v[186:189], v[124:127]
	v_mfma_f32_16x16x32_bf16 v[120:123], v[162:165], v[186:189], v[120:123]
	v_mfma_f32_16x16x32_bf16 v[116:119], v[154:157], v[194:197], v[116:119]
	v_mfma_f32_16x16x32_bf16 v[112:115], v[162:165], v[194:197], v[112:115]
	v_mfma_f32_16x16x32_bf16 v[100:103], v[154:157], v[202:205], v[100:103]
	v_mfma_f32_16x16x32_bf16 v[96:99], v[162:165], v[202:205], v[96:99]
	v_mfma_f32_16x16x32_bf16 v[84:87], v[154:157], v[210:213], v[84:87]
	v_mfma_f32_16x16x32_bf16 v[80:83], v[162:165], v[210:213], v[80:83]
	s_setprio 0
	s_setprio 1
	v_mfma_f32_16x16x32_bf16 v[108:111], v[166:169], v[182:185], v[108:111]
	v_mfma_f32_16x16x32_bf16 v[104:107], v[174:177], v[182:185], v[104:107]
	v_mfma_f32_16x16x32_bf16 v[92:95], v[166:169], v[190:193], v[92:95]
	v_mfma_f32_16x16x32_bf16 v[88:91], v[174:177], v[190:193], v[88:91]
	v_mfma_f32_16x16x32_bf16 v[76:79], v[166:169], v[198:201], v[76:79]
	v_mfma_f32_16x16x32_bf16 v[72:75], v[174:177], v[198:201], v[72:75]
	v_mfma_f32_16x16x32_bf16 v[68:71], v[166:169], v[206:209], v[68:71]
	v_mfma_f32_16x16x32_bf16 v[64:67], v[174:177], v[206:209], v[64:67]
	v_mfma_f32_16x16x32_bf16 v[108:111], v[170:173], v[186:189], v[108:111]
	v_mfma_f32_16x16x32_bf16 v[104:107], v[178:181], v[186:189], v[104:107]
	v_mfma_f32_16x16x32_bf16 v[92:95], v[170:173], v[194:197], v[92:95]
	v_mfma_f32_16x16x32_bf16 v[88:91], v[178:181], v[194:197], v[88:91]
	v_mfma_f32_16x16x32_bf16 v[76:79], v[170:173], v[202:205], v[76:79]
	v_mfma_f32_16x16x32_bf16 v[72:75], v[178:181], v[202:205], v[72:75]
	v_mfma_f32_16x16x32_bf16 v[68:71], v[170:173], v[210:213], v[68:71]
	v_mfma_f32_16x16x32_bf16 v[64:67], v[178:181], v[210:213], v[64:67]
	s_setprio 0
	s_barrier
; #define PG8_STAGE(bufoff, gbase, voff) do { _Pragma("unroll") for (int _i = 0; _i < 2; ++_i) \
;         __builtin_amdgcn_global_load_lds((const unsigned*)((const char*)(gbase) + (voff)[_i]), (LAS unsigned*)(lds + (bufoff) + ldsw + _i * 8192), 16, 0, 0); } while (0)
; #define PG8_LDA(dst, b, h) do { _Pragma("unroll") for (int m = 0; m < 4; ++m) _Pragma("unroll") for (int k = 0; k < 2; ++k) dst[m][k] = *(const LAS bf16x8*)(lds + PG8_SA(b, h) + aoff + m * 2048 + k * 1024); } while (0)
; #define PG8_MMA(ai, bj, At, Bt) do { __builtin_amdgcn_s_setprio(1); _Pragma("unroll") for (int m = 0; m < 4; ++m) _Pragma("unroll") for (int n = 0; n < 2; ++n) _Pragma("unroll") for (int k = 0; k < 2; ++k) \
;         acc[ai][bj][m][n] = __builtin_amdgcn_mfma_f32_16x16x32_bf16(Bt[n][k], At[m][k], acc[ai][bj][m][n], 0, 0, 0); __builtin_amdgcn_s_setprio(0); } while (0)
; #define PG8_WAIT_V(n) asm volatile("s_waitcnt vmcnt(" #n ")" ::: "memory")
; #define PG8_WAIT_L(n) asm volatile("s_waitcnt lgkmcnt(" #n ")" ::: "memory")
; #define PG8_BAR __builtin_amdgcn_s_barrier()
; #define PG8_SCHED __builtin_amdgcn_sched_barrier(0)
; template <class Epi>
; DI void gemm_phase(int wv, LAS unsigned char* lds, const Gemm g, const StaticOrder& S, const Epi& E) {
;     ...
;             PG8_LDA(At, 1, 1); PG8_STAGE(PG8_SB(1, 0), b3, voffB); PG8_STAGE(PG8_SB(1, 1), b3 + hB, voffB); PG8_STAGE(PG8_SA(1, 0), a3, voffA);
;             PG8_WAIT_V(8); PG8_WAIT_L(0); PG8_BAR; PG8_MMA(1, 0, At, B0); PG8_MMA(1, 1, At, B1); PG8_BAR; PG8_SCHED;
;         }
;         if (wr == 0) PG8_BAR;
	s_add_i32 s18, s60, s31
	v_lshl_add_u64 v[214:215], v[214:215], 0, s[10:11]
	s_mov_b32 m0, s18
	ds_read_b128 v[182:185], v149 offset:49152
	ds_read_b128 v[186:189], v149 offset:50176
	ds_read_b128 v[190:193], v149 offset:51200
	ds_read_b128 v[194:197], v149 offset:52224
	ds_read_b128 v[198:201], v149 offset:53248
	ds_read_b128 v[202:205], v149 offset:54272
	ds_read_b128 v[206:209], v149 offset:55296
	ds_read_b128 v[210:213], v149 offset:56320
	global_load_lds_dwordx4 v[214:215], off
	s_add_i32 m0, s18, 0x2000
	s_add_u32 s18, s22, 0xb0080
	v_lshl_add_u64 v[214:215], v[216:217], 0, s[10:11]
	s_addc_u32 s19, s23, 0
	s_add_i32 s22, s61, s31
	global_load_lds_dwordx4 v[214:215], off
	v_lshl_add_u64 v[214:215], s[18:19], 0, v[130:131]
	s_mov_b32 m0, s22
	s_nop 0
	global_load_lds_dwordx4 v[214:215], off
	v_lshl_add_u64 v[214:215], s[18:19], 0, v[134:135]
	s_add_i32 m0, s22, 0x2000
	s_nop 0
	global_load_lds_dwordx4 v[214:215], off
	v_lshl_add_u64 v[214:215], v[218:219], 0, s[10:11]
	s_mov_b32 m0, s41
	s_nop 0
	global_load_lds_dwordx4 v[214:215], off
	v_lshl_add_u64 v[214:215], v[220:221], 0, s[10:11]
	s_mov_b32 m0, s42
	s_nop 0
	global_load_lds_dwordx4 v[214:215], off
	s_waitcnt vmcnt(8)
	s_waitcnt lgkmcnt(0)
	s_barrier
	s_setprio 1
	s_waitcnt lgkmcnt(0)
	v_mfma_f32_16x16x32_bf16 v[60:63], v[150:153], v[182:185], v[60:63]
	v_mfma_f32_16x16x32_bf16 v[56:59], v[158:161], v[182:185], v[56:59]
	v_mfma_f32_16x16x32_bf16 v[52:55], v[150:153], v[190:193], v[52:55]
	v_mfma_f32_16x16x32_bf16 v[48:51], v[158:161], v[190:193], v[48:51]
	v_mfma_f32_16x16x32_bf16 v[36:39], v[150:153], v[198:201], v[36:39]
	v_mfma_f32_16x16x32_bf16 v[32:35], v[158:161], v[198:201], v[32:35]
	v_mfma_f32_16x16x32_bf16 v[20:23], v[150:153], v[206:209], v[20:23]
	v_mfma_f32_16x16x32_bf16 v[16:19], v[158:161], v[206:209], v[16:19]
	v_mfma_f32_16x16x32_bf16 v[60:63], v[154:157], v[186:189], v[60:63]
	v_mfma_f32_16x16x32_bf16 v[56:59], v[162:165], v[186:189], v[56:59]
	v_mfma_f32_16x16x32_bf16 v[52:55], v[154:157], v[194:197], v[52:55]
	v_mfma_f32_16x16x32_bf16 v[48:51], v[162:165], v[194:197], v[48:51]
	v_mfma_f32_16x16x32_bf16 v[36:39], v[154:157], v[202:205], v[36:39]
	v_mfma_f32_16x16x32_bf16 v[32:35], v[162:165], v[202:205], v[32:35]
	v_mfma_f32_16x16x32_bf16 v[20:23], v[154:157], v[210:213], v[20:23]
	v_mfma_f32_16x16x32_bf16 v[16:19], v[162:165], v[210:213], v[16:19]
	s_setprio 0
	s_setprio 1
	v_mfma_f32_16x16x32_bf16 v[44:47], v[166:169], v[182:185], v[44:47]
	v_mfma_f32_16x16x32_bf16 v[40:43], v[174:177], v[182:185], v[40:43]
	v_mfma_f32_16x16x32_bf16 v[28:31], v[166:169], v[190:193], v[28:31]
	v_mfma_f32_16x16x32_bf16 v[24:27], v[174:177], v[190:193], v[24:27]
	v_mfma_f32_16x16x32_bf16 v[12:15], v[166:169], v[198:201], v[12:15]
	v_mfma_f32_16x16x32_bf16 v[8:11], v[174:177], v[198:201], v[8:11]
	v_mfma_f32_16x16x32_bf16 v[4:7], v[166:169], v[206:209], v[4:7]
	v_mfma_f32_16x16x32_bf16 v[0:3], v[174:177], v[206:209], v[0:3]
	v_mfma_f32_16x16x32_bf16 v[44:47], v[170:173], v[186:189], v[44:47]
	v_mfma_f32_16x16x32_bf16 v[40:43], v[178:181], v[186:189], v[40:43]
	v_mfma_f32_16x16x32_bf16 v[28:31], v[170:173], v[194:197], v[28:31]
	v_mfma_f32_16x16x32_bf16 v[24:27], v[178:181], v[194:197], v[24:27]
	v_mfma_f32_16x16x32_bf16 v[12:15], v[170:173], v[202:205], v[12:15]
	v_mfma_f32_16x16x32_bf16 v[8:11], v[178:181], v[202:205], v[8:11]
	v_mfma_f32_16x16x32_bf16 v[4:7], v[170:173], v[210:213], v[4:7]
	v_mfma_f32_16x16x32_bf16 v[0:3], v[178:181], v[210:213], v[0:3]
	s_setprio 0
	s_add_i32 s57, s57, 2
	s_add_u32 s51, s51, 0x100
	s_addc_u32 s55, s55, 0
	s_cmp_gt_u32 s57, 41
	s_mov_b64 s[18:19], s[20:21]
	s_barrier
	s_cbranch_scc0 .LBB0_1969
	s_and_b64 vcc, exec, s[12:13]
	s_cbranch_vccz .LBB0_1972
	s_barrier

; #define PG8_STAGE(bufoff, gbase, voff) do { _Pragma("unroll") for (int _i = 0; _i < 2; ++_i) \
;         __builtin_amdgcn_global_load_lds((const unsigned*)((const char*)(gbase) + (voff)[_i]), (LAS unsigned*)(lds + (bufoff) + ldsw + _i * 8192), 16, 0, 0); } while (0)
; #define PG8_LDA(dst, b, h) do { _Pragma("unroll") for (int m = 0; m < 4; ++m) _Pragma("unroll") for (int k = 0; k < 2; ++k) dst[m][k] = *(const LAS bf16x8*)(lds + PG8_SA(b, h) + aoff + m * 2048 + k * 1024); } while (0)
; #define PG8_LDB(dst, b, h) do { _Pragma("unroll") for (int n = 0; n < 2; ++n) _Pragma("unroll") for (int k = 0; k < 2; ++k) dst[n][k] = *(const LAS bf16x8*)(lds + PG8_SB(b, h) + boff + n * 2048 + k * 1024); } while (0)
; #define PG8_MMA(ai, bj, At, Bt) do { __builtin_amdgcn_s_setprio(1); _Pragma("unroll") for (int m = 0; m < 4; ++m) _Pragma("unroll") for (int n = 0; n < 2; ++n) _Pragma("unroll") for (int k = 0; k < 2; ++k) \
;         acc[ai][bj][m][n] = __builtin_amdgcn_mfma_f32_16x16x32_bf16(Bt[n][k], At[m][k], acc[ai][bj][m][n], 0, 0, 0); __builtin_amdgcn_s_setprio(0); } while (0)
; #define PG8_WAIT_V(n) asm volatile("s_waitcnt vmcnt(" #n ")" ::: "memory")
; #define PG8_WAIT_L(n) asm volatile("s_waitcnt lgkmcnt(" #n ")" ::: "memory")
; #define PG8_BAR __builtin_amdgcn_s_barrier()
; #define PG8_SCHED __builtin_amdgcn_sched_barrier(0)
; template <class Epi>
; DI void gemm_phase(int wv, LAS unsigned char* lds, const Gemm g, const StaticOrder& S, const Epi& E) {
;     ...
;         for (int t = 0; t < nt; t += 2) {
;             const bool last = (t == nt - 2);
;             const char* a1 = cA + (size_t)(t + 1) * kstep;
;             const char* a2 = last ? nA : cA + (size_t)(t + 2) * kstep; const char* b2 = last ? nB : cB + (size_t)(t + 2) * kstep;
;             const char* a3 = a2 + kstep; const char* b3 = b2 + kstep;
;             PG8_LDB(B0, 0, 0); PG8_LDB(B1, 0, 1); PG8_SCHED; PG8_LDA(At, 0, 0); PG8_STAGE(PG8_SA(1, 1), a1 + hA, voffA);
;             PG8_WAIT_V(8); PG8_WAIT_L(0); PG8_BAR; PG8_MMA(0, 0, At, B0); PG8_MMA(0, 1, At, B1); PG8_BAR; PG8_SCHED;
;             PG8_LDA(At, 0, 1); PG8_STAGE(PG8_SB(0, 0), b2, voffB); PG8_STAGE(PG8_SB(0, 1), b2 + hB, voffB); PG8_STAGE(PG8_SA(0, 0), a2, voffA);
;             PG8_WAIT_V(8); PG8_WAIT_L(0); PG8_BAR; PG8_MMA(1, 0, At, B0); PG8_MMA(1, 1, At, B1); PG8_BAR; PG8_SCHED;
.LBB0_2381:
	ds_read_b128 v[150:153], v147
	ds_read_b128 v[154:157], v147 offset:1024
	ds_read_b128 v[158:161], v147 offset:2048
	ds_read_b128 v[162:165], v147 offset:3072
	ds_read_b128 v[166:169], v148
	ds_read_b128 v[170:173], v148 offset:1024
	ds_read_b128 v[174:177], v148 offset:2048
	ds_read_b128 v[178:181], v148 offset:3072
	s_add_u32 s26, s24, 0xfffc0080
	s_addc_u32 s27, s25, -1
	s_cmp_eq_u32 s60, 12
	s_cselect_b32 s29, s17, s27
	s_cselect_b32 s28, s51, s26
	s_cselect_b32 s27, s15, s57
	s_cselect_b32 s26, s54, s55
	v_lshl_add_u64 v[214:215], s[24:25], 0, v[138:139]
	s_add_i32 m0, s23, 0xc000
	ds_read_b128 v[182:185], v149
	ds_read_b128 v[186:189], v149 offset:1024
	ds_read_b128 v[190:193], v149 offset:2048
	ds_read_b128 v[194:197], v149 offset:3072
	ds_read_b128 v[198:201], v149 offset:4096
	ds_read_b128 v[202:205], v149 offset:5120
	ds_read_b128 v[206:209], v149 offset:6144
	ds_read_b128 v[210:213], v149 offset:7168
	global_load_lds_dwordx4 v[214:215], off
	v_lshl_add_u64 v[214:215], s[24:25], 0, v[136:137]
	s_add_i32 m0, s23, 0xe000
	s_nop 0
	global_load_lds_dwordx4 v[214:215], off
	s_waitcnt vmcnt(8)
	s_waitcnt lgkmcnt(0)
	s_barrier
	s_setprio 1
	s_waitcnt lgkmcnt(0)
	v_mfma_f32_16x16x32_bf16 v[124:127], v[150:153], v[182:185], v[124:127]
	v_mfma_f32_16x16x32_bf16 v[116:119], v[158:161], v[182:185], v[116:119]
	v_mfma_f32_16x16x32_bf16 v[108:111], v[150:153], v[190:193], v[108:111]
	v_mfma_f32_16x16x32_bf16 v[100:103], v[158:161], v[190:193], v[100:103]
	v_mfma_f32_16x16x32_bf16 v[92:95], v[150:153], v[198:201], v[92:95]
	v_mfma_f32_16x16x32_bf16 v[84:87], v[158:161], v[198:201], v[84:87]
	v_mfma_f32_16x16x32_bf16 v[76:79], v[150:153], v[206:209], v[76:79]
	v_mfma_f32_16x16x32_bf16 v[68:71], v[158:161], v[206:209], v[68:71]
	v_mfma_f32_16x16x32_bf16 v[124:127], v[154:157], v[186:189], v[124:127]
	v_mfma_f32_16x16x32_bf16 v[116:119], v[162:165], v[186:189], v[116:119]
	v_mfma_f32_16x16x32_bf16 v[108:111], v[154:157], v[194:197], v[108:111]
	v_mfma_f32_16x16x32_bf16 v[100:103], v[162:165], v[194:197], v[100:103]
	v_mfma_f32_16x16x32_bf16 v[92:95], v[154:157], v[202:205], v[92:95]
	v_mfma_f32_16x16x32_bf16 v[84:87], v[162:165], v[202:205], v[84:87]
	v_mfma_f32_16x16x32_bf16 v[76:79], v[154:157], v[210:213], v[76:79]
	v_mfma_f32_16x16x32_bf16 v[68:71], v[162:165], v[210:213], v[68:71]
	s_setprio 0
	s_setprio 1
	v_mfma_f32_16x16x32_bf16 v[120:123], v[166:169], v[182:185], v[120:123]
	v_mfma_f32_16x16x32_bf16 v[112:115], v[174:177], v[182:185], v[112:115]
	v_mfma_f32_16x16x32_bf16 v[104:107], v[166:169], v[190:193], v[104:107]
	v_mfma_f32_16x16x32_bf16 v[96:99], v[174:177], v[190:193], v[96:99]
	v_mfma_f32_16x16x32_bf16 v[88:91], v[166:169], v[198:201], v[88:91]
	v_mfma_f32_16x16x32_bf16 v[80:83], v[174:177], v[198:201], v[80:83]
	v_mfma_f32_16x16x32_bf16 v[72:75], v[166:169], v[206:209], v[72:75]
	v_mfma_f32_16x16x32_bf16 v[64:67], v[174:177], v[206:209], v[64:67]
	v_mfma_f32_16x16x32_bf16 v[120:123], v[170:173], v[186:189], v[120:123]
	v_mfma_f32_16x16x32_bf16 v[112:115], v[178:181], v[186:189], v[112:115]
	v_mfma_f32_16x16x32_bf16 v[104:107], v[170:173], v[194:197], v[104:107]
	v_mfma_f32_16x16x32_bf16 v[96:99], v[178:181], v[194:197], v[96:99]
	v_mfma_f32_16x16x32_bf16 v[88:91], v[170:173], v[202:205], v[88:91]
	v_mfma_f32_16x16x32_bf16 v[80:83], v[178:181], v[202:205], v[80:83]
	v_mfma_f32_16x16x32_bf16 v[72:75], v[170:173], v[210:213], v[72:75]
	v_mfma_f32_16x16x32_bf16 v[64:67], v[178:181], v[210:213], v[64:67]
	s_setprio 0
	s_barrier
	s_add_i32 s61, s45, s34
	v_lshl_add_u64 v[214:215], s[26:27], 0, v[132:133]
	s_mov_b32 m0, s61
	ds_read_b128 v[182:185], v149 offset:16384
	ds_read_b128 v[186:189], v149 offset:17408
	ds_read_b128 v[190:193], v149 offset:18432
	ds_read_b128 v[194:197], v149 offset:19456
	ds_read_b128 v[198:201], v149 offset:20480
	ds_read_b128 v[202:205], v149 offset:21504
	ds_read_b128 v[206:209], v149 offset:22528
	ds_read_b128 v[210:213], v149 offset:23552
	global_load_lds_dwordx4 v[214:215], off
	s_add_i32 m0, s61, 0x2000
	s_add_u32 s66, s26, 0x40000
	v_lshl_add_u64 v[216:217], s[26:27], 0, v[128:129]
	s_addc_u32 s67, s27, 0
	s_add_i32 s61, s46, s34
	global_load_lds_dwordx4 v[216:217], off
	v_lshl_add_u64 v[218:219], s[66:67], 0, v[132:133]
	s_mov_b32 m0, s61
	v_lshl_add_u64 v[220:221], s[28:29], 0, v[130:131]
	global_load_lds_dwordx4 v[218:219], off
	v_lshl_add_u64 v[218:219], s[66:67], 0, v[128:129]
	s_add_i32 m0, s61, 0x2000
	s_nop 0
	global_load_lds_dwordx4 v[218:219], off
	v_lshl_add_u64 v[218:219], s[28:29], 0, v[134:135]
	s_mov_b32 m0, s23
	s_nop 0
	global_load_lds_dwordx4 v[218:219], off
	s_mov_b32 m0, s37
	s_nop 0
	global_load_lds_dwordx4 v[220:221], off
	s_waitcnt vmcnt(8)
	s_waitcnt lgkmcnt(0)
	s_barrier
; #define PG8_STAGE(bufoff, gbase, voff) do { _Pragma("unroll") for (int _i = 0; _i < 2; ++_i) \
;         __builtin_amdgcn_global_load_lds((const unsigned*)((const char*)(gbase) + (voff)[_i]), (LAS unsigned*)(lds + (bufoff) + ldsw + _i * 8192), 16, 0, 0); } while (0)
; #define PG8_LDA(dst, b, h) do { _Pragma("unroll") for (int m = 0; m < 4; ++m) _Pragma("unroll") for (int k = 0; k < 2; ++k) dst[m][k] = *(const LAS bf16x8*)(lds + PG8_SA(b, h) + aoff + m * 2048 + k * 1024); } while (0)
; #define PG8_LDB(dst, b, h) do { _Pragma("unroll") for (int n = 0; n < 2; ++n) _Pragma("unroll") for (int k = 0; k < 2; ++k) dst[n][k] = *(const LAS bf16x8*)(lds + PG8_SB(b, h) + boff + n * 2048 + k * 1024); } while (0)
; #define PG8_MMA(ai, bj, At, Bt) do { __builtin_amdgcn_s_setprio(1); _Pragma("unroll") for (int m = 0; m < 4; ++m) _Pragma("unroll") for (int n = 0; n < 2; ++n) _Pragma("unroll") for (int k = 0; k < 2; ++k) \
;         acc[ai][bj][m][n] = __builtin_amdgcn_mfma_f32_16x16x32_bf16(Bt[n][k], At[m][k], acc[ai][bj][m][n], 0, 0, 0); __builtin_amdgcn_s_setprio(0); } while (0)
; #define PG8_WAIT_V(n) asm volatile("s_waitcnt vmcnt(" #n ")" ::: "memory")
; #define PG8_WAIT_L(n) asm volatile("s_waitcnt lgkmcnt(" #n ")" ::: "memory")
; #define PG8_BAR __builtin_amdgcn_s_barrier()
; #define PG8_SCHED __builtin_amdgcn_sched_barrier(0)
; template <class Epi>
; DI void gemm_phase(int wv, LAS unsigned char* lds, const Gemm g, const StaticOrder& S, const Epi& E) {
;     ...
;             PG8_WAIT_V(8); PG8_WAIT_L(0); PG8_BAR; PG8_MMA(1, 0, At, B0); PG8_MMA(1, 1, At, B1); PG8_BAR; PG8_SCHED;
;             PG8_LDB(B0, 1, 0); PG8_LDB(B1, 1, 1); PG8_SCHED; PG8_LDA(At, 1, 0); PG8_STAGE(PG8_SA(0, 1), a2 + hA, voffA);
;             PG8_WAIT_V(8); PG8_WAIT_L(0); PG8_BAR; PG8_MMA(0, 0, At, B0); PG8_MMA(0, 1, At, B1); PG8_BAR; PG8_SCHED;
	s_setprio 1
	s_waitcnt lgkmcnt(0)
	v_mfma_f32_16x16x32_bf16 v[60:63], v[150:153], v[182:185], v[60:63]
	v_mfma_f32_16x16x32_bf16 v[52:55], v[158:161], v[182:185], v[52:55]
	v_mfma_f32_16x16x32_bf16 v[44:47], v[150:153], v[190:193], v[44:47]
	v_mfma_f32_16x16x32_bf16 v[36:39], v[158:161], v[190:193], v[36:39]
	v_mfma_f32_16x16x32_bf16 v[28:31], v[150:153], v[198:201], v[28:31]
	v_mfma_f32_16x16x32_bf16 v[20:23], v[158:161], v[198:201], v[20:23]
	v_mfma_f32_16x16x32_bf16 v[12:15], v[150:153], v[206:209], v[12:15]
	v_mfma_f32_16x16x32_bf16 v[4:7], v[158:161], v[206:209], v[4:7]
	v_mfma_f32_16x16x32_bf16 v[60:63], v[154:157], v[186:189], v[60:63]
	v_mfma_f32_16x16x32_bf16 v[52:55], v[162:165], v[186:189], v[52:55]
	v_mfma_f32_16x16x32_bf16 v[44:47], v[154:157], v[194:197], v[44:47]
	v_mfma_f32_16x16x32_bf16 v[36:39], v[162:165], v[194:197], v[36:39]
	v_mfma_f32_16x16x32_bf16 v[28:31], v[154:157], v[202:205], v[28:31]
	v_mfma_f32_16x16x32_bf16 v[20:23], v[162:165], v[202:205], v[20:23]
	v_mfma_f32_16x16x32_bf16 v[12:15], v[154:157], v[210:213], v[12:15]
	v_mfma_f32_16x16x32_bf16 v[4:7], v[162:165], v[210:213], v[4:7]
	s_setprio 0
	s_setprio 1
	v_mfma_f32_16x16x32_bf16 v[56:59], v[166:169], v[182:185], v[56:59]
	v_mfma_f32_16x16x32_bf16 v[48:51], v[174:177], v[182:185], v[48:51]
	v_mfma_f32_16x16x32_bf16 v[40:43], v[166:169], v[190:193], v[40:43]
	v_mfma_f32_16x16x32_bf16 v[32:35], v[174:177], v[190:193], v[32:35]
	v_mfma_f32_16x16x32_bf16 v[24:27], v[166:169], v[198:201], v[24:27]
	v_mfma_f32_16x16x32_bf16 v[16:19], v[174:177], v[198:201], v[16:19]
	v_mfma_f32_16x16x32_bf16 v[8:11], v[166:169], v[206:209], v[8:11]
	v_mfma_f32_16x16x32_bf16 v[0:3], v[174:177], v[206:209], v[0:3]
	v_mfma_f32_16x16x32_bf16 v[56:59], v[170:173], v[186:189], v[56:59]
	v_mfma_f32_16x16x32_bf16 v[48:51], v[178:181], v[186:189], v[48:51]
	v_mfma_f32_16x16x32_bf16 v[40:43], v[170:173], v[194:197], v[40:43]
	v_mfma_f32_16x16x32_bf16 v[32:35], v[178:181], v[194:197], v[32:35]
	v_mfma_f32_16x16x32_bf16 v[24:27], v[170:173], v[202:205], v[24:27]
	v_mfma_f32_16x16x32_bf16 v[16:19], v[178:181], v[202:205], v[16:19]
	v_mfma_f32_16x16x32_bf16 v[8:11], v[170:173], v[210:213], v[8:11]
	v_mfma_f32_16x16x32_bf16 v[0:3], v[178:181], v[210:213], v[0:3]
	s_setprio 0
	s_barrier
	s_add_i32 s61, 0, 0x18000
	s_add_i32 s66, 0, 0x1c000
	v_add_u32_e32 v162, s61, v146
	v_add_u32_e32 v178, s66, v146
	ds_read_b128 v[150:153], v162
	ds_read_b128 v[154:157], v162 offset:1024
	ds_read_b128 v[158:161], v162 offset:2048
	ds_read_b128 v[162:165], v162 offset:3072
	ds_read_b128 v[166:169], v178
	ds_read_b128 v[170:173], v178 offset:1024
	ds_read_b128 v[174:177], v178 offset:2048
	ds_read_b128 v[178:181], v178 offset:3072
	s_add_u32 s28, s28, 0x40000
	s_addc_u32 s29, s29, 0
	s_mov_b32 m0, s38
	v_lshl_add_u64 v[222:223], s[28:29], 0, v[134:135]
	ds_read_b128 v[182:185], v149 offset:32768
	ds_read_b128 v[186:189], v149 offset:33792
	ds_read_b128 v[190:193], v149 offset:34816
	ds_read_b128 v[194:197], v149 offset:35840
	ds_read_b128 v[198:201], v149 offset:36864
	ds_read_b128 v[202:205], v149 offset:37888
	ds_read_b128 v[206:209], v149 offset:38912
	ds_read_b128 v[210:213], v149 offset:39936
	global_load_lds_dwordx4 v[222:223], off
	v_lshl_add_u64 v[222:223], s[28:29], 0, v[130:131]
	s_mov_b32 m0, s39
	s_nop 0
	global_load_lds_dwordx4 v[222:223], off
	s_waitcnt vmcnt(8)
	s_waitcnt lgkmcnt(0)
	s_barrier
	s_setprio 1
	s_waitcnt lgkmcnt(0)
	v_mfma_f32_16x16x32_bf16 v[124:127], v[150:153], v[182:185], v[124:127]
	v_mfma_f32_16x16x32_bf16 v[116:119], v[158:161], v[182:185], v[116:119]
	v_mfma_f32_16x16x32_bf16 v[108:111], v[150:153], v[190:193], v[108:111]
	v_mfma_f32_16x16x32_bf16 v[100:103], v[158:161], v[190:193], v[100:103]
	v_mfma_f32_16x16x32_bf16 v[92:95], v[150:153], v[198:201], v[92:95]
	v_mfma_f32_16x16x32_bf16 v[84:87], v[158:161], v[198:201], v[84:87]
	v_mfma_f32_16x16x32_bf16 v[76:79], v[150:153], v[206:209], v[76:79]
	v_mfma_f32_16x16x32_bf16 v[68:71], v[158:161], v[206:209], v[68:71]
	v_mfma_f32_16x16x32_bf16 v[124:127], v[154:157], v[186:189], v[124:127]
	v_mfma_f32_16x16x32_bf16 v[116:119], v[162:165], v[186:189], v[116:119]
	v_mfma_f32_16x16x32_bf16 v[108:111], v[154:157], v[194:197], v[108:111]
	v_mfma_f32_16x16x32_bf16 v[100:103], v[162:165], v[194:197], v[100:103]
	v_mfma_f32_16x16x32_bf16 v[92:95], v[154:157], v[202:205], v[92:95]
	v_mfma_f32_16x16x32_bf16 v[84:87], v[162:165], v[202:205], v[84:87]
	v_mfma_f32_16x16x32_bf16 v[76:79], v[154:157], v[210:213], v[76:79]
	v_mfma_f32_16x16x32_bf16 v[68:71], v[162:165], v[210:213], v[68:71]
	s_setprio 0
	s_setprio 1
	v_mfma_f32_16x16x32_bf16 v[120:123], v[166:169], v[182:185], v[120:123]
	v_mfma_f32_16x16x32_bf16 v[112:115], v[174:177], v[182:185], v[112:115]
	v_mfma_f32_16x16x32_bf16 v[104:107], v[166:169], v[190:193], v[104:107]
	v_mfma_f32_16x16x32_bf16 v[96:99], v[174:177], v[190:193], v[96:99]
	v_mfma_f32_16x16x32_bf16 v[88:91], v[166:169], v[198:201], v[88:91]
	v_mfma_f32_16x16x32_bf16 v[80:83], v[174:177], v[198:201], v[80:83]
	v_mfma_f32_16x16x32_bf16 v[72:75], v[166:169], v[206:209], v[72:75]
	v_mfma_f32_16x16x32_bf16 v[64:67], v[174:177], v[206:209], v[64:67]
	v_mfma_f32_16x16x32_bf16 v[120:123], v[170:173], v[186:189], v[120:123]
	v_mfma_f32_16x16x32_bf16 v[112:115], v[178:181], v[186:189], v[112:115]
	v_mfma_f32_16x16x32_bf16 v[104:107], v[170:173], v[194:197], v[104:107]
	v_mfma_f32_16x16x32_bf16 v[96:99], v[178:181], v[194:197], v[96:99]
	v_mfma_f32_16x16x32_bf16 v[88:91], v[170:173], v[202:205], v[88:91]
	v_mfma_f32_16x16x32_bf16 v[80:83], v[178:181], v[202:205], v[80:83]
	v_mfma_f32_16x16x32_bf16 v[72:75], v[170:173], v[210:213], v[72:75]
	v_mfma_f32_16x16x32_bf16 v[64:67], v[178:181], v[210:213], v[64:67]
	s_setprio 0
	s_barrier
; #define PG8_STAGE(bufoff, gbase, voff) do { _Pragma("unroll") for (int _i = 0; _i < 2; ++_i) \
;         __builtin_amdgcn_global_load_lds((const unsigned*)((const char*)(gbase) + (voff)[_i]), (LAS unsigned*)(lds + (bufoff) + ldsw + _i * 8192), 16, 0, 0); } while (0)
; #define PG8_LDA(dst, b, h) do { _Pragma("unroll") for (int m = 0; m < 4; ++m) _Pragma("unroll") for (int k = 0; k < 2; ++k) dst[m][k] = *(const LAS bf16x8*)(lds + PG8_SA(b, h) + aoff + m * 2048 + k * 1024); } while (0)
; #define PG8_MMA(ai, bj, At, Bt) do { __builtin_amdgcn_s_setprio(1); _Pragma("unroll") for (int m = 0; m < 4; ++m) _Pragma("unroll") for (int n = 0; n < 2; ++n) _Pragma("unroll") for (int k = 0; k < 2; ++k) \
;         acc[ai][bj][m][n] = __builtin_amdgcn_mfma_f32_16x16x32_bf16(Bt[n][k], At[m][k], acc[ai][bj][m][n], 0, 0, 0); __builtin_amdgcn_s_setprio(0); } while (0)
; #define PG8_WAIT_V(n) asm volatile("s_waitcnt vmcnt(" #n ")" ::: "memory")
; #define PG8_WAIT_L(n) asm volatile("s_waitcnt lgkmcnt(" #n ")" ::: "memory")
; #define PG8_BAR __builtin_amdgcn_s_barrier()
; #define PG8_SCHED __builtin_amdgcn_sched_barrier(0)
; template <class Epi>
; DI void gemm_phase(int wv, LAS unsigned char* lds, const Gemm g, const StaticOrder& S, const Epi& E) {
;     ...
;             PG8_LDA(At, 1, 1); PG8_STAGE(PG8_SB(1, 0), b3, voffB); PG8_STAGE(PG8_SB(1, 1), b3 + hB, voffB); PG8_STAGE(PG8_SA(1, 0), a3, voffA);
;             PG8_WAIT_V(8); PG8_WAIT_L(0); PG8_BAR; PG8_MMA(1, 0, At, B0); PG8_MMA(1, 1, At, B1); PG8_BAR; PG8_SCHED;
;         }
;         if (wr == 0) PG8_BAR;
	s_add_i32 s28, s61, s34
	v_lshl_add_u64 v[214:215], v[214:215], 0, s[10:11]
	s_mov_b32 m0, s28
	ds_read_b128 v[182:185], v149 offset:49152
	ds_read_b128 v[186:189], v149 offset:50176
	ds_read_b128 v[190:193], v149 offset:51200
	ds_read_b128 v[194:197], v149 offset:52224
	ds_read_b128 v[198:201], v149 offset:53248
	ds_read_b128 v[202:205], v149 offset:54272
	ds_read_b128 v[206:209], v149 offset:55296
	ds_read_b128 v[210:213], v149 offset:56320
	global_load_lds_dwordx4 v[214:215], off
	s_add_i32 m0, s28, 0x2000
	s_add_u32 s26, s26, 0x40080
	v_lshl_add_u64 v[214:215], v[216:217], 0, s[10:11]
	s_addc_u32 s27, s27, 0
	s_add_i32 s28, s66, s34
	global_load_lds_dwordx4 v[214:215], off
	v_lshl_add_u64 v[214:215], s[26:27], 0, v[132:133]
	s_mov_b32 m0, s28
	s_nop 0
	global_load_lds_dwordx4 v[214:215], off
	v_lshl_add_u64 v[214:215], s[26:27], 0, v[128:129]
	s_add_i32 m0, s28, 0x2000
	s_nop 0
	global_load_lds_dwordx4 v[214:215], off
	v_lshl_add_u64 v[214:215], v[218:219], 0, s[10:11]
	s_mov_b32 m0, s43
	s_nop 0
	global_load_lds_dwordx4 v[214:215], off
	v_lshl_add_u64 v[214:215], v[220:221], 0, s[10:11]
	s_mov_b32 m0, s44
	s_nop 0
	global_load_lds_dwordx4 v[214:215], off
	s_waitcnt vmcnt(8)
	s_waitcnt lgkmcnt(0)
	s_barrier
	s_setprio 1
	s_waitcnt lgkmcnt(0)
	v_mfma_f32_16x16x32_bf16 v[60:63], v[150:153], v[182:185], v[60:63]
	v_mfma_f32_16x16x32_bf16 v[52:55], v[158:161], v[182:185], v[52:55]
	v_mfma_f32_16x16x32_bf16 v[44:47], v[150:153], v[190:193], v[44:47]
	v_mfma_f32_16x16x32_bf16 v[36:39], v[158:161], v[190:193], v[36:39]
	v_mfma_f32_16x16x32_bf16 v[28:31], v[150:153], v[198:201], v[28:31]
	v_mfma_f32_16x16x32_bf16 v[20:23], v[158:161], v[198:201], v[20:23]
	v_mfma_f32_16x16x32_bf16 v[12:15], v[150:153], v[206:209], v[12:15]
	v_mfma_f32_16x16x32_bf16 v[4:7], v[158:161], v[206:209], v[4:7]
	v_mfma_f32_16x16x32_bf16 v[60:63], v[154:157], v[186:189], v[60:63]
	v_mfma_f32_16x16x32_bf16 v[52:55], v[162:165], v[186:189], v[52:55]
	v_mfma_f32_16x16x32_bf16 v[44:47], v[154:157], v[194:197], v[44:47]
	v_mfma_f32_16x16x32_bf16 v[36:39], v[162:165], v[194:197], v[36:39]
	v_mfma_f32_16x16x32_bf16 v[28:31], v[154:157], v[202:205], v[28:31]
	v_mfma_f32_16x16x32_bf16 v[20:23], v[162:165], v[202:205], v[20:23]
	v_mfma_f32_16x16x32_bf16 v[12:15], v[154:157], v[210:213], v[12:15]
	v_mfma_f32_16x16x32_bf16 v[4:7], v[162:165], v[210:213], v[4:7]
	s_setprio 0
	s_setprio 1
	v_mfma_f32_16x16x32_bf16 v[56:59], v[166:169], v[182:185], v[56:59]
	v_mfma_f32_16x16x32_bf16 v[48:51], v[174:177], v[182:185], v[48:51]
	v_mfma_f32_16x16x32_bf16 v[40:43], v[166:169], v[190:193], v[40:43]
	v_mfma_f32_16x16x32_bf16 v[32:35], v[174:177], v[190:193], v[32:35]
	v_mfma_f32_16x16x32_bf16 v[24:27], v[166:169], v[198:201], v[24:27]
	v_mfma_f32_16x16x32_bf16 v[16:19], v[174:177], v[198:201], v[16:19]
	v_mfma_f32_16x16x32_bf16 v[8:11], v[166:169], v[206:209], v[8:11]
	v_mfma_f32_16x16x32_bf16 v[0:3], v[174:177], v[206:209], v[0:3]
	v_mfma_f32_16x16x32_bf16 v[56:59], v[170:173], v[186:189], v[56:59]
	v_mfma_f32_16x16x32_bf16 v[48:51], v[178:181], v[186:189], v[48:51]
	v_mfma_f32_16x16x32_bf16 v[40:43], v[170:173], v[194:197], v[40:43]
	v_mfma_f32_16x16x32_bf16 v[32:35], v[178:181], v[194:197], v[32:35]
	v_mfma_f32_16x16x32_bf16 v[24:27], v[170:173], v[202:205], v[24:27]
	v_mfma_f32_16x16x32_bf16 v[16:19], v[178:181], v[202:205], v[16:19]
	v_mfma_f32_16x16x32_bf16 v[8:11], v[170:173], v[210:213], v[8:11]
	v_mfma_f32_16x16x32_bf16 v[0:3], v[178:181], v[210:213], v[0:3]
	s_setprio 0
	s_add_i32 s60, s60, 2
	s_add_u32 s55, s55, 0x100
	s_addc_u32 s57, s57, 0
	s_add_u32 s24, s24, 0x100
	s_addc_u32 s25, s25, 0
	s_cmp_gt_u32 s60, 13
	s_barrier
	s_cbranch_scc0 .LBB0_2381
	s_and_b64 vcc, exec, s[12:13]
	s_cbranch_vccz .LBB0_2384
	s_barrier

; #define PG8_STAGE(bufoff, gbase, voff) do { _Pragma("unroll") for (int _i = 0; _i < 2; ++_i) \
;         __builtin_amdgcn_global_load_lds((const unsigned*)((const char*)(gbase) + (voff)[_i]), (LAS unsigned*)(lds + (bufoff) + ldsw + _i * 8192), 16, 0, 0); } while (0)
; #define PG8_LDA(dst, b, h) do { _Pragma("unroll") for (int m = 0; m < 4; ++m) _Pragma("unroll") for (int k = 0; k < 2; ++k) dst[m][k] = *(const LAS bf16x8*)(lds + PG8_SA(b, h) + aoff + m * 2048 + k * 1024); } while (0)
; #define PG8_LDB(dst, b, h) do { _Pragma("unroll") for (int n = 0; n < 2; ++n) _Pragma("unroll") for (int k = 0; k < 2; ++k) dst[n][k] = *(const LAS bf16x8*)(lds + PG8_SB(b, h) + boff + n * 2048 + k * 1024); } while (0)
; #define PG8_MMA(ai, bj, At, Bt) do { __builtin_amdgcn_s_setprio(1); _Pragma("unroll") for (int m = 0; m < 4; ++m) _Pragma("unroll") for (int n = 0; n < 2; ++n) _Pragma("unroll") for (int k = 0; k < 2; ++k) \
;         acc[ai][bj][m][n] = __builtin_amdgcn_mfma_f32_16x16x32_bf16(Bt[n][k], At[m][k], acc[ai][bj][m][n], 0, 0, 0); __builtin_amdgcn_s_setprio(0); } while (0)
; #define PG8_WAIT_V(n) asm volatile("s_waitcnt vmcnt(" #n ")" ::: "memory")
; #define PG8_WAIT_L(n) asm volatile("s_waitcnt lgkmcnt(" #n ")" ::: "memory")
; #define PG8_BAR __builtin_amdgcn_s_barrier()
; #define PG8_SCHED __builtin_amdgcn_sched_barrier(0)
; template <class Epi>
; DI void gemm_phase(int wv, LAS unsigned char* lds, const Gemm g, const StaticOrder& S, const Epi& E) {
;     ...
;         for (int t = 0; t < nt; t += 2) {
;             const bool last = (t == nt - 2);
;             const char* a1 = cA + (size_t)(t + 1) * kstep;
;             const char* a2 = last ? nA : cA + (size_t)(t + 2) * kstep; const char* b2 = last ? nB : cB + (size_t)(t + 2) * kstep;
;             const char* a3 = a2 + kstep; const char* b3 = b2 + kstep;
;             PG8_LDB(B0, 0, 0); PG8_LDB(B1, 0, 1); PG8_SCHED; PG8_LDA(At, 0, 0); PG8_STAGE(PG8_SA(1, 1), a1 + hA, voffA);
;             PG8_WAIT_V(8); PG8_WAIT_L(0); PG8_BAR; PG8_MMA(0, 0, At, B0); PG8_MMA(0, 1, At, B1); PG8_BAR; PG8_SCHED;
;             PG8_LDA(At, 0, 1); PG8_STAGE(PG8_SB(0, 0), b2, voffB); PG8_STAGE(PG8_SB(0, 1), b2 + hB, voffB); PG8_STAGE(PG8_SA(0, 0), a2, voffA);
;             PG8_WAIT_V(8); PG8_WAIT_L(0); PG8_BAR; PG8_MMA(1, 0, At, B0); PG8_MMA(1, 1, At, B1); PG8_BAR; PG8_SCHED;
.LBB0_2462:
	ds_read_b128 v[150:153], v147
	ds_read_b128 v[154:157], v147 offset:1024
	ds_read_b128 v[158:161], v147 offset:2048
	ds_read_b128 v[162:165], v147 offset:3072
	ds_read_b128 v[166:169], v148
	ds_read_b128 v[170:173], v148 offset:1024
	ds_read_b128 v[174:177], v148 offset:2048
	ds_read_b128 v[178:181], v148 offset:3072
	s_add_u32 s20, s18, 0x100
	s_addc_u32 s21, s19, 0
	s_cmp_eq_u32 s55, 40
	s_cselect_b32 s25, s5, s21
	s_cselect_b32 s24, s4, s20
	s_cselect_b32 s23, s17, s54
	s_cselect_b32 s22, s16, s51
	v_lshl_add_u64 v[214:215], s[18:19], 0, v[138:139]
	s_add_i32 m0, s34, 0xc000
	ds_read_b128 v[182:185], v149
	ds_read_b128 v[186:189], v149 offset:1024
	ds_read_b128 v[190:193], v149 offset:2048
	ds_read_b128 v[194:197], v149 offset:3072
	ds_read_b128 v[198:201], v149 offset:4096
	ds_read_b128 v[202:205], v149 offset:5120
	ds_read_b128 v[206:209], v149 offset:6144
	ds_read_b128 v[210:213], v149 offset:7168
	global_load_lds_dwordx4 v[214:215], off
	v_lshl_add_u64 v[214:215], s[18:19], 0, v[136:137]
	s_add_i32 m0, s34, 0xe000
	s_nop 0
	global_load_lds_dwordx4 v[214:215], off
	s_waitcnt vmcnt(8)
	s_waitcnt lgkmcnt(0)
	s_barrier
	s_setprio 1
	s_waitcnt lgkmcnt(0)
	v_mfma_f32_16x16x32_bf16 v[124:127], v[150:153], v[182:185], v[124:127]
	v_mfma_f32_16x16x32_bf16 v[120:123], v[158:161], v[182:185], v[120:123]
	v_mfma_f32_16x16x32_bf16 v[116:119], v[150:153], v[190:193], v[116:119]
	v_mfma_f32_16x16x32_bf16 v[112:115], v[158:161], v[190:193], v[112:115]
	v_mfma_f32_16x16x32_bf16 v[100:103], v[150:153], v[198:201], v[100:103]
	v_mfma_f32_16x16x32_bf16 v[96:99], v[158:161], v[198:201], v[96:99]
	v_mfma_f32_16x16x32_bf16 v[84:87], v[150:153], v[206:209], v[84:87]
	v_mfma_f32_16x16x32_bf16 v[80:83], v[158:161], v[206:209], v[80:83]
	v_mfma_f32_16x16x32_bf16 v[124:127], v[154:157], v[186:189], v[124:127]
	v_mfma_f32_16x16x32_bf16 v[120:123], v[162:165], v[186:189], v[120:123]
	v_mfma_f32_16x16x32_bf16 v[116:119], v[154:157], v[194:197], v[116:119]
	v_mfma_f32_16x16x32_bf16 v[112:115], v[162:165], v[194:197], v[112:115]
	v_mfma_f32_16x16x32_bf16 v[100:103], v[154:157], v[202:205], v[100:103]
	v_mfma_f32_16x16x32_bf16 v[96:99], v[162:165], v[202:205], v[96:99]
	v_mfma_f32_16x16x32_bf16 v[84:87], v[154:157], v[210:213], v[84:87]
	v_mfma_f32_16x16x32_bf16 v[80:83], v[162:165], v[210:213], v[80:83]
	s_setprio 0
	s_setprio 1
	v_mfma_f32_16x16x32_bf16 v[108:111], v[166:169], v[182:185], v[108:111]
	v_mfma_f32_16x16x32_bf16 v[104:107], v[174:177], v[182:185], v[104:107]
	v_mfma_f32_16x16x32_bf16 v[92:95], v[166:169], v[190:193], v[92:95]
	v_mfma_f32_16x16x32_bf16 v[88:91], v[174:177], v[190:193], v[88:91]
	v_mfma_f32_16x16x32_bf16 v[76:79], v[166:169], v[198:201], v[76:79]
	v_mfma_f32_16x16x32_bf16 v[72:75], v[174:177], v[198:201], v[72:75]
	v_mfma_f32_16x16x32_bf16 v[68:71], v[166:169], v[206:209], v[68:71]
	v_mfma_f32_16x16x32_bf16 v[64:67], v[174:177], v[206:209], v[64:67]
	v_mfma_f32_16x16x32_bf16 v[108:111], v[170:173], v[186:189], v[108:111]
	v_mfma_f32_16x16x32_bf16 v[104:107], v[178:181], v[186:189], v[104:107]
	v_mfma_f32_16x16x32_bf16 v[92:95], v[170:173], v[194:197], v[92:95]
	v_mfma_f32_16x16x32_bf16 v[88:91], v[178:181], v[194:197], v[88:91]
	v_mfma_f32_16x16x32_bf16 v[76:79], v[170:173], v[202:205], v[76:79]
	v_mfma_f32_16x16x32_bf16 v[72:75], v[178:181], v[202:205], v[72:75]
	v_mfma_f32_16x16x32_bf16 v[68:71], v[170:173], v[210:213], v[68:71]
	v_mfma_f32_16x16x32_bf16 v[64:67], v[178:181], v[210:213], v[64:67]
	s_setprio 0
	s_barrier
	s_add_i32 s18, s43, s31
	v_lshl_add_u64 v[214:215], s[22:23], 0, v[130:131]
	s_mov_b32 m0, s18
	ds_read_b128 v[182:185], v149 offset:16384
	ds_read_b128 v[186:189], v149 offset:17408
	ds_read_b128 v[190:193], v149 offset:18432
	ds_read_b128 v[194:197], v149 offset:19456
	ds_read_b128 v[198:201], v149 offset:20480
	ds_read_b128 v[202:205], v149 offset:21504
	ds_read_b128 v[206:209], v149 offset:22528
	ds_read_b128 v[210:213], v149 offset:23552
	global_load_lds_dwordx4 v[214:215], off
	s_add_i32 m0, s18, 0x2000
	s_add_u32 s18, s22, 0xb0000
	v_lshl_add_u64 v[216:217], s[22:23], 0, v[134:135]
	s_addc_u32 s19, s23, 0
	s_add_i32 s57, s44, s31
	global_load_lds_dwordx4 v[216:217], off
	v_lshl_add_u64 v[218:219], s[18:19], 0, v[130:131]
	s_mov_b32 m0, s57
	v_lshl_add_u64 v[220:221], s[24:25], 0, v[132:133]
	global_load_lds_dwordx4 v[218:219], off
	v_lshl_add_u64 v[218:219], s[18:19], 0, v[134:135]
	s_add_i32 m0, s57, 0x2000
	s_nop 0
	global_load_lds_dwordx4 v[218:219], off
	v_lshl_add_u64 v[218:219], s[24:25], 0, v[128:129]
	s_mov_b32 m0, s34
	s_nop 0
	global_load_lds_dwordx4 v[218:219], off
	s_mov_b32 m0, s35
	s_nop 0
	global_load_lds_dwordx4 v[220:221], off
	s_waitcnt vmcnt(8)
	s_waitcnt lgkmcnt(0)
	s_barrier
; #define PG8_STAGE(bufoff, gbase, voff) do { _Pragma("unroll") for (int _i = 0; _i < 2; ++_i) \
;         __builtin_amdgcn_global_load_lds((const unsigned*)((const char*)(gbase) + (voff)[_i]), (LAS unsigned*)(lds + (bufoff) + ldsw + _i * 8192), 16, 0, 0); } while (0)
; #define PG8_LDA(dst, b, h) do { _Pragma("unroll") for (int m = 0; m < 4; ++m) _Pragma("unroll") for (int k = 0; k < 2; ++k) dst[m][k] = *(const LAS bf16x8*)(lds + PG8_SA(b, h) + aoff + m * 2048 + k * 1024); } while (0)
; #define PG8_LDB(dst, b, h) do { _Pragma("unroll") for (int n = 0; n < 2; ++n) _Pragma("unroll") for (int k = 0; k < 2; ++k) dst[n][k] = *(const LAS bf16x8*)(lds + PG8_SB(b, h) + boff + n * 2048 + k * 1024); } while (0)
; #define PG8_MMA(ai, bj, At, Bt) do { __builtin_amdgcn_s_setprio(1); _Pragma("unroll") for (int m = 0; m < 4; ++m) _Pragma("unroll") for (int n = 0; n < 2; ++n) _Pragma("unroll") for (int k = 0; k < 2; ++k) \
;         acc[ai][bj][m][n] = __builtin_amdgcn_mfma_f32_16x16x32_bf16(Bt[n][k], At[m][k], acc[ai][bj][m][n], 0, 0, 0); __builtin_amdgcn_s_setprio(0); } while (0)
; #define PG8_WAIT_V(n) asm volatile("s_waitcnt vmcnt(" #n ")" ::: "memory")
; #define PG8_WAIT_L(n) asm volatile("s_waitcnt lgkmcnt(" #n ")" ::: "memory")
; #define PG8_BAR __builtin_amdgcn_s_barrier()
; #define PG8_SCHED __builtin_amdgcn_sched_barrier(0)
; template <class Epi>
; DI void gemm_phase(int wv, LAS unsigned char* lds, const Gemm g, const StaticOrder& S, const Epi& E) {
;     ...
;             PG8_WAIT_V(8); PG8_WAIT_L(0); PG8_BAR; PG8_MMA(1, 0, At, B0); PG8_MMA(1, 1, At, B1); PG8_BAR; PG8_SCHED;
;             PG8_LDB(B0, 1, 0); PG8_LDB(B1, 1, 1); PG8_SCHED; PG8_LDA(At, 1, 0); PG8_STAGE(PG8_SA(0, 1), a2 + hA, voffA);
;             PG8_WAIT_V(8); PG8_WAIT_L(0); PG8_BAR; PG8_MMA(0, 0, At, B0); PG8_MMA(0, 1, At, B1); PG8_BAR; PG8_SCHED;
	s_setprio 1
	s_waitcnt lgkmcnt(0)
	v_mfma_f32_16x16x32_bf16 v[60:63], v[150:153], v[182:185], v[60:63]
	v_mfma_f32_16x16x32_bf16 v[56:59], v[158:161], v[182:185], v[56:59]
	v_mfma_f32_16x16x32_bf16 v[52:55], v[150:153], v[190:193], v[52:55]
	v_mfma_f32_16x16x32_bf16 v[48:51], v[158:161], v[190:193], v[48:51]
	v_mfma_f32_16x16x32_bf16 v[36:39], v[150:153], v[198:201], v[36:39]
	v_mfma_f32_16x16x32_bf16 v[32:35], v[158:161], v[198:201], v[32:35]
	v_mfma_f32_16x16x32_bf16 v[20:23], v[150:153], v[206:209], v[20:23]
	v_mfma_f32_16x16x32_bf16 v[16:19], v[158:161], v[206:209], v[16:19]
	v_mfma_f32_16x16x32_bf16 v[60:63], v[154:157], v[186:189], v[60:63]
	v_mfma_f32_16x16x32_bf16 v[56:59], v[162:165], v[186:189], v[56:59]
	v_mfma_f32_16x16x32_bf16 v[52:55], v[154:157], v[194:197], v[52:55]
	v_mfma_f32_16x16x32_bf16 v[48:51], v[162:165], v[194:197], v[48:51]
	v_mfma_f32_16x16x32_bf16 v[36:39], v[154:157], v[202:205], v[36:39]
	v_mfma_f32_16x16x32_bf16 v[32:35], v[162:165], v[202:205], v[32:35]
	v_mfma_f32_16x16x32_bf16 v[20:23], v[154:157], v[210:213], v[20:23]
	v_mfma_f32_16x16x32_bf16 v[16:19], v[162:165], v[210:213], v[16:19]
	s_setprio 0
	s_setprio 1
	v_mfma_f32_16x16x32_bf16 v[44:47], v[166:169], v[182:185], v[44:47]
	v_mfma_f32_16x16x32_bf16 v[40:43], v[174:177], v[182:185], v[40:43]
	v_mfma_f32_16x16x32_bf16 v[28:31], v[166:169], v[190:193], v[28:31]
	v_mfma_f32_16x16x32_bf16 v[24:27], v[174:177], v[190:193], v[24:27]
	v_mfma_f32_16x16x32_bf16 v[12:15], v[166:169], v[198:201], v[12:15]
	v_mfma_f32_16x16x32_bf16 v[8:11], v[174:177], v[198:201], v[8:11]
	v_mfma_f32_16x16x32_bf16 v[4:7], v[166:169], v[206:209], v[4:7]
	v_mfma_f32_16x16x32_bf16 v[0:3], v[174:177], v[206:209], v[0:3]
	v_mfma_f32_16x16x32_bf16 v[44:47], v[170:173], v[186:189], v[44:47]
	v_mfma_f32_16x16x32_bf16 v[40:43], v[178:181], v[186:189], v[40:43]
	v_mfma_f32_16x16x32_bf16 v[28:31], v[170:173], v[194:197], v[28:31]
	v_mfma_f32_16x16x32_bf16 v[24:27], v[178:181], v[194:197], v[24:27]
	v_mfma_f32_16x16x32_bf16 v[12:15], v[170:173], v[202:205], v[12:15]
	v_mfma_f32_16x16x32_bf16 v[8:11], v[178:181], v[202:205], v[8:11]
	v_mfma_f32_16x16x32_bf16 v[4:7], v[170:173], v[210:213], v[4:7]
	v_mfma_f32_16x16x32_bf16 v[0:3], v[178:181], v[210:213], v[0:3]
	s_setprio 0
	s_barrier
	s_add_i32 s57, 0, 0x18000
	s_add_i32 s60, 0, 0x1c000
	v_add_u32_e32 v162, s57, v146
	v_add_u32_e32 v178, s60, v146
	ds_read_b128 v[150:153], v162
	ds_read_b128 v[154:157], v162 offset:1024
	ds_read_b128 v[158:161], v162 offset:2048
	ds_read_b128 v[162:165], v162 offset:3072
	ds_read_b128 v[166:169], v178
	ds_read_b128 v[170:173], v178 offset:1024
	ds_read_b128 v[174:177], v178 offset:2048
	ds_read_b128 v[178:181], v178 offset:3072
	s_add_u32 s18, s24, 0xb0000
	s_addc_u32 s19, s25, 0
	s_mov_b32 m0, s36
	v_lshl_add_u64 v[222:223], s[18:19], 0, v[128:129]
	ds_read_b128 v[182:185], v149 offset:32768
	ds_read_b128 v[186:189], v149 offset:33792
	ds_read_b128 v[190:193], v149 offset:34816
	ds_read_b128 v[194:197], v149 offset:35840
	ds_read_b128 v[198:201], v149 offset:36864
	ds_read_b128 v[202:205], v149 offset:37888
	ds_read_b128 v[206:209], v149 offset:38912
	ds_read_b128 v[210:213], v149 offset:39936
	global_load_lds_dwordx4 v[222:223], off
	v_lshl_add_u64 v[222:223], s[18:19], 0, v[132:133]
	s_mov_b32 m0, s37
	s_nop 0
	global_load_lds_dwordx4 v[222:223], off
	s_waitcnt vmcnt(8)
	s_waitcnt lgkmcnt(0)
	s_barrier
	s_setprio 1
	s_waitcnt lgkmcnt(0)
	v_mfma_f32_16x16x32_bf16 v[124:127], v[150:153], v[182:185], v[124:127]
	v_mfma_f32_16x16x32_bf16 v[120:123], v[158:161], v[182:185], v[120:123]
	v_mfma_f32_16x16x32_bf16 v[116:119], v[150:153], v[190:193], v[116:119]
	v_mfma_f32_16x16x32_bf16 v[112:115], v[158:161], v[190:193], v[112:115]
	v_mfma_f32_16x16x32_bf16 v[100:103], v[150:153], v[198:201], v[100:103]
	v_mfma_f32_16x16x32_bf16 v[96:99], v[158:161], v[198:201], v[96:99]
	v_mfma_f32_16x16x32_bf16 v[84:87], v[150:153], v[206:209], v[84:87]
	v_mfma_f32_16x16x32_bf16 v[80:83], v[158:161], v[206:209], v[80:83]
	v_mfma_f32_16x16x32_bf16 v[124:127], v[154:157], v[186:189], v[124:127]
	v_mfma_f32_16x16x32_bf16 v[120:123], v[162:165], v[186:189], v[120:123]
	v_mfma_f32_16x16x32_bf16 v[116:119], v[154:157], v[194:197], v[116:119]
	v_mfma_f32_16x16x32_bf16 v[112:115], v[162:165], v[194:197], v[112:115]
	v_mfma_f32_16x16x32_bf16 v[100:103], v[154:157], v[202:205], v[100:103]
	v_mfma_f32_16x16x32_bf16 v[96:99], v[162:165], v[202:205], v[96:99]
	v_mfma_f32_16x16x32_bf16 v[84:87], v[154:157], v[210:213], v[84:87]
	v_mfma_f32_16x16x32_bf16 v[80:83], v[162:165], v[210:213], v[80:83]
	s_setprio 0
	s_setprio 1
	v_mfma_f32_16x16x32_bf16 v[108:111], v[166:169], v[182:185], v[108:111]
	v_mfma_f32_16x16x32_bf16 v[104:107], v[174:177], v[182:185], v[104:107]
	v_mfma_f32_16x16x32_bf16 v[92:95], v[166:169], v[190:193], v[92:95]
	v_mfma_f32_16x16x32_bf16 v[88:91], v[174:177], v[190:193], v[88:91]
	v_mfma_f32_16x16x32_bf16 v[76:79], v[166:169], v[198:201], v[76:79]
	v_mfma_f32_16x16x32_bf16 v[72:75], v[174:177], v[198:201], v[72:75]
	v_mfma_f32_16x16x32_bf16 v[68:71], v[166:169], v[206:209], v[68:71]
	v_mfma_f32_16x16x32_bf16 v[64:67], v[174:177], v[206:209], v[64:67]
	v_mfma_f32_16x16x32_bf16 v[108:111], v[170:173], v[186:189], v[108:111]
	v_mfma_f32_16x16x32_bf16 v[104:107], v[178:181], v[186:189], v[104:107]
	v_mfma_f32_16x16x32_bf16 v[92:95], v[170:173], v[194:197], v[92:95]
	v_mfma_f32_16x16x32_bf16 v[88:91], v[178:181], v[194:197], v[88:91]
	v_mfma_f32_16x16x32_bf16 v[76:79], v[170:173], v[202:205], v[76:79]
	v_mfma_f32_16x16x32_bf16 v[72:75], v[178:181], v[202:205], v[72:75]
	v_mfma_f32_16x16x32_bf16 v[68:71], v[170:173], v[210:213], v[68:71]
	v_mfma_f32_16x16x32_bf16 v[64:67], v[178:181], v[210:213], v[64:67]
	s_setprio 0
	s_barrier
; #define PG8_STAGE(bufoff, gbase, voff) do { _Pragma("unroll") for (int _i = 0; _i < 2; ++_i) \
;         __builtin_amdgcn_global_load_lds((const unsigned*)((const char*)(gbase) + (voff)[_i]), (LAS unsigned*)(lds + (bufoff) + ldsw + _i * 8192), 16, 0, 0); } while (0)
; #define PG8_LDA(dst, b, h) do { _Pragma("unroll") for (int m = 0; m < 4; ++m) _Pragma("unroll") for (int k = 0; k < 2; ++k) dst[m][k] = *(const LAS bf16x8*)(lds + PG8_SA(b, h) + aoff + m * 2048 + k * 1024); } while (0)
; #define PG8_MMA(ai, bj, At, Bt) do { __builtin_amdgcn_s_setprio(1); _Pragma("unroll") for (int m = 0; m < 4; ++m) _Pragma("unroll") for (int n = 0; n < 2; ++n) _Pragma("unroll") for (int k = 0; k < 2; ++k) \
;         acc[ai][bj][m][n] = __builtin_amdgcn_mfma_f32_16x16x32_bf16(Bt[n][k], At[m][k], acc[ai][bj][m][n], 0, 0, 0); __builtin_amdgcn_s_setprio(0); } while (0)
; #define PG8_WAIT_V(n) asm volatile("s_waitcnt vmcnt(" #n ")" ::: "memory")
; #define PG8_WAIT_L(n) asm volatile("s_waitcnt lgkmcnt(" #n ")" ::: "memory")
; #define PG8_BAR __builtin_amdgcn_s_barrier()
; #define PG8_SCHED __builtin_amdgcn_sched_barrier(0)
; template <class Epi>
; DI void gemm_phase(int wv, LAS unsigned char* lds, const Gemm g, const StaticOrder& S, const Epi& E) {
;     ...
;             PG8_LDA(At, 1, 1); PG8_STAGE(PG8_SB(1, 0), b3, voffB); PG8_STAGE(PG8_SB(1, 1), b3 + hB, voffB); PG8_STAGE(PG8_SA(1, 0), a3, voffA);
;             PG8_WAIT_V(8); PG8_WAIT_L(0); PG8_BAR; PG8_MMA(1, 0, At, B0); PG8_MMA(1, 1, At, B1); PG8_BAR; PG8_SCHED;
;         }
;         if (wr == 0) PG8_BAR;
	s_add_i32 s18, s57, s31
	v_lshl_add_u64 v[214:215], v[214:215], 0, s[10:11]
	s_mov_b32 m0, s18
	ds_read_b128 v[182:185], v149 offset:49152
	ds_read_b128 v[186:189], v149 offset:50176
	ds_read_b128 v[190:193], v149 offset:51200
	ds_read_b128 v[194:197], v149 offset:52224
	ds_read_b128 v[198:201], v149 offset:53248
	ds_read_b128 v[202:205], v149 offset:54272
	ds_read_b128 v[206:209], v149 offset:55296
	ds_read_b128 v[210:213], v149 offset:56320
	global_load_lds_dwordx4 v[214:215], off
	s_add_i32 m0, s18, 0x2000
	s_add_u32 s18, s22, 0xb0080
	v_lshl_add_u64 v[214:215], v[216:217], 0, s[10:11]
	s_addc_u32 s19, s23, 0
	s_add_i32 s22, s60, s31
	global_load_lds_dwordx4 v[214:215], off
	v_lshl_add_u64 v[214:215], s[18:19], 0, v[130:131]
	s_mov_b32 m0, s22
	s_nop 0
	global_load_lds_dwordx4 v[214:215], off
	v_lshl_add_u64 v[214:215], s[18:19], 0, v[134:135]
	s_add_i32 m0, s22, 0x2000
	s_nop 0
	global_load_lds_dwordx4 v[214:215], off
	v_lshl_add_u64 v[214:215], v[218:219], 0, s[10:11]
	s_mov_b32 m0, s41
	s_nop 0
	global_load_lds_dwordx4 v[214:215], off
	v_lshl_add_u64 v[214:215], v[220:221], 0, s[10:11]
	s_mov_b32 m0, s42
	s_nop 0
	global_load_lds_dwordx4 v[214:215], off
	s_waitcnt vmcnt(8)
	s_waitcnt lgkmcnt(0)
	s_barrier
	s_setprio 1
	s_waitcnt lgkmcnt(0)
	v_mfma_f32_16x16x32_bf16 v[60:63], v[150:153], v[182:185], v[60:63]
	v_mfma_f32_16x16x32_bf16 v[56:59], v[158:161], v[182:185], v[56:59]
	v_mfma_f32_16x16x32_bf16 v[52:55], v[150:153], v[190:193], v[52:55]
	v_mfma_f32_16x16x32_bf16 v[48:51], v[158:161], v[190:193], v[48:51]
	v_mfma_f32_16x16x32_bf16 v[36:39], v[150:153], v[198:201], v[36:39]
	v_mfma_f32_16x16x32_bf16 v[32:35], v[158:161], v[198:201], v[32:35]
	v_mfma_f32_16x16x32_bf16 v[20:23], v[150:153], v[206:209], v[20:23]
	v_mfma_f32_16x16x32_bf16 v[16:19], v[158:161], v[206:209], v[16:19]
	v_mfma_f32_16x16x32_bf16 v[60:63], v[154:157], v[186:189], v[60:63]
	v_mfma_f32_16x16x32_bf16 v[56:59], v[162:165], v[186:189], v[56:59]
	v_mfma_f32_16x16x32_bf16 v[52:55], v[154:157], v[194:197], v[52:55]
	v_mfma_f32_16x16x32_bf16 v[48:51], v[162:165], v[194:197], v[48:51]
	v_mfma_f32_16x16x32_bf16 v[36:39], v[154:157], v[202:205], v[36:39]
	v_mfma_f32_16x16x32_bf16 v[32:35], v[162:165], v[202:205], v[32:35]
	v_mfma_f32_16x16x32_bf16 v[20:23], v[154:157], v[210:213], v[20:23]
	v_mfma_f32_16x16x32_bf16 v[16:19], v[162:165], v[210:213], v[16:19]
	s_setprio 0
	s_setprio 1
	v_mfma_f32_16x16x32_bf16 v[44:47], v[166:169], v[182:185], v[44:47]
	v_mfma_f32_16x16x32_bf16 v[40:43], v[174:177], v[182:185], v[40:43]
	v_mfma_f32_16x16x32_bf16 v[28:31], v[166:169], v[190:193], v[28:31]
	v_mfma_f32_16x16x32_bf16 v[24:27], v[174:177], v[190:193], v[24:27]
	v_mfma_f32_16x16x32_bf16 v[12:15], v[166:169], v[198:201], v[12:15]
	v_mfma_f32_16x16x32_bf16 v[8:11], v[174:177], v[198:201], v[8:11]
	v_mfma_f32_16x16x32_bf16 v[4:7], v[166:169], v[206:209], v[4:7]
	v_mfma_f32_16x16x32_bf16 v[0:3], v[174:177], v[206:209], v[0:3]
	v_mfma_f32_16x16x32_bf16 v[44:47], v[170:173], v[186:189], v[44:47]
	v_mfma_f32_16x16x32_bf16 v[40:43], v[178:181], v[186:189], v[40:43]
	v_mfma_f32_16x16x32_bf16 v[28:31], v[170:173], v[194:197], v[28:31]
	v_mfma_f32_16x16x32_bf16 v[24:27], v[178:181], v[194:197], v[24:27]
	v_mfma_f32_16x16x32_bf16 v[12:15], v[170:173], v[202:205], v[12:15]
	v_mfma_f32_16x16x32_bf16 v[8:11], v[178:181], v[202:205], v[8:11]
	v_mfma_f32_16x16x32_bf16 v[4:7], v[170:173], v[210:213], v[4:7]
	v_mfma_f32_16x16x32_bf16 v[0:3], v[178:181], v[210:213], v[0:3]
	s_setprio 0
	s_add_i32 s55, s55, 2
	s_add_u32 s51, s51, 0x100
	s_addc_u32 s54, s54, 0
	s_cmp_gt_u32 s55, 41
	s_mov_b64 s[18:19], s[20:21]
	s_barrier
	s_cbranch_scc0 .LBB0_2462
	s_and_b64 vcc, exec, s[12:13]
	s_cbranch_vccz .LBB0_2465
	s_barrier

; #define PG8_STAGE(bufoff, gbase, voff) do { _Pragma("unroll") for (int _i = 0; _i < 2; ++_i) \
;         __builtin_amdgcn_global_load_lds((const unsigned*)((const char*)(gbase) + (voff)[_i]), (LAS unsigned*)(lds + (bufoff) + ldsw + _i * 8192), 16, 0, 0); } while (0)
; #define PG8_LDA(dst, b, h) do { _Pragma("unroll") for (int m = 0; m < 4; ++m) _Pragma("unroll") for (int k = 0; k < 2; ++k) dst[m][k] = *(const LAS bf16x8*)(lds + PG8_SA(b, h) + aoff + m * 2048 + k * 1024); } while (0)
; #define PG8_LDB(dst, b, h) do { _Pragma("unroll") for (int n = 0; n < 2; ++n) _Pragma("unroll") for (int k = 0; k < 2; ++k) dst[n][k] = *(const LAS bf16x8*)(lds + PG8_SB(b, h) + boff + n * 2048 + k * 1024); } while (0)
; #define PG8_MMA(ai, bj, At, Bt) do { __builtin_amdgcn_s_setprio(1); _Pragma("unroll") for (int m = 0; m < 4; ++m) _Pragma("unroll") for (int n = 0; n < 2; ++n) _Pragma("unroll") for (int k = 0; k < 2; ++k) \
;         acc[ai][bj][m][n] = __builtin_amdgcn_mfma_f32_16x16x32_bf16(Bt[n][k], At[m][k], acc[ai][bj][m][n], 0, 0, 0); __builtin_amdgcn_s_setprio(0); } while (0)
; #define PG8_WAIT_V(n) asm volatile("s_waitcnt vmcnt(" #n ")" ::: "memory")
; #define PG8_WAIT_L(n) asm volatile("s_waitcnt lgkmcnt(" #n ")" ::: "memory")
; #define PG8_BAR __builtin_amdgcn_s_barrier()
; #define PG8_SCHED __builtin_amdgcn_sched_barrier(0)
; template <class Epi>
; DI void gemm_phase(int wv, LAS unsigned char* lds, const Gemm g, const StaticOrder& S, const Epi& E) {
;     ...
;         for (int t = 0; t < nt; t += 2) {
;             const bool last = (t == nt - 2);
;             const char* a1 = cA + (size_t)(t + 1) * kstep;
;             const char* a2 = last ? nA : cA + (size_t)(t + 2) * kstep; const char* b2 = last ? nB : cB + (size_t)(t + 2) * kstep;
;             const char* a3 = a2 + kstep; const char* b3 = b2 + kstep;
;             PG8_LDB(B0, 0, 0); PG8_LDB(B1, 0, 1); PG8_SCHED; PG8_LDA(At, 0, 0); PG8_STAGE(PG8_SA(1, 1), a1 + hA, voffA);
;             PG8_WAIT_V(8); PG8_WAIT_L(0); PG8_BAR; PG8_MMA(0, 0, At, B0); PG8_MMA(0, 1, At, B1); PG8_BAR; PG8_SCHED;
;             PG8_LDA(At, 0, 1); PG8_STAGE(PG8_SB(0, 0), b2, voffB); PG8_STAGE(PG8_SB(0, 1), b2 + hB, voffB); PG8_STAGE(PG8_SA(0, 0), a2, voffA);
;             PG8_WAIT_V(8); PG8_WAIT_L(0); PG8_BAR; PG8_MMA(1, 0, At, B0); PG8_MMA(1, 1, At, B1); PG8_BAR; PG8_SCHED;
.LBB0_2871:
	ds_read_b128 v[128:131], v161
	ds_read_b128 v[132:135], v161 offset:1024
	ds_read_b128 v[152:155], v161 offset:2048
	ds_read_b128 v[164:167], v161 offset:3072
	ds_read_b128 v[168:171], v162
	ds_read_b128 v[172:175], v162 offset:1024
	ds_read_b128 v[176:179], v162 offset:2048
	ds_read_b128 v[180:183], v162 offset:3072
	s_add_u32 s6, s4, 0xfffc0080
	s_addc_u32 s7, s5, -1
	s_cmp_eq_u32 s70, 28
	s_cselect_b32 s35, s27, s7
	s_cselect_b32 s34, s36, s6
	s_cselect_b32 s7, s25, s69
	s_cselect_b32 s6, s37, s68
	v_lshl_add_u64 v[156:157], s[4:5], 0, v[146:147]
	s_add_i32 m0, s19, 0xc000
	ds_read_b128 v[184:187], v163
	ds_read_b128 v[188:191], v163 offset:1024
	ds_read_b128 v[192:195], v163 offset:2048
	ds_read_b128 v[196:199], v163 offset:3072
	ds_read_b128 v[200:203], v163 offset:4096
	ds_read_b128 v[204:207], v163 offset:5120
	ds_read_b128 v[208:211], v163 offset:6144
	ds_read_b128 v[212:215], v163 offset:7168
	global_load_lds_dwordx4 v[156:157], off
	v_lshl_add_u64 v[156:157], s[4:5], 0, v[144:145]
	s_add_i32 m0, s19, 0xe000
	s_nop 0
	global_load_lds_dwordx4 v[156:157], off
	s_waitcnt vmcnt(8)
	s_waitcnt lgkmcnt(0)
	s_barrier
	s_setprio 1
	s_waitcnt lgkmcnt(0)
	v_mfma_f32_16x16x32_bf16 v[124:127], v[128:131], v[184:187], v[124:127]
	v_mfma_f32_16x16x32_bf16 v[120:123], v[152:155], v[184:187], v[120:123]
	v_mfma_f32_16x16x32_bf16 v[116:119], v[128:131], v[192:195], v[116:119]
	v_mfma_f32_16x16x32_bf16 v[112:115], v[152:155], v[192:195], v[112:115]
	v_mfma_f32_16x16x32_bf16 v[100:103], v[128:131], v[200:203], v[100:103]
	v_mfma_f32_16x16x32_bf16 v[96:99], v[152:155], v[200:203], v[96:99]
	v_mfma_f32_16x16x32_bf16 v[84:87], v[128:131], v[208:211], v[84:87]
	v_mfma_f32_16x16x32_bf16 v[80:83], v[152:155], v[208:211], v[80:83]
	v_mfma_f32_16x16x32_bf16 v[124:127], v[132:135], v[188:191], v[124:127]
	v_mfma_f32_16x16x32_bf16 v[120:123], v[164:167], v[188:191], v[120:123]
	v_mfma_f32_16x16x32_bf16 v[116:119], v[132:135], v[196:199], v[116:119]
	v_mfma_f32_16x16x32_bf16 v[112:115], v[164:167], v[196:199], v[112:115]
	v_mfma_f32_16x16x32_bf16 v[100:103], v[132:135], v[204:207], v[100:103]
	v_mfma_f32_16x16x32_bf16 v[96:99], v[164:167], v[204:207], v[96:99]
	v_mfma_f32_16x16x32_bf16 v[84:87], v[132:135], v[212:215], v[84:87]
	v_mfma_f32_16x16x32_bf16 v[80:83], v[164:167], v[212:215], v[80:83]
	s_setprio 0
	s_setprio 1
	v_mfma_f32_16x16x32_bf16 v[108:111], v[168:171], v[184:187], v[108:111]
	v_mfma_f32_16x16x32_bf16 v[104:107], v[176:179], v[184:187], v[104:107]
	v_mfma_f32_16x16x32_bf16 v[92:95], v[168:171], v[192:195], v[92:95]
	v_mfma_f32_16x16x32_bf16 v[88:91], v[176:179], v[192:195], v[88:91]
	v_mfma_f32_16x16x32_bf16 v[76:79], v[168:171], v[200:203], v[76:79]
	v_mfma_f32_16x16x32_bf16 v[72:75], v[176:179], v[200:203], v[72:75]
	v_mfma_f32_16x16x32_bf16 v[68:71], v[168:171], v[208:211], v[68:71]
	v_mfma_f32_16x16x32_bf16 v[64:67], v[176:179], v[208:211], v[64:67]
	v_mfma_f32_16x16x32_bf16 v[108:111], v[172:175], v[188:191], v[108:111]
	v_mfma_f32_16x16x32_bf16 v[104:107], v[180:183], v[188:191], v[104:107]
	v_mfma_f32_16x16x32_bf16 v[92:95], v[172:175], v[196:199], v[92:95]
	v_mfma_f32_16x16x32_bf16 v[88:91], v[180:183], v[196:199], v[88:91]
	v_mfma_f32_16x16x32_bf16 v[76:79], v[172:175], v[204:207], v[76:79]
	v_mfma_f32_16x16x32_bf16 v[72:75], v[180:183], v[204:207], v[72:75]
	v_mfma_f32_16x16x32_bf16 v[68:71], v[172:175], v[212:215], v[68:71]
	v_mfma_f32_16x16x32_bf16 v[64:67], v[180:183], v[212:215], v[64:67]
	s_setprio 0
	s_barrier
	s_add_i32 s71, s59, s42
	v_lshl_add_u64 v[156:157], s[6:7], 0, v[138:139]
	s_mov_b32 m0, s71
	ds_read_b128 v[184:187], v163 offset:16384
	ds_read_b128 v[188:191], v163 offset:17408
	ds_read_b128 v[192:195], v163 offset:18432
	ds_read_b128 v[196:199], v163 offset:19456
	ds_read_b128 v[200:203], v163 offset:20480
	ds_read_b128 v[204:207], v163 offset:21504
	ds_read_b128 v[208:211], v163 offset:22528
	ds_read_b128 v[212:215], v163 offset:23552
	global_load_lds_dwordx4 v[156:157], off
	s_add_i32 m0, s71, 0x2000
	s_add_u32 s72, s6, 0x80000
	v_lshl_add_u64 v[216:217], s[6:7], 0, v[142:143]
	s_addc_u32 s73, s7, 0
	s_add_i32 s71, s60, s42
	global_load_lds_dwordx4 v[216:217], off
	v_lshl_add_u64 v[218:219], s[72:73], 0, v[138:139]
	s_mov_b32 m0, s71
	v_lshl_add_u64 v[220:221], s[34:35], 0, v[140:141]
	global_load_lds_dwordx4 v[218:219], off
	v_lshl_add_u64 v[218:219], s[72:73], 0, v[142:143]
	s_add_i32 m0, s71, 0x2000
	s_nop 0
	global_load_lds_dwordx4 v[218:219], off
	v_lshl_add_u64 v[218:219], s[34:35], 0, v[136:137]
	s_mov_b32 m0, s19
	s_nop 0
	global_load_lds_dwordx4 v[218:219], off
	s_mov_b32 m0, s21
	s_nop 0
	global_load_lds_dwordx4 v[220:221], off
	s_waitcnt vmcnt(8)
	s_waitcnt lgkmcnt(0)
	s_barrier
; #define PG8_STAGE(bufoff, gbase, voff) do { _Pragma("unroll") for (int _i = 0; _i < 2; ++_i) \
;         __builtin_amdgcn_global_load_lds((const unsigned*)((const char*)(gbase) + (voff)[_i]), (LAS unsigned*)(lds + (bufoff) + ldsw + _i * 8192), 16, 0, 0); } while (0)
; #define PG8_LDA(dst, b, h) do { _Pragma("unroll") for (int m = 0; m < 4; ++m) _Pragma("unroll") for (int k = 0; k < 2; ++k) dst[m][k] = *(const LAS bf16x8*)(lds + PG8_SA(b, h) + aoff + m * 2048 + k * 1024); } while (0)
; #define PG8_LDB(dst, b, h) do { _Pragma("unroll") for (int n = 0; n < 2; ++n) _Pragma("unroll") for (int k = 0; k < 2; ++k) dst[n][k] = *(const LAS bf16x8*)(lds + PG8_SB(b, h) + boff + n * 2048 + k * 1024); } while (0)
; #define PG8_MMA(ai, bj, At, Bt) do { __builtin_amdgcn_s_setprio(1); _Pragma("unroll") for (int m = 0; m < 4; ++m) _Pragma("unroll") for (int n = 0; n < 2; ++n) _Pragma("unroll") for (int k = 0; k < 2; ++k) \
;         acc[ai][bj][m][n] = __builtin_amdgcn_mfma_f32_16x16x32_bf16(Bt[n][k], At[m][k], acc[ai][bj][m][n], 0, 0, 0); __builtin_amdgcn_s_setprio(0); } while (0)
; #define PG8_WAIT_V(n) asm volatile("s_waitcnt vmcnt(" #n ")" ::: "memory")
; #define PG8_WAIT_L(n) asm volatile("s_waitcnt lgkmcnt(" #n ")" ::: "memory")
; #define PG8_BAR __builtin_amdgcn_s_barrier()
; #define PG8_SCHED __builtin_amdgcn_sched_barrier(0)
; template <class Epi>
; DI void gemm_phase(int wv, LAS unsigned char* lds, const Gemm g, const StaticOrder& S, const Epi& E) {
;     ...
;             PG8_WAIT_V(8); PG8_WAIT_L(0); PG8_BAR; PG8_MMA(1, 0, At, B0); PG8_MMA(1, 1, At, B1); PG8_BAR; PG8_SCHED;
;             PG8_LDB(B0, 1, 0); PG8_LDB(B1, 1, 1); PG8_SCHED; PG8_LDA(At, 1, 0); PG8_STAGE(PG8_SA(0, 1), a2 + hA, voffA);
;             PG8_WAIT_V(8); PG8_WAIT_L(0); PG8_BAR; PG8_MMA(0, 0, At, B0); PG8_MMA(0, 1, At, B1); PG8_BAR; PG8_SCHED;
	s_setprio 1
	s_waitcnt lgkmcnt(0)
	v_mfma_f32_16x16x32_bf16 v[60:63], v[128:131], v[184:187], v[60:63]
	v_mfma_f32_16x16x32_bf16 v[56:59], v[152:155], v[184:187], v[56:59]
	v_mfma_f32_16x16x32_bf16 v[52:55], v[128:131], v[192:195], v[52:55]
	v_mfma_f32_16x16x32_bf16 v[48:51], v[152:155], v[192:195], v[48:51]
	v_mfma_f32_16x16x32_bf16 v[36:39], v[128:131], v[200:203], v[36:39]
	v_mfma_f32_16x16x32_bf16 v[32:35], v[152:155], v[200:203], v[32:35]
	v_mfma_f32_16x16x32_bf16 v[20:23], v[128:131], v[208:211], v[20:23]
	v_mfma_f32_16x16x32_bf16 v[16:19], v[152:155], v[208:211], v[16:19]
	v_mfma_f32_16x16x32_bf16 v[60:63], v[132:135], v[188:191], v[60:63]
	v_mfma_f32_16x16x32_bf16 v[56:59], v[164:167], v[188:191], v[56:59]
	v_mfma_f32_16x16x32_bf16 v[52:55], v[132:135], v[196:199], v[52:55]
	v_mfma_f32_16x16x32_bf16 v[48:51], v[164:167], v[196:199], v[48:51]
	v_mfma_f32_16x16x32_bf16 v[36:39], v[132:135], v[204:207], v[36:39]
	v_mfma_f32_16x16x32_bf16 v[32:35], v[164:167], v[204:207], v[32:35]
	v_mfma_f32_16x16x32_bf16 v[20:23], v[132:135], v[212:215], v[20:23]
	v_mfma_f32_16x16x32_bf16 v[16:19], v[164:167], v[212:215], v[16:19]
	s_setprio 0
	s_setprio 1
	v_mfma_f32_16x16x32_bf16 v[44:47], v[168:171], v[184:187], v[44:47]
	v_mfma_f32_16x16x32_bf16 v[40:43], v[176:179], v[184:187], v[40:43]
	v_mfma_f32_16x16x32_bf16 v[28:31], v[168:171], v[192:195], v[28:31]
	v_mfma_f32_16x16x32_bf16 v[24:27], v[176:179], v[192:195], v[24:27]
	v_mfma_f32_16x16x32_bf16 v[12:15], v[168:171], v[200:203], v[12:15]
	v_mfma_f32_16x16x32_bf16 v[8:11], v[176:179], v[200:203], v[8:11]
	v_mfma_f32_16x16x32_bf16 v[4:7], v[168:171], v[208:211], v[4:7]
	v_mfma_f32_16x16x32_bf16 v[0:3], v[176:179], v[208:211], v[0:3]
	v_mfma_f32_16x16x32_bf16 v[44:47], v[172:175], v[188:191], v[44:47]
	v_mfma_f32_16x16x32_bf16 v[40:43], v[180:183], v[188:191], v[40:43]
	v_mfma_f32_16x16x32_bf16 v[28:31], v[172:175], v[196:199], v[28:31]
	v_mfma_f32_16x16x32_bf16 v[24:27], v[180:183], v[196:199], v[24:27]
	v_mfma_f32_16x16x32_bf16 v[12:15], v[172:175], v[204:207], v[12:15]
	v_mfma_f32_16x16x32_bf16 v[8:11], v[180:183], v[204:207], v[8:11]
	v_mfma_f32_16x16x32_bf16 v[4:7], v[172:175], v[212:215], v[4:7]
	v_mfma_f32_16x16x32_bf16 v[0:3], v[180:183], v[212:215], v[0:3]
	s_setprio 0
	s_barrier
	s_add_i32 s71, 0, 0x18000
	s_add_i32 s72, 0, 0x1c000
	v_add_u32_e32 v164, s71, v160
	v_add_u32_e32 v180, s72, v160
	ds_read_b128 v[128:131], v164
	ds_read_b128 v[132:135], v164 offset:1024
	ds_read_b128 v[152:155], v164 offset:2048
	ds_read_b128 v[164:167], v164 offset:3072
	ds_read_b128 v[168:171], v180
	ds_read_b128 v[172:175], v180 offset:1024
	ds_read_b128 v[176:179], v180 offset:2048
	ds_read_b128 v[180:183], v180 offset:3072
	s_add_u32 s34, s34, 0x40000
	s_addc_u32 s35, s35, 0
	s_mov_b32 m0, s43
	v_lshl_add_u64 v[222:223], s[34:35], 0, v[136:137]
	ds_read_b128 v[184:187], v163 offset:32768
	ds_read_b128 v[188:191], v163 offset:33792
	ds_read_b128 v[192:195], v163 offset:34816
	ds_read_b128 v[196:199], v163 offset:35840
	ds_read_b128 v[200:203], v163 offset:36864
	ds_read_b128 v[204:207], v163 offset:37888
	ds_read_b128 v[208:211], v163 offset:38912
	ds_read_b128 v[212:215], v163 offset:39936
	global_load_lds_dwordx4 v[222:223], off
	v_lshl_add_u64 v[222:223], s[34:35], 0, v[140:141]
	s_mov_b32 m0, s44
	s_nop 0
	global_load_lds_dwordx4 v[222:223], off
	s_waitcnt vmcnt(8)
	s_waitcnt lgkmcnt(0)
	s_barrier
	s_setprio 1
	s_waitcnt lgkmcnt(0)
	v_mfma_f32_16x16x32_bf16 v[124:127], v[128:131], v[184:187], v[124:127]
	v_mfma_f32_16x16x32_bf16 v[120:123], v[152:155], v[184:187], v[120:123]
	v_mfma_f32_16x16x32_bf16 v[116:119], v[128:131], v[192:195], v[116:119]
	v_mfma_f32_16x16x32_bf16 v[112:115], v[152:155], v[192:195], v[112:115]
	v_mfma_f32_16x16x32_bf16 v[100:103], v[128:131], v[200:203], v[100:103]
	v_mfma_f32_16x16x32_bf16 v[96:99], v[152:155], v[200:203], v[96:99]
	v_mfma_f32_16x16x32_bf16 v[84:87], v[128:131], v[208:211], v[84:87]
	v_mfma_f32_16x16x32_bf16 v[80:83], v[152:155], v[208:211], v[80:83]
	v_mfma_f32_16x16x32_bf16 v[124:127], v[132:135], v[188:191], v[124:127]
	v_mfma_f32_16x16x32_bf16 v[120:123], v[164:167], v[188:191], v[120:123]
	v_mfma_f32_16x16x32_bf16 v[116:119], v[132:135], v[196:199], v[116:119]
	v_mfma_f32_16x16x32_bf16 v[112:115], v[164:167], v[196:199], v[112:115]
	v_mfma_f32_16x16x32_bf16 v[100:103], v[132:135], v[204:207], v[100:103]
	v_mfma_f32_16x16x32_bf16 v[96:99], v[164:167], v[204:207], v[96:99]
	v_mfma_f32_16x16x32_bf16 v[84:87], v[132:135], v[212:215], v[84:87]
	v_mfma_f32_16x16x32_bf16 v[80:83], v[164:167], v[212:215], v[80:83]
	s_setprio 0
	s_setprio 1
	v_mfma_f32_16x16x32_bf16 v[108:111], v[168:171], v[184:187], v[108:111]
	v_mfma_f32_16x16x32_bf16 v[104:107], v[176:179], v[184:187], v[104:107]
	v_mfma_f32_16x16x32_bf16 v[92:95], v[168:171], v[192:195], v[92:95]
	v_mfma_f32_16x16x32_bf16 v[88:91], v[176:179], v[192:195], v[88:91]
	v_mfma_f32_16x16x32_bf16 v[76:79], v[168:171], v[200:203], v[76:79]
	v_mfma_f32_16x16x32_bf16 v[72:75], v[176:179], v[200:203], v[72:75]
	v_mfma_f32_16x16x32_bf16 v[68:71], v[168:171], v[208:211], v[68:71]
	v_mfma_f32_16x16x32_bf16 v[64:67], v[176:179], v[208:211], v[64:67]
	v_mfma_f32_16x16x32_bf16 v[108:111], v[172:175], v[188:191], v[108:111]
	v_mfma_f32_16x16x32_bf16 v[104:107], v[180:183], v[188:191], v[104:107]
	v_mfma_f32_16x16x32_bf16 v[92:95], v[172:175], v[196:199], v[92:95]
	v_mfma_f32_16x16x32_bf16 v[88:91], v[180:183], v[196:199], v[88:91]
	v_mfma_f32_16x16x32_bf16 v[76:79], v[172:175], v[204:207], v[76:79]
	v_mfma_f32_16x16x32_bf16 v[72:75], v[180:183], v[204:207], v[72:75]
	v_mfma_f32_16x16x32_bf16 v[68:71], v[172:175], v[212:215], v[68:71]
	v_mfma_f32_16x16x32_bf16 v[64:67], v[180:183], v[212:215], v[64:67]
	s_setprio 0
	s_barrier
; #define PG8_STAGE(bufoff, gbase, voff) do { _Pragma("unroll") for (int _i = 0; _i < 2; ++_i) \
;         __builtin_amdgcn_global_load_lds((const unsigned*)((const char*)(gbase) + (voff)[_i]), (LAS unsigned*)(lds + (bufoff) + ldsw + _i * 8192), 16, 0, 0); } while (0)
; #define PG8_LDA(dst, b, h) do { _Pragma("unroll") for (int m = 0; m < 4; ++m) _Pragma("unroll") for (int k = 0; k < 2; ++k) dst[m][k] = *(const LAS bf16x8*)(lds + PG8_SA(b, h) + aoff + m * 2048 + k * 1024); } while (0)
; #define PG8_MMA(ai, bj, At, Bt) do { __builtin_amdgcn_s_setprio(1); _Pragma("unroll") for (int m = 0; m < 4; ++m) _Pragma("unroll") for (int n = 0; n < 2; ++n) _Pragma("unroll") for (int k = 0; k < 2; ++k) \
;         acc[ai][bj][m][n] = __builtin_amdgcn_mfma_f32_16x16x32_bf16(Bt[n][k], At[m][k], acc[ai][bj][m][n], 0, 0, 0); __builtin_amdgcn_s_setprio(0); } while (0)
; #define PG8_WAIT_V(n) asm volatile("s_waitcnt vmcnt(" #n ")" ::: "memory")
; #define PG8_WAIT_L(n) asm volatile("s_waitcnt lgkmcnt(" #n ")" ::: "memory")
; #define PG8_BAR __builtin_amdgcn_s_barrier()
; #define PG8_SCHED __builtin_amdgcn_sched_barrier(0)
; template <class Epi>
; DI void gemm_phase(int wv, LAS unsigned char* lds, const Gemm g, const StaticOrder& S, const Epi& E) {
;     ...
;             PG8_LDA(At, 1, 1); PG8_STAGE(PG8_SB(1, 0), b3, voffB); PG8_STAGE(PG8_SB(1, 1), b3 + hB, voffB); PG8_STAGE(PG8_SA(1, 0), a3, voffA);
;             PG8_WAIT_V(8); PG8_WAIT_L(0); PG8_BAR; PG8_MMA(1, 0, At, B0); PG8_MMA(1, 1, At, B1); PG8_BAR; PG8_SCHED;
;         }
;         if (wr == 0) PG8_BAR;
	s_add_i32 s34, s71, s42
	v_lshl_add_u64 v[156:157], v[156:157], 0, s[14:15]
	s_mov_b32 m0, s34
	ds_read_b128 v[184:187], v163 offset:49152
	ds_read_b128 v[188:191], v163 offset:50176
	ds_read_b128 v[192:195], v163 offset:51200
	ds_read_b128 v[196:199], v163 offset:52224
	ds_read_b128 v[200:203], v163 offset:53248
	ds_read_b128 v[204:207], v163 offset:54272
	ds_read_b128 v[208:211], v163 offset:55296
	ds_read_b128 v[212:215], v163 offset:56320
	global_load_lds_dwordx4 v[156:157], off
	s_add_i32 m0, s34, 0x2000
	s_add_u32 s6, s6, 0x80080
	v_lshl_add_u64 v[156:157], v[216:217], 0, s[14:15]
	s_addc_u32 s7, s7, 0
	s_add_i32 s34, s72, s42
	global_load_lds_dwordx4 v[156:157], off
	v_lshl_add_u64 v[156:157], s[6:7], 0, v[138:139]
	s_mov_b32 m0, s34
	s_nop 0
	global_load_lds_dwordx4 v[156:157], off
	v_lshl_add_u64 v[156:157], s[6:7], 0, v[142:143]
	s_add_i32 m0, s34, 0x2000
	s_nop 0
	global_load_lds_dwordx4 v[156:157], off
	v_lshl_add_u64 v[156:157], v[218:219], 0, s[14:15]
	s_mov_b32 m0, s50
	s_nop 0
	global_load_lds_dwordx4 v[156:157], off
	v_lshl_add_u64 v[156:157], v[220:221], 0, s[14:15]
	s_mov_b32 m0, s51
	s_nop 0
	global_load_lds_dwordx4 v[156:157], off
	s_waitcnt vmcnt(8)
	s_waitcnt lgkmcnt(0)
	s_barrier
	s_setprio 1
	s_waitcnt lgkmcnt(0)
	v_mfma_f32_16x16x32_bf16 v[60:63], v[128:131], v[184:187], v[60:63]
	v_mfma_f32_16x16x32_bf16 v[56:59], v[152:155], v[184:187], v[56:59]
	v_mfma_f32_16x16x32_bf16 v[52:55], v[128:131], v[192:195], v[52:55]
	v_mfma_f32_16x16x32_bf16 v[48:51], v[152:155], v[192:195], v[48:51]
	v_mfma_f32_16x16x32_bf16 v[36:39], v[128:131], v[200:203], v[36:39]
	v_mfma_f32_16x16x32_bf16 v[32:35], v[152:155], v[200:203], v[32:35]
	v_mfma_f32_16x16x32_bf16 v[20:23], v[128:131], v[208:211], v[20:23]
	v_mfma_f32_16x16x32_bf16 v[16:19], v[152:155], v[208:211], v[16:19]
	v_mfma_f32_16x16x32_bf16 v[60:63], v[132:135], v[188:191], v[60:63]
	v_mfma_f32_16x16x32_bf16 v[56:59], v[164:167], v[188:191], v[56:59]
	v_mfma_f32_16x16x32_bf16 v[52:55], v[132:135], v[196:199], v[52:55]
	v_mfma_f32_16x16x32_bf16 v[48:51], v[164:167], v[196:199], v[48:51]
	v_mfma_f32_16x16x32_bf16 v[36:39], v[132:135], v[204:207], v[36:39]
	v_mfma_f32_16x16x32_bf16 v[32:35], v[164:167], v[204:207], v[32:35]
	v_mfma_f32_16x16x32_bf16 v[20:23], v[132:135], v[212:215], v[20:23]
	v_mfma_f32_16x16x32_bf16 v[16:19], v[164:167], v[212:215], v[16:19]
	s_setprio 0
	s_setprio 1
	v_mfma_f32_16x16x32_bf16 v[44:47], v[168:171], v[184:187], v[44:47]
	v_mfma_f32_16x16x32_bf16 v[40:43], v[176:179], v[184:187], v[40:43]
	v_mfma_f32_16x16x32_bf16 v[28:31], v[168:171], v[192:195], v[28:31]
	v_mfma_f32_16x16x32_bf16 v[24:27], v[176:179], v[192:195], v[24:27]
	v_mfma_f32_16x16x32_bf16 v[12:15], v[168:171], v[200:203], v[12:15]
	v_mfma_f32_16x16x32_bf16 v[8:11], v[176:179], v[200:203], v[8:11]
	v_mfma_f32_16x16x32_bf16 v[4:7], v[168:171], v[208:211], v[4:7]
	v_mfma_f32_16x16x32_bf16 v[0:3], v[176:179], v[208:211], v[0:3]
	v_mfma_f32_16x16x32_bf16 v[44:47], v[172:175], v[188:191], v[44:47]
	v_mfma_f32_16x16x32_bf16 v[40:43], v[180:183], v[188:191], v[40:43]
	v_mfma_f32_16x16x32_bf16 v[28:31], v[172:175], v[196:199], v[28:31]
	v_mfma_f32_16x16x32_bf16 v[24:27], v[180:183], v[196:199], v[24:27]
	v_mfma_f32_16x16x32_bf16 v[12:15], v[172:175], v[204:207], v[12:15]
	v_mfma_f32_16x16x32_bf16 v[8:11], v[180:183], v[204:207], v[8:11]
	v_mfma_f32_16x16x32_bf16 v[4:7], v[172:175], v[212:215], v[4:7]
	v_mfma_f32_16x16x32_bf16 v[0:3], v[180:183], v[212:215], v[0:3]
	s_setprio 0
	s_add_i32 s70, s70, 2
	s_add_u32 s68, s68, 0x100
	s_addc_u32 s69, s69, 0
	s_add_u32 s4, s4, 0x100
	s_addc_u32 s5, s5, 0
	s_cmp_gt_u32 s70, 29
	s_barrier
	s_cbranch_scc0 .LBB0_2871
	s_and_b64 vcc, exec, s[16:17]
	s_cbranch_vccz .LBB0_2874
	s_barrier

; #define PG8_STAGE(bufoff, gbase, voff) do { _Pragma("unroll") for (int _i = 0; _i < 2; ++_i) \
;         __builtin_amdgcn_global_load_lds((const unsigned*)((const char*)(gbase) + (voff)[_i]), (LAS unsigned*)(lds + (bufoff) + ldsw + _i * 8192), 16, 0, 0); } while (0)
; #define PG8_LDA(dst, b, h) do { _Pragma("unroll") for (int m = 0; m < 4; ++m) _Pragma("unroll") for (int k = 0; k < 2; ++k) dst[m][k] = *(const LAS bf16x8*)(lds + PG8_SA(b, h) + aoff + m * 2048 + k * 1024); } while (0)
; #define PG8_LDB(dst, b, h) do { _Pragma("unroll") for (int n = 0; n < 2; ++n) _Pragma("unroll") for (int k = 0; k < 2; ++k) dst[n][k] = *(const LAS bf16x8*)(lds + PG8_SB(b, h) + boff + n * 2048 + k * 1024); } while (0)
; #define PG8_MMA(ai, bj, At, Bt) do { __builtin_amdgcn_s_setprio(1); _Pragma("unroll") for (int m = 0; m < 4; ++m) _Pragma("unroll") for (int n = 0; n < 2; ++n) _Pragma("unroll") for (int k = 0; k < 2; ++k) \
;         acc[ai][bj][m][n] = __builtin_amdgcn_mfma_f32_16x16x32_bf16(Bt[n][k], At[m][k], acc[ai][bj][m][n], 0, 0, 0); __builtin_amdgcn_s_setprio(0); } while (0)
; #define PG8_WAIT_V(n) asm volatile("s_waitcnt vmcnt(" #n ")" ::: "memory")
; #define PG8_WAIT_L(n) asm volatile("s_waitcnt lgkmcnt(" #n ")" ::: "memory")
; #define PG8_BAR __builtin_amdgcn_s_barrier()
; #define PG8_SCHED __builtin_amdgcn_sched_barrier(0)
; template <class Epi>
; DI void gemm_phase(int wv, LAS unsigned char* lds, const Gemm g, const StaticOrder& S, const Epi& E) {
;     ...
;         for (int t = 0; t < nt; t += 2) {
;             const bool last = (t == nt - 2);
;             const char* a1 = cA + (size_t)(t + 1) * kstep;
;             const char* a2 = last ? nA : cA + (size_t)(t + 2) * kstep; const char* b2 = last ? nB : cB + (size_t)(t + 2) * kstep;
;             const char* a3 = a2 + kstep; const char* b3 = b2 + kstep;
;             PG8_LDB(B0, 0, 0); PG8_LDB(B1, 0, 1); PG8_SCHED; PG8_LDA(At, 0, 0); PG8_STAGE(PG8_SA(1, 1), a1 + hA, voffA);
;             PG8_WAIT_V(8); PG8_WAIT_L(0); PG8_BAR; PG8_MMA(0, 0, At, B0); PG8_MMA(0, 1, At, B1); PG8_BAR; PG8_SCHED;
;             PG8_LDA(At, 0, 1); PG8_STAGE(PG8_SB(0, 0), b2, voffB); PG8_STAGE(PG8_SB(0, 1), b2 + hB, voffB); PG8_STAGE(PG8_SA(0, 0), a2, voffA);
;             PG8_WAIT_V(8); PG8_WAIT_L(0); PG8_BAR; PG8_MMA(1, 0, At, B0); PG8_MMA(1, 1, At, B1); PG8_BAR; PG8_SCHED;
.LBB0_3413:
	ds_read_b128 v[150:153], v147
	ds_read_b128 v[154:157], v147 offset:1024
	ds_read_b128 v[158:161], v147 offset:2048
	ds_read_b128 v[162:165], v147 offset:3072
	ds_read_b128 v[166:169], v148
	ds_read_b128 v[170:173], v148 offset:1024
	ds_read_b128 v[174:177], v148 offset:2048
	ds_read_b128 v[178:181], v148 offset:3072
	s_add_u32 s24, s22, 0xfffc0080
	s_addc_u32 s25, s23, -1
	s_cmp_eq_u32 s54, 12
	s_cselect_b32 s27, s17, s25
	s_cselect_b32 s26, s46, s24
	s_cselect_b32 s25, s15, s51
	s_cselect_b32 s24, s47, s50
	v_lshl_add_u64 v[214:215], s[22:23], 0, v[138:139]
	s_add_i32 m0, s13, 0xc000
	ds_read_b128 v[182:185], v149
	ds_read_b128 v[186:189], v149 offset:1024
	ds_read_b128 v[190:193], v149 offset:2048
	ds_read_b128 v[194:197], v149 offset:3072
	ds_read_b128 v[198:201], v149 offset:4096
	ds_read_b128 v[202:205], v149 offset:5120
	ds_read_b128 v[206:209], v149 offset:6144
	ds_read_b128 v[210:213], v149 offset:7168
	global_load_lds_dwordx4 v[214:215], off
	v_lshl_add_u64 v[214:215], s[22:23], 0, v[136:137]
	s_add_i32 m0, s13, 0xe000
	s_nop 0
	global_load_lds_dwordx4 v[214:215], off
	s_waitcnt vmcnt(8)
	s_waitcnt lgkmcnt(0)
	s_barrier
	s_setprio 1
	s_waitcnt lgkmcnt(0)
	v_mfma_f32_16x16x32_bf16 v[124:127], v[150:153], v[182:185], v[124:127]
	v_mfma_f32_16x16x32_bf16 v[120:123], v[158:161], v[182:185], v[120:123]
	v_mfma_f32_16x16x32_bf16 v[116:119], v[150:153], v[190:193], v[116:119]
	v_mfma_f32_16x16x32_bf16 v[112:115], v[158:161], v[190:193], v[112:115]
	v_mfma_f32_16x16x32_bf16 v[100:103], v[150:153], v[198:201], v[100:103]
	v_mfma_f32_16x16x32_bf16 v[96:99], v[158:161], v[198:201], v[96:99]
	v_mfma_f32_16x16x32_bf16 v[84:87], v[150:153], v[206:209], v[84:87]
	v_mfma_f32_16x16x32_bf16 v[80:83], v[158:161], v[206:209], v[80:83]
	v_mfma_f32_16x16x32_bf16 v[124:127], v[154:157], v[186:189], v[124:127]
	v_mfma_f32_16x16x32_bf16 v[120:123], v[162:165], v[186:189], v[120:123]
	v_mfma_f32_16x16x32_bf16 v[116:119], v[154:157], v[194:197], v[116:119]
	v_mfma_f32_16x16x32_bf16 v[112:115], v[162:165], v[194:197], v[112:115]
	v_mfma_f32_16x16x32_bf16 v[100:103], v[154:157], v[202:205], v[100:103]
	v_mfma_f32_16x16x32_bf16 v[96:99], v[162:165], v[202:205], v[96:99]
	v_mfma_f32_16x16x32_bf16 v[84:87], v[154:157], v[210:213], v[84:87]
	v_mfma_f32_16x16x32_bf16 v[80:83], v[162:165], v[210:213], v[80:83]
	s_setprio 0
	s_setprio 1
	v_mfma_f32_16x16x32_bf16 v[108:111], v[166:169], v[182:185], v[108:111]
	v_mfma_f32_16x16x32_bf16 v[104:107], v[174:177], v[182:185], v[104:107]
	v_mfma_f32_16x16x32_bf16 v[92:95], v[166:169], v[190:193], v[92:95]
	v_mfma_f32_16x16x32_bf16 v[88:91], v[174:177], v[190:193], v[88:91]
	v_mfma_f32_16x16x32_bf16 v[76:79], v[166:169], v[198:201], v[76:79]
	v_mfma_f32_16x16x32_bf16 v[72:75], v[174:177], v[198:201], v[72:75]
	v_mfma_f32_16x16x32_bf16 v[68:71], v[166:169], v[206:209], v[68:71]
	v_mfma_f32_16x16x32_bf16 v[64:67], v[174:177], v[206:209], v[64:67]
	v_mfma_f32_16x16x32_bf16 v[108:111], v[170:173], v[186:189], v[108:111]
	v_mfma_f32_16x16x32_bf16 v[104:107], v[178:181], v[186:189], v[104:107]
	v_mfma_f32_16x16x32_bf16 v[92:95], v[170:173], v[194:197], v[92:95]
	v_mfma_f32_16x16x32_bf16 v[88:91], v[178:181], v[194:197], v[88:91]
	v_mfma_f32_16x16x32_bf16 v[76:79], v[170:173], v[202:205], v[76:79]
	v_mfma_f32_16x16x32_bf16 v[72:75], v[178:181], v[202:205], v[72:75]
	v_mfma_f32_16x16x32_bf16 v[68:71], v[170:173], v[210:213], v[68:71]
	v_mfma_f32_16x16x32_bf16 v[64:67], v[178:181], v[210:213], v[64:67]
	s_setprio 0
	s_barrier
	s_add_i32 s55, s43, s34
	v_lshl_add_u64 v[214:215], s[24:25], 0, v[130:131]
	s_mov_b32 m0, s55
	ds_read_b128 v[182:185], v149 offset:16384
	ds_read_b128 v[186:189], v149 offset:17408
	ds_read_b128 v[190:193], v149 offset:18432
	ds_read_b128 v[194:197], v149 offset:19456
	ds_read_b128 v[198:201], v149 offset:20480
	ds_read_b128 v[202:205], v149 offset:21504
	ds_read_b128 v[206:209], v149 offset:22528
	ds_read_b128 v[210:213], v149 offset:23552
	global_load_lds_dwordx4 v[214:215], off
	s_add_i32 m0, s55, 0x2000
	s_add_u32 s60, s24, 0x40000
	v_lshl_add_u64 v[216:217], s[24:25], 0, v[134:135]
	s_addc_u32 s61, s25, 0
	s_add_i32 s55, s44, s34
	global_load_lds_dwordx4 v[216:217], off
	v_lshl_add_u64 v[218:219], s[60:61], 0, v[130:131]
	s_mov_b32 m0, s55
	v_lshl_add_u64 v[220:221], s[26:27], 0, v[132:133]
	global_load_lds_dwordx4 v[218:219], off
	v_lshl_add_u64 v[218:219], s[60:61], 0, v[134:135]
	s_add_i32 m0, s55, 0x2000
	s_nop 0
	global_load_lds_dwordx4 v[218:219], off
	v_lshl_add_u64 v[218:219], s[26:27], 0, v[128:129]
	s_mov_b32 m0, s13
	s_nop 0
	global_load_lds_dwordx4 v[218:219], off
	s_mov_b32 m0, s35
	s_nop 0
	global_load_lds_dwordx4 v[220:221], off
	s_waitcnt vmcnt(8)
	s_waitcnt lgkmcnt(0)
	s_barrier
; #define PG8_STAGE(bufoff, gbase, voff) do { _Pragma("unroll") for (int _i = 0; _i < 2; ++_i) \
;         __builtin_amdgcn_global_load_lds((const unsigned*)((const char*)(gbase) + (voff)[_i]), (LAS unsigned*)(lds + (bufoff) + ldsw + _i * 8192), 16, 0, 0); } while (0)
; #define PG8_LDA(dst, b, h) do { _Pragma("unroll") for (int m = 0; m < 4; ++m) _Pragma("unroll") for (int k = 0; k < 2; ++k) dst[m][k] = *(const LAS bf16x8*)(lds + PG8_SA(b, h) + aoff + m * 2048 + k * 1024); } while (0)
; #define PG8_LDB(dst, b, h) do { _Pragma("unroll") for (int n = 0; n < 2; ++n) _Pragma("unroll") for (int k = 0; k < 2; ++k) dst[n][k] = *(const LAS bf16x8*)(lds + PG8_SB(b, h) + boff + n * 2048 + k * 1024); } while (0)
; #define PG8_MMA(ai, bj, At, Bt) do { __builtin_amdgcn_s_setprio(1); _Pragma("unroll") for (int m = 0; m < 4; ++m) _Pragma("unroll") for (int n = 0; n < 2; ++n) _Pragma("unroll") for (int k = 0; k < 2; ++k) \
;         acc[ai][bj][m][n] = __builtin_amdgcn_mfma_f32_16x16x32_bf16(Bt[n][k], At[m][k], acc[ai][bj][m][n], 0, 0, 0); __builtin_amdgcn_s_setprio(0); } while (0)
; #define PG8_WAIT_V(n) asm volatile("s_waitcnt vmcnt(" #n ")" ::: "memory")
; #define PG8_WAIT_L(n) asm volatile("s_waitcnt lgkmcnt(" #n ")" ::: "memory")
; #define PG8_BAR __builtin_amdgcn_s_barrier()
; #define PG8_SCHED __builtin_amdgcn_sched_barrier(0)
; template <class Epi>
; DI void gemm_phase(int wv, LAS unsigned char* lds, const Gemm g, const StaticOrder& S, const Epi& E) {
;     ...
;             PG8_WAIT_V(8); PG8_WAIT_L(0); PG8_BAR; PG8_MMA(1, 0, At, B0); PG8_MMA(1, 1, At, B1); PG8_BAR; PG8_SCHED;
;             PG8_LDB(B0, 1, 0); PG8_LDB(B1, 1, 1); PG8_SCHED; PG8_LDA(At, 1, 0); PG8_STAGE(PG8_SA(0, 1), a2 + hA, voffA);
;             PG8_WAIT_V(8); PG8_WAIT_L(0); PG8_BAR; PG8_MMA(0, 0, At, B0); PG8_MMA(0, 1, At, B1); PG8_BAR; PG8_SCHED;
	s_setprio 1
	s_waitcnt lgkmcnt(0)
	v_mfma_f32_16x16x32_bf16 v[60:63], v[150:153], v[182:185], v[60:63]
	v_mfma_f32_16x16x32_bf16 v[56:59], v[158:161], v[182:185], v[56:59]
	v_mfma_f32_16x16x32_bf16 v[52:55], v[150:153], v[190:193], v[52:55]
	v_mfma_f32_16x16x32_bf16 v[48:51], v[158:161], v[190:193], v[48:51]
	v_mfma_f32_16x16x32_bf16 v[36:39], v[150:153], v[198:201], v[36:39]
	v_mfma_f32_16x16x32_bf16 v[32:35], v[158:161], v[198:201], v[32:35]
	v_mfma_f32_16x16x32_bf16 v[20:23], v[150:153], v[206:209], v[20:23]
	v_mfma_f32_16x16x32_bf16 v[16:19], v[158:161], v[206:209], v[16:19]
	v_mfma_f32_16x16x32_bf16 v[60:63], v[154:157], v[186:189], v[60:63]
	v_mfma_f32_16x16x32_bf16 v[56:59], v[162:165], v[186:189], v[56:59]
	v_mfma_f32_16x16x32_bf16 v[52:55], v[154:157], v[194:197], v[52:55]
	v_mfma_f32_16x16x32_bf16 v[48:51], v[162:165], v[194:197], v[48:51]
	v_mfma_f32_16x16x32_bf16 v[36:39], v[154:157], v[202:205], v[36:39]
	v_mfma_f32_16x16x32_bf16 v[32:35], v[162:165], v[202:205], v[32:35]
	v_mfma_f32_16x16x32_bf16 v[20:23], v[154:157], v[210:213], v[20:23]
	v_mfma_f32_16x16x32_bf16 v[16:19], v[162:165], v[210:213], v[16:19]
	s_setprio 0
	s_setprio 1
	v_mfma_f32_16x16x32_bf16 v[44:47], v[166:169], v[182:185], v[44:47]
	v_mfma_f32_16x16x32_bf16 v[40:43], v[174:177], v[182:185], v[40:43]
	v_mfma_f32_16x16x32_bf16 v[28:31], v[166:169], v[190:193], v[28:31]
	v_mfma_f32_16x16x32_bf16 v[24:27], v[174:177], v[190:193], v[24:27]
	v_mfma_f32_16x16x32_bf16 v[12:15], v[166:169], v[198:201], v[12:15]
	v_mfma_f32_16x16x32_bf16 v[8:11], v[174:177], v[198:201], v[8:11]
	v_mfma_f32_16x16x32_bf16 v[4:7], v[166:169], v[206:209], v[4:7]
	v_mfma_f32_16x16x32_bf16 v[0:3], v[174:177], v[206:209], v[0:3]
	v_mfma_f32_16x16x32_bf16 v[44:47], v[170:173], v[186:189], v[44:47]
	v_mfma_f32_16x16x32_bf16 v[40:43], v[178:181], v[186:189], v[40:43]
	v_mfma_f32_16x16x32_bf16 v[28:31], v[170:173], v[194:197], v[28:31]
	v_mfma_f32_16x16x32_bf16 v[24:27], v[178:181], v[194:197], v[24:27]
	v_mfma_f32_16x16x32_bf16 v[12:15], v[170:173], v[202:205], v[12:15]
	v_mfma_f32_16x16x32_bf16 v[8:11], v[178:181], v[202:205], v[8:11]
	v_mfma_f32_16x16x32_bf16 v[4:7], v[170:173], v[210:213], v[4:7]
	v_mfma_f32_16x16x32_bf16 v[0:3], v[178:181], v[210:213], v[0:3]
	s_setprio 0
	s_barrier
	s_add_i32 s55, 0, 0x18000
	s_add_i32 s57, 0, 0x1c000
	v_add_u32_e32 v162, s55, v146
	v_add_u32_e32 v178, s57, v146
	ds_read_b128 v[150:153], v162
	ds_read_b128 v[154:157], v162 offset:1024
	ds_read_b128 v[158:161], v162 offset:2048
	ds_read_b128 v[162:165], v162 offset:3072
	ds_read_b128 v[166:169], v178
	ds_read_b128 v[170:173], v178 offset:1024
	ds_read_b128 v[174:177], v178 offset:2048
	ds_read_b128 v[178:181], v178 offset:3072
	s_add_u32 s26, s26, 0x40000
	s_addc_u32 s27, s27, 0
	s_mov_b32 m0, s36
	v_lshl_add_u64 v[222:223], s[26:27], 0, v[128:129]
	ds_read_b128 v[182:185], v149 offset:32768
	ds_read_b128 v[186:189], v149 offset:33792
	ds_read_b128 v[190:193], v149 offset:34816
	ds_read_b128 v[194:197], v149 offset:35840
	ds_read_b128 v[198:201], v149 offset:36864
	ds_read_b128 v[202:205], v149 offset:37888
	ds_read_b128 v[206:209], v149 offset:38912
	ds_read_b128 v[210:213], v149 offset:39936
	global_load_lds_dwordx4 v[222:223], off
	v_lshl_add_u64 v[222:223], s[26:27], 0, v[132:133]
	s_mov_b32 m0, s37
	s_nop 0
	global_load_lds_dwordx4 v[222:223], off
	s_waitcnt vmcnt(8)
	s_waitcnt lgkmcnt(0)
	s_barrier
	s_setprio 1
	s_waitcnt lgkmcnt(0)
	v_mfma_f32_16x16x32_bf16 v[124:127], v[150:153], v[182:185], v[124:127]
	v_mfma_f32_16x16x32_bf16 v[120:123], v[158:161], v[182:185], v[120:123]
	v_mfma_f32_16x16x32_bf16 v[116:119], v[150:153], v[190:193], v[116:119]
	v_mfma_f32_16x16x32_bf16 v[112:115], v[158:161], v[190:193], v[112:115]
	v_mfma_f32_16x16x32_bf16 v[100:103], v[150:153], v[198:201], v[100:103]
	v_mfma_f32_16x16x32_bf16 v[96:99], v[158:161], v[198:201], v[96:99]
	v_mfma_f32_16x16x32_bf16 v[84:87], v[150:153], v[206:209], v[84:87]
	v_mfma_f32_16x16x32_bf16 v[80:83], v[158:161], v[206:209], v[80:83]
	v_mfma_f32_16x16x32_bf16 v[124:127], v[154:157], v[186:189], v[124:127]
	v_mfma_f32_16x16x32_bf16 v[120:123], v[162:165], v[186:189], v[120:123]
	v_mfma_f32_16x16x32_bf16 v[116:119], v[154:157], v[194:197], v[116:119]
	v_mfma_f32_16x16x32_bf16 v[112:115], v[162:165], v[194:197], v[112:115]
	v_mfma_f32_16x16x32_bf16 v[100:103], v[154:157], v[202:205], v[100:103]
	v_mfma_f32_16x16x32_bf16 v[96:99], v[162:165], v[202:205], v[96:99]
	v_mfma_f32_16x16x32_bf16 v[84:87], v[154:157], v[210:213], v[84:87]
	v_mfma_f32_16x16x32_bf16 v[80:83], v[162:165], v[210:213], v[80:83]
	s_setprio 0
	s_setprio 1
	v_mfma_f32_16x16x32_bf16 v[108:111], v[166:169], v[182:185], v[108:111]
	v_mfma_f32_16x16x32_bf16 v[104:107], v[174:177], v[182:185], v[104:107]
	v_mfma_f32_16x16x32_bf16 v[92:95], v[166:169], v[190:193], v[92:95]
	v_mfma_f32_16x16x32_bf16 v[88:91], v[174:177], v[190:193], v[88:91]
	v_mfma_f32_16x16x32_bf16 v[76:79], v[166:169], v[198:201], v[76:79]
	v_mfma_f32_16x16x32_bf16 v[72:75], v[174:177], v[198:201], v[72:75]
	v_mfma_f32_16x16x32_bf16 v[68:71], v[166:169], v[206:209], v[68:71]
	v_mfma_f32_16x16x32_bf16 v[64:67], v[174:177], v[206:209], v[64:67]
	v_mfma_f32_16x16x32_bf16 v[108:111], v[170:173], v[186:189], v[108:111]
	v_mfma_f32_16x16x32_bf16 v[104:107], v[178:181], v[186:189], v[104:107]
	v_mfma_f32_16x16x32_bf16 v[92:95], v[170:173], v[194:197], v[92:95]
	v_mfma_f32_16x16x32_bf16 v[88:91], v[178:181], v[194:197], v[88:91]
	v_mfma_f32_16x16x32_bf16 v[76:79], v[170:173], v[202:205], v[76:79]
	v_mfma_f32_16x16x32_bf16 v[72:75], v[178:181], v[202:205], v[72:75]
	v_mfma_f32_16x16x32_bf16 v[68:71], v[170:173], v[210:213], v[68:71]
	v_mfma_f32_16x16x32_bf16 v[64:67], v[178:181], v[210:213], v[64:67]
	s_setprio 0
	s_barrier
; #define PG8_STAGE(bufoff, gbase, voff) do { _Pragma("unroll") for (int _i = 0; _i < 2; ++_i) \
;         __builtin_amdgcn_global_load_lds((const unsigned*)((const char*)(gbase) + (voff)[_i]), (LAS unsigned*)(lds + (bufoff) + ldsw + _i * 8192), 16, 0, 0); } while (0)
; #define PG8_LDA(dst, b, h) do { _Pragma("unroll") for (int m = 0; m < 4; ++m) _Pragma("unroll") for (int k = 0; k < 2; ++k) dst[m][k] = *(const LAS bf16x8*)(lds + PG8_SA(b, h) + aoff + m * 2048 + k * 1024); } while (0)
; #define PG8_MMA(ai, bj, At, Bt) do { __builtin_amdgcn_s_setprio(1); _Pragma("unroll") for (int m = 0; m < 4; ++m) _Pragma("unroll") for (int n = 0; n < 2; ++n) _Pragma("unroll") for (int k = 0; k < 2; ++k) \
;         acc[ai][bj][m][n] = __builtin_amdgcn_mfma_f32_16x16x32_bf16(Bt[n][k], At[m][k], acc[ai][bj][m][n], 0, 0, 0); __builtin_amdgcn_s_setprio(0); } while (0)
; #define PG8_WAIT_V(n) asm volatile("s_waitcnt vmcnt(" #n ")" ::: "memory")
; #define PG8_WAIT_L(n) asm volatile("s_waitcnt lgkmcnt(" #n ")" ::: "memory")
; #define PG8_BAR __builtin_amdgcn_s_barrier()
; #define PG8_SCHED __builtin_amdgcn_sched_barrier(0)
; template <class Epi>
; DI void gemm_phase(int wv, LAS unsigned char* lds, const Gemm g, const StaticOrder& S, const Epi& E) {
;     ...
;             PG8_LDA(At, 1, 1); PG8_STAGE(PG8_SB(1, 0), b3, voffB); PG8_STAGE(PG8_SB(1, 1), b3 + hB, voffB); PG8_STAGE(PG8_SA(1, 0), a3, voffA);
;             PG8_WAIT_V(8); PG8_WAIT_L(0); PG8_BAR; PG8_MMA(1, 0, At, B0); PG8_MMA(1, 1, At, B1); PG8_BAR; PG8_SCHED;
;         }
;         if (wr == 0) PG8_BAR;
	s_add_i32 s26, s55, s34
	v_lshl_add_u64 v[214:215], v[214:215], 0, s[6:7]
	s_mov_b32 m0, s26
	ds_read_b128 v[182:185], v149 offset:49152
	ds_read_b128 v[186:189], v149 offset:50176
	ds_read_b128 v[190:193], v149 offset:51200
	ds_read_b128 v[194:197], v149 offset:52224
	ds_read_b128 v[198:201], v149 offset:53248
	ds_read_b128 v[202:205], v149 offset:54272
	ds_read_b128 v[206:209], v149 offset:55296
	ds_read_b128 v[210:213], v149 offset:56320
	global_load_lds_dwordx4 v[214:215], off
	s_add_i32 m0, s26, 0x2000
	s_add_u32 s24, s24, 0x40080
	v_lshl_add_u64 v[214:215], v[216:217], 0, s[6:7]
	s_addc_u32 s25, s25, 0
	s_add_i32 s26, s57, s34
	global_load_lds_dwordx4 v[214:215], off
	v_lshl_add_u64 v[214:215], s[24:25], 0, v[130:131]
	s_mov_b32 m0, s26
	s_nop 0
	global_load_lds_dwordx4 v[214:215], off
	v_lshl_add_u64 v[214:215], s[24:25], 0, v[134:135]
	s_add_i32 m0, s26, 0x2000
	s_nop 0
	global_load_lds_dwordx4 v[214:215], off
	v_lshl_add_u64 v[214:215], v[218:219], 0, s[6:7]
	s_mov_b32 m0, s41
	s_nop 0
	global_load_lds_dwordx4 v[214:215], off
	v_lshl_add_u64 v[214:215], v[220:221], 0, s[6:7]
	s_mov_b32 m0, s42
	s_nop 0
	global_load_lds_dwordx4 v[214:215], off
	s_waitcnt vmcnt(8)
	s_waitcnt lgkmcnt(0)
	s_barrier
	s_setprio 1
	s_waitcnt lgkmcnt(0)
	v_mfma_f32_16x16x32_bf16 v[60:63], v[150:153], v[182:185], v[60:63]
	v_mfma_f32_16x16x32_bf16 v[56:59], v[158:161], v[182:185], v[56:59]
	v_mfma_f32_16x16x32_bf16 v[52:55], v[150:153], v[190:193], v[52:55]
	v_mfma_f32_16x16x32_bf16 v[48:51], v[158:161], v[190:193], v[48:51]
	v_mfma_f32_16x16x32_bf16 v[36:39], v[150:153], v[198:201], v[36:39]
	v_mfma_f32_16x16x32_bf16 v[32:35], v[158:161], v[198:201], v[32:35]
	v_mfma_f32_16x16x32_bf16 v[20:23], v[150:153], v[206:209], v[20:23]
	v_mfma_f32_16x16x32_bf16 v[16:19], v[158:161], v[206:209], v[16:19]
	v_mfma_f32_16x16x32_bf16 v[60:63], v[154:157], v[186:189], v[60:63]
	v_mfma_f32_16x16x32_bf16 v[56:59], v[162:165], v[186:189], v[56:59]
	v_mfma_f32_16x16x32_bf16 v[52:55], v[154:157], v[194:197], v[52:55]
	v_mfma_f32_16x16x32_bf16 v[48:51], v[162:165], v[194:197], v[48:51]
	v_mfma_f32_16x16x32_bf16 v[36:39], v[154:157], v[202:205], v[36:39]
	v_mfma_f32_16x16x32_bf16 v[32:35], v[162:165], v[202:205], v[32:35]
	v_mfma_f32_16x16x32_bf16 v[20:23], v[154:157], v[210:213], v[20:23]
	v_mfma_f32_16x16x32_bf16 v[16:19], v[162:165], v[210:213], v[16:19]
	s_setprio 0
	s_setprio 1
	v_mfma_f32_16x16x32_bf16 v[44:47], v[166:169], v[182:185], v[44:47]
	v_mfma_f32_16x16x32_bf16 v[40:43], v[174:177], v[182:185], v[40:43]
	v_mfma_f32_16x16x32_bf16 v[28:31], v[166:169], v[190:193], v[28:31]
	v_mfma_f32_16x16x32_bf16 v[24:27], v[174:177], v[190:193], v[24:27]
	v_mfma_f32_16x16x32_bf16 v[12:15], v[166:169], v[198:201], v[12:15]
	v_mfma_f32_16x16x32_bf16 v[8:11], v[174:177], v[198:201], v[8:11]
	v_mfma_f32_16x16x32_bf16 v[4:7], v[166:169], v[206:209], v[4:7]
	v_mfma_f32_16x16x32_bf16 v[0:3], v[174:177], v[206:209], v[0:3]
	v_mfma_f32_16x16x32_bf16 v[44:47], v[170:173], v[186:189], v[44:47]
	v_mfma_f32_16x16x32_bf16 v[40:43], v[178:181], v[186:189], v[40:43]
	v_mfma_f32_16x16x32_bf16 v[28:31], v[170:173], v[194:197], v[28:31]
	v_mfma_f32_16x16x32_bf16 v[24:27], v[178:181], v[194:197], v[24:27]
	v_mfma_f32_16x16x32_bf16 v[12:15], v[170:173], v[202:205], v[12:15]
	v_mfma_f32_16x16x32_bf16 v[8:11], v[178:181], v[202:205], v[8:11]
	v_mfma_f32_16x16x32_bf16 v[4:7], v[170:173], v[210:213], v[4:7]
	v_mfma_f32_16x16x32_bf16 v[0:3], v[178:181], v[210:213], v[0:3]
	s_setprio 0
	s_add_i32 s54, s54, 2
	s_add_u32 s50, s50, 0x100
	s_addc_u32 s51, s51, 0
	s_add_u32 s22, s22, 0x100
	s_addc_u32 s23, s23, 0
	s_cmp_gt_u32 s54, 13
	s_barrier
	s_cbranch_scc0 .LBB0_3413
	s_and_b64 vcc, exec, s[8:9]
	s_cbranch_vccz .LBB0_3416
	s_barrier

; #define PG8_STAGE(bufoff, gbase, voff) do { _Pragma("unroll") for (int _i = 0; _i < 2; ++_i) \
;         __builtin_amdgcn_global_load_lds((const unsigned*)((const char*)(gbase) + (voff)[_i]), (LAS unsigned*)(lds + (bufoff) + ldsw + _i * 8192), 16, 0, 0); } while (0)
; #define PG8_LDA(dst, b, h) do { _Pragma("unroll") for (int m = 0; m < 4; ++m) _Pragma("unroll") for (int k = 0; k < 2; ++k) dst[m][k] = *(const LAS bf16x8*)(lds + PG8_SA(b, h) + aoff + m * 2048 + k * 1024); } while (0)
; #define PG8_LDB(dst, b, h) do { _Pragma("unroll") for (int n = 0; n < 2; ++n) _Pragma("unroll") for (int k = 0; k < 2; ++k) dst[n][k] = *(const LAS bf16x8*)(lds + PG8_SB(b, h) + boff + n * 2048 + k * 1024); } while (0)
; #define PG8_MMA(ai, bj, At, Bt) do { __builtin_amdgcn_s_setprio(1); _Pragma("unroll") for (int m = 0; m < 4; ++m) _Pragma("unroll") for (int n = 0; n < 2; ++n) _Pragma("unroll") for (int k = 0; k < 2; ++k) \
;         acc[ai][bj][m][n] = __builtin_amdgcn_mfma_f32_16x16x32_bf16(Bt[n][k], At[m][k], acc[ai][bj][m][n], 0, 0, 0); __builtin_amdgcn_s_setprio(0); } while (0)
; #define PG8_WAIT_V(n) asm volatile("s_waitcnt vmcnt(" #n ")" ::: "memory")
; #define PG8_WAIT_L(n) asm volatile("s_waitcnt lgkmcnt(" #n ")" ::: "memory")
; #define PG8_BAR __builtin_amdgcn_s_barrier()
; #define PG8_SCHED __builtin_amdgcn_sched_barrier(0)
; template <class Epi>
; DI void gemm_phase(int wv, LAS unsigned char* lds, const Gemm g, const StaticOrder& S, const Epi& E) {
;     ...
;         for (int t = 0; t < nt; t += 2) {
;             const bool last = (t == nt - 2);
;             const char* a1 = cA + (size_t)(t + 1) * kstep;
;             const char* a2 = last ? nA : cA + (size_t)(t + 2) * kstep; const char* b2 = last ? nB : cB + (size_t)(t + 2) * kstep;
;             const char* a3 = a2 + kstep; const char* b3 = b2 + kstep;
;             PG8_LDB(B0, 0, 0); PG8_LDB(B1, 0, 1); PG8_SCHED; PG8_LDA(At, 0, 0); PG8_STAGE(PG8_SA(1, 1), a1 + hA, voffA);
;             PG8_WAIT_V(8); PG8_WAIT_L(0); PG8_BAR; PG8_MMA(0, 0, At, B0); PG8_MMA(0, 1, At, B1); PG8_BAR; PG8_SCHED;
;             PG8_LDA(At, 0, 1); PG8_STAGE(PG8_SB(0, 0), b2, voffB); PG8_STAGE(PG8_SB(0, 1), b2 + hB, voffB); PG8_STAGE(PG8_SA(0, 0), a2, voffA);
;             PG8_WAIT_V(8); PG8_WAIT_L(0); PG8_BAR; PG8_MMA(1, 0, At, B0); PG8_MMA(1, 1, At, B1); PG8_BAR; PG8_SCHED;
.LBB0_3532:
	ds_read_b128 v[150:153], v147
	ds_read_b128 v[154:157], v147 offset:1024
	ds_read_b128 v[158:161], v147 offset:2048
	ds_read_b128 v[162:165], v147 offset:3072
	ds_read_b128 v[166:169], v148
	ds_read_b128 v[170:173], v148 offset:1024
	ds_read_b128 v[174:177], v148 offset:2048
	ds_read_b128 v[178:181], v148 offset:3072
	s_add_u32 s24, s22, 0xfffc0080
	s_addc_u32 s25, s23, -1
	s_cmp_eq_u32 s54, 12
	s_cselect_b32 s27, s15, s25
	s_cselect_b32 s26, s46, s24
	s_cselect_b32 s25, s13, s51
	s_cselect_b32 s24, s47, s50
	v_lshl_add_u64 v[214:215], s[22:23], 0, v[138:139]
	s_add_i32 m0, s21, 0xc000
	ds_read_b128 v[182:185], v149
	ds_read_b128 v[186:189], v149 offset:1024
	ds_read_b128 v[190:193], v149 offset:2048
	ds_read_b128 v[194:197], v149 offset:3072
	ds_read_b128 v[198:201], v149 offset:4096
	ds_read_b128 v[202:205], v149 offset:5120
	ds_read_b128 v[206:209], v149 offset:6144
	ds_read_b128 v[210:213], v149 offset:7168
	global_load_lds_dwordx4 v[214:215], off
	v_lshl_add_u64 v[214:215], s[22:23], 0, v[136:137]
	s_add_i32 m0, s21, 0xe000
	s_nop 0
	global_load_lds_dwordx4 v[214:215], off
	s_waitcnt vmcnt(8)
	s_waitcnt lgkmcnt(0)
	s_barrier
	s_setprio 1
	s_waitcnt lgkmcnt(0)
	v_mfma_f32_16x16x32_bf16 v[124:127], v[150:153], v[182:185], v[124:127]
	v_mfma_f32_16x16x32_bf16 v[116:119], v[158:161], v[182:185], v[116:119]
	v_mfma_f32_16x16x32_bf16 v[108:111], v[150:153], v[190:193], v[108:111]
	v_mfma_f32_16x16x32_bf16 v[100:103], v[158:161], v[190:193], v[100:103]
	v_mfma_f32_16x16x32_bf16 v[92:95], v[150:153], v[198:201], v[92:95]
	v_mfma_f32_16x16x32_bf16 v[84:87], v[158:161], v[198:201], v[84:87]
	v_mfma_f32_16x16x32_bf16 v[76:79], v[150:153], v[206:209], v[76:79]
	v_mfma_f32_16x16x32_bf16 v[68:71], v[158:161], v[206:209], v[68:71]
	v_mfma_f32_16x16x32_bf16 v[124:127], v[154:157], v[186:189], v[124:127]
	v_mfma_f32_16x16x32_bf16 v[116:119], v[162:165], v[186:189], v[116:119]
	v_mfma_f32_16x16x32_bf16 v[108:111], v[154:157], v[194:197], v[108:111]
	v_mfma_f32_16x16x32_bf16 v[100:103], v[162:165], v[194:197], v[100:103]
	v_mfma_f32_16x16x32_bf16 v[92:95], v[154:157], v[202:205], v[92:95]
	v_mfma_f32_16x16x32_bf16 v[84:87], v[162:165], v[202:205], v[84:87]
	v_mfma_f32_16x16x32_bf16 v[76:79], v[154:157], v[210:213], v[76:79]
	v_mfma_f32_16x16x32_bf16 v[68:71], v[162:165], v[210:213], v[68:71]
	s_setprio 0
	s_setprio 1
	v_mfma_f32_16x16x32_bf16 v[120:123], v[166:169], v[182:185], v[120:123]
	v_mfma_f32_16x16x32_bf16 v[112:115], v[174:177], v[182:185], v[112:115]
	v_mfma_f32_16x16x32_bf16 v[104:107], v[166:169], v[190:193], v[104:107]
	v_mfma_f32_16x16x32_bf16 v[96:99], v[174:177], v[190:193], v[96:99]
	v_mfma_f32_16x16x32_bf16 v[88:91], v[166:169], v[198:201], v[88:91]
	v_mfma_f32_16x16x32_bf16 v[80:83], v[174:177], v[198:201], v[80:83]
	v_mfma_f32_16x16x32_bf16 v[72:75], v[166:169], v[206:209], v[72:75]
	v_mfma_f32_16x16x32_bf16 v[64:67], v[174:177], v[206:209], v[64:67]
	v_mfma_f32_16x16x32_bf16 v[120:123], v[170:173], v[186:189], v[120:123]
	v_mfma_f32_16x16x32_bf16 v[112:115], v[178:181], v[186:189], v[112:115]
	v_mfma_f32_16x16x32_bf16 v[104:107], v[170:173], v[194:197], v[104:107]
	v_mfma_f32_16x16x32_bf16 v[96:99], v[178:181], v[194:197], v[96:99]
	v_mfma_f32_16x16x32_bf16 v[88:91], v[170:173], v[202:205], v[88:91]
	v_mfma_f32_16x16x32_bf16 v[80:83], v[178:181], v[202:205], v[80:83]
	v_mfma_f32_16x16x32_bf16 v[72:75], v[170:173], v[210:213], v[72:75]
	v_mfma_f32_16x16x32_bf16 v[64:67], v[178:181], v[210:213], v[64:67]
	s_setprio 0
	s_barrier
	s_add_i32 s55, s42, s30
	v_lshl_add_u64 v[214:215], s[24:25], 0, v[132:133]
	s_mov_b32 m0, s55
	ds_read_b128 v[182:185], v149 offset:16384
	ds_read_b128 v[186:189], v149 offset:17408
	ds_read_b128 v[190:193], v149 offset:18432
	ds_read_b128 v[194:197], v149 offset:19456
	ds_read_b128 v[198:201], v149 offset:20480
	ds_read_b128 v[202:205], v149 offset:21504
	ds_read_b128 v[206:209], v149 offset:22528
	ds_read_b128 v[210:213], v149 offset:23552
	global_load_lds_dwordx4 v[214:215], off
	s_add_i32 m0, s55, 0x2000
	s_add_u32 s60, s24, 0x40000
	v_lshl_add_u64 v[216:217], s[24:25], 0, v[128:129]
	s_addc_u32 s61, s25, 0
	s_add_i32 s55, s43, s30
	global_load_lds_dwordx4 v[216:217], off
	v_lshl_add_u64 v[218:219], s[60:61], 0, v[132:133]
	s_mov_b32 m0, s55
	v_lshl_add_u64 v[220:221], s[26:27], 0, v[130:131]
	global_load_lds_dwordx4 v[218:219], off
	v_lshl_add_u64 v[218:219], s[60:61], 0, v[128:129]
	s_add_i32 m0, s55, 0x2000
	s_nop 0
	global_load_lds_dwordx4 v[218:219], off
	v_lshl_add_u64 v[218:219], s[26:27], 0, v[134:135]
	s_mov_b32 m0, s21
	s_nop 0
	global_load_lds_dwordx4 v[218:219], off
	s_mov_b32 m0, s34
	s_nop 0
	global_load_lds_dwordx4 v[220:221], off
	s_waitcnt vmcnt(8)
	s_waitcnt lgkmcnt(0)
	s_barrier
; #define PG8_STAGE(bufoff, gbase, voff) do { _Pragma("unroll") for (int _i = 0; _i < 2; ++_i) \
;         __builtin_amdgcn_global_load_lds((const unsigned*)((const char*)(gbase) + (voff)[_i]), (LAS unsigned*)(lds + (bufoff) + ldsw + _i * 8192), 16, 0, 0); } while (0)
; #define PG8_LDA(dst, b, h) do { _Pragma("unroll") for (int m = 0; m < 4; ++m) _Pragma("unroll") for (int k = 0; k < 2; ++k) dst[m][k] = *(const LAS bf16x8*)(lds + PG8_SA(b, h) + aoff + m * 2048 + k * 1024); } while (0)
; #define PG8_LDB(dst, b, h) do { _Pragma("unroll") for (int n = 0; n < 2; ++n) _Pragma("unroll") for (int k = 0; k < 2; ++k) dst[n][k] = *(const LAS bf16x8*)(lds + PG8_SB(b, h) + boff + n * 2048 + k * 1024); } while (0)
; #define PG8_MMA(ai, bj, At, Bt) do { __builtin_amdgcn_s_setprio(1); _Pragma("unroll") for (int m = 0; m < 4; ++m) _Pragma("unroll") for (int n = 0; n < 2; ++n) _Pragma("unroll") for (int k = 0; k < 2; ++k) \
;         acc[ai][bj][m][n] = __builtin_amdgcn_mfma_f32_16x16x32_bf16(Bt[n][k], At[m][k], acc[ai][bj][m][n], 0, 0, 0); __builtin_amdgcn_s_setprio(0); } while (0)
; #define PG8_WAIT_V(n) asm volatile("s_waitcnt vmcnt(" #n ")" ::: "memory")
; #define PG8_WAIT_L(n) asm volatile("s_waitcnt lgkmcnt(" #n ")" ::: "memory")
; #define PG8_BAR __builtin_amdgcn_s_barrier()
; #define PG8_SCHED __builtin_amdgcn_sched_barrier(0)
; template <class Epi>
; DI void gemm_phase(int wv, LAS unsigned char* lds, const Gemm g, const StaticOrder& S, const Epi& E) {
;     ...
;             PG8_WAIT_V(8); PG8_WAIT_L(0); PG8_BAR; PG8_MMA(1, 0, At, B0); PG8_MMA(1, 1, At, B1); PG8_BAR; PG8_SCHED;
;             PG8_LDB(B0, 1, 0); PG8_LDB(B1, 1, 1); PG8_SCHED; PG8_LDA(At, 1, 0); PG8_STAGE(PG8_SA(0, 1), a2 + hA, voffA);
;             PG8_WAIT_V(8); PG8_WAIT_L(0); PG8_BAR; PG8_MMA(0, 0, At, B0); PG8_MMA(0, 1, At, B1); PG8_BAR; PG8_SCHED;
	s_setprio 1
	s_waitcnt lgkmcnt(0)
	v_mfma_f32_16x16x32_bf16 v[60:63], v[150:153], v[182:185], v[60:63]
	v_mfma_f32_16x16x32_bf16 v[52:55], v[158:161], v[182:185], v[52:55]
	v_mfma_f32_16x16x32_bf16 v[44:47], v[150:153], v[190:193], v[44:47]
	v_mfma_f32_16x16x32_bf16 v[36:39], v[158:161], v[190:193], v[36:39]
	v_mfma_f32_16x16x32_bf16 v[28:31], v[150:153], v[198:201], v[28:31]
	v_mfma_f32_16x16x32_bf16 v[20:23], v[158:161], v[198:201], v[20:23]
	v_mfma_f32_16x16x32_bf16 v[12:15], v[150:153], v[206:209], v[12:15]
	v_mfma_f32_16x16x32_bf16 v[4:7], v[158:161], v[206:209], v[4:7]
	v_mfma_f32_16x16x32_bf16 v[60:63], v[154:157], v[186:189], v[60:63]
	v_mfma_f32_16x16x32_bf16 v[52:55], v[162:165], v[186:189], v[52:55]
	v_mfma_f32_16x16x32_bf16 v[44:47], v[154:157], v[194:197], v[44:47]
	v_mfma_f32_16x16x32_bf16 v[36:39], v[162:165], v[194:197], v[36:39]
	v_mfma_f32_16x16x32_bf16 v[28:31], v[154:157], v[202:205], v[28:31]
	v_mfma_f32_16x16x32_bf16 v[20:23], v[162:165], v[202:205], v[20:23]
	v_mfma_f32_16x16x32_bf16 v[12:15], v[154:157], v[210:213], v[12:15]
	v_mfma_f32_16x16x32_bf16 v[4:7], v[162:165], v[210:213], v[4:7]
	s_setprio 0
	s_setprio 1
	v_mfma_f32_16x16x32_bf16 v[56:59], v[166:169], v[182:185], v[56:59]
	v_mfma_f32_16x16x32_bf16 v[48:51], v[174:177], v[182:185], v[48:51]
	v_mfma_f32_16x16x32_bf16 v[40:43], v[166:169], v[190:193], v[40:43]
	v_mfma_f32_16x16x32_bf16 v[32:35], v[174:177], v[190:193], v[32:35]
	v_mfma_f32_16x16x32_bf16 v[24:27], v[166:169], v[198:201], v[24:27]
	v_mfma_f32_16x16x32_bf16 v[16:19], v[174:177], v[198:201], v[16:19]
	v_mfma_f32_16x16x32_bf16 v[8:11], v[166:169], v[206:209], v[8:11]
	v_mfma_f32_16x16x32_bf16 v[0:3], v[174:177], v[206:209], v[0:3]
	v_mfma_f32_16x16x32_bf16 v[56:59], v[170:173], v[186:189], v[56:59]
	v_mfma_f32_16x16x32_bf16 v[48:51], v[178:181], v[186:189], v[48:51]
	v_mfma_f32_16x16x32_bf16 v[40:43], v[170:173], v[194:197], v[40:43]
	v_mfma_f32_16x16x32_bf16 v[32:35], v[178:181], v[194:197], v[32:35]
	v_mfma_f32_16x16x32_bf16 v[24:27], v[170:173], v[202:205], v[24:27]
	v_mfma_f32_16x16x32_bf16 v[16:19], v[178:181], v[202:205], v[16:19]
	v_mfma_f32_16x16x32_bf16 v[8:11], v[170:173], v[210:213], v[8:11]
	v_mfma_f32_16x16x32_bf16 v[0:3], v[178:181], v[210:213], v[0:3]
	s_setprio 0
	s_barrier
	s_add_i32 s55, 0, 0x18000
	s_add_i32 s57, 0, 0x1c000
	v_add_u32_e32 v162, s55, v146
	v_add_u32_e32 v178, s57, v146
	ds_read_b128 v[150:153], v162
	ds_read_b128 v[154:157], v162 offset:1024
	ds_read_b128 v[158:161], v162 offset:2048
	ds_read_b128 v[162:165], v162 offset:3072
	ds_read_b128 v[166:169], v178
	ds_read_b128 v[170:173], v178 offset:1024
	ds_read_b128 v[174:177], v178 offset:2048
	ds_read_b128 v[178:181], v178 offset:3072
	s_add_u32 s26, s26, 0x40000
	s_addc_u32 s27, s27, 0
	s_mov_b32 m0, s35
	v_lshl_add_u64 v[222:223], s[26:27], 0, v[134:135]
	ds_read_b128 v[182:185], v149 offset:32768
	ds_read_b128 v[186:189], v149 offset:33792
	ds_read_b128 v[190:193], v149 offset:34816
	ds_read_b128 v[194:197], v149 offset:35840
	ds_read_b128 v[198:201], v149 offset:36864
	ds_read_b128 v[202:205], v149 offset:37888
	ds_read_b128 v[206:209], v149 offset:38912
	ds_read_b128 v[210:213], v149 offset:39936
	global_load_lds_dwordx4 v[222:223], off
	v_lshl_add_u64 v[222:223], s[26:27], 0, v[130:131]
	s_mov_b32 m0, s36
	s_nop 0
	global_load_lds_dwordx4 v[222:223], off
	s_waitcnt vmcnt(8)
	s_waitcnt lgkmcnt(0)
	s_barrier
	s_setprio 1
	s_waitcnt lgkmcnt(0)
	v_mfma_f32_16x16x32_bf16 v[124:127], v[150:153], v[182:185], v[124:127]
	v_mfma_f32_16x16x32_bf16 v[116:119], v[158:161], v[182:185], v[116:119]
	v_mfma_f32_16x16x32_bf16 v[108:111], v[150:153], v[190:193], v[108:111]
	v_mfma_f32_16x16x32_bf16 v[100:103], v[158:161], v[190:193], v[100:103]
	v_mfma_f32_16x16x32_bf16 v[92:95], v[150:153], v[198:201], v[92:95]
	v_mfma_f32_16x16x32_bf16 v[84:87], v[158:161], v[198:201], v[84:87]
	v_mfma_f32_16x16x32_bf16 v[76:79], v[150:153], v[206:209], v[76:79]
	v_mfma_f32_16x16x32_bf16 v[68:71], v[158:161], v[206:209], v[68:71]
	v_mfma_f32_16x16x32_bf16 v[124:127], v[154:157], v[186:189], v[124:127]
	v_mfma_f32_16x16x32_bf16 v[116:119], v[162:165], v[186:189], v[116:119]
	v_mfma_f32_16x16x32_bf16 v[108:111], v[154:157], v[194:197], v[108:111]
	v_mfma_f32_16x16x32_bf16 v[100:103], v[162:165], v[194:197], v[100:103]
	v_mfma_f32_16x16x32_bf16 v[92:95], v[154:157], v[202:205], v[92:95]
	v_mfma_f32_16x16x32_bf16 v[84:87], v[162:165], v[202:205], v[84:87]
	v_mfma_f32_16x16x32_bf16 v[76:79], v[154:157], v[210:213], v[76:79]
	v_mfma_f32_16x16x32_bf16 v[68:71], v[162:165], v[210:213], v[68:71]
	s_setprio 0
	s_setprio 1
	v_mfma_f32_16x16x32_bf16 v[120:123], v[166:169], v[182:185], v[120:123]
	v_mfma_f32_16x16x32_bf16 v[112:115], v[174:177], v[182:185], v[112:115]
	v_mfma_f32_16x16x32_bf16 v[104:107], v[166:169], v[190:193], v[104:107]
	v_mfma_f32_16x16x32_bf16 v[96:99], v[174:177], v[190:193], v[96:99]
	v_mfma_f32_16x16x32_bf16 v[88:91], v[166:169], v[198:201], v[88:91]
	v_mfma_f32_16x16x32_bf16 v[80:83], v[174:177], v[198:201], v[80:83]
	v_mfma_f32_16x16x32_bf16 v[72:75], v[166:169], v[206:209], v[72:75]
	v_mfma_f32_16x16x32_bf16 v[64:67], v[174:177], v[206:209], v[64:67]
	v_mfma_f32_16x16x32_bf16 v[120:123], v[170:173], v[186:189], v[120:123]
	v_mfma_f32_16x16x32_bf16 v[112:115], v[178:181], v[186:189], v[112:115]
	v_mfma_f32_16x16x32_bf16 v[104:107], v[170:173], v[194:197], v[104:107]
	v_mfma_f32_16x16x32_bf16 v[96:99], v[178:181], v[194:197], v[96:99]
	v_mfma_f32_16x16x32_bf16 v[88:91], v[170:173], v[202:205], v[88:91]
	v_mfma_f32_16x16x32_bf16 v[80:83], v[178:181], v[202:205], v[80:83]
	v_mfma_f32_16x16x32_bf16 v[72:75], v[170:173], v[210:213], v[72:75]
	v_mfma_f32_16x16x32_bf16 v[64:67], v[178:181], v[210:213], v[64:67]
	s_setprio 0
	s_barrier
; #define PG8_STAGE(bufoff, gbase, voff) do { _Pragma("unroll") for (int _i = 0; _i < 2; ++_i) \
;         __builtin_amdgcn_global_load_lds((const unsigned*)((const char*)(gbase) + (voff)[_i]), (LAS unsigned*)(lds + (bufoff) + ldsw + _i * 8192), 16, 0, 0); } while (0)
; #define PG8_LDA(dst, b, h) do { _Pragma("unroll") for (int m = 0; m < 4; ++m) _Pragma("unroll") for (int k = 0; k < 2; ++k) dst[m][k] = *(const LAS bf16x8*)(lds + PG8_SA(b, h) + aoff + m * 2048 + k * 1024); } while (0)
; #define PG8_MMA(ai, bj, At, Bt) do { __builtin_amdgcn_s_setprio(1); _Pragma("unroll") for (int m = 0; m < 4; ++m) _Pragma("unroll") for (int n = 0; n < 2; ++n) _Pragma("unroll") for (int k = 0; k < 2; ++k) \
;         acc[ai][bj][m][n] = __builtin_amdgcn_mfma_f32_16x16x32_bf16(Bt[n][k], At[m][k], acc[ai][bj][m][n], 0, 0, 0); __builtin_amdgcn_s_setprio(0); } while (0)
; #define PG8_WAIT_V(n) asm volatile("s_waitcnt vmcnt(" #n ")" ::: "memory")
; #define PG8_WAIT_L(n) asm volatile("s_waitcnt lgkmcnt(" #n ")" ::: "memory")
; #define PG8_BAR __builtin_amdgcn_s_barrier()
; #define PG8_SCHED __builtin_amdgcn_sched_barrier(0)
; template <class Epi>
; DI void gemm_phase(int wv, LAS unsigned char* lds, const Gemm g, const StaticOrder& S, const Epi& E) {
;     ...
;             PG8_LDA(At, 1, 1); PG8_STAGE(PG8_SB(1, 0), b3, voffB); PG8_STAGE(PG8_SB(1, 1), b3 + hB, voffB); PG8_STAGE(PG8_SA(1, 0), a3, voffA);
;             PG8_WAIT_V(8); PG8_WAIT_L(0); PG8_BAR; PG8_MMA(1, 0, At, B0); PG8_MMA(1, 1, At, B1); PG8_BAR; PG8_SCHED;
;         }
	s_add_i32 s26, s55, s30
	v_lshl_add_u64 v[214:215], v[214:215], 0, s[8:9]
	s_mov_b32 m0, s26
	ds_read_b128 v[182:185], v149 offset:49152
	ds_read_b128 v[186:189], v149 offset:50176
	ds_read_b128 v[190:193], v149 offset:51200
	ds_read_b128 v[194:197], v149 offset:52224
	ds_read_b128 v[198:201], v149 offset:53248
	ds_read_b128 v[202:205], v149 offset:54272
	ds_read_b128 v[206:209], v149 offset:55296
	ds_read_b128 v[210:213], v149 offset:56320
	global_load_lds_dwordx4 v[214:215], off
	s_add_i32 m0, s26, 0x2000
	s_add_u32 s24, s24, 0x40080
	v_lshl_add_u64 v[214:215], v[216:217], 0, s[8:9]
	s_addc_u32 s25, s25, 0
	s_add_i32 s26, s57, s30
	global_load_lds_dwordx4 v[214:215], off
	v_lshl_add_u64 v[214:215], s[24:25], 0, v[132:133]
	s_mov_b32 m0, s26
	s_nop 0
	global_load_lds_dwordx4 v[214:215], off
	v_lshl_add_u64 v[214:215], s[24:25], 0, v[128:129]
	s_add_i32 m0, s26, 0x2000
	s_nop 0
	global_load_lds_dwordx4 v[214:215], off
	v_lshl_add_u64 v[214:215], v[218:219], 0, s[8:9]
	s_mov_b32 m0, s40
	s_nop 0
	global_load_lds_dwordx4 v[214:215], off
	v_lshl_add_u64 v[214:215], v[220:221], 0, s[8:9]
	s_mov_b32 m0, s41
	s_nop 0
	global_load_lds_dwordx4 v[214:215], off
	s_waitcnt vmcnt(8)
	s_waitcnt lgkmcnt(0)
	s_barrier
	s_setprio 1
	s_waitcnt lgkmcnt(0)
	v_mfma_f32_16x16x32_bf16 v[60:63], v[150:153], v[182:185], v[60:63]
	v_mfma_f32_16x16x32_bf16 v[52:55], v[158:161], v[182:185], v[52:55]
	v_mfma_f32_16x16x32_bf16 v[44:47], v[150:153], v[190:193], v[44:47]
	v_mfma_f32_16x16x32_bf16 v[36:39], v[158:161], v[190:193], v[36:39]
	v_mfma_f32_16x16x32_bf16 v[28:31], v[150:153], v[198:201], v[28:31]
	v_mfma_f32_16x16x32_bf16 v[20:23], v[158:161], v[198:201], v[20:23]
	v_mfma_f32_16x16x32_bf16 v[12:15], v[150:153], v[206:209], v[12:15]
	v_mfma_f32_16x16x32_bf16 v[4:7], v[158:161], v[206:209], v[4:7]
	v_mfma_f32_16x16x32_bf16 v[60:63], v[154:157], v[186:189], v[60:63]
	v_mfma_f32_16x16x32_bf16 v[52:55], v[162:165], v[186:189], v[52:55]
	v_mfma_f32_16x16x32_bf16 v[44:47], v[154:157], v[194:197], v[44:47]
	v_mfma_f32_16x16x32_bf16 v[36:39], v[162:165], v[194:197], v[36:39]
	v_mfma_f32_16x16x32_bf16 v[28:31], v[154:157], v[202:205], v[28:31]
	v_mfma_f32_16x16x32_bf16 v[20:23], v[162:165], v[202:205], v[20:23]
	v_mfma_f32_16x16x32_bf16 v[12:15], v[154:157], v[210:213], v[12:15]
	v_mfma_f32_16x16x32_bf16 v[4:7], v[162:165], v[210:213], v[4:7]
	s_setprio 0
	s_setprio 1
	v_mfma_f32_16x16x32_bf16 v[56:59], v[166:169], v[182:185], v[56:59]
	v_mfma_f32_16x16x32_bf16 v[48:51], v[174:177], v[182:185], v[48:51]
	v_mfma_f32_16x16x32_bf16 v[40:43], v[166:169], v[190:193], v[40:43]
	v_mfma_f32_16x16x32_bf16 v[32:35], v[174:177], v[190:193], v[32:35]
	v_mfma_f32_16x16x32_bf16 v[24:27], v[166:169], v[198:201], v[24:27]
	v_mfma_f32_16x16x32_bf16 v[16:19], v[174:177], v[198:201], v[16:19]
	v_mfma_f32_16x16x32_bf16 v[8:11], v[166:169], v[206:209], v[8:11]
	v_mfma_f32_16x16x32_bf16 v[0:3], v[174:177], v[206:209], v[0:3]
	v_mfma_f32_16x16x32_bf16 v[56:59], v[170:173], v[186:189], v[56:59]
	v_mfma_f32_16x16x32_bf16 v[48:51], v[178:181], v[186:189], v[48:51]
	v_mfma_f32_16x16x32_bf16 v[40:43], v[170:173], v[194:197], v[40:43]
	v_mfma_f32_16x16x32_bf16 v[32:35], v[178:181], v[194:197], v[32:35]
	v_mfma_f32_16x16x32_bf16 v[24:27], v[170:173], v[202:205], v[24:27]
	v_mfma_f32_16x16x32_bf16 v[16:19], v[178:181], v[202:205], v[16:19]
	v_mfma_f32_16x16x32_bf16 v[8:11], v[170:173], v[210:213], v[8:11]
	v_mfma_f32_16x16x32_bf16 v[0:3], v[178:181], v[210:213], v[0:3]
	s_setprio 0
	s_add_i32 s54, s54, 2
	s_add_u32 s50, s50, 0x100
	s_addc_u32 s51, s51, 0
	s_add_u32 s22, s22, 0x100
	s_addc_u32 s23, s23, 0
	s_cmp_gt_u32 s54, 13
	s_barrier
	s_cbranch_scc0 .LBB0_3532
	s_and_b64 vcc, exec, s[10:11]
	s_cbranch_vccz .LBB0_3535
	s_barrier

; #define PG8_STAGE(bufoff, gbase, voff) do { _Pragma("unroll") for (int _i = 0; _i < 2; ++_i) \
;         __builtin_amdgcn_global_load_lds((const unsigned*)((const char*)(gbase) + (voff)[_i]), (LAS unsigned*)(lds + (bufoff) + ldsw + _i * 8192), 16, 0, 0); } while (0)
; #define PG8_LDA(dst, b, h) do { _Pragma("unroll") for (int m = 0; m < 4; ++m) _Pragma("unroll") for (int k = 0; k < 2; ++k) dst[m][k] = *(const LAS bf16x8*)(lds + PG8_SA(b, h) + aoff + m * 2048 + k * 1024); } while (0)
; #define PG8_LDB(dst, b, h) do { _Pragma("unroll") for (int n = 0; n < 2; ++n) _Pragma("unroll") for (int k = 0; k < 2; ++k) dst[n][k] = *(const LAS bf16x8*)(lds + PG8_SB(b, h) + boff + n * 2048 + k * 1024); } while (0)
; #define PG8_MMA(ai, bj, At, Bt) do { __builtin_amdgcn_s_setprio(1); _Pragma("unroll") for (int m = 0; m < 4; ++m) _Pragma("unroll") for (int n = 0; n < 2; ++n) _Pragma("unroll") for (int k = 0; k < 2; ++k) \
;         acc[ai][bj][m][n] = __builtin_amdgcn_mfma_f32_16x16x32_bf16(Bt[n][k], At[m][k], acc[ai][bj][m][n], 0, 0, 0); __builtin_amdgcn_s_setprio(0); } while (0)
; #define PG8_WAIT_V(n) asm volatile("s_waitcnt vmcnt(" #n ")" ::: "memory")
; #define PG8_WAIT_L(n) asm volatile("s_waitcnt lgkmcnt(" #n ")" ::: "memory")
; #define PG8_BAR __builtin_amdgcn_s_barrier()
; #define PG8_SCHED __builtin_amdgcn_sched_barrier(0)
; template <class Epi>
; DI void gemm_phase(int wv, LAS unsigned char* lds, const Gemm g, const StaticOrder& S, const Epi& E) {
;     ...
;         for (int t = 0; t < nt; t += 2) {
;             const bool last = (t == nt - 2);
;             const char* a1 = cA + (size_t)(t + 1) * kstep;
;             const char* a2 = last ? nA : cA + (size_t)(t + 2) * kstep; const char* b2 = last ? nB : cB + (size_t)(t + 2) * kstep;
;             const char* a3 = a2 + kstep; const char* b3 = b2 + kstep;
;             PG8_LDB(B0, 0, 0); PG8_LDB(B1, 0, 1); PG8_SCHED; PG8_LDA(At, 0, 0); PG8_STAGE(PG8_SA(1, 1), a1 + hA, voffA);
;             PG8_WAIT_V(8); PG8_WAIT_L(0); PG8_BAR; PG8_MMA(0, 0, At, B0); PG8_MMA(0, 1, At, B1); PG8_BAR; PG8_SCHED;
;             PG8_LDA(At, 0, 1); PG8_STAGE(PG8_SB(0, 0), b2, voffB); PG8_STAGE(PG8_SB(0, 1), b2 + hB, voffB); PG8_STAGE(PG8_SA(0, 0), a2, voffA);
.LBB0_3613:
	ds_read_b128 v[150:153], v147
	ds_read_b128 v[154:157], v147 offset:1024
	ds_read_b128 v[158:161], v147 offset:2048
	ds_read_b128 v[162:165], v147 offset:3072
	ds_read_b128 v[166:169], v148
	ds_read_b128 v[170:173], v148 offset:1024
	ds_read_b128 v[174:177], v148 offset:2048
	ds_read_b128 v[178:181], v148 offset:3072
	s_add_u32 s18, s16, 0x100
	s_addc_u32 s19, s17, 0
	s_cmp_eq_u32 s50, 40
	s_cselect_b32 s23, s3, s19
	s_cselect_b32 s22, s2, s18
	s_cselect_b32 s21, s15, s47
	s_cselect_b32 s20, s14, s46
	v_lshl_add_u64 v[214:215], s[16:17], 0, v[138:139]
	s_add_i32 m0, s30, 0xc000
	ds_read_b128 v[182:185], v149
	ds_read_b128 v[186:189], v149 offset:1024
	ds_read_b128 v[190:193], v149 offset:2048
	ds_read_b128 v[194:197], v149 offset:3072
	ds_read_b128 v[198:201], v149 offset:4096
	ds_read_b128 v[202:205], v149 offset:5120
	ds_read_b128 v[206:209], v149 offset:6144
	ds_read_b128 v[210:213], v149 offset:7168
	global_load_lds_dwordx4 v[214:215], off
	v_lshl_add_u64 v[214:215], s[16:17], 0, v[136:137]
	s_add_i32 m0, s30, 0xe000
	s_nop 0
	global_load_lds_dwordx4 v[214:215], off
	s_waitcnt vmcnt(8)
	s_waitcnt lgkmcnt(0)
	s_barrier
	s_setprio 1
	s_waitcnt lgkmcnt(0)
	v_mfma_f32_16x16x32_bf16 v[124:127], v[150:153], v[182:185], v[124:127]
	v_mfma_f32_16x16x32_bf16 v[120:123], v[158:161], v[182:185], v[120:123]
	v_mfma_f32_16x16x32_bf16 v[116:119], v[150:153], v[190:193], v[116:119]
	v_mfma_f32_16x16x32_bf16 v[112:115], v[158:161], v[190:193], v[112:115]
	v_mfma_f32_16x16x32_bf16 v[100:103], v[150:153], v[198:201], v[100:103]
	v_mfma_f32_16x16x32_bf16 v[96:99], v[158:161], v[198:201], v[96:99]
	v_mfma_f32_16x16x32_bf16 v[84:87], v[150:153], v[206:209], v[84:87]
	v_mfma_f32_16x16x32_bf16 v[80:83], v[158:161], v[206:209], v[80:83]
	v_mfma_f32_16x16x32_bf16 v[124:127], v[154:157], v[186:189], v[124:127]
	v_mfma_f32_16x16x32_bf16 v[120:123], v[162:165], v[186:189], v[120:123]
	v_mfma_f32_16x16x32_bf16 v[116:119], v[154:157], v[194:197], v[116:119]
	v_mfma_f32_16x16x32_bf16 v[112:115], v[162:165], v[194:197], v[112:115]
	v_mfma_f32_16x16x32_bf16 v[100:103], v[154:157], v[202:205], v[100:103]
	v_mfma_f32_16x16x32_bf16 v[96:99], v[162:165], v[202:205], v[96:99]
	v_mfma_f32_16x16x32_bf16 v[84:87], v[154:157], v[210:213], v[84:87]
	v_mfma_f32_16x16x32_bf16 v[80:83], v[162:165], v[210:213], v[80:83]
	s_setprio 0
	s_setprio 1
	v_mfma_f32_16x16x32_bf16 v[108:111], v[166:169], v[182:185], v[108:111]
	v_mfma_f32_16x16x32_bf16 v[104:107], v[174:177], v[182:185], v[104:107]
	v_mfma_f32_16x16x32_bf16 v[92:95], v[166:169], v[190:193], v[92:95]
	v_mfma_f32_16x16x32_bf16 v[88:91], v[174:177], v[190:193], v[88:91]
	v_mfma_f32_16x16x32_bf16 v[76:79], v[166:169], v[198:201], v[76:79]
	v_mfma_f32_16x16x32_bf16 v[72:75], v[174:177], v[198:201], v[72:75]
	v_mfma_f32_16x16x32_bf16 v[68:71], v[166:169], v[206:209], v[68:71]
	v_mfma_f32_16x16x32_bf16 v[64:67], v[174:177], v[206:209], v[64:67]
	v_mfma_f32_16x16x32_bf16 v[108:111], v[170:173], v[186:189], v[108:111]
	v_mfma_f32_16x16x32_bf16 v[104:107], v[178:181], v[186:189], v[104:107]
	v_mfma_f32_16x16x32_bf16 v[92:95], v[170:173], v[194:197], v[92:95]
	v_mfma_f32_16x16x32_bf16 v[88:91], v[178:181], v[194:197], v[88:91]
	v_mfma_f32_16x16x32_bf16 v[76:79], v[170:173], v[202:205], v[76:79]
	v_mfma_f32_16x16x32_bf16 v[72:75], v[178:181], v[202:205], v[72:75]
	v_mfma_f32_16x16x32_bf16 v[68:71], v[170:173], v[210:213], v[68:71]
	v_mfma_f32_16x16x32_bf16 v[64:67], v[178:181], v[210:213], v[64:67]
	s_setprio 0
	s_barrier
	s_add_i32 s16, s40, s29
	v_lshl_add_u64 v[214:215], s[20:21], 0, v[130:131]
	s_mov_b32 m0, s16
	ds_read_b128 v[182:185], v149 offset:16384
	ds_read_b128 v[186:189], v149 offset:17408
	ds_read_b128 v[190:193], v149 offset:18432
	ds_read_b128 v[194:197], v149 offset:19456
	ds_read_b128 v[198:201], v149 offset:20480
	ds_read_b128 v[202:205], v149 offset:21504
	ds_read_b128 v[206:209], v149 offset:22528
	ds_read_b128 v[210:213], v149 offset:23552
	global_load_lds_dwordx4 v[214:215], off
	s_add_i32 m0, s16, 0x2000
	s_add_u32 s16, s20, 0xb0000
	v_lshl_add_u64 v[216:217], s[20:21], 0, v[134:135]
	s_addc_u32 s17, s21, 0
	s_add_i32 s51, s41, s29
	global_load_lds_dwordx4 v[216:217], off
	v_lshl_add_u64 v[218:219], s[16:17], 0, v[130:131]
	s_mov_b32 m0, s51
	v_lshl_add_u64 v[220:221], s[22:23], 0, v[132:133]
	global_load_lds_dwordx4 v[218:219], off
	v_lshl_add_u64 v[218:219], s[16:17], 0, v[134:135]
	s_add_i32 m0, s51, 0x2000
	s_nop 0
	global_load_lds_dwordx4 v[218:219], off
	v_lshl_add_u64 v[218:219], s[22:23], 0, v[128:129]
	s_mov_b32 m0, s30
	s_nop 0
	global_load_lds_dwordx4 v[218:219], off
	s_mov_b32 m0, s31
	s_nop 0
	global_load_lds_dwordx4 v[220:221], off
	s_waitcnt vmcnt(8)
	s_waitcnt lgkmcnt(0)
	s_barrier
; #define PG8_STAGE(bufoff, gbase, voff) do { _Pragma("unroll") for (int _i = 0; _i < 2; ++_i) \
;         __builtin_amdgcn_global_load_lds((const unsigned*)((const char*)(gbase) + (voff)[_i]), (LAS unsigned*)(lds + (bufoff) + ldsw + _i * 8192), 16, 0, 0); } while (0)
; #define PG8_LDA(dst, b, h) do { _Pragma("unroll") for (int m = 0; m < 4; ++m) _Pragma("unroll") for (int k = 0; k < 2; ++k) dst[m][k] = *(const LAS bf16x8*)(lds + PG8_SA(b, h) + aoff + m * 2048 + k * 1024); } while (0)
; #define PG8_LDB(dst, b, h) do { _Pragma("unroll") for (int n = 0; n < 2; ++n) _Pragma("unroll") for (int k = 0; k < 2; ++k) dst[n][k] = *(const LAS bf16x8*)(lds + PG8_SB(b, h) + boff + n * 2048 + k * 1024); } while (0)
; #define PG8_MMA(ai, bj, At, Bt) do { __builtin_amdgcn_s_setprio(1); _Pragma("unroll") for (int m = 0; m < 4; ++m) _Pragma("unroll") for (int n = 0; n < 2; ++n) _Pragma("unroll") for (int k = 0; k < 2; ++k) \
;         acc[ai][bj][m][n] = __builtin_amdgcn_mfma_f32_16x16x32_bf16(Bt[n][k], At[m][k], acc[ai][bj][m][n], 0, 0, 0); __builtin_amdgcn_s_setprio(0); } while (0)
; #define PG8_WAIT_V(n) asm volatile("s_waitcnt vmcnt(" #n ")" ::: "memory")
; #define PG8_WAIT_L(n) asm volatile("s_waitcnt lgkmcnt(" #n ")" ::: "memory")
; #define PG8_BAR __builtin_amdgcn_s_barrier()
; #define PG8_SCHED __builtin_amdgcn_sched_barrier(0)
; template <class Epi>
; DI void gemm_phase(int wv, LAS unsigned char* lds, const Gemm g, const StaticOrder& S, const Epi& E) {
;     ...
;             PG8_WAIT_V(8); PG8_WAIT_L(0); PG8_BAR; PG8_MMA(1, 0, At, B0); PG8_MMA(1, 1, At, B1); PG8_BAR; PG8_SCHED;
;             PG8_LDB(B0, 1, 0); PG8_LDB(B1, 1, 1); PG8_SCHED; PG8_LDA(At, 1, 0); PG8_STAGE(PG8_SA(0, 1), a2 + hA, voffA);
;             PG8_WAIT_V(8); PG8_WAIT_L(0); PG8_BAR; PG8_MMA(0, 0, At, B0); PG8_MMA(0, 1, At, B1); PG8_BAR; PG8_SCHED;
	s_setprio 1
	s_waitcnt lgkmcnt(0)
	v_mfma_f32_16x16x32_bf16 v[60:63], v[150:153], v[182:185], v[60:63]
	v_mfma_f32_16x16x32_bf16 v[56:59], v[158:161], v[182:185], v[56:59]
	v_mfma_f32_16x16x32_bf16 v[52:55], v[150:153], v[190:193], v[52:55]
	v_mfma_f32_16x16x32_bf16 v[48:51], v[158:161], v[190:193], v[48:51]
	v_mfma_f32_16x16x32_bf16 v[36:39], v[150:153], v[198:201], v[36:39]
	v_mfma_f32_16x16x32_bf16 v[32:35], v[158:161], v[198:201], v[32:35]
	v_mfma_f32_16x16x32_bf16 v[20:23], v[150:153], v[206:209], v[20:23]
	v_mfma_f32_16x16x32_bf16 v[16:19], v[158:161], v[206:209], v[16:19]
	v_mfma_f32_16x16x32_bf16 v[60:63], v[154:157], v[186:189], v[60:63]
	v_mfma_f32_16x16x32_bf16 v[56:59], v[162:165], v[186:189], v[56:59]
	v_mfma_f32_16x16x32_bf16 v[52:55], v[154:157], v[194:197], v[52:55]
	v_mfma_f32_16x16x32_bf16 v[48:51], v[162:165], v[194:197], v[48:51]
	v_mfma_f32_16x16x32_bf16 v[36:39], v[154:157], v[202:205], v[36:39]
	v_mfma_f32_16x16x32_bf16 v[32:35], v[162:165], v[202:205], v[32:35]
	v_mfma_f32_16x16x32_bf16 v[20:23], v[154:157], v[210:213], v[20:23]
	v_mfma_f32_16x16x32_bf16 v[16:19], v[162:165], v[210:213], v[16:19]
	s_setprio 0
	s_setprio 1
	v_mfma_f32_16x16x32_bf16 v[44:47], v[166:169], v[182:185], v[44:47]
	v_mfma_f32_16x16x32_bf16 v[40:43], v[174:177], v[182:185], v[40:43]
	v_mfma_f32_16x16x32_bf16 v[28:31], v[166:169], v[190:193], v[28:31]
	v_mfma_f32_16x16x32_bf16 v[24:27], v[174:177], v[190:193], v[24:27]
	v_mfma_f32_16x16x32_bf16 v[12:15], v[166:169], v[198:201], v[12:15]
	v_mfma_f32_16x16x32_bf16 v[8:11], v[174:177], v[198:201], v[8:11]
	v_mfma_f32_16x16x32_bf16 v[4:7], v[166:169], v[206:209], v[4:7]
	v_mfma_f32_16x16x32_bf16 v[0:3], v[174:177], v[206:209], v[0:3]
	v_mfma_f32_16x16x32_bf16 v[44:47], v[170:173], v[186:189], v[44:47]
	v_mfma_f32_16x16x32_bf16 v[40:43], v[178:181], v[186:189], v[40:43]
	v_mfma_f32_16x16x32_bf16 v[28:31], v[170:173], v[194:197], v[28:31]
	v_mfma_f32_16x16x32_bf16 v[24:27], v[178:181], v[194:197], v[24:27]
	v_mfma_f32_16x16x32_bf16 v[12:15], v[170:173], v[202:205], v[12:15]
	v_mfma_f32_16x16x32_bf16 v[8:11], v[178:181], v[202:205], v[8:11]
	v_mfma_f32_16x16x32_bf16 v[4:7], v[170:173], v[210:213], v[4:7]
	v_mfma_f32_16x16x32_bf16 v[0:3], v[178:181], v[210:213], v[0:3]
	s_setprio 0
	s_barrier
	s_add_i32 s51, 0, 0x18000
	s_add_i32 s54, 0, 0x1c000
	v_add_u32_e32 v162, s51, v146
	v_add_u32_e32 v178, s54, v146
	ds_read_b128 v[150:153], v162
	ds_read_b128 v[154:157], v162 offset:1024
	ds_read_b128 v[158:161], v162 offset:2048
	ds_read_b128 v[162:165], v162 offset:3072
	ds_read_b128 v[166:169], v178
	ds_read_b128 v[170:173], v178 offset:1024
	ds_read_b128 v[174:177], v178 offset:2048
	ds_read_b128 v[178:181], v178 offset:3072
	s_add_u32 s16, s22, 0xb0000
	s_addc_u32 s17, s23, 0
	s_mov_b32 m0, s33
	v_lshl_add_u64 v[222:223], s[16:17], 0, v[128:129]
	ds_read_b128 v[182:185], v149 offset:32768
	ds_read_b128 v[186:189], v149 offset:33792
	ds_read_b128 v[190:193], v149 offset:34816
	ds_read_b128 v[194:197], v149 offset:35840
	ds_read_b128 v[198:201], v149 offset:36864
	ds_read_b128 v[202:205], v149 offset:37888
	ds_read_b128 v[206:209], v149 offset:38912
	ds_read_b128 v[210:213], v149 offset:39936
	global_load_lds_dwordx4 v[222:223], off
	v_lshl_add_u64 v[222:223], s[16:17], 0, v[132:133]
	s_mov_b32 m0, s34
	s_nop 0
	global_load_lds_dwordx4 v[222:223], off
	s_waitcnt vmcnt(8)
	s_waitcnt lgkmcnt(0)
	s_barrier
	s_setprio 1
	s_waitcnt lgkmcnt(0)
	v_mfma_f32_16x16x32_bf16 v[124:127], v[150:153], v[182:185], v[124:127]
	v_mfma_f32_16x16x32_bf16 v[120:123], v[158:161], v[182:185], v[120:123]
	v_mfma_f32_16x16x32_bf16 v[116:119], v[150:153], v[190:193], v[116:119]
	v_mfma_f32_16x16x32_bf16 v[112:115], v[158:161], v[190:193], v[112:115]
	v_mfma_f32_16x16x32_bf16 v[100:103], v[150:153], v[198:201], v[100:103]
	v_mfma_f32_16x16x32_bf16 v[96:99], v[158:161], v[198:201], v[96:99]
	v_mfma_f32_16x16x32_bf16 v[84:87], v[150:153], v[206:209], v[84:87]
	v_mfma_f32_16x16x32_bf16 v[80:83], v[158:161], v[206:209], v[80:83]
	v_mfma_f32_16x16x32_bf16 v[124:127], v[154:157], v[186:189], v[124:127]
	v_mfma_f32_16x16x32_bf16 v[120:123], v[162:165], v[186:189], v[120:123]
	v_mfma_f32_16x16x32_bf16 v[116:119], v[154:157], v[194:197], v[116:119]
	v_mfma_f32_16x16x32_bf16 v[112:115], v[162:165], v[194:197], v[112:115]
	v_mfma_f32_16x16x32_bf16 v[100:103], v[154:157], v[202:205], v[100:103]
	v_mfma_f32_16x16x32_bf16 v[96:99], v[162:165], v[202:205], v[96:99]
	v_mfma_f32_16x16x32_bf16 v[84:87], v[154:157], v[210:213], v[84:87]
	v_mfma_f32_16x16x32_bf16 v[80:83], v[162:165], v[210:213], v[80:83]
	s_setprio 0
	s_setprio 1
	v_mfma_f32_16x16x32_bf16 v[108:111], v[166:169], v[182:185], v[108:111]
	v_mfma_f32_16x16x32_bf16 v[104:107], v[174:177], v[182:185], v[104:107]
	v_mfma_f32_16x16x32_bf16 v[92:95], v[166:169], v[190:193], v[92:95]
	v_mfma_f32_16x16x32_bf16 v[88:91], v[174:177], v[190:193], v[88:91]
	v_mfma_f32_16x16x32_bf16 v[76:79], v[166:169], v[198:201], v[76:79]
	v_mfma_f32_16x16x32_bf16 v[72:75], v[174:177], v[198:201], v[72:75]
	v_mfma_f32_16x16x32_bf16 v[68:71], v[166:169], v[206:209], v[68:71]
	v_mfma_f32_16x16x32_bf16 v[64:67], v[174:177], v[206:209], v[64:67]
	v_mfma_f32_16x16x32_bf16 v[108:111], v[170:173], v[186:189], v[108:111]
	v_mfma_f32_16x16x32_bf16 v[104:107], v[178:181], v[186:189], v[104:107]
	v_mfma_f32_16x16x32_bf16 v[92:95], v[170:173], v[194:197], v[92:95]
	v_mfma_f32_16x16x32_bf16 v[88:91], v[178:181], v[194:197], v[88:91]
	v_mfma_f32_16x16x32_bf16 v[76:79], v[170:173], v[202:205], v[76:79]
	v_mfma_f32_16x16x32_bf16 v[72:75], v[178:181], v[202:205], v[72:75]
	v_mfma_f32_16x16x32_bf16 v[68:71], v[170:173], v[210:213], v[68:71]
	v_mfma_f32_16x16x32_bf16 v[64:67], v[178:181], v[210:213], v[64:67]
	s_setprio 0
	s_barrier
; #define PG8_STAGE(bufoff, gbase, voff) do { _Pragma("unroll") for (int _i = 0; _i < 2; ++_i) \
;         __builtin_amdgcn_global_load_lds((const unsigned*)((const char*)(gbase) + (voff)[_i]), (LAS unsigned*)(lds + (bufoff) + ldsw + _i * 8192), 16, 0, 0); } while (0)
; #define PG8_LDA(dst, b, h) do { _Pragma("unroll") for (int m = 0; m < 4; ++m) _Pragma("unroll") for (int k = 0; k < 2; ++k) dst[m][k] = *(const LAS bf16x8*)(lds + PG8_SA(b, h) + aoff + m * 2048 + k * 1024); } while (0)
; #define PG8_MMA(ai, bj, At, Bt) do { __builtin_amdgcn_s_setprio(1); _Pragma("unroll") for (int m = 0; m < 4; ++m) _Pragma("unroll") for (int n = 0; n < 2; ++n) _Pragma("unroll") for (int k = 0; k < 2; ++k) \
;         acc[ai][bj][m][n] = __builtin_amdgcn_mfma_f32_16x16x32_bf16(Bt[n][k], At[m][k], acc[ai][bj][m][n], 0, 0, 0); __builtin_amdgcn_s_setprio(0); } while (0)
; #define PG8_WAIT_V(n) asm volatile("s_waitcnt vmcnt(" #n ")" ::: "memory")
; #define PG8_WAIT_L(n) asm volatile("s_waitcnt lgkmcnt(" #n ")" ::: "memory")
; #define PG8_BAR __builtin_amdgcn_s_barrier()
; #define PG8_SCHED __builtin_amdgcn_sched_barrier(0)
; template <class Epi>
; DI void gemm_phase(int wv, LAS unsigned char* lds, const Gemm g, const StaticOrder& S, const Epi& E) {
;     ...
;             PG8_LDA(At, 1, 1); PG8_STAGE(PG8_SB(1, 0), b3, voffB); PG8_STAGE(PG8_SB(1, 1), b3 + hB, voffB); PG8_STAGE(PG8_SA(1, 0), a3, voffA);
;             PG8_WAIT_V(8); PG8_WAIT_L(0); PG8_BAR; PG8_MMA(1, 0, At, B0); PG8_MMA(1, 1, At, B1); PG8_BAR; PG8_SCHED;
;         }
	s_add_i32 s16, s51, s29
	v_lshl_add_u64 v[214:215], v[214:215], 0, s[8:9]
	s_mov_b32 m0, s16
	ds_read_b128 v[182:185], v149 offset:49152
	ds_read_b128 v[186:189], v149 offset:50176
	ds_read_b128 v[190:193], v149 offset:51200
	ds_read_b128 v[194:197], v149 offset:52224
	ds_read_b128 v[198:201], v149 offset:53248
	ds_read_b128 v[202:205], v149 offset:54272
	ds_read_b128 v[206:209], v149 offset:55296
	ds_read_b128 v[210:213], v149 offset:56320
	global_load_lds_dwordx4 v[214:215], off
	s_add_i32 m0, s16, 0x2000
	s_add_u32 s16, s20, 0xb0080
	v_lshl_add_u64 v[214:215], v[216:217], 0, s[8:9]
	s_addc_u32 s17, s21, 0
	s_add_i32 s20, s54, s29
	global_load_lds_dwordx4 v[214:215], off
	v_lshl_add_u64 v[214:215], s[16:17], 0, v[130:131]
	s_mov_b32 m0, s20
	s_nop 0
	global_load_lds_dwordx4 v[214:215], off
	v_lshl_add_u64 v[214:215], s[16:17], 0, v[134:135]
	s_add_i32 m0, s20, 0x2000
	s_nop 0
	global_load_lds_dwordx4 v[214:215], off
	v_lshl_add_u64 v[214:215], v[218:219], 0, s[8:9]
	s_mov_b32 m0, s38
	s_nop 0
	global_load_lds_dwordx4 v[214:215], off
	v_lshl_add_u64 v[214:215], v[220:221], 0, s[8:9]
	s_mov_b32 m0, s39
	s_nop 0
	global_load_lds_dwordx4 v[214:215], off
	s_waitcnt vmcnt(8)
	s_waitcnt lgkmcnt(0)
	s_barrier
	s_setprio 1
	s_waitcnt lgkmcnt(0)
	v_mfma_f32_16x16x32_bf16 v[60:63], v[150:153], v[182:185], v[60:63]
	v_mfma_f32_16x16x32_bf16 v[56:59], v[158:161], v[182:185], v[56:59]
	v_mfma_f32_16x16x32_bf16 v[52:55], v[150:153], v[190:193], v[52:55]
	v_mfma_f32_16x16x32_bf16 v[48:51], v[158:161], v[190:193], v[48:51]
	v_mfma_f32_16x16x32_bf16 v[36:39], v[150:153], v[198:201], v[36:39]
	v_mfma_f32_16x16x32_bf16 v[32:35], v[158:161], v[198:201], v[32:35]
	v_mfma_f32_16x16x32_bf16 v[20:23], v[150:153], v[206:209], v[20:23]
	v_mfma_f32_16x16x32_bf16 v[16:19], v[158:161], v[206:209], v[16:19]
	v_mfma_f32_16x16x32_bf16 v[60:63], v[154:157], v[186:189], v[60:63]
	v_mfma_f32_16x16x32_bf16 v[56:59], v[162:165], v[186:189], v[56:59]
	v_mfma_f32_16x16x32_bf16 v[52:55], v[154:157], v[194:197], v[52:55]
	v_mfma_f32_16x16x32_bf16 v[48:51], v[162:165], v[194:197], v[48:51]
	v_mfma_f32_16x16x32_bf16 v[36:39], v[154:157], v[202:205], v[36:39]
	v_mfma_f32_16x16x32_bf16 v[32:35], v[162:165], v[202:205], v[32:35]
	v_mfma_f32_16x16x32_bf16 v[20:23], v[154:157], v[210:213], v[20:23]
	v_mfma_f32_16x16x32_bf16 v[16:19], v[162:165], v[210:213], v[16:19]
	s_setprio 0
	s_setprio 1
	v_mfma_f32_16x16x32_bf16 v[44:47], v[166:169], v[182:185], v[44:47]
	v_mfma_f32_16x16x32_bf16 v[40:43], v[174:177], v[182:185], v[40:43]
	v_mfma_f32_16x16x32_bf16 v[28:31], v[166:169], v[190:193], v[28:31]
	v_mfma_f32_16x16x32_bf16 v[24:27], v[174:177], v[190:193], v[24:27]
	v_mfma_f32_16x16x32_bf16 v[12:15], v[166:169], v[198:201], v[12:15]
	v_mfma_f32_16x16x32_bf16 v[8:11], v[174:177], v[198:201], v[8:11]
	v_mfma_f32_16x16x32_bf16 v[4:7], v[166:169], v[206:209], v[4:7]
	v_mfma_f32_16x16x32_bf16 v[0:3], v[174:177], v[206:209], v[0:3]
	v_mfma_f32_16x16x32_bf16 v[44:47], v[170:173], v[186:189], v[44:47]
	v_mfma_f32_16x16x32_bf16 v[40:43], v[178:181], v[186:189], v[40:43]
	v_mfma_f32_16x16x32_bf16 v[28:31], v[170:173], v[194:197], v[28:31]
	v_mfma_f32_16x16x32_bf16 v[24:27], v[178:181], v[194:197], v[24:27]
	v_mfma_f32_16x16x32_bf16 v[12:15], v[170:173], v[202:205], v[12:15]
	v_mfma_f32_16x16x32_bf16 v[8:11], v[178:181], v[202:205], v[8:11]
	v_mfma_f32_16x16x32_bf16 v[4:7], v[170:173], v[210:213], v[4:7]
	v_mfma_f32_16x16x32_bf16 v[0:3], v[178:181], v[210:213], v[0:3]
	s_setprio 0
	s_add_i32 s50, s50, 2
	s_add_u32 s46, s46, 0x100
	s_addc_u32 s47, s47, 0
	s_cmp_gt_u32 s50, 41
	s_mov_b64 s[16:17], s[18:19]
	s_barrier
	s_cbranch_scc0 .LBB0_3613
	s_and_b64 vcc, exec, s[10:11]
	s_cbranch_vccz .LBB0_3616
	s_barrier
